# stack2 + write-through (sc0 sc1) stores only in single-round phases ahead of grid barriers (ATT, COMB, G_br, G_out, G_dn, G_ple final)
# baseline (speedup 1.0000x reference)
; __device__ __forceinline__ int crow(int r, int hi) { return (r & 3) + 8 * (r >> 2) + 4 * hi; }
; __device__ __forceinline__ unsigned cvtpk(float lo, float hi) { unsigned r; asm volatile("v_cvt_pk_bf16_f32 %0, %1, %2" : "=v"(r) : "v"(lo), "v"(hi)); return r; }
; __device__ __forceinline__ void attn_unit(const bf16_t* __restrict__ Qb, const bf16_t* __restrict__ Kh, const bf16_t* __restrict__ Vh, bf16_t* __restrict__ Ob,
;                                           int NT, int ntw, int qpos0, int nvalid, char* lds) {
;     ...
;     asm volatile("s_waitcnt vmcnt(0)" ::: "memory");
;     __syncthreads();
;   }
;   if (hi == 0) li_l[r32] = l_reg; asm volatile("s_waitcnt lgkmcnt(0)" ::: "memory");
;   if (act) {
;     float rli[16];
; #pragma unroll
;     for (int r = 0; r < 16; ++r) rli[r] = __builtin_amdgcn_rcpf(li_l[crow(r, hi)]);
;     bf16_t* st = (bf16_t*)(lds + wid * 8192);
;     bf16_t* Ow = Ob + (long)(wid * QBLK) * LD;
; #pragma unroll
;     for (int hv = 0; hv < 2; ++hv) {
;       const int pr = r32 & 1; bf16_t* stl = st + pr * 128 + (r32 & ~1);
; #pragma unroll
;       for (int r = 0; r < 16; r += 2) { const int orow = crow(r, hi);
; #pragma unroll
;         for (int d0 = 0; d0 < 4; ++d0) { const float a = o[hv * 4 + d0][r] * rli[r], b = o[hv * 4 + d0][r + 1] * rli[r + 1];
;           const float snd = pr ? a : b; const float rcv = __int_as_float(__builtin_amdgcn_mov_dpp(__float_as_int(snd), 0xB1, 0xF, 0xF, true));
;           *reinterpret_cast<unsigned*>(stl + orow * 128 + d0 * 32) = cvtpk(pr ? rcv : a, pr ? b : rcv); } }
.LBB0_315:
	s_waitcnt vmcnt(0)
	s_add_i32 s10, s10, 64
	s_add_i32 s87, s87, 0x8000
	s_addk_i32 s38, 0x4000
	s_cmp_eq_u32 s41, s39
	s_waitcnt vmcnt(0) lgkmcnt(0)
	s_barrier
	s_cbranch_scc0 .LBB0_303
	s_and_saveexec_b64 s[12:13], s[42:43]
	ds_write_b32 v232, v242
	s_or_b64 exec, exec, s[12:13]
	s_waitcnt lgkmcnt(0)
	s_andn2_b64 vcc, exec, s[84:85]
	s_cbranch_vccnz .LBB0_284
	v_add_u32_e32 v138, v224, v178
	ds_read_b128 v[130:133], v138
	ds_read_b128 v[134:137], v138 offset:32
	v_lshl_add_u32 v152, v185, 13, 0
	v_lshrrev_b32_e32 v153, 3, v222
	s_lshl_b64 s[12:13], s[82:83], 1
	s_waitcnt lgkmcnt(1)
	v_rcp_f32_e32 v142, v130
	v_rcp_f32_e32 v143, v131
	v_rcp_f32_e32 v144, v132
	v_rcp_f32_e32 v145, v133
	ds_read_b128 v[130:133], v138 offset:64
	s_waitcnt lgkmcnt(1)
	v_rcp_f32_e32 v146, v134
	v_rcp_f32_e32 v147, v135
	v_rcp_f32_e32 v148, v136
	v_rcp_f32_e32 v149, v137
	ds_read_b128 v[134:137], v138 offset:96
	s_waitcnt lgkmcnt(1)
	v_rcp_f32_e32 v141, v133
	v_and_b32_e32 v133, 1, v220
	v_mul_f32_e32 v66, v66, v142
	v_mul_f32_e32 v67, v67, v143
	v_cmp_eq_u32_e32 vcc, 0, v133
	v_rcp_f32_e32 v140, v132
	v_lshl_add_u32 v132, v133, 8, v152
	v_cndmask_b32_e32 v133, v66, v67, vcc
	s_waitcnt lgkmcnt(0)
	v_rcp_f32_e32 v138, v134
	v_rcp_f32_e32 v134, v136
	v_and_b32_e32 v136, 30, v220
	v_mov_b32_dpp v133, v133 quad_perm:[1,0,3,2] row_mask:0xf bank_mask:0xf bound_ctrl:1
	v_rcp_f32_e32 v139, v135
	v_rcp_f32_e32 v135, v137
	v_lshlrev_b32_e32 v136, 1, v136
	v_lshlrev_b32_e32 v137, 10, v221
	v_cndmask_b32_e32 v66, v133, v66, vcc
	v_add3_u32 v136, v132, v136, v137
	v_cndmask_b32_e32 v67, v67, v133, vcc
	v_cvt_pk_bf16_f32 v66, v66, v67
	ds_write_b32 v136, v66
	v_mul_f32_e32 v66, v114, v142
	v_mul_f32_e32 v67, v115, v143
	v_cndmask_b32_e32 v114, v66, v67, vcc
	v_rcp_f32_e32 v150, v130
	v_rcp_f32_e32 v151, v131
	v_mov_b32_dpp v114, v114 quad_perm:[1,0,3,2] row_mask:0xf bank_mask:0xf bound_ctrl:1
	v_cndmask_b32_e32 v66, v114, v66, vcc
	v_cndmask_b32_e32 v67, v67, v114, vcc
	v_cvt_pk_bf16_f32 v66, v66, v67
	ds_write_b32 v136, v66 offset:64
	v_mul_f32_e32 v66, v98, v142
	v_mul_f32_e32 v67, v99, v143
	v_cndmask_b32_e32 v98, v66, v67, vcc
	v_lshlrev_b32_e32 v132, 1, v223
	v_lshlrev_b32_e32 v137, 8, v153
	v_mov_b32_dpp v98, v98 quad_perm:[1,0,3,2] row_mask:0xf bank_mask:0xf bound_ctrl:1
	v_cndmask_b32_e32 v66, v98, v66, vcc
	v_cndmask_b32_e32 v67, v67, v98, vcc
	v_cvt_pk_bf16_f32 v66, v66, v67
	ds_write_b32 v136, v66 offset:128
	v_mul_f32_e32 v66, v82, v142
	v_mul_f32_e32 v67, v83, v143
	v_cndmask_b32_e32 v82, v66, v67, vcc
	v_and_b32_e32 v132, 0x70, v132
	v_add3_u32 v137, v152, v137, v132
	v_mov_b32_dpp v82, v82 quad_perm:[1,0,3,2] row_mask:0xf bank_mask:0xf bound_ctrl:1
	v_cndmask_b32_e32 v66, v82, v66, vcc
	v_cndmask_b32_e32 v67, v67, v82, vcc
	v_cvt_pk_bf16_f32 v66, v66, v67
	ds_write_b32 v136, v66 offset:192
	v_mul_f32_e32 v66, v68, v144
	v_mul_f32_e32 v67, v69, v145
	v_cndmask_b32_e32 v68, v66, v67, vcc
	s_add_u32 s12, s96, s12
	v_ashrrev_i32_e32 v185, 31, v184
	v_mov_b32_dpp v68, v68 quad_perm:[1,0,3,2] row_mask:0xf bank_mask:0xf bound_ctrl:1
	v_cndmask_b32_e32 v66, v68, v66, vcc
	v_cndmask_b32_e32 v67, v67, v68, vcc
	v_cvt_pk_bf16_f32 v66, v66, v67
	ds_write_b32 v136, v66 offset:512
	v_mul_f32_e32 v66, v116, v144
	v_mul_f32_e32 v67, v117, v145
	v_cndmask_b32_e32 v68, v66, v67, vcc
	s_addc_u32 s13, s97, s13
	v_lshlrev_b64 v[130:131], 12, v[184:185]
	v_mov_b32_dpp v68, v68 quad_perm:[1,0,3,2] row_mask:0xf bank_mask:0xf bound_ctrl:1
	v_cndmask_b32_e32 v66, v68, v66, vcc
	v_cndmask_b32_e32 v67, v67, v68, vcc
	v_cvt_pk_bf16_f32 v66, v66, v67
	ds_write_b32 v136, v66 offset:576
	v_mul_f32_e32 v66, v100, v144
	v_mul_f32_e32 v67, v101, v145
	v_cndmask_b32_e32 v68, v66, v67, vcc
	v_lshl_add_u64 v[130:131], s[12:13], 0, v[130:131]
	v_lshlrev_b32_e32 v178, 12, v153
	v_mov_b32_dpp v68, v68 quad_perm:[1,0,3,2] row_mask:0xf bank_mask:0xf bound_ctrl:1
	v_cndmask_b32_e32 v66, v68, v66, vcc
	v_cndmask_b32_e32 v67, v67, v68, vcc
	v_cvt_pk_bf16_f32 v66, v66, v67
	ds_write_b32 v136, v66 offset:640
	v_mul_f32_e32 v66, v84, v144
	v_mul_f32_e32 v67, v85, v145
	v_cndmask_b32_e32 v68, v66, v67, vcc
	v_mov_b32_e32 v133, v179
	v_mul_f32_e32 v50, v50, v142
	v_mov_b32_dpp v68, v68 quad_perm:[1,0,3,2] row_mask:0xf bank_mask:0xf bound_ctrl:1
	v_cndmask_b32_e32 v66, v68, v66, vcc
	v_cndmask_b32_e32 v67, v67, v68, vcc
	v_cvt_pk_bf16_f32 v66, v66, v67
	ds_write_b32 v136, v66 offset:704
	v_mul_f32_e32 v66, v70, v146
	v_mul_f32_e32 v67, v71, v147
	v_cndmask_b32_e32 v68, v66, v67, vcc
	v_mul_f32_e32 v51, v51, v143
	v_mul_f32_e32 v34, v34, v142
	v_mov_b32_dpp v68, v68 quad_perm:[1,0,3,2] row_mask:0xf bank_mask:0xf bound_ctrl:1
	v_cndmask_b32_e32 v66, v68, v66, vcc
	v_cndmask_b32_e32 v67, v67, v68, vcc
	v_cvt_pk_bf16_f32 v66, v66, v67
	ds_write_b32 v136, v66 offset:2048
	v_mul_f32_e32 v66, v118, v146
	v_mul_f32_e32 v67, v119, v147
	v_cndmask_b32_e32 v68, v66, v67, vcc
	v_mul_f32_e32 v35, v35, v143
	v_mul_f32_e32 v18, v18, v142
	v_mov_b32_dpp v68, v68 quad_perm:[1,0,3,2] row_mask:0xf bank_mask:0xf bound_ctrl:1
	v_cndmask_b32_e32 v66, v68, v66, vcc
	v_cndmask_b32_e32 v67, v67, v68, vcc
	v_cvt_pk_bf16_f32 v66, v66, v67
	ds_write_b32 v136, v66 offset:2112
	v_mul_f32_e32 v66, v102, v146
	v_mul_f32_e32 v67, v103, v147
	v_cndmask_b32_e32 v68, v66, v67, vcc
	v_mul_f32_e32 v19, v19, v143
	v_mul_f32_e32 v2, v2, v142
	v_mov_b32_dpp v68, v68 quad_perm:[1,0,3,2] row_mask:0xf bank_mask:0xf bound_ctrl:1
	v_cndmask_b32_e32 v66, v68, v66, vcc
	v_cndmask_b32_e32 v67, v67, v68, vcc
	v_cvt_pk_bf16_f32 v66, v66, v67
	ds_write_b32 v136, v66 offset:2176
	v_mul_f32_e32 v66, v86, v146
	v_mul_f32_e32 v67, v87, v147
; __device__ __forceinline__ int crow(int r, int hi) { return (r & 3) + 8 * (r >> 2) + 4 * hi; }
; __device__ __forceinline__ unsigned cvtpk(float lo, float hi) { unsigned r; asm volatile("v_cvt_pk_bf16_f32 %0, %1, %2" : "=v"(r) : "v"(lo), "v"(hi)); return r; }
; __device__ __forceinline__ void attn_unit(const bf16_t* __restrict__ Qb, const bf16_t* __restrict__ Kh, const bf16_t* __restrict__ Vh, bf16_t* __restrict__ Ob,
;                                           int NT, int ntw, int qpos0, int nvalid, char* lds) {
;     ...
;     for (int hv = 0; hv < 2; ++hv) {
;       const int pr = r32 & 1; bf16_t* stl = st + pr * 128 + (r32 & ~1);
; #pragma unroll
;       for (int r = 0; r < 16; r += 2) { const int orow = crow(r, hi);
; #pragma unroll
;         for (int d0 = 0; d0 < 4; ++d0) { const float a = o[hv * 4 + d0][r] * rli[r], b = o[hv * 4 + d0][r + 1] * rli[r + 1];
;           const float snd = pr ? a : b; const float rcv = __int_as_float(__builtin_amdgcn_mov_dpp(__float_as_int(snd), 0xB1, 0xF, 0xF, true));
;           *reinterpret_cast<unsigned*>(stl + orow * 128 + d0 * 32) = cvtpk(pr ? rcv : a, pr ? b : rcv); } }
	v_cndmask_b32_e32 v68, v66, v67, vcc
	v_mul_f32_e32 v3, v3, v143
	s_nop 0
	v_mov_b32_dpp v68, v68 quad_perm:[1,0,3,2] row_mask:0xf bank_mask:0xf bound_ctrl:1
	v_cndmask_b32_e32 v66, v68, v66, vcc
	v_cndmask_b32_e32 v67, v67, v68, vcc
	v_cvt_pk_bf16_f32 v66, v66, v67
	ds_write_b32 v136, v66 offset:2240
	v_mul_f32_e32 v66, v72, v148
	v_mul_f32_e32 v67, v73, v149
	v_cndmask_b32_e32 v68, v66, v67, vcc
	s_nop 1
	v_mov_b32_dpp v68, v68 quad_perm:[1,0,3,2] row_mask:0xf bank_mask:0xf bound_ctrl:1
	v_cndmask_b32_e32 v66, v68, v66, vcc
	v_cndmask_b32_e32 v67, v67, v68, vcc
	v_cvt_pk_bf16_f32 v66, v66, v67
	ds_write_b32 v136, v66 offset:2560
	v_mul_f32_e32 v66, v120, v148
	v_mul_f32_e32 v67, v121, v149
	v_cndmask_b32_e32 v68, v66, v67, vcc
	s_nop 1
	v_mov_b32_dpp v68, v68 quad_perm:[1,0,3,2] row_mask:0xf bank_mask:0xf bound_ctrl:1
	v_cndmask_b32_e32 v66, v68, v66, vcc
	v_cndmask_b32_e32 v67, v67, v68, vcc
	v_cvt_pk_bf16_f32 v66, v66, v67
	ds_write_b32 v136, v66 offset:2624
	v_mul_f32_e32 v66, v104, v148
	v_mul_f32_e32 v67, v105, v149
	v_cndmask_b32_e32 v68, v66, v67, vcc
	s_nop 1
	v_mov_b32_dpp v68, v68 quad_perm:[1,0,3,2] row_mask:0xf bank_mask:0xf bound_ctrl:1
	v_cndmask_b32_e32 v66, v68, v66, vcc
	v_cndmask_b32_e32 v67, v67, v68, vcc
	v_cvt_pk_bf16_f32 v66, v66, v67
	ds_write_b32 v136, v66 offset:2688
	v_mul_f32_e32 v66, v88, v148
	v_mul_f32_e32 v67, v89, v149
	v_cndmask_b32_e32 v68, v66, v67, vcc
	s_nop 1
	v_mov_b32_dpp v68, v68 quad_perm:[1,0,3,2] row_mask:0xf bank_mask:0xf bound_ctrl:1
	v_cndmask_b32_e32 v66, v68, v66, vcc
	v_cndmask_b32_e32 v67, v67, v68, vcc
	v_cvt_pk_bf16_f32 v66, v66, v67
	ds_write_b32 v136, v66 offset:2752
	v_mul_f32_e32 v66, v74, v150
	v_mul_f32_e32 v67, v75, v151
	v_cndmask_b32_e32 v68, v66, v67, vcc
	s_nop 1
	v_mov_b32_dpp v68, v68 quad_perm:[1,0,3,2] row_mask:0xf bank_mask:0xf bound_ctrl:1
	v_cndmask_b32_e32 v66, v68, v66, vcc
	v_cndmask_b32_e32 v67, v67, v68, vcc
	v_cvt_pk_bf16_f32 v66, v66, v67
	ds_write_b32 v136, v66 offset:4096
	v_mul_f32_e32 v66, v122, v150
	v_mul_f32_e32 v67, v123, v151
	v_cndmask_b32_e32 v68, v66, v67, vcc
	s_nop 1
	v_mov_b32_dpp v68, v68 quad_perm:[1,0,3,2] row_mask:0xf bank_mask:0xf bound_ctrl:1
	v_cndmask_b32_e32 v66, v68, v66, vcc
	v_cndmask_b32_e32 v67, v67, v68, vcc
	v_cvt_pk_bf16_f32 v66, v66, v67
	ds_write_b32 v136, v66 offset:4160
	v_mul_f32_e32 v66, v106, v150
	v_mul_f32_e32 v67, v107, v151
	v_cndmask_b32_e32 v68, v66, v67, vcc
	s_nop 1
	v_mov_b32_dpp v68, v68 quad_perm:[1,0,3,2] row_mask:0xf bank_mask:0xf bound_ctrl:1
	v_cndmask_b32_e32 v66, v68, v66, vcc
	v_cndmask_b32_e32 v67, v67, v68, vcc
	v_cvt_pk_bf16_f32 v66, v66, v67
	ds_write_b32 v136, v66 offset:4224
	v_mul_f32_e32 v66, v90, v150
	v_mul_f32_e32 v67, v91, v151
	v_cndmask_b32_e32 v68, v66, v67, vcc
	s_nop 1
	v_mov_b32_dpp v68, v68 quad_perm:[1,0,3,2] row_mask:0xf bank_mask:0xf bound_ctrl:1
	v_cndmask_b32_e32 v66, v68, v66, vcc
	v_cndmask_b32_e32 v67, v67, v68, vcc
	v_cvt_pk_bf16_f32 v66, v66, v67
	ds_write_b32 v136, v66 offset:4288
	v_mul_f32_e32 v66, v76, v140
	v_mul_f32_e32 v67, v77, v141
	v_cndmask_b32_e32 v68, v66, v67, vcc
	s_nop 1
	v_mov_b32_dpp v68, v68 quad_perm:[1,0,3,2] row_mask:0xf bank_mask:0xf bound_ctrl:1
	v_cndmask_b32_e32 v66, v68, v66, vcc
	v_cndmask_b32_e32 v67, v67, v68, vcc
	v_cvt_pk_bf16_f32 v66, v66, v67
	ds_write_b32 v136, v66 offset:4608
	v_mul_f32_e32 v66, v124, v140
	v_mul_f32_e32 v67, v125, v141
	v_cndmask_b32_e32 v68, v66, v67, vcc
	s_nop 1
	v_mov_b32_dpp v68, v68 quad_perm:[1,0,3,2] row_mask:0xf bank_mask:0xf bound_ctrl:1
	v_cndmask_b32_e32 v66, v68, v66, vcc
	v_cndmask_b32_e32 v67, v67, v68, vcc
	v_cvt_pk_bf16_f32 v66, v66, v67
	ds_write_b32 v136, v66 offset:4672
	v_mul_f32_e32 v66, v108, v140
	v_mul_f32_e32 v67, v109, v141
	v_cndmask_b32_e32 v68, v66, v67, vcc
	s_nop 1
	v_mov_b32_dpp v68, v68 quad_perm:[1,0,3,2] row_mask:0xf bank_mask:0xf bound_ctrl:1
	v_cndmask_b32_e32 v66, v68, v66, vcc
	v_cndmask_b32_e32 v67, v67, v68, vcc
	v_cvt_pk_bf16_f32 v66, v66, v67
	ds_write_b32 v136, v66 offset:4736
	v_mul_f32_e32 v66, v92, v140
	v_mul_f32_e32 v67, v93, v141
	v_cndmask_b32_e32 v68, v66, v67, vcc
	s_nop 1
	v_mov_b32_dpp v68, v68 quad_perm:[1,0,3,2] row_mask:0xf bank_mask:0xf bound_ctrl:1
	v_cndmask_b32_e32 v66, v68, v66, vcc
	v_cndmask_b32_e32 v67, v67, v68, vcc
	v_cvt_pk_bf16_f32 v66, v66, v67
	ds_write_b32 v136, v66 offset:4800
	v_mul_f32_e32 v66, v78, v138
	v_mul_f32_e32 v67, v79, v139
	v_cndmask_b32_e32 v68, v66, v67, vcc
	s_nop 1
	v_mov_b32_dpp v68, v68 quad_perm:[1,0,3,2] row_mask:0xf bank_mask:0xf bound_ctrl:1
	v_cndmask_b32_e32 v66, v68, v66, vcc
	v_cndmask_b32_e32 v67, v67, v68, vcc
	v_cvt_pk_bf16_f32 v66, v66, v67
	ds_write_b32 v136, v66 offset:6144
	v_mul_f32_e32 v66, v126, v138
	v_mul_f32_e32 v67, v127, v139
	v_cndmask_b32_e32 v68, v66, v67, vcc
	s_nop 1
	v_mov_b32_dpp v68, v68 quad_perm:[1,0,3,2] row_mask:0xf bank_mask:0xf bound_ctrl:1
	v_cndmask_b32_e32 v66, v68, v66, vcc
	v_cndmask_b32_e32 v67, v67, v68, vcc
	v_cvt_pk_bf16_f32 v66, v66, v67
	ds_write_b32 v136, v66 offset:6208
	v_mul_f32_e32 v66, v110, v138
	v_mul_f32_e32 v67, v111, v139
	v_cndmask_b32_e32 v68, v66, v67, vcc
	s_nop 1
	v_mov_b32_dpp v68, v68 quad_perm:[1,0,3,2] row_mask:0xf bank_mask:0xf bound_ctrl:1
	v_cndmask_b32_e32 v66, v68, v66, vcc
	v_cndmask_b32_e32 v67, v67, v68, vcc
	v_cvt_pk_bf16_f32 v66, v66, v67
	ds_write_b32 v136, v66 offset:6272
	v_mul_f32_e32 v66, v94, v138
	v_mul_f32_e32 v67, v95, v139
	v_cndmask_b32_e32 v68, v66, v67, vcc
	s_nop 1
	v_mov_b32_dpp v68, v68 quad_perm:[1,0,3,2] row_mask:0xf bank_mask:0xf bound_ctrl:1
	v_cndmask_b32_e32 v66, v68, v66, vcc
	v_cndmask_b32_e32 v67, v67, v68, vcc
; __device__ __forceinline__ int crow(int r, int hi) { return (r & 3) + 8 * (r >> 2) + 4 * hi; }
; __device__ __forceinline__ unsigned cvtpk(float lo, float hi) { unsigned r; asm volatile("v_cvt_pk_bf16_f32 %0, %1, %2" : "=v"(r) : "v"(lo), "v"(hi)); return r; }
; __device__ __forceinline__ void attn_unit(const bf16_t* __restrict__ Qb, const bf16_t* __restrict__ Kh, const bf16_t* __restrict__ Vh, bf16_t* __restrict__ Ob,
;                                           int NT, int ntw, int qpos0, int nvalid, char* lds) {
;     ...
;     for (int hv = 0; hv < 2; ++hv) {
;       const int pr = r32 & 1; bf16_t* stl = st + pr * 128 + (r32 & ~1);
; #pragma unroll
;       for (int r = 0; r < 16; r += 2) { const int orow = crow(r, hi);
; #pragma unroll
;         for (int d0 = 0; d0 < 4; ++d0) { const float a = o[hv * 4 + d0][r] * rli[r], b = o[hv * 4 + d0][r + 1] * rli[r + 1];
;           const float snd = pr ? a : b; const float rcv = __int_as_float(__builtin_amdgcn_mov_dpp(__float_as_int(snd), 0xB1, 0xF, 0xF, true));
;           *reinterpret_cast<unsigned*>(stl + orow * 128 + d0 * 32) = cvtpk(pr ? rcv : a, pr ? b : rcv); } }
;       asm volatile("s_waitcnt lgkmcnt(0)" ::: "memory");
; #pragma unroll
;       for (int i = 0; i < 4; ++i) { const int row = i * 8 + (lane >> 3), ch = lane & 7; const u32x4 v = *(const u32x4*)(st + row * 128 + ch * 8), v2 = *(const u32x4*)(st + row * 128 + 64 + ch * 8);
;         *(u32x4*)(Ow + (long)row * LD + hv * 128 + ch * 8) = v; *(u32x4*)(Ow + (long)row * LD + hv * 128 + 64 + ch * 8) = v2; }
	v_cvt_pk_bf16_f32 v66, v66, v67
	ds_write_b32 v136, v66 offset:6336
	v_mul_f32_e32 v66, v80, v134
	v_mul_f32_e32 v67, v81, v135
	v_cndmask_b32_e32 v68, v66, v67, vcc
	s_nop 1
	v_mov_b32_dpp v68, v68 quad_perm:[1,0,3,2] row_mask:0xf bank_mask:0xf bound_ctrl:1
	v_cndmask_b32_e32 v66, v68, v66, vcc
	v_cndmask_b32_e32 v67, v67, v68, vcc
	v_cvt_pk_bf16_f32 v66, v66, v67
	ds_write_b32 v136, v66 offset:6656
	v_mul_f32_e32 v66, v128, v134
	v_mul_f32_e32 v67, v129, v135
	v_cndmask_b32_e32 v68, v66, v67, vcc
	s_nop 1
	v_mov_b32_dpp v68, v68 quad_perm:[1,0,3,2] row_mask:0xf bank_mask:0xf bound_ctrl:1
	v_cndmask_b32_e32 v66, v68, v66, vcc
	v_cndmask_b32_e32 v67, v67, v68, vcc
	v_cvt_pk_bf16_f32 v66, v66, v67
	ds_write_b32 v136, v66 offset:6720
	v_mul_f32_e32 v66, v112, v134
	v_mul_f32_e32 v67, v113, v135
	v_cndmask_b32_e32 v68, v66, v67, vcc
	s_nop 1
	v_mov_b32_dpp v68, v68 quad_perm:[1,0,3,2] row_mask:0xf bank_mask:0xf bound_ctrl:1
	v_cndmask_b32_e32 v66, v68, v66, vcc
	v_cndmask_b32_e32 v67, v67, v68, vcc
	v_cvt_pk_bf16_f32 v66, v66, v67
	ds_write_b32 v136, v66 offset:6784
	v_mul_f32_e32 v66, v96, v134
	v_mul_f32_e32 v67, v97, v135
	v_cndmask_b32_e32 v68, v66, v67, vcc
	s_nop 1
	v_mov_b32_dpp v68, v68 quad_perm:[1,0,3,2] row_mask:0xf bank_mask:0xf bound_ctrl:1
	v_cndmask_b32_e32 v66, v68, v66, vcc
	v_cndmask_b32_e32 v67, v67, v68, vcc
	v_cvt_pk_bf16_f32 v66, v66, v67
	ds_write_b32 v136, v66 offset:6848
	s_waitcnt lgkmcnt(0)
	ds_read_b128 v[68:71], v137
	ds_read_b128 v[72:75], v137 offset:128
	v_lshl_add_u64 v[66:67], v[130:131], 0, v[178:179]
	v_lshl_add_u64 v[66:67], v[66:67], 0, v[132:133]
	s_waitcnt lgkmcnt(1)
	global_store_dwordx4 v[66:67], v[68:71], off sc0 sc1
	s_waitcnt lgkmcnt(0)
	global_store_dwordx4 v[66:67], v[72:75], off offset:128 sc0 sc1
	v_or_b32_e32 v68, 8, v153
	v_lshlrev_b32_e32 v69, 8, v68
	v_add3_u32 v82, v152, v69, v132
	ds_read_b128 v[70:73], v82
	ds_read_b128 v[74:77], v82 offset:128
	v_lshlrev_b32_e32 v178, 12, v68
	v_lshl_add_u64 v[68:69], v[130:131], 0, v[178:179]
	v_lshl_add_u64 v[68:69], v[68:69], 0, v[132:133]
	s_waitcnt lgkmcnt(1)
	global_store_dwordx4 v[68:69], v[70:73], off sc0 sc1
	s_waitcnt lgkmcnt(0)
	global_store_dwordx4 v[68:69], v[74:77], off offset:128 sc0 sc1
	v_or_b32_e32 v70, 16, v153
	v_lshlrev_b32_e32 v71, 8, v70
	v_add3_u32 v83, v152, v71, v132
	ds_read_b128 v[72:75], v83
	ds_read_b128 v[76:79], v83 offset:128
	v_lshlrev_b32_e32 v178, 12, v70
	v_lshl_add_u64 v[70:71], v[130:131], 0, v[178:179]
	v_lshl_add_u64 v[70:71], v[70:71], 0, v[132:133]
	s_waitcnt lgkmcnt(1)
	global_store_dwordx4 v[70:71], v[72:75], off sc0 sc1
	s_waitcnt lgkmcnt(0)
	global_store_dwordx4 v[70:71], v[76:79], off offset:128 sc0 sc1
	v_or_b32_e32 v72, 24, v153
	v_lshlrev_b32_e32 v73, 8, v72
	v_add3_u32 v84, v152, v73, v132
	ds_read_b128 v[74:77], v84
	ds_read_b128 v[78:81], v84 offset:128
	v_lshlrev_b32_e32 v178, 12, v72
	v_lshl_add_u64 v[72:73], v[130:131], 0, v[178:179]
	v_lshl_add_u64 v[72:73], v[72:73], 0, v[132:133]
	s_waitcnt lgkmcnt(1)
	global_store_dwordx4 v[72:73], v[74:77], off sc0 sc1
	s_waitcnt lgkmcnt(0)
	global_store_dwordx4 v[72:73], v[78:81], off offset:128 sc0 sc1
	v_cndmask_b32_e32 v74, v50, v51, vcc
	s_waitcnt lgkmcnt(0)
	s_nop 1
	v_mov_b32_dpp v74, v74 quad_perm:[1,0,3,2] row_mask:0xf bank_mask:0xf bound_ctrl:1
	v_cndmask_b32_e32 v50, v74, v50, vcc
	v_cndmask_b32_e32 v51, v51, v74, vcc
	v_cvt_pk_bf16_f32 v50, v50, v51
	ds_write_b32 v136, v50
	v_cndmask_b32_e32 v50, v34, v35, vcc
	s_nop 1
	v_mov_b32_dpp v50, v50 quad_perm:[1,0,3,2] row_mask:0xf bank_mask:0xf bound_ctrl:1
	v_cndmask_b32_e32 v34, v50, v34, vcc
	v_cndmask_b32_e32 v35, v35, v50, vcc
	v_cvt_pk_bf16_f32 v34, v34, v35
	ds_write_b32 v136, v34 offset:64
	v_cndmask_b32_e32 v34, v18, v19, vcc
	s_nop 1
	v_mov_b32_dpp v34, v34 quad_perm:[1,0,3,2] row_mask:0xf bank_mask:0xf bound_ctrl:1
	v_cndmask_b32_e32 v18, v34, v18, vcc
	v_cndmask_b32_e32 v19, v19, v34, vcc
	v_cvt_pk_bf16_f32 v18, v18, v19
	ds_write_b32 v136, v18 offset:128
	v_cndmask_b32_e32 v18, v2, v3, vcc
	s_nop 1
	v_mov_b32_dpp v18, v18 quad_perm:[1,0,3,2] row_mask:0xf bank_mask:0xf bound_ctrl:1
	v_cndmask_b32_e32 v2, v18, v2, vcc
	v_cndmask_b32_e32 v3, v3, v18, vcc
	v_cvt_pk_bf16_f32 v2, v2, v3
	ds_write_b32 v136, v2 offset:192
	v_mul_f32_e32 v2, v52, v144
	v_mul_f32_e32 v3, v53, v145
	v_cndmask_b32_e32 v18, v2, v3, vcc
	s_nop 1
	v_mov_b32_dpp v18, v18 quad_perm:[1,0,3,2] row_mask:0xf bank_mask:0xf bound_ctrl:1
	v_cndmask_b32_e32 v2, v18, v2, vcc
	v_cndmask_b32_e32 v3, v3, v18, vcc
	v_cvt_pk_bf16_f32 v2, v2, v3
	ds_write_b32 v136, v2 offset:512
	v_mul_f32_e32 v2, v36, v144
	v_mul_f32_e32 v3, v37, v145
	v_cndmask_b32_e32 v18, v2, v3, vcc
	s_nop 1
	v_mov_b32_dpp v18, v18 quad_perm:[1,0,3,2] row_mask:0xf bank_mask:0xf bound_ctrl:1
	v_cndmask_b32_e32 v2, v18, v2, vcc
	v_cndmask_b32_e32 v3, v3, v18, vcc
	v_cvt_pk_bf16_f32 v2, v2, v3
	ds_write_b32 v136, v2 offset:576
	v_mul_f32_e32 v2, v20, v144
	v_mul_f32_e32 v3, v21, v145
	v_cndmask_b32_e32 v18, v2, v3, vcc
	s_nop 1
	v_mov_b32_dpp v18, v18 quad_perm:[1,0,3,2] row_mask:0xf bank_mask:0xf bound_ctrl:1
	v_cndmask_b32_e32 v2, v18, v2, vcc
	v_cndmask_b32_e32 v3, v3, v18, vcc
	v_cvt_pk_bf16_f32 v2, v2, v3
	ds_write_b32 v136, v2 offset:640
	v_mul_f32_e32 v2, v4, v144
	v_mul_f32_e32 v3, v5, v145
	v_cndmask_b32_e32 v4, v2, v3, vcc
	s_nop 1
	v_mov_b32_dpp v4, v4 quad_perm:[1,0,3,2] row_mask:0xf bank_mask:0xf bound_ctrl:1
	v_cndmask_b32_e32 v2, v4, v2, vcc
	v_cndmask_b32_e32 v3, v3, v4, vcc
	v_cvt_pk_bf16_f32 v2, v2, v3
	ds_write_b32 v136, v2 offset:704
	v_mul_f32_e32 v2, v54, v146
	v_mul_f32_e32 v3, v55, v147
	v_cndmask_b32_e32 v4, v2, v3, vcc
	s_nop 1
; __device__ __forceinline__ int crow(int r, int hi) { return (r & 3) + 8 * (r >> 2) + 4 * hi; }
; __device__ __forceinline__ unsigned cvtpk(float lo, float hi) { unsigned r; asm volatile("v_cvt_pk_bf16_f32 %0, %1, %2" : "=v"(r) : "v"(lo), "v"(hi)); return r; }
; __device__ __forceinline__ void attn_unit(const bf16_t* __restrict__ Qb, const bf16_t* __restrict__ Kh, const bf16_t* __restrict__ Vh, bf16_t* __restrict__ Ob,
;                                           int NT, int ntw, int qpos0, int nvalid, char* lds) {
;     ...
;     for (int hv = 0; hv < 2; ++hv) {
;       const int pr = r32 & 1; bf16_t* stl = st + pr * 128 + (r32 & ~1);
; #pragma unroll
;       for (int r = 0; r < 16; r += 2) { const int orow = crow(r, hi);
; #pragma unroll
;         for (int d0 = 0; d0 < 4; ++d0) { const float a = o[hv * 4 + d0][r] * rli[r], b = o[hv * 4 + d0][r + 1] * rli[r + 1];
;           const float snd = pr ? a : b; const float rcv = __int_as_float(__builtin_amdgcn_mov_dpp(__float_as_int(snd), 0xB1, 0xF, 0xF, true));
;           *reinterpret_cast<unsigned*>(stl + orow * 128 + d0 * 32) = cvtpk(pr ? rcv : a, pr ? b : rcv); } }
	v_mov_b32_dpp v4, v4 quad_perm:[1,0,3,2] row_mask:0xf bank_mask:0xf bound_ctrl:1
	v_cndmask_b32_e32 v2, v4, v2, vcc
	v_cndmask_b32_e32 v3, v3, v4, vcc
	v_cvt_pk_bf16_f32 v2, v2, v3
	ds_write_b32 v136, v2 offset:2048
	v_mul_f32_e32 v2, v38, v146
	v_mul_f32_e32 v3, v39, v147
	v_cndmask_b32_e32 v4, v2, v3, vcc
	s_nop 1
	v_mov_b32_dpp v4, v4 quad_perm:[1,0,3,2] row_mask:0xf bank_mask:0xf bound_ctrl:1
	v_cndmask_b32_e32 v2, v4, v2, vcc
	v_cndmask_b32_e32 v3, v3, v4, vcc
	v_cvt_pk_bf16_f32 v2, v2, v3
	ds_write_b32 v136, v2 offset:2112
	v_mul_f32_e32 v2, v22, v146
	v_mul_f32_e32 v3, v23, v147
	v_cndmask_b32_e32 v4, v2, v3, vcc
	s_nop 1
	v_mov_b32_dpp v4, v4 quad_perm:[1,0,3,2] row_mask:0xf bank_mask:0xf bound_ctrl:1
	v_cndmask_b32_e32 v2, v4, v2, vcc
	v_cndmask_b32_e32 v3, v3, v4, vcc
	v_cvt_pk_bf16_f32 v2, v2, v3
	ds_write_b32 v136, v2 offset:2176
	v_mul_f32_e32 v2, v6, v146
	v_mul_f32_e32 v3, v7, v147
	v_cndmask_b32_e32 v4, v2, v3, vcc
	s_nop 1
	v_mov_b32_dpp v4, v4 quad_perm:[1,0,3,2] row_mask:0xf bank_mask:0xf bound_ctrl:1
	v_cndmask_b32_e32 v2, v4, v2, vcc
	v_cndmask_b32_e32 v3, v3, v4, vcc
	v_cvt_pk_bf16_f32 v2, v2, v3
	ds_write_b32 v136, v2 offset:2240
	v_mul_f32_e32 v2, v56, v148
	v_mul_f32_e32 v3, v57, v149
	v_cndmask_b32_e32 v4, v2, v3, vcc
	s_nop 1
	v_mov_b32_dpp v4, v4 quad_perm:[1,0,3,2] row_mask:0xf bank_mask:0xf bound_ctrl:1
	v_cndmask_b32_e32 v2, v4, v2, vcc
	v_cndmask_b32_e32 v3, v3, v4, vcc
	v_cvt_pk_bf16_f32 v2, v2, v3
	ds_write_b32 v136, v2 offset:2560
	v_mul_f32_e32 v2, v40, v148
	v_mul_f32_e32 v3, v41, v149
	v_cndmask_b32_e32 v4, v2, v3, vcc
	s_nop 1
	v_mov_b32_dpp v4, v4 quad_perm:[1,0,3,2] row_mask:0xf bank_mask:0xf bound_ctrl:1
	v_cndmask_b32_e32 v2, v4, v2, vcc
	v_cndmask_b32_e32 v3, v3, v4, vcc
	v_cvt_pk_bf16_f32 v2, v2, v3
	ds_write_b32 v136, v2 offset:2624
	v_mul_f32_e32 v2, v24, v148
	v_mul_f32_e32 v3, v25, v149
	v_cndmask_b32_e32 v4, v2, v3, vcc
	s_nop 1
	v_mov_b32_dpp v4, v4 quad_perm:[1,0,3,2] row_mask:0xf bank_mask:0xf bound_ctrl:1
	v_cndmask_b32_e32 v2, v4, v2, vcc
	v_cndmask_b32_e32 v3, v3, v4, vcc
	v_cvt_pk_bf16_f32 v2, v2, v3
	ds_write_b32 v136, v2 offset:2688
	v_mul_f32_e32 v2, v8, v148
	v_mul_f32_e32 v3, v9, v149
	v_cndmask_b32_e32 v4, v2, v3, vcc
	s_nop 1
	v_mov_b32_dpp v4, v4 quad_perm:[1,0,3,2] row_mask:0xf bank_mask:0xf bound_ctrl:1
	v_cndmask_b32_e32 v2, v4, v2, vcc
	v_cndmask_b32_e32 v3, v3, v4, vcc
	v_cvt_pk_bf16_f32 v2, v2, v3
	ds_write_b32 v136, v2 offset:2752
	v_mul_f32_e32 v2, v58, v150
	v_mul_f32_e32 v3, v59, v151
	v_cndmask_b32_e32 v4, v2, v3, vcc
	s_nop 1
	v_mov_b32_dpp v4, v4 quad_perm:[1,0,3,2] row_mask:0xf bank_mask:0xf bound_ctrl:1
	v_cndmask_b32_e32 v2, v4, v2, vcc
	v_cndmask_b32_e32 v3, v3, v4, vcc
	v_cvt_pk_bf16_f32 v2, v2, v3
	ds_write_b32 v136, v2 offset:4096
	v_mul_f32_e32 v2, v42, v150
	v_mul_f32_e32 v3, v43, v151
	v_cndmask_b32_e32 v4, v2, v3, vcc
	s_nop 1
	v_mov_b32_dpp v4, v4 quad_perm:[1,0,3,2] row_mask:0xf bank_mask:0xf bound_ctrl:1
	v_cndmask_b32_e32 v2, v4, v2, vcc
	v_cndmask_b32_e32 v3, v3, v4, vcc
	v_cvt_pk_bf16_f32 v2, v2, v3
	ds_write_b32 v136, v2 offset:4160
	v_mul_f32_e32 v2, v26, v150
	v_mul_f32_e32 v3, v27, v151
	v_cndmask_b32_e32 v4, v2, v3, vcc
	s_nop 1
	v_mov_b32_dpp v4, v4 quad_perm:[1,0,3,2] row_mask:0xf bank_mask:0xf bound_ctrl:1
	v_cndmask_b32_e32 v2, v4, v2, vcc
	v_cndmask_b32_e32 v3, v3, v4, vcc
	v_cvt_pk_bf16_f32 v2, v2, v3
	ds_write_b32 v136, v2 offset:4224
	v_mul_f32_e32 v2, v10, v150
	v_mul_f32_e32 v3, v11, v151
	v_cndmask_b32_e32 v4, v2, v3, vcc
	s_nop 1
	v_mov_b32_dpp v4, v4 quad_perm:[1,0,3,2] row_mask:0xf bank_mask:0xf bound_ctrl:1
	v_cndmask_b32_e32 v2, v4, v2, vcc
	v_cndmask_b32_e32 v3, v3, v4, vcc
	v_cvt_pk_bf16_f32 v2, v2, v3
	ds_write_b32 v136, v2 offset:4288
	v_mul_f32_e32 v2, v60, v140
	v_mul_f32_e32 v3, v61, v141
	v_cndmask_b32_e32 v4, v2, v3, vcc
	s_nop 1
	v_mov_b32_dpp v4, v4 quad_perm:[1,0,3,2] row_mask:0xf bank_mask:0xf bound_ctrl:1
	v_cndmask_b32_e32 v2, v4, v2, vcc
	v_cndmask_b32_e32 v3, v3, v4, vcc
	v_cvt_pk_bf16_f32 v2, v2, v3
	ds_write_b32 v136, v2 offset:4608
	v_mul_f32_e32 v2, v44, v140
	v_mul_f32_e32 v3, v45, v141
	v_cndmask_b32_e32 v4, v2, v3, vcc
	s_nop 1
	v_mov_b32_dpp v4, v4 quad_perm:[1,0,3,2] row_mask:0xf bank_mask:0xf bound_ctrl:1
	v_cndmask_b32_e32 v2, v4, v2, vcc
; __device__ __forceinline__ int crow(int r, int hi) { return (r & 3) + 8 * (r >> 2) + 4 * hi; }
; __device__ __forceinline__ unsigned cvtpk(float lo, float hi) { unsigned r; asm volatile("v_cvt_pk_bf16_f32 %0, %1, %2" : "=v"(r) : "v"(lo), "v"(hi)); return r; }
; __device__ __forceinline__ void attn_unit(const bf16_t* __restrict__ Qb, const bf16_t* __restrict__ Kh, const bf16_t* __restrict__ Vh, bf16_t* __restrict__ Ob,
;                                           int NT, int ntw, int qpos0, int nvalid, char* lds) {
;     ...
;     for (int hv = 0; hv < 2; ++hv) {
;       const int pr = r32 & 1; bf16_t* stl = st + pr * 128 + (r32 & ~1);
; #pragma unroll
;       for (int r = 0; r < 16; r += 2) { const int orow = crow(r, hi);
; #pragma unroll
;         for (int d0 = 0; d0 < 4; ++d0) { const float a = o[hv * 4 + d0][r] * rli[r], b = o[hv * 4 + d0][r + 1] * rli[r + 1];
;           const float snd = pr ? a : b; const float rcv = __int_as_float(__builtin_amdgcn_mov_dpp(__float_as_int(snd), 0xB1, 0xF, 0xF, true));
;           *reinterpret_cast<unsigned*>(stl + orow * 128 + d0 * 32) = cvtpk(pr ? rcv : a, pr ? b : rcv); } }
;       asm volatile("s_waitcnt lgkmcnt(0)" ::: "memory");
; #pragma unroll
;       for (int i = 0; i < 4; ++i) { const int row = i * 8 + (lane >> 3), ch = lane & 7; const u32x4 v = *(const u32x4*)(st + row * 128 + ch * 8), v2 = *(const u32x4*)(st + row * 128 + 64 + ch * 8);
;         *(u32x4*)(Ow + (long)row * LD + hv * 128 + ch * 8) = v; *(u32x4*)(Ow + (long)row * LD + hv * 128 + 64 + ch * 8) = v2; }
;       asm volatile("s_waitcnt lgkmcnt(0)" ::: "memory");
;     }
	v_cndmask_b32_e32 v3, v3, v4, vcc
	v_cvt_pk_bf16_f32 v2, v2, v3
	ds_write_b32 v136, v2 offset:4672
	v_mul_f32_e32 v2, v28, v140
	v_mul_f32_e32 v3, v29, v141
	v_cndmask_b32_e32 v4, v2, v3, vcc
	s_nop 1
	v_mov_b32_dpp v4, v4 quad_perm:[1,0,3,2] row_mask:0xf bank_mask:0xf bound_ctrl:1
	v_cndmask_b32_e32 v2, v4, v2, vcc
	v_cndmask_b32_e32 v3, v3, v4, vcc
	v_cvt_pk_bf16_f32 v2, v2, v3
	ds_write_b32 v136, v2 offset:4736
	v_mul_f32_e32 v2, v12, v140
	v_mul_f32_e32 v3, v13, v141
	v_cndmask_b32_e32 v4, v2, v3, vcc
	s_nop 1
	v_mov_b32_dpp v4, v4 quad_perm:[1,0,3,2] row_mask:0xf bank_mask:0xf bound_ctrl:1
	v_cndmask_b32_e32 v2, v4, v2, vcc
	v_cndmask_b32_e32 v3, v3, v4, vcc
	v_cvt_pk_bf16_f32 v2, v2, v3
	ds_write_b32 v136, v2 offset:4800
	v_mul_f32_e32 v2, v62, v138
	v_mul_f32_e32 v3, v63, v139
	v_cndmask_b32_e32 v4, v2, v3, vcc
	s_nop 1
	v_mov_b32_dpp v4, v4 quad_perm:[1,0,3,2] row_mask:0xf bank_mask:0xf bound_ctrl:1
	v_cndmask_b32_e32 v2, v4, v2, vcc
	v_cndmask_b32_e32 v3, v3, v4, vcc
	v_cvt_pk_bf16_f32 v2, v2, v3
	ds_write_b32 v136, v2 offset:6144
	v_mul_f32_e32 v2, v46, v138
	v_mul_f32_e32 v3, v47, v139
	v_cndmask_b32_e32 v4, v2, v3, vcc
	s_nop 1
	v_mov_b32_dpp v4, v4 quad_perm:[1,0,3,2] row_mask:0xf bank_mask:0xf bound_ctrl:1
	v_cndmask_b32_e32 v2, v4, v2, vcc
	v_cndmask_b32_e32 v3, v3, v4, vcc
	v_cvt_pk_bf16_f32 v2, v2, v3
	ds_write_b32 v136, v2 offset:6208
	v_mul_f32_e32 v2, v30, v138
	v_mul_f32_e32 v3, v31, v139
	v_cndmask_b32_e32 v4, v2, v3, vcc
	s_nop 1
	v_mov_b32_dpp v4, v4 quad_perm:[1,0,3,2] row_mask:0xf bank_mask:0xf bound_ctrl:1
	v_cndmask_b32_e32 v2, v4, v2, vcc
	v_cndmask_b32_e32 v3, v3, v4, vcc
	v_cvt_pk_bf16_f32 v2, v2, v3
	ds_write_b32 v136, v2 offset:6272
	v_mul_f32_e32 v2, v14, v138
	v_mul_f32_e32 v3, v15, v139
	v_cndmask_b32_e32 v4, v2, v3, vcc
	s_nop 1
	v_mov_b32_dpp v4, v4 quad_perm:[1,0,3,2] row_mask:0xf bank_mask:0xf bound_ctrl:1
	v_cndmask_b32_e32 v2, v4, v2, vcc
	v_cndmask_b32_e32 v3, v3, v4, vcc
	v_cvt_pk_bf16_f32 v2, v2, v3
	ds_write_b32 v136, v2 offset:6336
	v_mul_f32_e32 v2, v64, v134
	v_mul_f32_e32 v3, v65, v135
	v_cndmask_b32_e32 v4, v2, v3, vcc
	s_nop 1
	v_mov_b32_dpp v4, v4 quad_perm:[1,0,3,2] row_mask:0xf bank_mask:0xf bound_ctrl:1
	v_cndmask_b32_e32 v2, v4, v2, vcc
	v_cndmask_b32_e32 v3, v3, v4, vcc
	v_cvt_pk_bf16_f32 v2, v2, v3
	ds_write_b32 v136, v2 offset:6656
	v_mul_f32_e32 v2, v48, v134
	v_mul_f32_e32 v3, v49, v135
	v_cndmask_b32_e32 v4, v2, v3, vcc
	s_nop 1
	v_mov_b32_dpp v4, v4 quad_perm:[1,0,3,2] row_mask:0xf bank_mask:0xf bound_ctrl:1
	v_cndmask_b32_e32 v2, v4, v2, vcc
	v_cndmask_b32_e32 v3, v3, v4, vcc
	v_cvt_pk_bf16_f32 v2, v2, v3
	ds_write_b32 v136, v2 offset:6720
	v_mul_f32_e32 v2, v32, v134
	v_mul_f32_e32 v3, v33, v135
	v_cndmask_b32_e32 v4, v2, v3, vcc
	s_nop 1
	v_mov_b32_dpp v4, v4 quad_perm:[1,0,3,2] row_mask:0xf bank_mask:0xf bound_ctrl:1
	v_cndmask_b32_e32 v2, v4, v2, vcc
	v_cndmask_b32_e32 v3, v3, v4, vcc
	v_cvt_pk_bf16_f32 v2, v2, v3
	ds_write_b32 v136, v2 offset:6784
	v_mul_f32_e32 v2, v16, v134
	v_mul_f32_e32 v3, v17, v135
	v_cndmask_b32_e32 v4, v2, v3, vcc
	s_nop 1
	v_mov_b32_dpp v4, v4 quad_perm:[1,0,3,2] row_mask:0xf bank_mask:0xf bound_ctrl:1
	v_cndmask_b32_e32 v2, v4, v2, vcc
	v_cndmask_b32_e32 v3, v3, v4, vcc
	v_cvt_pk_bf16_f32 v2, v2, v3
	ds_write_b32 v136, v2 offset:6848
	s_waitcnt lgkmcnt(0)
	ds_read_b128 v[2:5], v137
	ds_read_b128 v[6:9], v137 offset:128
	ds_read_b128 v[10:13], v82
	s_waitcnt lgkmcnt(2)
	global_store_dwordx4 v[66:67], v[2:5], off offset:256
	s_waitcnt lgkmcnt(1)
	global_store_dwordx4 v[66:67], v[6:9], off offset:384
	s_waitcnt lgkmcnt(0)
	global_store_dwordx4 v[68:69], v[10:13], off offset:256
	ds_read_b128 v[2:5], v82 offset:128
	ds_read_b128 v[6:9], v83
	ds_read_b128 v[10:13], v83 offset:128
	ds_read_b128 v[14:17], v84
	ds_read_b128 v[18:21], v84 offset:128
	s_waitcnt lgkmcnt(4)
	global_store_dwordx4 v[68:69], v[2:5], off offset:384
	s_waitcnt lgkmcnt(3)
	global_store_dwordx4 v[70:71], v[6:9], off offset:256
	s_waitcnt lgkmcnt(2)
	global_store_dwordx4 v[70:71], v[10:13], off offset:384
	s_waitcnt lgkmcnt(1)
	global_store_dwordx4 v[72:73], v[14:17], off offset:256
	s_waitcnt lgkmcnt(0)
	global_store_dwordx4 v[72:73], v[18:21], off offset:384
	s_waitcnt lgkmcnt(0)
	s_branch .LBB0_284

; #define GAS __attribute__((address_space(1)))
; __device__ __forceinline__ unsigned pk2(float lo, float hi) { return f2bf(lo) | (f2bf(hi) << 16); }
; __global__ void __launch_bounds__(NWAVES * 64, 2) trunk_fwd(Args args) {
;     ...
;             for (int m = gw; m < M; m += NGW) {
;                 const bf16* o1 = OP + (size_t)m * DM; const bf16* o2 = OP + (size_t)M * DM + (size_t)m * DM; bf16* orow = ABR + (size_t)m * KBR + DCONV;
;                 v4u aw[4], cw2[4];
; #pragma unroll
;                 for (int i = 0; i < 4; ++i) { aw[i] = ((const GAS v4u*)(o1 + i * 512))[lane]; cw2[i] = ((const GAS v4u*)(o2 + i * 512))[lane]; }
; #pragma unroll
;                 for (int i = 0; i < 4; ++i) {
;                     const f32x4 d0 = (f32x4){bf_lo(aw[i].x), bf_hi(aw[i].x), bf_lo(aw[i].y), bf_hi(aw[i].y)} - lam * (f32x4){bf_lo(cw2[i].x), bf_hi(cw2[i].x), bf_lo(cw2[i].y), bf_hi(cw2[i].y)};
;                     const f32x4 d1 = (f32x4){bf_lo(aw[i].z), bf_hi(aw[i].z), bf_lo(aw[i].w), bf_hi(aw[i].w)} - lam * (f32x4){bf_lo(cw2[i].z), bf_hi(cw2[i].z), bf_lo(cw2[i].w), bf_hi(cw2[i].w)};
;                     const float ss = half_sum(((d0.x * d0.x + d0.y * d0.y) + (d0.z * d0.z + d0.w * d0.w)) + ((d1.x * d1.x + d1.y * d1.y) + (d1.z * d1.z + d1.w * d1.w)));
;                     const float r = osc / sqrtf(ss * (1.f / 256.f) + EPS);
;                     v4u w; w.x = pk2(d0.x * r * gs0.x, d0.y * r * gs0.y); w.y = pk2(d0.z * r * gs0.z, d0.w * r * gs0.w); w.z = pk2(d1.x * r * gs1.x, d1.y * r * gs1.y); w.w = pk2(d1.z * r * gs1.z, d1.w * r * gs1.w);
;                     ((GAS v4u*)(orow + i * 512))[lane] = w;
;                 }
;             }
.LBB0_380:
	v_lshl_add_u64 v[4:5], s[50:51], 0, v[178:179]
	v_add_co_u32_e32 v12, vcc, 0x54900000, v4
	v_xor_b32_e32 v41, 0x80000000, v11
	s_nop 0
	v_addc_co_u32_e32 v13, vcc, 0, v5, vcc
	global_load_dwordx4 v[44:47], v[12:13], off
	v_add_co_u32_e32 v4, vcc, 0x56b00000, v4
	v_xor_b32_e32 v40, 0x80000000, v10
	s_nop 0
	v_addc_co_u32_e32 v5, vcc, 0, v5, vcc
	global_load_dwordx4 v[48:51], v[4:5], off
	global_load_dwordx4 v[32:35], v[12:13], off offset:1024
	global_load_dwordx4 v[28:31], v[4:5], off offset:1024
	global_load_dwordx4 v[24:27], v[12:13], off offset:2048
	global_load_dwordx4 v[20:23], v[4:5], off offset:2048
	global_load_dwordx4 v[16:19], v[12:13], off offset:3072
	s_nop 0
	global_load_dwordx4 v[12:15], v[4:5], off offset:3072
	v_lshl_add_u64 v[4:5], s[48:49], 0, v[178:179]
	s_add_i32 s10, s10, s52
	s_waitcnt vmcnt(6)
	v_lshlrev_b32_e32 v54, 16, v48
	v_lshlrev_b32_e32 v52, 16, v44
	v_and_b32_e32 v53, 0xffff0000, v44
	v_lshlrev_b32_e32 v44, 16, v45
	v_and_b32_e32 v45, 0xffff0000, v45
	v_and_b32_e32 v55, 0xffff0000, v48
	v_lshlrev_b32_e32 v48, 16, v49
	v_and_b32_e32 v49, 0xffff0000, v49
	v_pk_fma_f32 v[44:45], v[40:41], v[48:49], v[44:45]
	v_pk_fma_f32 v[48:49], v[36:37], v[54:55], v[52:53] neg_lo:[1,0,0] neg_hi:[1,0,0]
	v_lshlrev_b32_e32 v52, 16, v46
	v_and_b32_e32 v53, 0xffff0000, v46
	v_lshlrev_b32_e32 v46, 16, v47
	v_and_b32_e32 v47, 0xffff0000, v47
	v_lshlrev_b32_e32 v54, 16, v50
	v_and_b32_e32 v55, 0xffff0000, v50
	v_lshlrev_b32_e32 v50, 16, v51
	v_and_b32_e32 v51, 0xffff0000, v51
	v_pk_fma_f32 v[46:47], v[40:41], v[50:51], v[46:47]
	v_pk_fma_f32 v[50:51], v[36:37], v[54:55], v[52:53] neg_lo:[1,0,0] neg_hi:[1,0,0]
	v_mov_b32_e32 v54, v49
	v_mov_b32_e32 v55, v51
	v_mov_b32_e32 v52, v48
	v_mov_b32_e32 v53, v50
	v_pk_mul_f32 v[54:55], v[54:55], v[54:55]
	v_mov_b32_e32 v56, v45
	v_mov_b32_e32 v57, v47
	v_pk_fma_f32 v[52:53], v[52:53], v[52:53], v[54:55]
	v_mov_b32_e32 v54, v44
	v_mov_b32_e32 v55, v46
	v_pk_mul_f32 v[56:57], v[56:57], v[56:57]
	s_nop 0
	v_pk_fma_f32 v[54:55], v[54:55], v[54:55], v[56:57]
	s_nop 0
	v_pk_add_f32 v[52:53], v[52:53], v[54:55]
	s_nop 0
	v_add_f32_e32 v52, v52, v53
	ds_swizzle_b32 v53, v52 offset:swizzle(SWAP,1)
	s_waitcnt lgkmcnt(0)
	v_add_f32_e32 v52, v52, v53
	ds_swizzle_b32 v53, v52 offset:swizzle(SWAP,2)
	s_waitcnt lgkmcnt(0)
	v_add_f32_e32 v52, v52, v53
	ds_swizzle_b32 v53, v52 offset:swizzle(SWAP,4)
	s_waitcnt lgkmcnt(0)
	v_add_f32_e32 v52, v52, v53
	ds_swizzle_b32 v53, v52 offset:swizzle(SWAP,8)
	s_waitcnt lgkmcnt(0)
	v_add_f32_e32 v52, v52, v53
	ds_swizzle_b32 v53, v52 offset:swizzle(SWAP,16)
	s_waitcnt lgkmcnt(0)
	v_add_f32_e32 v52, v52, v53
	v_fmamk_f32 v52, v52, 0x3b800000, v1
	v_cmp_gt_f32_e32 vcc, s45, v52
	v_mul_f32_e32 v53, 0x4f800000, v52
	s_nop 0
	v_cndmask_b32_e32 v52, v52, v53, vcc
	v_sqrt_f32_e32 v53, v52
	s_nop 0
	v_add_u32_e32 v54, -1, v53
	v_fma_f32 v55, -v54, v53, v52
	v_cmp_ge_f32_e64 s[38:39], 0, v55
	v_add_u32_e32 v55, 1, v53
	s_nop 0
	v_cndmask_b32_e64 v54, v53, v54, s[38:39]
	v_fma_f32 v53, -v55, v53, v52
	v_cmp_lt_f32_e64 s[38:39], 0, v53
	s_nop 1
	v_cndmask_b32_e64 v53, v54, v55, s[38:39]
	v_mul_f32_e32 v54, 0x37800000, v53
	v_cndmask_b32_e32 v53, v53, v54, vcc
	v_cmp_class_f32_e32 vcc, v52, v237
	s_nop 1
	v_cndmask_b32_e32 v52, v53, v52, vcc
	v_div_scale_f32 v53, s[2:3], v52, v52, v43
	v_rcp_f32_e32 v54, v53
	s_mov_b32 s2, 0x5d100000
	v_fma_f32 v55, -v53, v54, 1.0
	v_fmac_f32_e32 v54, v55, v54
	v_div_scale_f32 v55, vcc, v43, v52, v43
	v_mul_f32_e32 v56, v55, v54
	v_fma_f32 v57, -v53, v56, v55
	v_fmac_f32_e32 v56, v57, v54
	v_fma_f32 v53, -v53, v56, v55
	v_div_fmas_f32 v53, v53, v54, v56
	v_div_fixup_f32 v52, v53, v52, v43
	v_mov_b32_e32 v55, v44
	v_mov_b32_e32 v44, v49
	v_mov_b32_e32 v54, v48
	v_pk_mul_f32 v[44:45], v[44:45], v[52:53] op_sel_hi:[1,0]
	v_mov_b32_e32 v48, v50
	v_mov_b32_e32 v49, v46
	v_mov_b32_e32 v46, v51
	v_pk_mul_f32 v[44:45], v[38:39], v[44:45]
	v_pk_mul_f32 v[48:49], v[48:49], v[52:53] op_sel_hi:[1,0]
	v_pk_mul_f32 v[46:47], v[46:47], v[52:53] op_sel_hi:[1,0]
	v_pk_mul_f32 v[54:55], v[54:55], v[52:53] op_sel_hi:[1,0]
	v_pk_mul_f32 v[48:49], v[2:3], v[48:49]
	v_pk_mul_f32 v[46:47], v[8:9], v[46:47]
	v_bfe_u32 v52, v45, 16, 1
	v_pk_mul_f32 v[54:55], v[6:7], v[54:55]
	v_bfe_u32 v50, v47, 16, 1
	v_bfe_u32 v51, v46, 16, 1
	v_bfe_u32 v53, v44, 16, 1
	v_add3_u32 v45, v45, v52, s57
	v_bfe_u32 v52, v48, 16, 1
	v_add3_u32 v44, v44, v53, s57
	v_add3_u32 v46, v46, v51, s57
	v_add3_u32 v47, v47, v50, s57
	v_bfe_u32 v50, v54, 16, 1
	v_bfe_u32 v51, v55, 16, 1
	v_bfe_u32 v53, v49, 16, 1
	v_add3_u32 v48, v48, v52, s57
	v_add3_u32 v49, v49, v53, s57
	v_add3_u32 v51, v55, v51, s57
	v_add3_u32 v50, v54, v50, s57
	v_lshrrev_b32_e32 v48, 16, v48
	v_lshrrev_b32_e32 v50, 16, v50
	v_lshrrev_b32_e32 v51, 16, v51
	v_lshrrev_b32_e32 v49, 16, v49
	v_and_or_b32 v46, v46, s33, v48
	v_add_co_u32_e32 v48, vcc, s2, v4
	v_and_or_b32 v47, v47, s33, v49
	v_and_or_b32 v45, v45, s33, v51
	v_and_or_b32 v44, v44, s33, v50
	v_addc_co_u32_e32 v49, vcc, 0, v5, vcc
	global_store_dwordx4 v[48:49], v[44:47], off offset:2048 sc0 sc1
	s_waitcnt vmcnt(6)
	s_nop 0
	v_lshlrev_b32_e32 v44, 16, v32
	v_and_b32_e32 v45, 0xffff0000, v32
	v_lshlrev_b32_e32 v32, 16, v33
	v_and_b32_e32 v33, 0xffff0000, v33
	s_waitcnt vmcnt(5)
; #define GAS __attribute__((address_space(1)))
; __device__ __forceinline__ unsigned pk2(float lo, float hi) { return f2bf(lo) | (f2bf(hi) << 16); }
; __global__ void __launch_bounds__(NWAVES * 64, 2) trunk_fwd(Args args) {
;     ...
;                 for (int i = 0; i < 4; ++i) {
;                     const f32x4 d0 = (f32x4){bf_lo(aw[i].x), bf_hi(aw[i].x), bf_lo(aw[i].y), bf_hi(aw[i].y)} - lam * (f32x4){bf_lo(cw2[i].x), bf_hi(cw2[i].x), bf_lo(cw2[i].y), bf_hi(cw2[i].y)};
;                     const f32x4 d1 = (f32x4){bf_lo(aw[i].z), bf_hi(aw[i].z), bf_lo(aw[i].w), bf_hi(aw[i].w)} - lam * (f32x4){bf_lo(cw2[i].z), bf_hi(cw2[i].z), bf_lo(cw2[i].w), bf_hi(cw2[i].w)};
;                     const float ss = half_sum(((d0.x * d0.x + d0.y * d0.y) + (d0.z * d0.z + d0.w * d0.w)) + ((d1.x * d1.x + d1.y * d1.y) + (d1.z * d1.z + d1.w * d1.w)));
;                     const float r = osc / sqrtf(ss * (1.f / 256.f) + EPS);
;                     v4u w; w.x = pk2(d0.x * r * gs0.x, d0.y * r * gs0.y); w.y = pk2(d0.z * r * gs0.z, d0.w * r * gs0.w); w.z = pk2(d1.x * r * gs1.x, d1.y * r * gs1.y); w.w = pk2(d1.z * r * gs1.z, d1.w * r * gs1.w);
;                     ((GAS v4u*)(orow + i * 512))[lane] = w;
	v_lshlrev_b32_e32 v46, 16, v28
	v_and_b32_e32 v47, 0xffff0000, v28
	v_lshlrev_b32_e32 v28, 16, v29
	v_and_b32_e32 v29, 0xffff0000, v29
	v_pk_fma_f32 v[28:29], v[40:41], v[28:29], v[32:33]
	v_pk_fma_f32 v[32:33], v[36:37], v[46:47], v[44:45] neg_lo:[1,0,0] neg_hi:[1,0,0]
	v_lshlrev_b32_e32 v44, 16, v34
	v_and_b32_e32 v45, 0xffff0000, v34
	v_lshlrev_b32_e32 v34, 16, v35
	v_and_b32_e32 v35, 0xffff0000, v35
	v_lshlrev_b32_e32 v46, 16, v30
	v_and_b32_e32 v47, 0xffff0000, v30
	v_lshlrev_b32_e32 v30, 16, v31
	v_and_b32_e32 v31, 0xffff0000, v31
	v_pk_fma_f32 v[30:31], v[40:41], v[30:31], v[34:35]
	v_pk_fma_f32 v[34:35], v[36:37], v[46:47], v[44:45] neg_lo:[1,0,0] neg_hi:[1,0,0]
	v_mov_b32_e32 v46, v33
	v_mov_b32_e32 v47, v35
	v_mov_b32_e32 v44, v32
	v_mov_b32_e32 v45, v34
	v_pk_mul_f32 v[46:47], v[46:47], v[46:47]
	v_mov_b32_e32 v50, v29
	v_mov_b32_e32 v51, v31
	v_pk_fma_f32 v[44:45], v[44:45], v[44:45], v[46:47]
	v_mov_b32_e32 v46, v28
	v_mov_b32_e32 v47, v30
	v_pk_mul_f32 v[50:51], v[50:51], v[50:51]
	s_nop 0
	v_pk_fma_f32 v[46:47], v[46:47], v[46:47], v[50:51]
	s_nop 0
	v_pk_add_f32 v[44:45], v[44:45], v[46:47]
	s_nop 0
	v_add_f32_e32 v44, v44, v45
	ds_swizzle_b32 v45, v44 offset:swizzle(SWAP,1)
	s_waitcnt lgkmcnt(0)
	v_add_f32_e32 v44, v44, v45
	ds_swizzle_b32 v45, v44 offset:swizzle(SWAP,2)
	s_waitcnt lgkmcnt(0)
	v_add_f32_e32 v44, v44, v45
	ds_swizzle_b32 v45, v44 offset:swizzle(SWAP,4)
	s_waitcnt lgkmcnt(0)
	v_add_f32_e32 v44, v44, v45
	ds_swizzle_b32 v45, v44 offset:swizzle(SWAP,8)
	s_waitcnt lgkmcnt(0)
	v_add_f32_e32 v44, v44, v45
	ds_swizzle_b32 v45, v44 offset:swizzle(SWAP,16)
	s_waitcnt lgkmcnt(0)
	v_add_f32_e32 v44, v44, v45
	v_fmamk_f32 v44, v44, 0x3b800000, v1
	v_cmp_gt_f32_e32 vcc, s45, v44
	v_mul_f32_e32 v45, 0x4f800000, v44
	s_nop 0
	v_cndmask_b32_e32 v44, v44, v45, vcc
	v_sqrt_f32_e32 v45, v44
	s_nop 0
	v_add_u32_e32 v46, -1, v45
	v_fma_f32 v47, -v46, v45, v44
	v_cmp_ge_f32_e64 s[38:39], 0, v47
	v_add_u32_e32 v47, 1, v45
	s_nop 0
	v_cndmask_b32_e64 v46, v45, v46, s[38:39]
	v_fma_f32 v45, -v47, v45, v44
	v_cmp_lt_f32_e64 s[38:39], 0, v45
	s_nop 1
	v_cndmask_b32_e64 v45, v46, v47, s[38:39]
	v_mul_f32_e32 v46, 0x37800000, v45
	v_cndmask_b32_e32 v45, v45, v46, vcc
	v_cmp_class_f32_e32 vcc, v44, v237
	s_nop 1
	v_cndmask_b32_e32 v44, v45, v44, vcc
	v_div_scale_f32 v45, s[2:3], v44, v44, v43
	v_rcp_f32_e32 v46, v45
	s_nop 0
	v_fma_f32 v47, -v45, v46, 1.0
	v_fmac_f32_e32 v46, v47, v46
	v_div_scale_f32 v47, vcc, v43, v44, v43
	v_mul_f32_e32 v50, v47, v46
	v_fma_f32 v51, -v45, v50, v47
	v_fmac_f32_e32 v50, v51, v46
	v_fma_f32 v45, -v45, v50, v47
	v_div_fmas_f32 v45, v45, v46, v50
	v_div_fixup_f32 v44, v45, v44, v43
	v_mov_b32_e32 v47, v28
	v_mov_b32_e32 v28, v33
	v_mov_b32_e32 v33, v30
	v_mov_b32_e32 v30, v35
	v_mov_b32_e32 v46, v32
	v_pk_mul_f32 v[28:29], v[28:29], v[44:45] op_sel_hi:[1,0]
	v_mov_b32_e32 v32, v34
	v_pk_mul_f32 v[30:31], v[30:31], v[44:45] op_sel_hi:[1,0]
	v_pk_mul_f32 v[46:47], v[46:47], v[44:45] op_sel_hi:[1,0]
	v_pk_mul_f32 v[28:29], v[38:39], v[28:29]
	v_pk_mul_f32 v[32:33], v[32:33], v[44:45] op_sel_hi:[1,0]
	v_pk_mul_f32 v[30:31], v[8:9], v[30:31]
	v_pk_mul_f32 v[46:47], v[6:7], v[46:47]
	v_pk_mul_f32 v[32:33], v[2:3], v[32:33]
	v_bfe_u32 v34, v31, 16, 1
	v_bfe_u32 v35, v30, 16, 1
	v_bfe_u32 v44, v29, 16, 1
	v_bfe_u32 v45, v28, 16, 1
	v_add3_u32 v28, v28, v45, s57
	v_add3_u32 v29, v29, v44, s57
	v_add3_u32 v30, v30, v35, s57
	v_add3_u32 v31, v31, v34, s57
	v_bfe_u32 v34, v46, 16, 1
	v_bfe_u32 v35, v47, 16, 1
	v_bfe_u32 v44, v32, 16, 1
	v_bfe_u32 v45, v33, 16, 1
	v_add3_u32 v33, v33, v45, s57
	v_add3_u32 v32, v32, v44, s57
	v_add3_u32 v35, v47, v35, s57
	v_add3_u32 v34, v46, v34, s57
	v_lshrrev_b32_e32 v34, 16, v34
	v_lshrrev_b32_e32 v35, 16, v35
	v_lshrrev_b32_e32 v32, 16, v32
	v_lshrrev_b32_e32 v33, 16, v33
	v_and_or_b32 v31, v31, s33, v33
	v_and_or_b32 v30, v30, s33, v32
	v_and_or_b32 v29, v29, s33, v35
	v_and_or_b32 v28, v28, s33, v34
	global_store_dwordx4 v[48:49], v[28:31], off offset:3072 sc0 sc1
	s_waitcnt vmcnt(5)
	s_nop 0
	v_lshlrev_b32_e32 v28, 16, v24
	v_and_b32_e32 v29, 0xffff0000, v24
	v_lshlrev_b32_e32 v24, 16, v25
	v_and_b32_e32 v25, 0xffff0000, v25
	s_waitcnt vmcnt(4)
	v_lshlrev_b32_e32 v30, 16, v20
	v_and_b32_e32 v31, 0xffff0000, v20
	v_lshlrev_b32_e32 v20, 16, v21
	v_and_b32_e32 v21, 0xffff0000, v21
	v_pk_fma_f32 v[20:21], v[40:41], v[20:21], v[24:25]
	v_pk_fma_f32 v[24:25], v[36:37], v[30:31], v[28:29] neg_lo:[1,0,0] neg_hi:[1,0,0]
	v_lshlrev_b32_e32 v28, 16, v26
	v_and_b32_e32 v29, 0xffff0000, v26
	v_lshlrev_b32_e32 v26, 16, v27
	v_and_b32_e32 v27, 0xffff0000, v27
	v_lshlrev_b32_e32 v30, 16, v22
	v_and_b32_e32 v31, 0xffff0000, v22
	v_lshlrev_b32_e32 v22, 16, v23
	v_and_b32_e32 v23, 0xffff0000, v23
	v_pk_fma_f32 v[22:23], v[40:41], v[22:23], v[26:27]
	v_pk_fma_f32 v[26:27], v[36:37], v[30:31], v[28:29] neg_lo:[1,0,0] neg_hi:[1,0,0]
	v_mov_b32_e32 v30, v25
	v_mov_b32_e32 v31, v27
	v_mov_b32_e32 v28, v24
	v_mov_b32_e32 v29, v26
	v_pk_mul_f32 v[30:31], v[30:31], v[30:31]
	v_mov_b32_e32 v32, v21
	v_mov_b32_e32 v33, v23
	v_pk_fma_f32 v[28:29], v[28:29], v[28:29], v[30:31]
	v_mov_b32_e32 v30, v20
	v_mov_b32_e32 v31, v22
	v_pk_mul_f32 v[32:33], v[32:33], v[32:33]
	s_nop 0
	v_pk_fma_f32 v[30:31], v[30:31], v[30:31], v[32:33]
	s_nop 0
	v_pk_add_f32 v[28:29], v[28:29], v[30:31]
	s_nop 0
	v_add_f32_e32 v28, v28, v29
	ds_swizzle_b32 v29, v28 offset:swizzle(SWAP,1)
	s_waitcnt lgkmcnt(0)
	v_add_f32_e32 v28, v28, v29
	ds_swizzle_b32 v29, v28 offset:swizzle(SWAP,2)
	s_waitcnt lgkmcnt(0)
	v_add_f32_e32 v28, v28, v29
	ds_swizzle_b32 v29, v28 offset:swizzle(SWAP,4)
	s_waitcnt lgkmcnt(0)
; #define GAS __attribute__((address_space(1)))
; __device__ __forceinline__ unsigned pk2(float lo, float hi) { return f2bf(lo) | (f2bf(hi) << 16); }
; __global__ void __launch_bounds__(NWAVES * 64, 2) trunk_fwd(Args args) {
;     ...
;                 for (int i = 0; i < 4; ++i) {
;                     const f32x4 d0 = (f32x4){bf_lo(aw[i].x), bf_hi(aw[i].x), bf_lo(aw[i].y), bf_hi(aw[i].y)} - lam * (f32x4){bf_lo(cw2[i].x), bf_hi(cw2[i].x), bf_lo(cw2[i].y), bf_hi(cw2[i].y)};
;                     const f32x4 d1 = (f32x4){bf_lo(aw[i].z), bf_hi(aw[i].z), bf_lo(aw[i].w), bf_hi(aw[i].w)} - lam * (f32x4){bf_lo(cw2[i].z), bf_hi(cw2[i].z), bf_lo(cw2[i].w), bf_hi(cw2[i].w)};
;                     const float ss = half_sum(((d0.x * d0.x + d0.y * d0.y) + (d0.z * d0.z + d0.w * d0.w)) + ((d1.x * d1.x + d1.y * d1.y) + (d1.z * d1.z + d1.w * d1.w)));
;                     const float r = osc / sqrtf(ss * (1.f / 256.f) + EPS);
;                     v4u w; w.x = pk2(d0.x * r * gs0.x, d0.y * r * gs0.y); w.y = pk2(d0.z * r * gs0.z, d0.w * r * gs0.w); w.z = pk2(d1.x * r * gs1.x, d1.y * r * gs1.y); w.w = pk2(d1.z * r * gs1.z, d1.w * r * gs1.w);
;                     ((GAS v4u*)(orow + i * 512))[lane] = w;
;                 }
;             }
	v_add_f32_e32 v28, v28, v29
	ds_swizzle_b32 v29, v28 offset:swizzle(SWAP,8)
	s_waitcnt lgkmcnt(0)
	v_add_f32_e32 v28, v28, v29
	ds_swizzle_b32 v29, v28 offset:swizzle(SWAP,16)
	s_waitcnt lgkmcnt(0)
	v_add_f32_e32 v28, v28, v29
	v_fmamk_f32 v28, v28, 0x3b800000, v1
	v_cmp_gt_f32_e32 vcc, s45, v28
	v_mul_f32_e32 v29, 0x4f800000, v28
	s_nop 0
	v_cndmask_b32_e32 v28, v28, v29, vcc
	v_sqrt_f32_e32 v29, v28
	s_nop 0
	v_add_u32_e32 v30, -1, v29
	v_fma_f32 v31, -v30, v29, v28
	v_cmp_ge_f32_e64 s[38:39], 0, v31
	v_add_u32_e32 v31, 1, v29
	s_nop 0
	v_cndmask_b32_e64 v30, v29, v30, s[38:39]
	v_fma_f32 v29, -v31, v29, v28
	v_cmp_lt_f32_e64 s[38:39], 0, v29
	s_nop 1
	v_cndmask_b32_e64 v29, v30, v31, s[38:39]
	v_mul_f32_e32 v30, 0x37800000, v29
	v_cndmask_b32_e32 v29, v29, v30, vcc
	v_cmp_class_f32_e32 vcc, v28, v237
	s_nop 1
	v_cndmask_b32_e32 v28, v29, v28, vcc
	v_div_scale_f32 v29, s[2:3], v28, v28, v43
	v_rcp_f32_e32 v30, v29
	s_mov_b32 s2, 0x5d101000
	v_fma_f32 v31, -v29, v30, 1.0
	v_fmac_f32_e32 v30, v31, v30
	v_div_scale_f32 v31, vcc, v43, v28, v43
	v_mul_f32_e32 v32, v31, v30
	v_fma_f32 v33, -v29, v32, v31
	v_fmac_f32_e32 v32, v33, v30
	v_fma_f32 v29, -v29, v32, v31
	v_div_fmas_f32 v29, v29, v30, v32
	v_div_fixup_f32 v28, v29, v28, v43
	v_mov_b32_e32 v31, v20
	v_mov_b32_e32 v20, v25
	v_mov_b32_e32 v25, v22
	v_mov_b32_e32 v22, v27
	v_mov_b32_e32 v30, v24
	v_pk_mul_f32 v[20:21], v[20:21], v[28:29] op_sel_hi:[1,0]
	v_mov_b32_e32 v24, v26
	v_pk_mul_f32 v[22:23], v[22:23], v[28:29] op_sel_hi:[1,0]
	v_pk_mul_f32 v[30:31], v[30:31], v[28:29] op_sel_hi:[1,0]
	v_pk_mul_f32 v[20:21], v[38:39], v[20:21]
	v_pk_mul_f32 v[24:25], v[24:25], v[28:29] op_sel_hi:[1,0]
	v_pk_mul_f32 v[22:23], v[8:9], v[22:23]
	v_pk_mul_f32 v[30:31], v[6:7], v[30:31]
	v_pk_mul_f32 v[24:25], v[2:3], v[24:25]
	v_bfe_u32 v26, v23, 16, 1
	v_bfe_u32 v27, v22, 16, 1
	v_bfe_u32 v28, v21, 16, 1
	v_bfe_u32 v29, v20, 16, 1
	v_add3_u32 v20, v20, v29, s57
	v_add3_u32 v21, v21, v28, s57
	v_add3_u32 v22, v22, v27, s57
	v_add3_u32 v23, v23, v26, s57
	v_bfe_u32 v26, v30, 16, 1
	v_bfe_u32 v27, v31, 16, 1
	v_bfe_u32 v28, v24, 16, 1
	v_bfe_u32 v29, v25, 16, 1
	v_add3_u32 v25, v25, v29, s57
	v_add3_u32 v24, v24, v28, s57
	v_add3_u32 v27, v31, v27, s57
	v_add3_u32 v26, v30, v26, s57
	v_lshrrev_b32_e32 v26, 16, v26
	v_lshrrev_b32_e32 v27, 16, v27
	v_lshrrev_b32_e32 v24, 16, v24
	v_lshrrev_b32_e32 v25, 16, v25
	v_add_co_u32_e32 v4, vcc, s2, v4
	v_and_or_b32 v23, v23, s33, v25
	v_and_or_b32 v22, v22, s33, v24
	v_and_or_b32 v21, v21, s33, v27
	v_and_or_b32 v20, v20, s33, v26
	v_addc_co_u32_e32 v5, vcc, 0, v5, vcc
	global_store_dwordx4 v[4:5], v[20:23], off sc0 sc1
	s_waitcnt vmcnt(4)
	s_nop 0
	v_lshlrev_b32_e32 v20, 16, v16
	v_and_b32_e32 v21, 0xffff0000, v16
	v_lshlrev_b32_e32 v16, 16, v17
	v_and_b32_e32 v17, 0xffff0000, v17
	s_waitcnt vmcnt(3)
	v_lshlrev_b32_e32 v22, 16, v12
	v_and_b32_e32 v23, 0xffff0000, v12
	v_lshlrev_b32_e32 v12, 16, v13
	v_and_b32_e32 v13, 0xffff0000, v13
	v_pk_fma_f32 v[12:13], v[40:41], v[12:13], v[16:17]
	v_pk_fma_f32 v[16:17], v[36:37], v[22:23], v[20:21] neg_lo:[1,0,0] neg_hi:[1,0,0]
	v_lshlrev_b32_e32 v20, 16, v18
	v_and_b32_e32 v21, 0xffff0000, v18
	v_lshlrev_b32_e32 v18, 16, v19
	v_and_b32_e32 v19, 0xffff0000, v19
	v_lshlrev_b32_e32 v22, 16, v14
	v_and_b32_e32 v23, 0xffff0000, v14
	v_lshlrev_b32_e32 v14, 16, v15
	v_and_b32_e32 v15, 0xffff0000, v15
	v_pk_fma_f32 v[14:15], v[40:41], v[14:15], v[18:19]
	v_pk_fma_f32 v[18:19], v[36:37], v[22:23], v[20:21] neg_lo:[1,0,0] neg_hi:[1,0,0]
	v_mov_b32_e32 v22, v17
	v_mov_b32_e32 v23, v19
	v_mov_b32_e32 v20, v16
	v_mov_b32_e32 v21, v18
	v_pk_mul_f32 v[22:23], v[22:23], v[22:23]
	v_mov_b32_e32 v24, v13
	v_mov_b32_e32 v25, v15
	v_pk_fma_f32 v[20:21], v[20:21], v[20:21], v[22:23]
	v_mov_b32_e32 v22, v12
	v_mov_b32_e32 v23, v14
	v_pk_mul_f32 v[24:25], v[24:25], v[24:25]
	s_nop 0
	v_pk_fma_f32 v[22:23], v[22:23], v[22:23], v[24:25]
	s_nop 0
	v_pk_add_f32 v[20:21], v[20:21], v[22:23]
	s_nop 0
	v_add_f32_e32 v20, v20, v21
	ds_swizzle_b32 v21, v20 offset:swizzle(SWAP,1)
	s_waitcnt lgkmcnt(0)
	v_add_f32_e32 v20, v20, v21
	ds_swizzle_b32 v21, v20 offset:swizzle(SWAP,2)
	s_waitcnt lgkmcnt(0)
	v_add_f32_e32 v20, v20, v21
	ds_swizzle_b32 v21, v20 offset:swizzle(SWAP,4)
	s_waitcnt lgkmcnt(0)
	v_add_f32_e32 v20, v20, v21
	ds_swizzle_b32 v21, v20 offset:swizzle(SWAP,8)
	s_waitcnt lgkmcnt(0)
	v_add_f32_e32 v20, v20, v21
	ds_swizzle_b32 v21, v20 offset:swizzle(SWAP,16)
	s_waitcnt lgkmcnt(0)
	v_add_f32_e32 v20, v20, v21
	v_fmamk_f32 v20, v20, 0x3b800000, v1
	v_cmp_gt_f32_e32 vcc, s45, v20
	v_mul_f32_e32 v21, 0x4f800000, v20
	s_nop 0
	v_cndmask_b32_e32 v20, v20, v21, vcc
	v_sqrt_f32_e32 v21, v20
	s_nop 0
	v_add_u32_e32 v22, -1, v21
	v_fma_f32 v23, -v22, v21, v20
	v_cmp_ge_f32_e64 s[38:39], 0, v23
	v_add_u32_e32 v23, 1, v21
	s_nop 0
	v_cndmask_b32_e64 v22, v21, v22, s[38:39]
	v_fma_f32 v21, -v23, v21, v20
	v_cmp_lt_f32_e64 s[38:39], 0, v21
	s_nop 1
	v_cndmask_b32_e64 v21, v22, v23, s[38:39]
	v_mul_f32_e32 v22, 0x37800000, v21
	v_cndmask_b32_e32 v21, v21, v22, vcc
	v_cmp_class_f32_e32 vcc, v20, v237
	s_nop 1
	v_cndmask_b32_e32 v20, v21, v20, vcc
	v_div_scale_f32 v21, s[2:3], v20, v20, v43
	v_rcp_f32_e32 v22, v21
	s_mul_i32 s2, s52, 0x1800
	s_add_u32 s48, s48, s2
	s_mul_hi_i32 s2, s52, 0x1800
	v_fma_f32 v23, -v21, v22, 1.0
	v_fmac_f32_e32 v22, v23, v22
	v_div_scale_f32 v23, vcc, v43, v20, v43
	v_mul_f32_e32 v24, v23, v22
	v_fma_f32 v25, -v21, v24, v23
	v_fmac_f32_e32 v24, v25, v22
	v_fma_f32 v21, -v21, v24, v23
	v_div_fmas_f32 v21, v21, v22, v24
	v_div_fixup_f32 v20, v21, v20, v43
	v_mov_b32_e32 v23, v12
	v_mov_b32_e32 v12, v17
	v_mov_b32_e32 v17, v14
	v_mov_b32_e32 v14, v19
	v_mov_b32_e32 v22, v16
	v_pk_mul_f32 v[12:13], v[12:13], v[20:21] op_sel_hi:[1,0]
	v_mov_b32_e32 v16, v18
	v_pk_mul_f32 v[14:15], v[14:15], v[20:21] op_sel_hi:[1,0]
	v_pk_mul_f32 v[22:23], v[22:23], v[20:21] op_sel_hi:[1,0]
	v_pk_mul_f32 v[12:13], v[38:39], v[12:13]
	v_pk_mul_f32 v[16:17], v[16:17], v[20:21] op_sel_hi:[1,0]
	v_pk_mul_f32 v[14:15], v[8:9], v[14:15]
	v_pk_mul_f32 v[22:23], v[6:7], v[22:23]
	v_pk_mul_f32 v[16:17], v[2:3], v[16:17]
	v_bfe_u32 v18, v15, 16, 1
	v_bfe_u32 v19, v14, 16, 1
	v_bfe_u32 v20, v13, 16, 1
	v_bfe_u32 v21, v12, 16, 1
	v_add3_u32 v12, v12, v21, s57
	v_add3_u32 v13, v13, v20, s57
	v_add3_u32 v14, v14, v19, s57
	v_add3_u32 v15, v15, v18, s57
	v_bfe_u32 v18, v22, 16, 1
	v_bfe_u32 v19, v23, 16, 1
	v_bfe_u32 v20, v16, 16, 1
	v_bfe_u32 v21, v17, 16, 1
	s_addc_u32 s49, s49, s2
	v_add3_u32 v17, v17, v21, s57
	v_add3_u32 v16, v16, v20, s57
	v_add3_u32 v19, v23, v19, s57
	v_add3_u32 v18, v22, v18, s57
	s_add_u32 s50, s50, s16
	v_lshrrev_b32_e32 v18, 16, v18
	v_lshrrev_b32_e32 v19, 16, v19
	v_lshrrev_b32_e32 v16, 16, v16
	v_lshrrev_b32_e32 v17, 16, v17
	s_addc_u32 s51, s51, s17
	v_and_or_b32 v15, v15, s33, v17
	v_and_or_b32 v14, v14, s33, v16
	v_and_or_b32 v13, v13, s33, v19
	v_and_or_b32 v12, v12, s33, v18
	s_cmpk_gt_i32 s10, 0x21ff
	global_store_dwordx4 v[4:5], v[12:15], off offset:1024 sc0 sc1
	s_cbranch_scc0 .LBB0_380

; #define GAS __attribute__((address_space(1)))
; __device__ __forceinline__ unsigned pk2(float lo, float hi) { return f2bf(lo) | (f2bf(hi) << 16); }
; #define CONV_U(U, C, Xx) do { U[0] = bf_lo(C.x) * bf_lo(Xx.x); U[1] = bf_hi(C.x) * bf_hi(Xx.x); U[2] = bf_lo(C.y) * bf_lo(Xx.y); U[3] = bf_hi(C.y) * bf_hi(Xx.y); \
;                         U[4] = bf_lo(C.z) * bf_lo(Xx.z); U[5] = bf_hi(C.z) * bf_hi(Xx.z); U[6] = bf_lo(C.w) * bf_lo(Xx.w); U[7] = bf_hi(C.w) * bf_hi(Xx.w); } while (0)
; __global__ void __launch_bounds__(NWAVES * 64, 2) trunk_fwd(Args args) {
;     ...
; #pragma unroll
;                     for (int p = 0; p < 4; ++p) {
;                         float u[8], bv[8], a[8];
;                         CONV_U(u, cc[2 + p], xx[2 + p]);
;                         const v4u b4 = bb[p];
;                         bv[0] = bf_lo(b4.x); bv[1] = bf_hi(b4.x); bv[2] = bf_lo(b4.y); bv[3] = bf_hi(b4.y); bv[4] = bf_lo(b4.z); bv[5] = bf_hi(b4.z); bv[6] = bf_lo(b4.w); bv[7] = bf_hi(b4.w);
; #pragma unroll
;                         for (int i = 0; i < 8; ++i) { a[i] = bv[i] * (w0[i] * um2[i] + w1[i] * um1[i] + w2[i] * u[i]); um2[i] = um1[i]; um1[i] = u[i]; }
;                         v4u o; o.x = pk2(a[0], a[1]); o.y = pk2(a[2], a[3]); o.z = pk2(a[4], a[5]); o.w = pk2(a[6], a[7]);
;                         *(GAS v4u*)(ABR + (size_t)(r0 + p) * KBR + c0) = o;
;                     }
.LBB0_398:
	s_waitcnt vmcnt(17)
	v_lshlrev_b32_e32 v79, 16, v67
	v_lshlrev_b32_e32 v78, 16, v66
	s_waitcnt vmcnt(15)
	v_lshlrev_b32_e32 v87, 16, v71
	v_lshlrev_b32_e32 v86, 16, v70
	v_and_b32_e32 v67, 0xffff0000, v67
	v_and_b32_e32 v66, 0xffff0000, v66
	v_and_b32_e32 v71, 0xffff0000, v71
	v_and_b32_e32 v70, 0xffff0000, v70
	v_pk_mul_f32 v[78:79], v[78:79], v[86:87]
	v_pk_mul_f32 v[86:87], v[66:67], v[70:71]
	s_waitcnt vmcnt(2)
	v_mov_b32_e32 v70, v26
	v_mov_b32_e32 v71, v28
	v_mov_b32_e32 v28, v27
	v_lshlrev_b32_e32 v95, 16, v63
	v_lshlrev_b32_e32 v94, 16, v62
	v_and_b32_e32 v97, 0xffff0000, v63
	v_and_b32_e32 v96, 0xffff0000, v62
	v_mov_b32_e32 v62, v18
	v_mov_b32_e32 v63, v20
	v_pk_mul_f32 v[66:67], v[74:75], v[70:71]
	v_mov_b32_e32 v20, v19
	v_pk_mul_f32 v[18:19], v[80:81], v[28:29]
	v_pk_fma_f32 v[92:93], v[92:93], v[62:63], v[66:67]
	s_waitcnt vmcnt(0)
	v_mov_b32_e32 v67, v24
	v_pk_fma_f32 v[18:19], v[88:89], v[20:21], v[18:19]
	v_mov_b32_e32 v24, v23
	v_mov_b32_e32 v66, v22
	v_pk_fma_f32 v[18:19], v[24:25], v[86:87], v[18:19]
	v_pk_fma_f32 v[92:93], v[66:67], v[78:79], v[92:93]
	v_pk_mul_f32 v[88:89], v[18:19], v[96:97]
	v_lshlrev_b32_e32 v19, 16, v69
	v_lshlrev_b32_e32 v18, 16, v68
	v_lshlrev_b32_e32 v23, 16, v73
	v_lshlrev_b32_e32 v22, 16, v72
	v_pk_mul_f32 v[92:93], v[92:93], v[94:95]
	v_pk_mul_f32 v[94:95], v[18:19], v[22:23]
	v_and_b32_e32 v19, 0xffff0000, v69
	v_and_b32_e32 v18, 0xffff0000, v68
	v_and_b32_e32 v23, 0xffff0000, v73
	v_and_b32_e32 v22, 0xffff0000, v72
	v_mov_b32_e32 v26, v10
	v_mov_b32_e32 v27, v12
	v_mov_b32_e32 v12, v11
	v_pk_mul_f32 v[68:69], v[18:19], v[22:23]
	v_mov_b32_e32 v18, v2
	v_mov_b32_e32 v19, v4
	v_pk_mul_f32 v[22:23], v[82:83], v[26:27]
	v_mov_b32_e32 v4, v3
	v_pk_mul_f32 v[2:3], v[76:77], v[12:13]
	v_pk_fma_f32 v[90:91], v[90:91], v[18:19], v[22:23]
	v_mov_b32_e32 v23, v8
	v_pk_fma_f32 v[2:3], v[84:85], v[4:5], v[2:3]
	v_mov_b32_e32 v8, v7
	v_lshlrev_b32_e32 v73, 16, v65
	v_lshlrev_b32_e32 v72, 16, v64
	v_and_b32_e32 v65, 0xffff0000, v65
	v_and_b32_e32 v64, 0xffff0000, v64
	v_mov_b32_e32 v22, v6
	v_pk_fma_f32 v[2:3], v[8:9], v[68:69], v[2:3]
	v_pk_fma_f32 v[90:91], v[22:23], v[94:95], v[90:91]
	v_pk_mul_f32 v[2:3], v[2:3], v[64:65]
	v_pk_mul_f32 v[72:73], v[90:91], v[72:73]
	v_bfe_u32 v6, v3, 16, 1
	v_bfe_u32 v7, v2, 16, 1
	v_add3_u32 v2, v2, v7, s57
	v_add3_u32 v3, v3, v6, s57
	v_bfe_u32 v6, v92, 16, 1
	v_bfe_u32 v7, v93, 16, 1
	v_bfe_u32 v64, v72, 16, 1
	v_bfe_u32 v65, v73, 16, 1
	v_bfe_u32 v10, v89, 16, 1
	v_bfe_u32 v11, v88, 16, 1
	v_add3_u32 v65, v73, v65, s57
	v_add3_u32 v64, v72, v64, s57
	v_add3_u32 v7, v93, v7, s57
	v_add3_u32 v6, v92, v6, s57
	v_add3_u32 v11, v88, v11, s57
	v_add3_u32 v10, v89, v10, s57
	v_lshrrev_b32_e32 v6, 16, v6
	v_lshrrev_b32_e32 v7, 16, v7
	v_lshrrev_b32_e32 v64, 16, v64
	v_lshrrev_b32_e32 v65, 16, v65
	v_and_or_b32 v91, v3, s33, v65
	v_and_or_b32 v90, v2, s33, v64
	v_and_or_b32 v89, v10, s33, v7
	v_and_or_b32 v88, v11, s33, v6
	v_lshl_add_u64 v[2:3], v[106:107], 0, s[54:55]
	global_store_dwordx4 v[2:3], v[88:91], off sc0 sc1
	v_lshlrev_b32_e32 v3, 16, v59
	v_lshlrev_b32_e32 v2, 16, v58
	v_lshlrev_b32_e32 v7, 16, v55
	v_lshlrev_b32_e32 v6, 16, v54
	v_and_b32_e32 v11, 0xffff0000, v55
	v_and_b32_e32 v10, 0xffff0000, v54
	v_pk_mul_f32 v[54:55], v[78:79], v[70:71]
	v_pk_mul_f32 v[2:3], v[2:3], v[6:7]
	v_and_b32_e32 v7, 0xffff0000, v59
	v_and_b32_e32 v6, 0xffff0000, v58
	v_pk_fma_f32 v[54:55], v[74:75], v[62:63], v[54:55]
	v_pk_mul_f32 v[6:7], v[6:7], v[10:11]
	v_lshlrev_b32_e32 v11, 16, v51
	v_lshlrev_b32_e32 v10, 16, v50
	v_pk_fma_f32 v[54:55], v[66:67], v[2:3], v[54:55]
	v_and_b32_e32 v51, 0xffff0000, v51
	v_pk_mul_f32 v[10:11], v[54:55], v[10:11]
	v_pk_mul_f32 v[54:55], v[86:87], v[28:29]
	v_and_b32_e32 v50, 0xffff0000, v50
	v_pk_fma_f32 v[54:55], v[80:81], v[20:21], v[54:55]
	v_lshlrev_b32_e32 v59, 16, v57
	v_pk_fma_f32 v[54:55], v[24:25], v[6:7], v[54:55]
	v_lshlrev_b32_e32 v58, 16, v56
	v_pk_mul_f32 v[50:51], v[54:55], v[50:51]
	v_lshlrev_b32_e32 v55, 16, v61
	v_lshlrev_b32_e32 v54, 16, v60
	v_pk_mul_f32 v[54:55], v[54:55], v[58:59]
	v_and_b32_e32 v59, 0xffff0000, v61
	v_and_b32_e32 v58, 0xffff0000, v60
	v_pk_mul_f32 v[60:61], v[94:95], v[26:27]
	v_and_b32_e32 v57, 0xffff0000, v57
	v_and_b32_e32 v56, 0xffff0000, v56
	v_pk_fma_f32 v[60:61], v[82:83], v[18:19], v[60:61]
	v_pk_mul_f32 v[56:57], v[58:59], v[56:57]
	v_lshlrev_b32_e32 v59, 16, v53
	v_lshlrev_b32_e32 v58, 16, v52
	v_pk_fma_f32 v[60:61], v[22:23], v[54:55], v[60:61]
	v_and_b32_e32 v53, 0xffff0000, v53
	v_pk_mul_f32 v[58:59], v[60:61], v[58:59]
	v_pk_mul_f32 v[60:61], v[68:69], v[12:13]
	v_and_b32_e32 v52, 0xffff0000, v52
	v_pk_fma_f32 v[60:61], v[76:77], v[4:5], v[60:61]
	v_bfe_u32 v64, v51, 16, 1
	v_pk_fma_f32 v[60:61], v[8:9], v[56:57], v[60:61]
	v_bfe_u32 v65, v50, 16, 1
	v_pk_mul_f32 v[52:53], v[60:61], v[52:53]
	v_add3_u32 v50, v50, v65, s57
	v_bfe_u32 v60, v53, 16, 1
	v_bfe_u32 v61, v52, 16, 1
	v_add3_u32 v51, v51, v64, s57
	v_add3_u32 v52, v52, v61, s57
	v_add3_u32 v53, v53, v60, s57
	v_bfe_u32 v60, v10, 16, 1
	v_bfe_u32 v61, v11, 16, 1
	v_bfe_u32 v64, v58, 16, 1
	v_bfe_u32 v65, v59, 16, 1
	v_add3_u32 v59, v59, v65, s57
	v_add3_u32 v58, v58, v64, s57
	v_add3_u32 v11, v11, v61, s57
	v_add3_u32 v10, v10, v60, s57
	v_lshrrev_b32_e32 v10, 16, v10
	v_lshrrev_b32_e32 v11, 16, v11
	v_lshrrev_b32_e32 v58, 16, v58
	v_lshrrev_b32_e32 v59, 16, v59
	v_and_or_b32 v53, v53, s33, v59
	v_and_or_b32 v52, v52, s33, v58
	v_and_or_b32 v51, v51, s33, v11
	v_and_or_b32 v50, v50, s33, v10
	v_lshl_add_u64 v[10:11], v[106:107], 0, s[52:53]
	global_store_dwordx4 v[10:11], v[50:53], off sc0 sc1
	v_lshlrev_b32_e32 v10, 16, v42
; #define GAS __attribute__((address_space(1)))
; __device__ __forceinline__ unsigned pk2(float lo, float hi) { return f2bf(lo) | (f2bf(hi) << 16); }
; #define CONV_U(U, C, Xx) do { U[0] = bf_lo(C.x) * bf_lo(Xx.x); U[1] = bf_hi(C.x) * bf_hi(Xx.x); U[2] = bf_lo(C.y) * bf_lo(Xx.y); U[3] = bf_hi(C.y) * bf_hi(Xx.y); \
;                         U[4] = bf_lo(C.z) * bf_lo(Xx.z); U[5] = bf_hi(C.z) * bf_hi(Xx.z); U[6] = bf_lo(C.w) * bf_lo(Xx.w); U[7] = bf_hi(C.w) * bf_hi(Xx.w); } while (0)
; __global__ void __launch_bounds__(NWAVES * 64, 2) trunk_fwd(Args args) {
;     ...
; #pragma unroll
;                     for (int p = 0; p < 4; ++p) {
;                         float u[8], bv[8], a[8];
;                         CONV_U(u, cc[2 + p], xx[2 + p]);
;                         const v4u b4 = bb[p];
;                         bv[0] = bf_lo(b4.x); bv[1] = bf_hi(b4.x); bv[2] = bf_lo(b4.y); bv[3] = bf_hi(b4.y); bv[4] = bf_lo(b4.z); bv[5] = bf_hi(b4.z); bv[6] = bf_lo(b4.w); bv[7] = bf_hi(b4.w);
; #pragma unroll
;                         for (int i = 0; i < 8; ++i) { a[i] = bv[i] * (w0[i] * um2[i] + w1[i] * um1[i] + w2[i] * u[i]); um2[i] = um1[i]; um1[i] = u[i]; }
;                         v4u o; o.x = pk2(a[0], a[1]); o.y = pk2(a[2], a[3]); o.z = pk2(a[4], a[5]); o.w = pk2(a[6], a[7]);
;                         *(GAS v4u*)(ABR + (size_t)(r0 + p) * KBR + c0) = o;
;                     }
;     ...
;                     if (tpos + 4 == slen) {
;                         float* co = prompt ? out + O_CP + ((size_t)(L * NB + sb) * 2) * DCONV + c0 : out + O_CS + ((size_t)(L * DB + sb) * 2) * DCONV + c0;
; #pragma unroll
;                         for (int i = 0; i < 8; ++i) { co[i] = um2[i]; co[DCONV + i] = um1[i]; }
;                     }
	v_and_b32_e32 v11, 0xffff0000, v42
	v_lshlrev_b32_e32 v50, 16, v46
	v_and_b32_e32 v51, 0xffff0000, v46
	v_pk_mul_f32 v[50:51], v[10:11], v[50:51]
	v_lshlrev_b32_e32 v10, 16, v43
	v_and_b32_e32 v11, 0xffff0000, v43
	v_lshlrev_b32_e32 v42, 16, v47
	v_and_b32_e32 v43, 0xffff0000, v47
	v_pk_mul_f32 v[52:53], v[10:11], v[42:43]
	v_lshlrev_b32_e32 v10, 16, v44
	v_and_b32_e32 v11, 0xffff0000, v44
	v_lshlrev_b32_e32 v42, 16, v48
	v_and_b32_e32 v43, 0xffff0000, v48
	v_pk_mul_f32 v[46:47], v[2:3], v[70:71]
	v_pk_mul_f32 v[42:43], v[10:11], v[42:43]
	v_lshlrev_b32_e32 v10, 16, v45
	v_and_b32_e32 v11, 0xffff0000, v45
	v_lshlrev_b32_e32 v44, 16, v49
	v_and_b32_e32 v45, 0xffff0000, v49
	v_pk_fma_f32 v[46:47], v[78:79], v[62:63], v[46:47]
	v_mov_b32_e32 v48, v50
	v_mov_b32_e32 v49, v52
	v_pk_mul_f32 v[44:45], v[10:11], v[44:45]
	v_lshlrev_b32_e32 v11, 16, v39
	v_lshlrev_b32_e32 v10, 16, v38
	v_pk_fma_f32 v[46:47], v[66:67], v[48:49], v[46:47]
	v_mov_b32_e32 v58, v51
	v_pk_mul_f32 v[10:11], v[46:47], v[10:11]
	v_pk_mul_f32 v[46:47], v[6:7], v[28:29]
	v_mov_b32_e32 v59, v53
	v_pk_fma_f32 v[46:47], v[86:87], v[20:21], v[46:47]
	v_pk_mul_f32 v[60:61], v[54:55], v[26:27]
	v_and_b32_e32 v39, 0xffff0000, v39
	v_and_b32_e32 v38, 0xffff0000, v38
	v_pk_fma_f32 v[46:47], v[24:25], v[58:59], v[46:47]
	v_pk_fma_f32 v[60:61], v[94:95], v[18:19], v[60:61]
	v_mov_b32_e32 v64, v42
	v_mov_b32_e32 v65, v44
	v_pk_mul_f32 v[38:39], v[46:47], v[38:39]
	v_lshlrev_b32_e32 v47, 16, v41
	v_lshlrev_b32_e32 v46, 16, v40
	v_pk_fma_f32 v[60:61], v[22:23], v[64:65], v[60:61]
	v_and_b32_e32 v41, 0xffff0000, v41
	v_pk_mul_f32 v[46:47], v[60:61], v[46:47]
	v_pk_mul_f32 v[60:61], v[56:57], v[12:13]
	v_and_b32_e32 v40, 0xffff0000, v40
	v_pk_fma_f32 v[60:61], v[68:69], v[4:5], v[60:61]
	v_mov_b32_e32 v68, v43
	v_mov_b32_e32 v69, v45
	v_pk_fma_f32 v[60:61], v[8:9], v[68:69], v[60:61]
	v_bfe_u32 v72, v39, 16, 1
	v_pk_mul_f32 v[40:41], v[60:61], v[40:41]
	v_bfe_u32 v73, v38, 16, 1
	v_bfe_u32 v60, v41, 16, 1
	v_bfe_u32 v61, v40, 16, 1
	v_add3_u32 v38, v38, v73, s57
	v_add3_u32 v39, v39, v72, s57
	v_add3_u32 v40, v40, v61, s57
	v_add3_u32 v41, v41, v60, s57
	v_bfe_u32 v60, v10, 16, 1
	v_bfe_u32 v61, v11, 16, 1
	v_bfe_u32 v72, v46, 16, 1
	v_bfe_u32 v73, v47, 16, 1
	v_add3_u32 v47, v47, v73, s57
	v_add3_u32 v46, v46, v72, s57
	v_add3_u32 v11, v11, v61, s57
	v_add3_u32 v10, v10, v60, s57
	v_lshrrev_b32_e32 v10, 16, v10
	v_lshrrev_b32_e32 v11, 16, v11
	v_lshrrev_b32_e32 v46, 16, v46
	v_lshrrev_b32_e32 v47, 16, v47
	v_and_or_b32 v41, v41, s33, v47
	v_and_or_b32 v40, v40, s33, v46
	v_and_or_b32 v39, v39, s33, v11
	v_and_or_b32 v38, v38, s33, v10
	v_lshl_add_u64 v[10:11], v[106:107], 0, s[50:51]
	global_store_dwordx4 v[10:11], v[38:41], off sc0 sc1
	v_lshlrev_b32_e32 v10, 16, v34
	v_and_b32_e32 v11, 0xffff0000, v34
	v_lshlrev_b32_e32 v38, 16, v30
	v_and_b32_e32 v39, 0xffff0000, v30
	v_pk_mul_f32 v[38:39], v[10:11], v[38:39]
	v_lshlrev_b32_e32 v10, 16, v35
	v_and_b32_e32 v11, 0xffff0000, v35
	v_lshlrev_b32_e32 v30, 16, v31
	v_and_b32_e32 v31, 0xffff0000, v31
	v_pk_mul_f32 v[40:41], v[10:11], v[30:31]
	v_lshlrev_b32_e32 v10, 16, v36
	v_and_b32_e32 v11, 0xffff0000, v36
	v_lshlrev_b32_e32 v30, 16, v32
	v_and_b32_e32 v31, 0xffff0000, v32
	v_pk_mul_f32 v[34:35], v[48:49], v[70:71]
	v_pk_mul_f32 v[30:31], v[10:11], v[30:31]
	v_lshlrev_b32_e32 v10, 16, v37
	v_and_b32_e32 v11, 0xffff0000, v37
	v_lshlrev_b32_e32 v32, 16, v33
	v_and_b32_e32 v33, 0xffff0000, v33
	v_pk_fma_f32 v[2:3], v[2:3], v[62:63], v[34:35]
	v_mov_b32_e32 v34, v38
	v_mov_b32_e32 v35, v40
	v_pk_mul_f32 v[32:33], v[10:11], v[32:33]
	v_lshlrev_b32_e32 v11, 16, v15
	v_lshlrev_b32_e32 v10, 16, v14
	v_pk_fma_f32 v[2:3], v[66:67], v[34:35], v[2:3]
	s_ashr_i32 s67, s18, 9
	v_pk_mul_f32 v[2:3], v[2:3], v[10:11]
	v_pk_mul_f32 v[10:11], v[58:59], v[28:29]
	v_and_b32_e32 v15, 0xffff0000, v15
	v_pk_fma_f32 v[6:7], v[6:7], v[20:21], v[10:11]
	v_mov_b32_e32 v10, v39
	v_mov_b32_e32 v11, v41
	v_and_b32_e32 v14, 0xffff0000, v14
	v_pk_fma_f32 v[6:7], v[24:25], v[10:11], v[6:7]
	v_pk_mul_f32 v[12:13], v[68:69], v[12:13]
	s_cmp_eq_u32 s78, s77
	v_pk_mul_f32 v[6:7], v[6:7], v[14:15]
	v_lshlrev_b32_e32 v11, 16, v17
	v_lshlrev_b32_e32 v10, 16, v16
	v_and_b32_e32 v15, 0xffff0000, v17
	v_and_b32_e32 v14, 0xffff0000, v16
	v_pk_mul_f32 v[16:17], v[64:65], v[26:27]
	v_pk_fma_f32 v[4:5], v[56:57], v[4:5], v[12:13]
	v_mov_b32_e32 v12, v31
	v_mov_b32_e32 v13, v33
	s_cselect_b64 s[82:83], -1, 0
	s_add_u32 s10, s12, s84
	v_pk_fma_f32 v[16:17], v[54:55], v[18:19], v[16:17]
	v_mov_b32_e32 v18, v30
	v_mov_b32_e32 v19, v32
	v_pk_fma_f32 v[4:5], v[8:9], v[12:13], v[4:5]
	s_addc_u32 s66, s13, s85
	s_add_i32 vcc_lo, s67, s16
	v_pk_fma_f32 v[16:17], v[22:23], v[18:19], v[16:17]
	v_pk_mul_f32 v[4:5], v[4:5], v[14:15]
	s_ashr_i32 vcc_hi, vcc_lo, 31
	v_pk_mul_f32 v[10:11], v[16:17], v[10:11]
	v_bfe_u32 v8, v5, 16, 1
	v_bfe_u32 v9, v4, 16, 1
	v_bfe_u32 v12, v7, 16, 1
	v_bfe_u32 v13, v6, 16, 1
	s_lshl_b64 vcc, vcc, 13
	v_add3_u32 v6, v6, v13, s57
	v_add3_u32 v7, v7, v12, s57
	v_add3_u32 v4, v4, v9, s57
	v_add3_u32 v5, v5, v8, s57
	v_bfe_u32 v8, v2, 16, 1
	v_bfe_u32 v9, v3, 16, 1
	v_bfe_u32 v12, v10, 16, 1
	v_bfe_u32 v13, v11, 16, 1
	s_add_u32 s67, s19, vcc_lo
	v_add3_u32 v11, v11, v13, s57
	v_add3_u32 v10, v10, v12, s57
	v_add3_u32 v3, v3, v9, s57
	v_add3_u32 v2, v2, v8, s57
	s_addc_u32 s68, s45, vcc_hi
	v_lshrrev_b32_e32 v2, 16, v2
	v_lshrrev_b32_e32 v3, 16, v3
	v_lshrrev_b32_e32 v8, 16, v10
	v_lshrrev_b32_e32 v9, 16, v11
	s_cmp_lg_u32 s78, s77
	v_and_or_b32 v5, v5, s33, v9
	v_and_or_b32 v4, v4, s33, v8
	v_and_or_b32 v3, v7, s33, v3
	v_and_or_b32 v2, v6, s33, v2
	v_lshl_add_u64 v[6:7], v[106:107], 0, s[48:49]
	v_lshlrev_b32_e32 v116, 2, v98
	global_store_dwordx4 v[6:7], v[2:5], off sc0 sc1
	s_cbranch_scc1 .LBB0_400
	s_and_b64 s[78:79], s[42:43], exec
	s_cselect_b32 s79, s68, s66
	s_cselect_b32 s78, s67, s10
	v_mov_b32_e32 v117, v179
	v_lshl_add_u64 v[2:3], s[78:79], 0, v[116:117]
	v_add_co_u32_e32 v2, vcc, 0x1000, v2
	global_store_dwordx4 v116, v[50:53], s[78:79] sc0 sc1
	s_nop 0
	v_addc_co_u32_e32 v3, vcc, 0, v3, vcc
	global_store_dwordx4 v[2:3], v[38:41], off sc0 sc1
	global_store_dwordx4 v116, v[42:45], s[78:79] offset:16 sc0 sc1
	v_readlane_b32 s79, v254, 35
	global_store_dwordx4 v[2:3], v[30:33], off offset:16 sc0 sc1

; #define GAS __attribute__((address_space(1)))
; __device__ __forceinline__ unsigned pk2(float lo, float hi) { return f2bf(lo) | (f2bf(hi) << 16); }
; #define CONV_U(U, C, Xx) do { U[0] = bf_lo(C.x) * bf_lo(Xx.x); U[1] = bf_hi(C.x) * bf_hi(Xx.x); U[2] = bf_lo(C.y) * bf_lo(Xx.y); U[3] = bf_hi(C.y) * bf_hi(Xx.y); \
;                         U[4] = bf_lo(C.z) * bf_lo(Xx.z); U[5] = bf_hi(C.z) * bf_hi(Xx.z); U[6] = bf_lo(C.w) * bf_lo(Xx.w); U[7] = bf_hi(C.w) * bf_hi(Xx.w); } while (0)
; __global__ void __launch_bounds__(NWAVES * 64, 2) trunk_fwd(Args args) {
;     ...
; #pragma unroll
;                     for (int p = 0; p < 4; ++p) {
;                         float u[8], bv[8], a[8];
;                         CONV_U(u, cc[2 + p], xx[2 + p]);
;                         const v4u b4 = bb[p];
;                         bv[0] = bf_lo(b4.x); bv[1] = bf_hi(b4.x); bv[2] = bf_lo(b4.y); bv[3] = bf_hi(b4.y); bv[4] = bf_lo(b4.z); bv[5] = bf_hi(b4.z); bv[6] = bf_lo(b4.w); bv[7] = bf_hi(b4.w);
; #pragma unroll
;                         for (int i = 0; i < 8; ++i) { a[i] = bv[i] * (w0[i] * um2[i] + w1[i] * um1[i] + w2[i] * u[i]); um2[i] = um1[i]; um1[i] = u[i]; }
;                         v4u o; o.x = pk2(a[0], a[1]); o.y = pk2(a[2], a[3]); o.z = pk2(a[4], a[5]); o.w = pk2(a[6], a[7]);
;                         *(GAS v4u*)(ABR + (size_t)(r0 + p) * KBR + c0) = o;
;                     }
.LBB0_414:
	s_waitcnt vmcnt(17)
	v_lshlrev_b32_e32 v63, 16, v75
	v_lshlrev_b32_e32 v62, 16, v74
	s_waitcnt vmcnt(15)
	v_lshlrev_b32_e32 v79, 16, v71
	v_lshlrev_b32_e32 v78, 16, v70
	v_pk_mul_f32 v[78:79], v[62:63], v[78:79]
	v_and_b32_e32 v63, 0xffff0000, v75
	v_and_b32_e32 v62, 0xffff0000, v74
	v_and_b32_e32 v71, 0xffff0000, v71
	v_and_b32_e32 v70, 0xffff0000, v70
	v_pk_mul_f32 v[74:75], v[62:63], v[70:71]
	s_waitcnt vmcnt(2)
	v_mov_b32_e32 v70, v26
	v_mov_b32_e32 v71, v28
	v_mov_b32_e32 v28, v27
	v_lshlrev_b32_e32 v87, 16, v67
	v_lshlrev_b32_e32 v86, 16, v66
	v_and_b32_e32 v97, 0xffff0000, v67
	v_and_b32_e32 v96, 0xffff0000, v66
	v_mov_b32_e32 v62, v18
	v_mov_b32_e32 v63, v20
	v_pk_mul_f32 v[66:67], v[90:91], v[70:71]
	v_mov_b32_e32 v20, v19
	v_pk_mul_f32 v[18:19], v[80:81], v[28:29]
	v_pk_fma_f32 v[94:95], v[94:95], v[62:63], v[66:67]
	s_waitcnt vmcnt(0)
	v_mov_b32_e32 v67, v24
	v_pk_fma_f32 v[18:19], v[88:89], v[20:21], v[18:19]
	v_mov_b32_e32 v24, v23
	v_mov_b32_e32 v66, v22
	v_pk_fma_f32 v[18:19], v[24:25], v[74:75], v[18:19]
	v_pk_fma_f32 v[94:95], v[66:67], v[78:79], v[94:95]
	v_pk_mul_f32 v[88:89], v[18:19], v[96:97]
	v_lshlrev_b32_e32 v19, 16, v77
	v_lshlrev_b32_e32 v18, 16, v76
	v_lshlrev_b32_e32 v23, 16, v73
	v_lshlrev_b32_e32 v22, 16, v72
	v_pk_mul_f32 v[86:87], v[94:95], v[86:87]
	v_pk_mul_f32 v[94:95], v[18:19], v[22:23]
	v_and_b32_e32 v19, 0xffff0000, v77
	v_and_b32_e32 v18, 0xffff0000, v76
	v_and_b32_e32 v23, 0xffff0000, v73
	v_and_b32_e32 v22, 0xffff0000, v72
	v_mov_b32_e32 v26, v10
	v_mov_b32_e32 v27, v12
	v_mov_b32_e32 v12, v11
	v_pk_mul_f32 v[72:73], v[18:19], v[22:23]
	v_mov_b32_e32 v18, v2
	v_mov_b32_e32 v19, v4
	v_pk_mul_f32 v[22:23], v[82:83], v[26:27]
	v_mov_b32_e32 v4, v3
	v_pk_mul_f32 v[2:3], v[64:65], v[12:13]
	v_pk_fma_f32 v[92:93], v[92:93], v[18:19], v[22:23]
	v_mov_b32_e32 v23, v8
	v_pk_fma_f32 v[2:3], v[84:85], v[4:5], v[2:3]
	v_mov_b32_e32 v8, v7
	v_lshlrev_b32_e32 v77, 16, v69
	v_lshlrev_b32_e32 v76, 16, v68
	v_and_b32_e32 v69, 0xffff0000, v69
	v_and_b32_e32 v68, 0xffff0000, v68
	v_mov_b32_e32 v22, v6
	v_pk_fma_f32 v[2:3], v[8:9], v[72:73], v[2:3]
	v_pk_fma_f32 v[92:93], v[22:23], v[94:95], v[92:93]
	v_pk_mul_f32 v[2:3], v[2:3], v[68:69]
	v_pk_mul_f32 v[76:77], v[92:93], v[76:77]
	v_bfe_u32 v6, v3, 16, 1
	v_bfe_u32 v7, v2, 16, 1
	v_add3_u32 v2, v2, v7, s57
	v_add3_u32 v3, v3, v6, s57
	v_bfe_u32 v6, v86, 16, 1
	v_bfe_u32 v7, v87, 16, 1
	v_bfe_u32 v68, v76, 16, 1
	v_bfe_u32 v69, v77, 16, 1
	v_bfe_u32 v10, v89, 16, 1
	v_bfe_u32 v11, v88, 16, 1
	v_add3_u32 v69, v77, v69, s57
	v_add3_u32 v68, v76, v68, s57
	v_add3_u32 v7, v87, v7, s57
	v_add3_u32 v6, v86, v6, s57
	v_add3_u32 v11, v88, v11, s57
	v_add3_u32 v10, v89, v10, s57
	v_lshrrev_b32_e32 v6, 16, v6
	v_lshrrev_b32_e32 v7, 16, v7
	v_lshrrev_b32_e32 v68, 16, v68
	v_lshrrev_b32_e32 v69, 16, v69
	v_and_or_b32 v87, v3, s33, v69
	v_and_or_b32 v86, v2, s33, v68
	v_and_or_b32 v85, v10, s33, v7
	v_and_or_b32 v84, v11, s33, v6
	v_lshl_add_u64 v[2:3], v[114:115], 0, s[54:55]
	global_store_dwordx4 v[2:3], v[84:87], off sc0 sc1
	v_lshlrev_b32_e32 v3, 16, v59
	v_lshlrev_b32_e32 v2, 16, v58
	v_lshlrev_b32_e32 v7, 16, v55
	v_lshlrev_b32_e32 v6, 16, v54
	v_and_b32_e32 v11, 0xffff0000, v55
	v_and_b32_e32 v10, 0xffff0000, v54
	v_pk_mul_f32 v[54:55], v[78:79], v[70:71]
	v_pk_mul_f32 v[2:3], v[2:3], v[6:7]
	v_and_b32_e32 v7, 0xffff0000, v59
	v_and_b32_e32 v6, 0xffff0000, v58
	v_pk_fma_f32 v[54:55], v[90:91], v[62:63], v[54:55]
	v_pk_mul_f32 v[6:7], v[6:7], v[10:11]
	v_lshlrev_b32_e32 v11, 16, v51
	v_lshlrev_b32_e32 v10, 16, v50
	v_pk_fma_f32 v[54:55], v[66:67], v[2:3], v[54:55]
	v_and_b32_e32 v51, 0xffff0000, v51
	v_pk_mul_f32 v[10:11], v[54:55], v[10:11]
	v_pk_mul_f32 v[54:55], v[74:75], v[28:29]
	v_and_b32_e32 v50, 0xffff0000, v50
	v_pk_fma_f32 v[54:55], v[80:81], v[20:21], v[54:55]
	v_lshlrev_b32_e32 v59, 16, v57
	v_pk_fma_f32 v[54:55], v[24:25], v[6:7], v[54:55]
	v_lshlrev_b32_e32 v58, 16, v56
	v_pk_mul_f32 v[50:51], v[54:55], v[50:51]
	v_lshlrev_b32_e32 v55, 16, v61
	v_lshlrev_b32_e32 v54, 16, v60
	v_pk_mul_f32 v[54:55], v[54:55], v[58:59]
	v_and_b32_e32 v59, 0xffff0000, v61
	v_and_b32_e32 v58, 0xffff0000, v60
	v_pk_mul_f32 v[60:61], v[94:95], v[26:27]
	v_and_b32_e32 v57, 0xffff0000, v57
	v_and_b32_e32 v56, 0xffff0000, v56
	v_pk_fma_f32 v[60:61], v[82:83], v[18:19], v[60:61]
	v_pk_mul_f32 v[56:57], v[58:59], v[56:57]
	v_lshlrev_b32_e32 v59, 16, v53
	v_lshlrev_b32_e32 v58, 16, v52
	v_pk_fma_f32 v[60:61], v[22:23], v[54:55], v[60:61]
	v_and_b32_e32 v53, 0xffff0000, v53
	v_pk_mul_f32 v[58:59], v[60:61], v[58:59]
	v_pk_mul_f32 v[60:61], v[72:73], v[12:13]
	v_and_b32_e32 v52, 0xffff0000, v52
	v_pk_fma_f32 v[60:61], v[64:65], v[4:5], v[60:61]
	v_bfe_u32 v64, v51, 16, 1
	v_pk_fma_f32 v[60:61], v[8:9], v[56:57], v[60:61]
	v_bfe_u32 v65, v50, 16, 1
	v_pk_mul_f32 v[52:53], v[60:61], v[52:53]
	v_add3_u32 v50, v50, v65, s57
	v_bfe_u32 v60, v53, 16, 1
	v_bfe_u32 v61, v52, 16, 1
	v_add3_u32 v51, v51, v64, s57
	v_add3_u32 v52, v52, v61, s57
	v_add3_u32 v53, v53, v60, s57
	v_bfe_u32 v60, v10, 16, 1
	v_bfe_u32 v61, v11, 16, 1
	v_bfe_u32 v64, v58, 16, 1
	v_bfe_u32 v65, v59, 16, 1
	v_add3_u32 v59, v59, v65, s57
	v_add3_u32 v58, v58, v64, s57
	v_add3_u32 v11, v11, v61, s57
	v_add3_u32 v10, v10, v60, s57
	v_lshrrev_b32_e32 v10, 16, v10
	v_lshrrev_b32_e32 v11, 16, v11
	v_lshrrev_b32_e32 v58, 16, v58
	v_lshrrev_b32_e32 v59, 16, v59
	v_and_or_b32 v53, v53, s33, v59
	v_and_or_b32 v52, v52, s33, v58
	v_and_or_b32 v51, v51, s33, v11
	v_and_or_b32 v50, v50, s33, v10
	v_lshl_add_u64 v[10:11], v[114:115], 0, s[52:53]
	global_store_dwordx4 v[10:11], v[50:53], off sc0 sc1
	v_lshlrev_b32_e32 v10, 16, v46
; #define GAS __attribute__((address_space(1)))
; __device__ __forceinline__ unsigned pk2(float lo, float hi) { return f2bf(lo) | (f2bf(hi) << 16); }
; #define CONV_U(U, C, Xx) do { U[0] = bf_lo(C.x) * bf_lo(Xx.x); U[1] = bf_hi(C.x) * bf_hi(Xx.x); U[2] = bf_lo(C.y) * bf_lo(Xx.y); U[3] = bf_hi(C.y) * bf_hi(Xx.y); \
;                         U[4] = bf_lo(C.z) * bf_lo(Xx.z); U[5] = bf_hi(C.z) * bf_hi(Xx.z); U[6] = bf_lo(C.w) * bf_lo(Xx.w); U[7] = bf_hi(C.w) * bf_hi(Xx.w); } while (0)
; __global__ void __launch_bounds__(NWAVES * 64, 2) trunk_fwd(Args args) {
;     ...
; #pragma unroll
;                     for (int p = 0; p < 4; ++p) {
;                         float u[8], bv[8], a[8];
;                         CONV_U(u, cc[2 + p], xx[2 + p]);
;                         const v4u b4 = bb[p];
;                         bv[0] = bf_lo(b4.x); bv[1] = bf_hi(b4.x); bv[2] = bf_lo(b4.y); bv[3] = bf_hi(b4.y); bv[4] = bf_lo(b4.z); bv[5] = bf_hi(b4.z); bv[6] = bf_lo(b4.w); bv[7] = bf_hi(b4.w);
; #pragma unroll
;                         for (int i = 0; i < 8; ++i) { a[i] = bv[i] * (w0[i] * um2[i] + w1[i] * um1[i] + w2[i] * u[i]); um2[i] = um1[i]; um1[i] = u[i]; }
;                         v4u o; o.x = pk2(a[0], a[1]); o.y = pk2(a[2], a[3]); o.z = pk2(a[4], a[5]); o.w = pk2(a[6], a[7]);
;                         *(GAS v4u*)(ABR + (size_t)(r0 + p) * KBR + c0) = o;
;                     }
;     ...
;                     if (tpos + 4 == slen) {
;                         float* co = prompt ? out + O_CP + ((size_t)(L * NB + sb) * 2) * DCONV + c0 : out + O_CS + ((size_t)(L * DB + sb) * 2) * DCONV + c0;
; #pragma unroll
;                         for (int i = 0; i < 8; ++i) { co[i] = um2[i]; co[DCONV + i] = um1[i]; }
;                     }
	v_and_b32_e32 v11, 0xffff0000, v46
	v_lshlrev_b32_e32 v50, 16, v42
	v_and_b32_e32 v51, 0xffff0000, v42
	v_pk_mul_f32 v[50:51], v[10:11], v[50:51]
	v_lshlrev_b32_e32 v10, 16, v47
	v_and_b32_e32 v11, 0xffff0000, v47
	v_lshlrev_b32_e32 v42, 16, v43
	v_and_b32_e32 v43, 0xffff0000, v43
	v_pk_mul_f32 v[52:53], v[10:11], v[42:43]
	v_lshlrev_b32_e32 v10, 16, v48
	v_and_b32_e32 v11, 0xffff0000, v48
	v_lshlrev_b32_e32 v42, 16, v44
	v_and_b32_e32 v43, 0xffff0000, v44
	v_pk_mul_f32 v[46:47], v[2:3], v[70:71]
	v_pk_mul_f32 v[42:43], v[10:11], v[42:43]
	v_lshlrev_b32_e32 v10, 16, v49
	v_and_b32_e32 v11, 0xffff0000, v49
	v_lshlrev_b32_e32 v44, 16, v45
	v_and_b32_e32 v45, 0xffff0000, v45
	v_pk_fma_f32 v[46:47], v[78:79], v[62:63], v[46:47]
	v_mov_b32_e32 v48, v50
	v_mov_b32_e32 v49, v52
	v_pk_mul_f32 v[44:45], v[10:11], v[44:45]
	v_lshlrev_b32_e32 v11, 16, v39
	v_lshlrev_b32_e32 v10, 16, v38
	v_pk_fma_f32 v[46:47], v[66:67], v[48:49], v[46:47]
	v_mov_b32_e32 v58, v51
	v_pk_mul_f32 v[10:11], v[46:47], v[10:11]
	v_pk_mul_f32 v[46:47], v[6:7], v[28:29]
	v_mov_b32_e32 v59, v53
	v_pk_fma_f32 v[46:47], v[74:75], v[20:21], v[46:47]
	v_pk_mul_f32 v[60:61], v[54:55], v[26:27]
	v_and_b32_e32 v39, 0xffff0000, v39
	v_and_b32_e32 v38, 0xffff0000, v38
	v_pk_fma_f32 v[46:47], v[24:25], v[58:59], v[46:47]
	v_pk_fma_f32 v[60:61], v[94:95], v[18:19], v[60:61]
	v_mov_b32_e32 v64, v42
	v_mov_b32_e32 v65, v44
	v_pk_mul_f32 v[38:39], v[46:47], v[38:39]
	v_lshlrev_b32_e32 v47, 16, v41
	v_lshlrev_b32_e32 v46, 16, v40
	v_pk_fma_f32 v[60:61], v[22:23], v[64:65], v[60:61]
	v_mov_b32_e32 v68, v43
	v_pk_mul_f32 v[46:47], v[60:61], v[46:47]
	v_pk_mul_f32 v[60:61], v[56:57], v[12:13]
	v_mov_b32_e32 v69, v45
	v_pk_fma_f32 v[60:61], v[72:73], v[4:5], v[60:61]
	v_and_b32_e32 v41, 0xffff0000, v41
	v_and_b32_e32 v40, 0xffff0000, v40
	v_pk_fma_f32 v[60:61], v[8:9], v[68:69], v[60:61]
	v_bfe_u32 v72, v39, 16, 1
	v_pk_mul_f32 v[40:41], v[60:61], v[40:41]
	v_bfe_u32 v73, v38, 16, 1
	v_bfe_u32 v60, v41, 16, 1
	v_bfe_u32 v61, v40, 16, 1
	v_add3_u32 v38, v38, v73, s57
	v_add3_u32 v39, v39, v72, s57
	v_add3_u32 v40, v40, v61, s57
	v_add3_u32 v41, v41, v60, s57
	v_bfe_u32 v60, v10, 16, 1
	v_bfe_u32 v61, v11, 16, 1
	v_bfe_u32 v72, v46, 16, 1
	v_bfe_u32 v73, v47, 16, 1
	v_add3_u32 v47, v47, v73, s57
	v_add3_u32 v46, v46, v72, s57
	v_add3_u32 v11, v11, v61, s57
	v_add3_u32 v10, v10, v60, s57
	v_lshrrev_b32_e32 v10, 16, v10
	v_lshrrev_b32_e32 v11, 16, v11
	v_lshrrev_b32_e32 v46, 16, v46
	v_lshrrev_b32_e32 v47, 16, v47
	v_and_or_b32 v41, v41, s33, v47
	v_and_or_b32 v40, v40, s33, v46
	v_and_or_b32 v39, v39, s33, v11
	v_and_or_b32 v38, v38, s33, v10
	v_lshl_add_u64 v[10:11], v[114:115], 0, s[50:51]
	global_store_dwordx4 v[10:11], v[38:41], off sc0 sc1
	v_lshlrev_b32_e32 v10, 16, v34
	v_and_b32_e32 v11, 0xffff0000, v34
	v_lshlrev_b32_e32 v38, 16, v30
	v_and_b32_e32 v39, 0xffff0000, v30
	v_pk_mul_f32 v[38:39], v[10:11], v[38:39]
	v_lshlrev_b32_e32 v10, 16, v35
	v_and_b32_e32 v11, 0xffff0000, v35
	v_lshlrev_b32_e32 v30, 16, v31
	v_and_b32_e32 v31, 0xffff0000, v31
	v_pk_mul_f32 v[40:41], v[10:11], v[30:31]
	v_lshlrev_b32_e32 v10, 16, v36
	v_and_b32_e32 v11, 0xffff0000, v36
	v_lshlrev_b32_e32 v30, 16, v32
	v_and_b32_e32 v31, 0xffff0000, v32
	v_pk_mul_f32 v[34:35], v[48:49], v[70:71]
	v_pk_mul_f32 v[30:31], v[10:11], v[30:31]
	v_lshlrev_b32_e32 v10, 16, v37
	v_and_b32_e32 v11, 0xffff0000, v37
	v_lshlrev_b32_e32 v32, 16, v33
	v_and_b32_e32 v33, 0xffff0000, v33
	v_pk_fma_f32 v[2:3], v[2:3], v[62:63], v[34:35]
	v_mov_b32_e32 v34, v38
	v_mov_b32_e32 v35, v40
	v_pk_mul_f32 v[32:33], v[10:11], v[32:33]
	v_lshlrev_b32_e32 v11, 16, v15
	v_lshlrev_b32_e32 v10, 16, v14
	v_pk_fma_f32 v[2:3], v[66:67], v[34:35], v[2:3]
	v_and_b32_e32 v15, 0xffff0000, v15
	v_pk_mul_f32 v[2:3], v[2:3], v[10:11]
	v_pk_mul_f32 v[10:11], v[58:59], v[28:29]
	v_and_b32_e32 v14, 0xffff0000, v14
	v_pk_fma_f32 v[6:7], v[6:7], v[20:21], v[10:11]
	v_mov_b32_e32 v10, v39
	v_mov_b32_e32 v11, v41
	v_pk_fma_f32 v[6:7], v[24:25], v[10:11], v[6:7]
	v_pk_mul_f32 v[12:13], v[68:69], v[12:13]
	v_pk_mul_f32 v[6:7], v[6:7], v[14:15]
	v_lshlrev_b32_e32 v11, 16, v17
	v_lshlrev_b32_e32 v10, 16, v16
	v_and_b32_e32 v15, 0xffff0000, v17
	v_and_b32_e32 v14, 0xffff0000, v16
	v_pk_mul_f32 v[16:17], v[64:65], v[26:27]
	v_pk_fma_f32 v[4:5], v[56:57], v[4:5], v[12:13]
	v_mov_b32_e32 v12, v31
	v_mov_b32_e32 v13, v33
	v_pk_fma_f32 v[16:17], v[54:55], v[18:19], v[16:17]
	v_mov_b32_e32 v18, v30
	v_mov_b32_e32 v19, v32
	v_pk_fma_f32 v[4:5], v[8:9], v[12:13], v[4:5]
	v_pk_fma_f32 v[16:17], v[22:23], v[18:19], v[16:17]
	v_pk_mul_f32 v[4:5], v[4:5], v[14:15]
	v_pk_mul_f32 v[10:11], v[16:17], v[10:11]
	v_bfe_u32 v8, v5, 16, 1
	v_bfe_u32 v9, v4, 16, 1
	v_bfe_u32 v12, v7, 16, 1
	v_bfe_u32 v13, v6, 16, 1
	v_add3_u32 v6, v6, v13, s57
	v_add3_u32 v7, v7, v12, s57
	v_add3_u32 v4, v4, v9, s57
	v_add3_u32 v5, v5, v8, s57
	v_bfe_u32 v8, v2, 16, 1
	v_bfe_u32 v9, v3, 16, 1
	v_bfe_u32 v12, v10, 16, 1
	v_bfe_u32 v13, v11, 16, 1
	v_add3_u32 v11, v11, v13, s57
	v_add3_u32 v10, v10, v12, s57
	v_add3_u32 v3, v3, v9, s57
	v_add3_u32 v2, v2, v8, s57
	v_lshrrev_b32_e32 v2, 16, v2
	v_lshrrev_b32_e32 v3, 16, v3
	v_lshrrev_b32_e32 v8, 16, v10
	v_lshrrev_b32_e32 v9, 16, v11
	v_and_or_b32 v5, v5, s33, v9
	v_and_or_b32 v4, v4, s33, v8
	v_and_or_b32 v3, v7, s33, v3
	v_and_or_b32 v2, v6, s33, v2
	v_lshl_add_u64 v[6:7], v[114:115], 0, s[48:49]
	s_andn2_b64 vcc, exec, s[82:83]
	global_store_dwordx4 v[6:7], v[2:5], off
	s_cbranch_vccnz .LBB0_383
	s_and_b64 s[38:39], s[42:43], exec
	s_cselect_b32 s39, s68, s66
	s_cselect_b32 s38, s67, s10
	v_mov_b32_e32 v117, v179
	v_lshl_add_u64 v[2:3], s[38:39], 0, v[116:117]
	v_add_co_u32_e32 v2, vcc, 0x1000, v2
	global_store_dwordx4 v116, v[50:53], s[38:39] offset:2048
	s_nop 0
	v_addc_co_u32_e32 v3, vcc, 0, v3, vcc
	global_store_dwordx4 v[2:3], v[38:41], off offset:2048
	global_store_dwordx4 v116, v[42:45], s[38:39] offset:2064
	global_store_dwordx4 v[2:3], v[30:33], off offset:2064
	s_branch .LBB0_383

;     __device__ __forceinline__ void operator()(const f32x4 (&acc)[2][2][4][2], const Unit& u, int wr, int wc, int fr, int fq) const {
;         const int rowt = u.pm * BM + wr * 64 + fr, col0 = u.pn * BM + wc * 32 + 8 * fq;
;     ...
;         u32x4 gb[2][4][2];
; #pragma unroll
;         for (int ai = 0; ai < 2; ++ai)
; #pragma unroll
;             for (int m = 0; m < 4; ++m)
; #pragma unroll
;                 for (int bj = 0; bj < 2; ++bj) gb[ai][m][bj] = *(const u32x4*)(gg + (size_t)(rowt + ai * HALF + m * 16) * 4096 + 2048 + col0 + bj * HALF);
;         asm volatile("" ::: "memory");
.LBB0_510:
	s_cmp_lg_u32 s45, 0
	v_mov_b32_e32 v138, v0
	s_cselect_b64 s[16:17], -1, 0
	s_lshl_b32 s3, s90, 8
	v_readlane_b32 s12, v254, 53
	s_add_i32 s3, s3, s12
	s_lshl_b32 s40, s2, 8
	v_readlane_b32 s2, v254, 47
	v_and_b32_e32 v243, 15, v138
	v_lshrrev_b32_e32 v138, 1, v138
	s_or_b32 s2, s40, s2
	v_or_b32_e32 v200, s3, v243
	v_and_b32_e32 v178, 24, v138
	v_or_b32_e32 v202, s2, v178
	v_or_b32_e32 v226, 16, v200
	v_or_b32_e32 v224, 32, v200
	v_or_b32_e32 v222, 48, v200
	s_cmp_eq_u32 s45, 0
	v_ashrrev_i32_e32 v203, 31, v202
	v_ashrrev_i32_e32 v201, 31, v200
	v_ashrrev_i32_e32 v227, 31, v226
	v_ashrrev_i32_e32 v225, 31, v224
	v_ashrrev_i32_e32 v223, 31, v222
	s_cbranch_scc1 .LBB0_518
	v_lshlrev_b64 v[138:139], 13, v[200:201]
	v_lshl_add_u64 v[138:139], s[42:43], 0, v[138:139]
	v_lshlrev_b64 v[220:221], 1, v[202:203]
	v_lshl_add_u64 v[138:139], v[138:139], 0, v[220:221]
	s_mov_b64 s[2:3], 0x1000
	v_lshl_add_u64 v[140:141], v[138:139], 0, s[2:3]
	v_add_co_u32_e32 v138, vcc, 0x1000, v138
	v_add_u32_e32 v234, 0x80, v200
	s_nop 0
	v_addc_co_u32_e32 v139, vcc, 0, v139, vcc
	global_load_dwordx4 v[244:247], v[138:139], off
	global_load_dwordx4 v[196:199], v[140:141], off offset:256
	v_lshlrev_b64 v[138:139], 13, v[226:227]
	v_lshl_add_u64 v[138:139], s[42:43], 0, v[138:139]
	v_lshl_add_u64 v[138:139], v[138:139], 0, v[220:221]
	v_lshl_add_u64 v[140:141], v[138:139], 0, s[2:3]
	v_add_co_u32_e32 v138, vcc, 0x1000, v138
	v_ashrrev_i32_e32 v235, 31, v234
	s_nop 0
	v_addc_co_u32_e32 v139, vcc, 0, v139, vcc
	global_load_dwordx4 v[192:195], v[138:139], off
	global_load_dwordx4 v[188:191], v[140:141], off offset:256
	v_lshlrev_b64 v[138:139], 13, v[224:225]
	v_lshl_add_u64 v[138:139], s[42:43], 0, v[138:139]
	v_lshl_add_u64 v[138:139], v[138:139], 0, v[220:221]
	v_lshl_add_u64 v[140:141], v[138:139], 0, s[2:3]
	v_add_co_u32_e32 v138, vcc, 0x1000, v138
	v_add_u32_e32 v232, 0x90, v200
	s_nop 0
	v_addc_co_u32_e32 v139, vcc, 0, v139, vcc
	global_load_dwordx4 v[184:187], v[138:139], off
	global_load_dwordx4 v[180:183], v[140:141], off offset:256
	v_lshlrev_b64 v[138:139], 13, v[222:223]
	v_lshl_add_u64 v[138:139], s[42:43], 0, v[138:139]
	v_lshl_add_u64 v[138:139], v[138:139], 0, v[220:221]
	v_lshl_add_u64 v[140:141], v[138:139], 0, s[2:3]
	v_add_co_u32_e32 v138, vcc, 0x1000, v138
	v_ashrrev_i32_e32 v233, 31, v232
	s_nop 0
	v_addc_co_u32_e32 v139, vcc, 0, v139, vcc
	global_load_dwordx4 v[174:177], v[138:139], off
	global_load_dwordx4 v[170:173], v[140:141], off offset:256
	v_lshlrev_b64 v[138:139], 13, v[234:235]
	v_lshl_add_u64 v[138:139], s[42:43], 0, v[138:139]
	v_lshl_add_u64 v[138:139], v[138:139], 0, v[220:221]
	v_lshl_add_u64 v[140:141], v[138:139], 0, s[2:3]
	v_add_co_u32_e32 v138, vcc, 0x1000, v138
	v_add_u32_e32 v230, 0xa0, v200
	s_nop 0
	v_addc_co_u32_e32 v139, vcc, 0, v139, vcc
	global_load_dwordx4 v[166:169], v[138:139], off
	global_load_dwordx4 v[162:165], v[140:141], off offset:256
	v_lshlrev_b64 v[138:139], 13, v[232:233]
	v_lshl_add_u64 v[138:139], s[42:43], 0, v[138:139]
	v_lshl_add_u64 v[138:139], v[138:139], 0, v[220:221]
	v_lshl_add_u64 v[140:141], v[138:139], 0, s[2:3]
	v_add_co_u32_e32 v138, vcc, 0x1000, v138
	v_ashrrev_i32_e32 v231, 31, v230
	s_nop 0
	v_addc_co_u32_e32 v139, vcc, 0, v139, vcc
	global_load_dwordx4 v[158:161], v[138:139], off
	global_load_dwordx4 v[154:157], v[140:141], off offset:256
	v_lshlrev_b64 v[138:139], 13, v[230:231]
	v_lshl_add_u64 v[138:139], s[42:43], 0, v[138:139]
	v_lshl_add_u64 v[138:139], v[138:139], 0, v[220:221]
	v_lshl_add_u64 v[140:141], v[138:139], 0, s[2:3]
	v_add_co_u32_e32 v138, vcc, 0x1000, v138
	v_add_u32_e32 v228, 0xb0, v200
	s_nop 0
	v_addc_co_u32_e32 v139, vcc, 0, v139, vcc
	v_ashrrev_i32_e32 v229, 31, v228
	global_load_dwordx4 v[150:153], v[138:139], off
	global_load_dwordx4 v[146:149], v[140:141], off offset:256
	v_lshlrev_b64 v[138:139], 13, v[228:229]
	v_lshl_add_u64 v[138:139], s[42:43], 0, v[138:139]
	v_lshl_add_u64 v[138:139], v[138:139], 0, v[220:221]
	v_lshl_add_u64 v[140:141], v[138:139], 0, s[2:3]
	v_add_co_u32_e32 v138, vcc, 0x1000, v138
	v_lshlrev_b64 v[208:209], 12, v[200:201]
	s_nop 0
	v_addc_co_u32_e32 v139, vcc, 0, v139, vcc
	v_lshl_add_u64 v[208:209], s[48:49], 0, v[208:209]
	v_lshl_add_u64 v[208:209], v[208:209], 0, v[220:221]
	s_lshl_b32 s2, s90, 4
	s_addk_i32 s2, 0x2000
	s_waitcnt vmcnt(0)
; __device__ __forceinline__ u32x4 pack8(const f32x4& a, const f32x4& b) { u32x4 w; w.x = cvt_pk_bf16(a[0], a[1]); w.y = cvt_pk_bf16(a[2], a[3]); w.z = cvt_pk_bf16(b[0], b[1]); w.w = cvt_pk_bf16(b[2], b[3]); return w; }
; #define PG8_SB(B) __builtin_amdgcn_rcpf(1.f + expneg(B))
; #define PG8_SB(B) __builtin_amdgcn_rcpf(1.f + expneg(B))
;     __device__ __forceinline__ void operator()(const f32x4 (&acc)[2][2][4][2], const Unit& u, int wr, int wc, int fr, int fq) const {
;     ...
; #pragma unroll
;         for (int ai = 0; ai < 2; ++ai)
; #pragma unroll
;             for (int m = 0; m < 4; ++m) { const size_t r = (size_t)(rowt + ai * HALF + m * 16);
; #pragma unroll
;                 for (int bj = 0; bj < 2; ++bj) { const u32x4 b = gb[ai][m][bj];
;                     f32x4 v0 = acc[ai][bj][m][0], v1 = acc[ai][bj][m][1];
;                     v0[0] *= PG8_SB(bflo(b.x)); v0[1] *= PG8_SB(bfhi(b.x)); v0[2] *= PG8_SB(bflo(b.y)); v0[3] *= PG8_SB(bfhi(b.y));
;                     v1[0] *= PG8_SB(bflo(b.z)); v1[1] *= PG8_SB(bfhi(b.z)); v1[2] *= PG8_SB(bflo(b.w)); v1[3] *= PG8_SB(bfhi(b.w));
;                     *(u32x4*)(mb + r * 2048 + col0 + bj * HALF) = pack8(v0, v1); } }
	v_lshlrev_b32_e32 v142, 16, v244
	v_and_b32_e32 v244, 0xffff0000, v244
	v_mul_f32_e32 v142, 0xbfb8aa3b, v142
	v_mul_f32_e32 v244, 0xbfb8aa3b, v244
	v_min_f32_e32 v142, 0x42a00000, v142
	v_min_f32_e32 v244, 0x42a00000, v244
	v_exp_f32_e32 v248, v142
	v_exp_f32_e32 v244, v244
	v_lshlrev_b32_e32 v249, 16, v245
	v_and_b32_e32 v245, 0xffff0000, v245
	v_lshlrev_b32_e32 v250, 16, v246
	v_and_b32_e32 v246, 0xffff0000, v246
	v_lshlrev_b32_e32 v251, 16, v247
	v_and_b32_e32 v247, 0xffff0000, v247
	v_mul_f32_e32 v245, 0xbfb8aa3b, v245
	v_mul_f32_e32 v246, 0xbfb8aa3b, v246
	v_mul_f32_e32 v247, 0xbfb8aa3b, v247
	v_mul_f32_e32 v249, 0xbfb8aa3b, v249
	v_min_f32_e32 v245, 0x42a00000, v245
	v_mul_f32_e32 v250, 0xbfb8aa3b, v250
	v_min_f32_e32 v246, 0x42a00000, v246
	v_mul_f32_e32 v251, 0xbfb8aa3b, v251
	v_min_f32_e32 v247, 0x42a00000, v247
	v_min_f32_e32 v249, 0x42a00000, v249
	v_exp_f32_e32 v245, v245
	v_min_f32_e32 v250, 0x42a00000, v250
	v_exp_f32_e32 v246, v246
	v_min_f32_e32 v251, 0x42a00000, v251
	v_exp_f32_e32 v247, v247
	v_add_f32_e32 v248, 1.0, v248
	v_exp_f32_e32 v249, v249
	v_add_f32_e32 v244, 1.0, v244
	v_exp_f32_e32 v250, v250
	v_exp_f32_e32 v251, v251
	v_rcp_f32_e32 v248, v248
	v_rcp_f32_e32 v244, v244
	v_add_f32_e32 v245, 1.0, v245
	v_add_f32_e32 v246, 1.0, v246
	v_add_f32_e32 v247, 1.0, v247
	v_add_f32_e32 v249, 1.0, v249
	v_rcp_f32_e32 v245, v245
	v_add_f32_e32 v250, 1.0, v250
	v_rcp_f32_e32 v246, v246
	v_add_f32_e32 v251, 1.0, v251
	v_rcp_f32_e32 v247, v247
	v_rcp_f32_e32 v249, v249
	v_mul_f32_e32 v248, v134, v248
	v_mul_f32_e32 v244, v135, v244
	v_rcp_f32_e32 v250, v250
	v_rcp_f32_e32 v251, v251
	global_load_dwordx4 v[142:145], v[138:139], off
	s_nop 0
	global_load_dwordx4 v[138:141], v[140:141], off offset:256
	v_cvt_pk_bf16_f32 v244, v248, v244
	v_lshlrev_b32_e32 v248, 16, v196
	v_and_b32_e32 v196, 0xffff0000, v196
	v_mul_f32_e32 v248, 0xbfb8aa3b, v248
	v_mul_f32_e32 v196, 0xbfb8aa3b, v196
	v_mul_f32_e32 v245, v137, v245
	v_mul_f32_e32 v246, v131, v246
	v_mul_f32_e32 v247, v133, v247
	v_min_f32_e32 v248, 0x42a00000, v248
	v_min_f32_e32 v196, 0x42a00000, v196
	v_mul_f32_e32 v249, v136, v249
	v_mul_f32_e32 v250, v130, v250
	v_mul_f32_e32 v251, v132, v251
	v_cvt_pk_bf16_f32 v245, v249, v245
	v_cvt_pk_bf16_f32 v246, v250, v246
	v_cvt_pk_bf16_f32 v247, v251, v247
	v_exp_f32_e32 v248, v248
	v_exp_f32_e32 v196, v196
	global_store_dwordx4 v[208:209], v[244:247], off sc0 sc1
	v_add_f32_e32 v196, 1.0, v196
	s_nop 0
	v_lshlrev_b32_e32 v245, 16, v197
	v_and_b32_e32 v197, 0xffff0000, v197
	v_lshlrev_b32_e32 v246, 16, v198
	v_and_b32_e32 v198, 0xffff0000, v198
	v_lshlrev_b32_e32 v247, 16, v199
	v_and_b32_e32 v199, 0xffff0000, v199
	v_mul_f32_e32 v197, 0xbfb8aa3b, v197
	v_mul_f32_e32 v198, 0xbfb8aa3b, v198
	v_mul_f32_e32 v199, 0xbfb8aa3b, v199
	v_mul_f32_e32 v245, 0xbfb8aa3b, v245
	v_min_f32_e32 v197, 0x42a00000, v197
	v_mul_f32_e32 v246, 0xbfb8aa3b, v246
	v_min_f32_e32 v198, 0x42a00000, v198
	v_mul_f32_e32 v247, 0xbfb8aa3b, v247
	v_min_f32_e32 v199, 0x42a00000, v199
	v_add_f32_e32 v244, 1.0, v248
	v_min_f32_e32 v245, 0x42a00000, v245
	v_exp_f32_e32 v197, v197
	v_min_f32_e32 v246, 0x42a00000, v246
	v_exp_f32_e32 v198, v198
	v_min_f32_e32 v247, 0x42a00000, v247
	v_exp_f32_e32 v199, v199
	v_exp_f32_e32 v245, v245
	v_rcp_f32_e32 v244, v244
	v_rcp_f32_e32 v196, v196
	v_exp_f32_e32 v246, v246
	v_exp_f32_e32 v247, v247
	v_add_f32_e32 v197, 1.0, v197
	v_add_f32_e32 v198, 1.0, v198
	v_add_f32_e32 v199, 1.0, v199
	v_add_f32_e32 v245, 1.0, v245
	v_mul_f32_e32 v244, v102, v244
	v_mul_f32_e32 v196, v103, v196
	v_rcp_f32_e32 v197, v197
	v_add_f32_e32 v246, 1.0, v246
	v_rcp_f32_e32 v198, v198
	v_add_f32_e32 v247, 1.0, v247
	v_rcp_f32_e32 v199, v199
	v_rcp_f32_e32 v245, v245
	v_rcp_f32_e32 v246, v246
	v_rcp_f32_e32 v247, v247
	v_cvt_pk_bf16_f32 v196, v244, v196
	v_lshlrev_b32_e32 v244, 16, v192
	v_and_b32_e32 v192, 0xffff0000, v192
	v_mul_f32_e32 v244, 0xbfb8aa3b, v244
	v_mul_f32_e32 v192, 0xbfb8aa3b, v192
	v_min_f32_e32 v244, 0x42a00000, v244
	v_min_f32_e32 v192, 0x42a00000, v192
	v_mul_f32_e32 v197, v105, v197
	v_mul_f32_e32 v198, v99, v198
	v_mul_f32_e32 v199, v101, v199
	v_exp_f32_e32 v244, v244
	v_exp_f32_e32 v192, v192
	v_mul_f32_e32 v245, v104, v245
	v_mul_f32_e32 v246, v98, v246
	v_mul_f32_e32 v247, v100, v247
	v_cvt_pk_bf16_f32 v197, v245, v197
	v_cvt_pk_bf16_f32 v198, v246, v198
	v_cvt_pk_bf16_f32 v199, v247, v199
	global_store_dwordx4 v[208:209], v[196:199], off offset:256 sc0 sc1
	v_lshlrev_b32_e32 v208, 16, v194
	v_and_b32_e32 v194, 0xffff0000, v194
	v_lshlrev_b32_e32 v199, 16, v193
	v_and_b32_e32 v193, 0xffff0000, v193
	v_lshlrev_b32_e32 v209, 16, v195
	v_and_b32_e32 v195, 0xffff0000, v195
	v_mul_f32_e32 v193, 0xbfb8aa3b, v193
	v_mul_f32_e32 v194, 0xbfb8aa3b, v194
	v_mul_f32_e32 v195, 0xbfb8aa3b, v195
	v_add_f32_e32 v198, 1.0, v244
	v_mul_f32_e32 v199, 0xbfb8aa3b, v199
	v_add_f32_e32 v192, 1.0, v192
	v_min_f32_e32 v193, 0x42a00000, v193
	v_mul_f32_e32 v208, 0xbfb8aa3b, v208
	v_min_f32_e32 v194, 0x42a00000, v194
	v_mul_f32_e32 v209, 0xbfb8aa3b, v209
	v_min_f32_e32 v195, 0x42a00000, v195
	v_min_f32_e32 v199, 0x42a00000, v199
	v_rcp_f32_e32 v198, v198
	v_rcp_f32_e32 v192, v192
	v_exp_f32_e32 v193, v193
	v_min_f32_e32 v208, 0x42a00000, v208
	v_exp_f32_e32 v194, v194
	v_min_f32_e32 v209, 0x42a00000, v209
	v_exp_f32_e32 v195, v195
	v_exp_f32_e32 v199, v199
	v_exp_f32_e32 v208, v208
	v_exp_f32_e32 v209, v209
	v_mul_f32_e32 v198, v126, v198
	v_mul_f32_e32 v192, v127, v192
	v_add_f32_e32 v193, 1.0, v193
	v_add_f32_e32 v194, 1.0, v194
	v_add_f32_e32 v195, 1.0, v195
	v_add_f32_e32 v199, 1.0, v199
	v_rcp_f32_e32 v193, v193
	v_add_f32_e32 v208, 1.0, v208
; __device__ __forceinline__ u32x4 pack8(const f32x4& a, const f32x4& b) { u32x4 w; w.x = cvt_pk_bf16(a[0], a[1]); w.y = cvt_pk_bf16(a[2], a[3]); w.z = cvt_pk_bf16(b[0], b[1]); w.w = cvt_pk_bf16(b[2], b[3]); return w; }
; #define PG8_SB(B) __builtin_amdgcn_rcpf(1.f + expneg(B))
; #define PG8_SB(B) __builtin_amdgcn_rcpf(1.f + expneg(B))
;     __device__ __forceinline__ void operator()(const f32x4 (&acc)[2][2][4][2], const Unit& u, int wr, int wc, int fr, int fq) const {
;     ...
; #pragma unroll
;         for (int ai = 0; ai < 2; ++ai)
; #pragma unroll
;             for (int m = 0; m < 4; ++m) { const size_t r = (size_t)(rowt + ai * HALF + m * 16);
; #pragma unroll
;                 for (int bj = 0; bj < 2; ++bj) { const u32x4 b = gb[ai][m][bj];
;                     f32x4 v0 = acc[ai][bj][m][0], v1 = acc[ai][bj][m][1];
;                     v0[0] *= PG8_SB(bflo(b.x)); v0[1] *= PG8_SB(bfhi(b.x)); v0[2] *= PG8_SB(bflo(b.y)); v0[3] *= PG8_SB(bfhi(b.y));
;                     v1[0] *= PG8_SB(bflo(b.z)); v1[1] *= PG8_SB(bfhi(b.z)); v1[2] *= PG8_SB(bflo(b.w)); v1[3] *= PG8_SB(bfhi(b.w));
;                     *(u32x4*)(mb + r * 2048 + col0 + bj * HALF) = pack8(v0, v1); } }
	v_rcp_f32_e32 v194, v194
	v_add_f32_e32 v209, 1.0, v209
	v_rcp_f32_e32 v195, v195
	v_cvt_pk_bf16_f32 v192, v198, v192
	v_lshlrev_b32_e32 v198, 16, v188
	v_and_b32_e32 v188, 0xffff0000, v188
	v_rcp_f32_e32 v199, v199
	v_rcp_f32_e32 v208, v208
	v_rcp_f32_e32 v209, v209
	v_mul_f32_e32 v198, 0xbfb8aa3b, v198
	v_mul_f32_e32 v188, 0xbfb8aa3b, v188
	v_min_f32_e32 v198, 0x42a00000, v198
	v_min_f32_e32 v188, 0x42a00000, v188
	v_lshlrev_b64 v[196:197], 12, v[226:227]
	v_exp_f32_e32 v198, v198
	v_exp_f32_e32 v188, v188
	v_mul_f32_e32 v193, v129, v193
	v_mul_f32_e32 v194, v123, v194
	v_mul_f32_e32 v195, v125, v195
	v_lshl_add_u64 v[196:197], s[48:49], 0, v[196:197]
	v_mul_f32_e32 v199, v128, v199
	v_mul_f32_e32 v208, v122, v208
	v_mul_f32_e32 v209, v124, v209
	v_cvt_pk_bf16_f32 v193, v199, v193
	v_cvt_pk_bf16_f32 v194, v208, v194
	v_cvt_pk_bf16_f32 v195, v209, v195
	v_lshl_add_u64 v[196:197], v[196:197], 0, v[220:221]
	global_store_dwordx4 v[196:197], v[192:195], off sc0 sc1
	v_add_f32_e32 v188, 1.0, v188
	v_rcp_f32_e32 v188, v188
	v_lshlrev_b32_e32 v193, 16, v189
	v_and_b32_e32 v189, 0xffff0000, v189
	v_lshlrev_b32_e32 v194, 16, v190
	v_and_b32_e32 v190, 0xffff0000, v190
	v_lshlrev_b32_e32 v195, 16, v191
	v_and_b32_e32 v191, 0xffff0000, v191
	v_add_f32_e32 v192, 1.0, v198
	v_mul_f32_e32 v189, 0xbfb8aa3b, v189
	v_mul_f32_e32 v190, 0xbfb8aa3b, v190
	v_mul_f32_e32 v191, 0xbfb8aa3b, v191
	v_mul_f32_e32 v193, 0xbfb8aa3b, v193
	v_rcp_f32_e32 v192, v192
	v_min_f32_e32 v189, 0x42a00000, v189
	v_mul_f32_e32 v194, 0xbfb8aa3b, v194
	v_min_f32_e32 v190, 0x42a00000, v190
	v_mul_f32_e32 v195, 0xbfb8aa3b, v195
	v_min_f32_e32 v191, 0x42a00000, v191
	v_min_f32_e32 v193, 0x42a00000, v193
	v_exp_f32_e32 v189, v189
	v_min_f32_e32 v194, 0x42a00000, v194
	v_exp_f32_e32 v190, v190
	v_min_f32_e32 v195, 0x42a00000, v195
	v_exp_f32_e32 v191, v191
	v_exp_f32_e32 v193, v193
	v_exp_f32_e32 v194, v194
	v_exp_f32_e32 v195, v195
	v_mul_f32_e32 v192, v90, v192
	v_mul_f32_e32 v188, v91, v188
	v_add_f32_e32 v189, 1.0, v189
	v_add_f32_e32 v190, 1.0, v190
	v_add_f32_e32 v191, 1.0, v191
	v_cvt_pk_bf16_f32 v188, v192, v188
	v_lshlrev_b32_e32 v192, 16, v184
	v_add_f32_e32 v193, 1.0, v193
	v_rcp_f32_e32 v189, v189
	v_add_f32_e32 v194, 1.0, v194
	v_rcp_f32_e32 v190, v190
	v_add_f32_e32 v195, 1.0, v195
	v_rcp_f32_e32 v191, v191
	v_mul_f32_e32 v192, 0xbfb8aa3b, v192
	v_rcp_f32_e32 v193, v193
	v_rcp_f32_e32 v194, v194
	v_rcp_f32_e32 v195, v195
	v_min_f32_e32 v192, 0x42a00000, v192
	v_and_b32_e32 v184, 0xffff0000, v184
	v_exp_f32_e32 v192, v192
	v_mul_f32_e32 v184, 0xbfb8aa3b, v184
	v_min_f32_e32 v184, 0x42a00000, v184
	v_mul_f32_e32 v189, v93, v189
	v_mul_f32_e32 v190, v87, v190
	v_mul_f32_e32 v191, v89, v191
	v_exp_f32_e32 v184, v184
	v_mul_f32_e32 v193, v92, v193
	v_mul_f32_e32 v194, v86, v194
	v_mul_f32_e32 v195, v88, v195
	v_cvt_pk_bf16_f32 v189, v193, v189
	v_cvt_pk_bf16_f32 v190, v194, v190
	v_cvt_pk_bf16_f32 v191, v195, v191
	global_store_dwordx4 v[196:197], v[188:191], off offset:256 sc0 sc1
	v_lshlrev_b32_e32 v193, 16, v187
	v_and_b32_e32 v187, 0xffff0000, v187
	v_add_f32_e32 v190, 1.0, v192
	v_lshlrev_b32_e32 v191, 16, v185
	v_and_b32_e32 v185, 0xffff0000, v185
	v_lshlrev_b32_e32 v192, 16, v186
	v_and_b32_e32 v186, 0xffff0000, v186
	v_mul_f32_e32 v185, 0xbfb8aa3b, v185
	v_mul_f32_e32 v186, 0xbfb8aa3b, v186
	v_mul_f32_e32 v187, 0xbfb8aa3b, v187
	v_mul_f32_e32 v191, 0xbfb8aa3b, v191
	v_add_f32_e32 v184, 1.0, v184
	v_min_f32_e32 v185, 0x42a00000, v185
	v_mul_f32_e32 v192, 0xbfb8aa3b, v192
	v_min_f32_e32 v186, 0x42a00000, v186
	v_mul_f32_e32 v193, 0xbfb8aa3b, v193
	v_min_f32_e32 v187, 0x42a00000, v187
	v_min_f32_e32 v191, 0x42a00000, v191
	v_rcp_f32_e32 v190, v190
	v_rcp_f32_e32 v184, v184
	v_exp_f32_e32 v185, v185
	v_min_f32_e32 v192, 0x42a00000, v192
	v_exp_f32_e32 v186, v186
	v_min_f32_e32 v193, 0x42a00000, v193
	v_exp_f32_e32 v187, v187
	v_exp_f32_e32 v191, v191
	v_exp_f32_e32 v192, v192
	v_exp_f32_e32 v193, v193
	v_mul_f32_e32 v190, v118, v190
	v_mul_f32_e32 v184, v119, v184
	v_add_f32_e32 v185, 1.0, v185
	v_add_f32_e32 v186, 1.0, v186
	v_add_f32_e32 v187, 1.0, v187
	v_add_f32_e32 v191, 1.0, v191
	v_rcp_f32_e32 v185, v185
	v_add_f32_e32 v192, 1.0, v192
	v_rcp_f32_e32 v186, v186
	v_add_f32_e32 v193, 1.0, v193
	v_rcp_f32_e32 v187, v187
	v_cvt_pk_bf16_f32 v184, v190, v184
	v_lshlrev_b32_e32 v190, 16, v180
	v_and_b32_e32 v180, 0xffff0000, v180
	v_rcp_f32_e32 v191, v191
	v_rcp_f32_e32 v192, v192
	v_rcp_f32_e32 v193, v193
	v_mul_f32_e32 v190, 0xbfb8aa3b, v190
	v_mul_f32_e32 v180, 0xbfb8aa3b, v180
	v_min_f32_e32 v190, 0x42a00000, v190
	v_min_f32_e32 v180, 0x42a00000, v180
	v_lshlrev_b64 v[188:189], 12, v[224:225]
	v_exp_f32_e32 v190, v190
	v_exp_f32_e32 v180, v180
	v_mul_f32_e32 v185, v121, v185
	v_mul_f32_e32 v186, v115, v186
	v_mul_f32_e32 v187, v117, v187
	v_lshl_add_u64 v[188:189], s[48:49], 0, v[188:189]
	v_mul_f32_e32 v191, v120, v191
	v_mul_f32_e32 v192, v114, v192
	v_mul_f32_e32 v193, v116, v193
	v_cvt_pk_bf16_f32 v185, v191, v185
	v_cvt_pk_bf16_f32 v186, v192, v186
	v_cvt_pk_bf16_f32 v187, v193, v187
	v_lshl_add_u64 v[188:189], v[188:189], 0, v[220:221]
	global_store_dwordx4 v[188:189], v[184:187], off sc0 sc1
	v_add_f32_e32 v180, 1.0, v180
	v_rcp_f32_e32 v180, v180
	v_lshlrev_b32_e32 v185, 16, v181
	v_and_b32_e32 v181, 0xffff0000, v181
	v_lshlrev_b32_e32 v186, 16, v182
	v_and_b32_e32 v182, 0xffff0000, v182
	v_lshlrev_b32_e32 v187, 16, v183
	v_and_b32_e32 v183, 0xffff0000, v183
	v_add_f32_e32 v184, 1.0, v190
	v_mul_f32_e32 v181, 0xbfb8aa3b, v181
	v_mul_f32_e32 v182, 0xbfb8aa3b, v182
	v_mul_f32_e32 v183, 0xbfb8aa3b, v183
	v_mul_f32_e32 v185, 0xbfb8aa3b, v185
	v_rcp_f32_e32 v184, v184
; __device__ __forceinline__ u32x4 pack8(const f32x4& a, const f32x4& b) { u32x4 w; w.x = cvt_pk_bf16(a[0], a[1]); w.y = cvt_pk_bf16(a[2], a[3]); w.z = cvt_pk_bf16(b[0], b[1]); w.w = cvt_pk_bf16(b[2], b[3]); return w; }
; #define PG8_SB(B) __builtin_amdgcn_rcpf(1.f + expneg(B))
; #define PG8_SB(B) __builtin_amdgcn_rcpf(1.f + expneg(B))
;     __device__ __forceinline__ void operator()(const f32x4 (&acc)[2][2][4][2], const Unit& u, int wr, int wc, int fr, int fq) const {
;     ...
; #pragma unroll
;         for (int ai = 0; ai < 2; ++ai)
; #pragma unroll
;             for (int m = 0; m < 4; ++m) { const size_t r = (size_t)(rowt + ai * HALF + m * 16);
; #pragma unroll
;                 for (int bj = 0; bj < 2; ++bj) { const u32x4 b = gb[ai][m][bj];
;                     f32x4 v0 = acc[ai][bj][m][0], v1 = acc[ai][bj][m][1];
;                     v0[0] *= PG8_SB(bflo(b.x)); v0[1] *= PG8_SB(bfhi(b.x)); v0[2] *= PG8_SB(bflo(b.y)); v0[3] *= PG8_SB(bfhi(b.y));
;                     v1[0] *= PG8_SB(bflo(b.z)); v1[1] *= PG8_SB(bfhi(b.z)); v1[2] *= PG8_SB(bflo(b.w)); v1[3] *= PG8_SB(bfhi(b.w));
;                     *(u32x4*)(mb + r * 2048 + col0 + bj * HALF) = pack8(v0, v1); } }
	v_min_f32_e32 v181, 0x42a00000, v181
	v_mul_f32_e32 v186, 0xbfb8aa3b, v186
	v_min_f32_e32 v182, 0x42a00000, v182
	v_mul_f32_e32 v187, 0xbfb8aa3b, v187
	v_min_f32_e32 v183, 0x42a00000, v183
	v_min_f32_e32 v185, 0x42a00000, v185
	v_exp_f32_e32 v181, v181
	v_min_f32_e32 v186, 0x42a00000, v186
	v_exp_f32_e32 v182, v182
	v_min_f32_e32 v187, 0x42a00000, v187
	v_exp_f32_e32 v183, v183
	v_exp_f32_e32 v185, v185
	v_exp_f32_e32 v186, v186
	v_exp_f32_e32 v187, v187
	v_mul_f32_e32 v184, v78, v184
	v_mul_f32_e32 v180, v79, v180
	v_add_f32_e32 v181, 1.0, v181
	v_add_f32_e32 v182, 1.0, v182
	v_add_f32_e32 v183, 1.0, v183
	v_cvt_pk_bf16_f32 v180, v184, v180
	v_lshlrev_b32_e32 v184, 16, v174
	v_add_f32_e32 v185, 1.0, v185
	v_rcp_f32_e32 v181, v181
	v_add_f32_e32 v186, 1.0, v186
	v_rcp_f32_e32 v182, v182
	v_add_f32_e32 v187, 1.0, v187
	v_rcp_f32_e32 v183, v183
	v_mul_f32_e32 v184, 0xbfb8aa3b, v184
	v_rcp_f32_e32 v185, v185
	v_rcp_f32_e32 v186, v186
	v_rcp_f32_e32 v187, v187
	v_min_f32_e32 v184, 0x42a00000, v184
	v_and_b32_e32 v174, 0xffff0000, v174
	v_exp_f32_e32 v184, v184
	v_mul_f32_e32 v174, 0xbfb8aa3b, v174
	v_min_f32_e32 v174, 0x42a00000, v174
	v_mul_f32_e32 v181, v81, v181
	v_mul_f32_e32 v182, v75, v182
	v_mul_f32_e32 v183, v77, v183
	v_exp_f32_e32 v174, v174
	v_mul_f32_e32 v185, v80, v185
	v_mul_f32_e32 v186, v74, v186
	v_mul_f32_e32 v187, v76, v187
	v_cvt_pk_bf16_f32 v181, v185, v181
	v_cvt_pk_bf16_f32 v182, v186, v182
	v_cvt_pk_bf16_f32 v183, v187, v183
	global_store_dwordx4 v[188:189], v[180:183], off offset:256 sc0 sc1
	v_lshlrev_b32_e32 v185, 16, v177
	v_and_b32_e32 v177, 0xffff0000, v177
	v_add_f32_e32 v182, 1.0, v184
	v_lshlrev_b32_e32 v183, 16, v175
	v_and_b32_e32 v175, 0xffff0000, v175
	v_lshlrev_b32_e32 v184, 16, v176
	v_and_b32_e32 v176, 0xffff0000, v176
	v_mul_f32_e32 v175, 0xbfb8aa3b, v175
	v_mul_f32_e32 v176, 0xbfb8aa3b, v176
	v_mul_f32_e32 v177, 0xbfb8aa3b, v177
	v_mul_f32_e32 v183, 0xbfb8aa3b, v183
	v_add_f32_e32 v174, 1.0, v174
	v_min_f32_e32 v175, 0x42a00000, v175
	v_mul_f32_e32 v184, 0xbfb8aa3b, v184
	v_min_f32_e32 v176, 0x42a00000, v176
	v_mul_f32_e32 v185, 0xbfb8aa3b, v185
	v_min_f32_e32 v177, 0x42a00000, v177
	v_min_f32_e32 v183, 0x42a00000, v183
	v_rcp_f32_e32 v182, v182
	v_rcp_f32_e32 v174, v174
	v_exp_f32_e32 v175, v175
	v_min_f32_e32 v184, 0x42a00000, v184
	v_exp_f32_e32 v176, v176
	v_min_f32_e32 v185, 0x42a00000, v185
	v_exp_f32_e32 v177, v177
	v_exp_f32_e32 v183, v183
	v_exp_f32_e32 v184, v184
	v_exp_f32_e32 v185, v185
	v_mul_f32_e32 v182, v110, v182
	v_mul_f32_e32 v174, v111, v174
	v_add_f32_e32 v175, 1.0, v175
	v_add_f32_e32 v176, 1.0, v176
	v_add_f32_e32 v177, 1.0, v177
	v_add_f32_e32 v183, 1.0, v183
	v_rcp_f32_e32 v175, v175
	v_add_f32_e32 v184, 1.0, v184
	v_rcp_f32_e32 v176, v176
	v_add_f32_e32 v185, 1.0, v185
	v_rcp_f32_e32 v177, v177
	v_cvt_pk_bf16_f32 v174, v182, v174
	v_lshlrev_b32_e32 v182, 16, v170
	v_and_b32_e32 v170, 0xffff0000, v170
	v_rcp_f32_e32 v183, v183
	v_rcp_f32_e32 v184, v184
	v_rcp_f32_e32 v185, v185
	v_mul_f32_e32 v182, 0xbfb8aa3b, v182
	v_mul_f32_e32 v170, 0xbfb8aa3b, v170
	v_min_f32_e32 v182, 0x42a00000, v182
	v_min_f32_e32 v170, 0x42a00000, v170
	v_lshlrev_b64 v[180:181], 12, v[222:223]
	v_exp_f32_e32 v182, v182
	v_exp_f32_e32 v170, v170
	v_mul_f32_e32 v175, v113, v175
	v_mul_f32_e32 v176, v107, v176
	v_mul_f32_e32 v177, v109, v177
	v_lshl_add_u64 v[180:181], s[48:49], 0, v[180:181]
	v_mul_f32_e32 v183, v112, v183
	v_mul_f32_e32 v184, v106, v184
	v_mul_f32_e32 v185, v108, v185
	v_cvt_pk_bf16_f32 v175, v183, v175
	v_cvt_pk_bf16_f32 v176, v184, v176
	v_cvt_pk_bf16_f32 v177, v185, v177
	v_lshl_add_u64 v[180:181], v[180:181], 0, v[220:221]
	global_store_dwordx4 v[180:181], v[174:177], off sc0 sc1
	v_add_f32_e32 v170, 1.0, v170
	v_rcp_f32_e32 v170, v170
	v_lshlrev_b32_e32 v175, 16, v171
	v_and_b32_e32 v171, 0xffff0000, v171
	v_lshlrev_b32_e32 v176, 16, v172
	v_and_b32_e32 v172, 0xffff0000, v172
	v_lshlrev_b32_e32 v177, 16, v173
	v_and_b32_e32 v173, 0xffff0000, v173
	v_add_f32_e32 v174, 1.0, v182
	v_mul_f32_e32 v171, 0xbfb8aa3b, v171
	v_mul_f32_e32 v172, 0xbfb8aa3b, v172
	v_mul_f32_e32 v173, 0xbfb8aa3b, v173
	v_mul_f32_e32 v175, 0xbfb8aa3b, v175
	v_rcp_f32_e32 v174, v174
	v_min_f32_e32 v171, 0x42a00000, v171
	v_mul_f32_e32 v176, 0xbfb8aa3b, v176
	v_min_f32_e32 v172, 0x42a00000, v172
	v_mul_f32_e32 v177, 0xbfb8aa3b, v177
	v_min_f32_e32 v173, 0x42a00000, v173
	v_min_f32_e32 v175, 0x42a00000, v175
	v_exp_f32_e32 v171, v171
	v_min_f32_e32 v176, 0x42a00000, v176
	v_exp_f32_e32 v172, v172
	v_min_f32_e32 v177, 0x42a00000, v177
	v_exp_f32_e32 v173, v173
	v_exp_f32_e32 v175, v175
	v_exp_f32_e32 v176, v176
	v_exp_f32_e32 v177, v177
	v_mul_f32_e32 v174, v70, v174
	v_mul_f32_e32 v170, v71, v170
	v_add_f32_e32 v171, 1.0, v171
	v_add_f32_e32 v172, 1.0, v172
	v_add_f32_e32 v173, 1.0, v173
	v_cvt_pk_bf16_f32 v170, v174, v170
	v_lshlrev_b32_e32 v174, 16, v166
	v_add_f32_e32 v175, 1.0, v175
	v_rcp_f32_e32 v171, v171
	v_add_f32_e32 v176, 1.0, v176
	v_rcp_f32_e32 v172, v172
	v_add_f32_e32 v177, 1.0, v177
	v_rcp_f32_e32 v173, v173
	v_mul_f32_e32 v174, 0xbfb8aa3b, v174
	v_rcp_f32_e32 v175, v175
	v_rcp_f32_e32 v176, v176
	v_rcp_f32_e32 v177, v177
	v_min_f32_e32 v174, 0x42a00000, v174
	v_and_b32_e32 v166, 0xffff0000, v166
	v_exp_f32_e32 v174, v174
	v_mul_f32_e32 v166, 0xbfb8aa3b, v166
	v_min_f32_e32 v166, 0x42a00000, v166
	v_mul_f32_e32 v171, v73, v171
	v_mul_f32_e32 v172, v67, v172
	v_mul_f32_e32 v173, v69, v173
	v_exp_f32_e32 v166, v166
	v_mul_f32_e32 v175, v72, v175
	v_mul_f32_e32 v176, v66, v176
	v_mul_f32_e32 v177, v68, v177
	v_cvt_pk_bf16_f32 v171, v175, v171
	v_cvt_pk_bf16_f32 v172, v176, v172
	v_cvt_pk_bf16_f32 v173, v177, v173
; __device__ __forceinline__ u32x4 pack8(const f32x4& a, const f32x4& b) { u32x4 w; w.x = cvt_pk_bf16(a[0], a[1]); w.y = cvt_pk_bf16(a[2], a[3]); w.z = cvt_pk_bf16(b[0], b[1]); w.w = cvt_pk_bf16(b[2], b[3]); return w; }
; #define PG8_SB(B) __builtin_amdgcn_rcpf(1.f + expneg(B))
; #define PG8_SB(B) __builtin_amdgcn_rcpf(1.f + expneg(B))
;     __device__ __forceinline__ void operator()(const f32x4 (&acc)[2][2][4][2], const Unit& u, int wr, int wc, int fr, int fq) const {
;     ...
; #pragma unroll
;         for (int ai = 0; ai < 2; ++ai)
; #pragma unroll
;             for (int m = 0; m < 4; ++m) { const size_t r = (size_t)(rowt + ai * HALF + m * 16);
; #pragma unroll
;                 for (int bj = 0; bj < 2; ++bj) { const u32x4 b = gb[ai][m][bj];
;                     f32x4 v0 = acc[ai][bj][m][0], v1 = acc[ai][bj][m][1];
;                     v0[0] *= PG8_SB(bflo(b.x)); v0[1] *= PG8_SB(bfhi(b.x)); v0[2] *= PG8_SB(bflo(b.y)); v0[3] *= PG8_SB(bfhi(b.y));
;                     v1[0] *= PG8_SB(bflo(b.z)); v1[1] *= PG8_SB(bfhi(b.z)); v1[2] *= PG8_SB(bflo(b.w)); v1[3] *= PG8_SB(bfhi(b.w));
;                     *(u32x4*)(mb + r * 2048 + col0 + bj * HALF) = pack8(v0, v1); } }
	global_store_dwordx4 v[180:181], v[170:173], off offset:256 sc0 sc1
	v_lshlrev_b32_e32 v175, 16, v169
	v_and_b32_e32 v169, 0xffff0000, v169
	v_add_f32_e32 v172, 1.0, v174
	v_lshlrev_b32_e32 v173, 16, v167
	v_and_b32_e32 v167, 0xffff0000, v167
	v_lshlrev_b32_e32 v174, 16, v168
	v_and_b32_e32 v168, 0xffff0000, v168
	v_mul_f32_e32 v167, 0xbfb8aa3b, v167
	v_mul_f32_e32 v168, 0xbfb8aa3b, v168
	v_mul_f32_e32 v169, 0xbfb8aa3b, v169
	v_mul_f32_e32 v173, 0xbfb8aa3b, v173
	v_add_f32_e32 v166, 1.0, v166
	v_min_f32_e32 v167, 0x42a00000, v167
	v_mul_f32_e32 v174, 0xbfb8aa3b, v174
	v_min_f32_e32 v168, 0x42a00000, v168
	v_mul_f32_e32 v175, 0xbfb8aa3b, v175
	v_min_f32_e32 v169, 0x42a00000, v169
	v_min_f32_e32 v173, 0x42a00000, v173
	v_rcp_f32_e32 v172, v172
	v_rcp_f32_e32 v166, v166
	v_exp_f32_e32 v167, v167
	v_min_f32_e32 v174, 0x42a00000, v174
	v_exp_f32_e32 v168, v168
	v_min_f32_e32 v175, 0x42a00000, v175
	v_exp_f32_e32 v169, v169
	v_exp_f32_e32 v173, v173
	v_exp_f32_e32 v174, v174
	v_exp_f32_e32 v175, v175
	v_mul_f32_e32 v172, v62, v172
	v_mul_f32_e32 v166, v63, v166
	v_add_f32_e32 v167, 1.0, v167
	v_add_f32_e32 v168, 1.0, v168
	v_add_f32_e32 v169, 1.0, v169
	v_add_f32_e32 v173, 1.0, v173
	v_rcp_f32_e32 v167, v167
	v_add_f32_e32 v174, 1.0, v174
	v_rcp_f32_e32 v168, v168
	v_add_f32_e32 v175, 1.0, v175
	v_rcp_f32_e32 v169, v169
	v_cvt_pk_bf16_f32 v166, v172, v166
	v_lshlrev_b32_e32 v172, 16, v162
	v_and_b32_e32 v162, 0xffff0000, v162
	v_rcp_f32_e32 v173, v173
	v_rcp_f32_e32 v174, v174
	v_rcp_f32_e32 v175, v175
	v_mul_f32_e32 v172, 0xbfb8aa3b, v172
	v_mul_f32_e32 v162, 0xbfb8aa3b, v162
	v_min_f32_e32 v172, 0x42a00000, v172
	v_min_f32_e32 v162, 0x42a00000, v162
	v_lshlrev_b64 v[170:171], 12, v[234:235]
	v_exp_f32_e32 v172, v172
	v_exp_f32_e32 v162, v162
	v_mul_f32_e32 v167, v65, v167
	v_mul_f32_e32 v168, v59, v168
	v_mul_f32_e32 v169, v61, v169
	v_lshl_add_u64 v[170:171], s[48:49], 0, v[170:171]
	v_mul_f32_e32 v173, v64, v173
	v_mul_f32_e32 v174, v58, v174
	v_mul_f32_e32 v175, v60, v175
	v_cvt_pk_bf16_f32 v167, v173, v167
	v_cvt_pk_bf16_f32 v168, v174, v168
	v_cvt_pk_bf16_f32 v169, v175, v169
	v_lshl_add_u64 v[170:171], v[170:171], 0, v[220:221]
	global_store_dwordx4 v[170:171], v[166:169], off sc0 sc1
	v_add_f32_e32 v162, 1.0, v162
	v_rcp_f32_e32 v162, v162
	v_lshlrev_b32_e32 v167, 16, v163
	v_and_b32_e32 v163, 0xffff0000, v163
	v_lshlrev_b32_e32 v168, 16, v164
	v_and_b32_e32 v164, 0xffff0000, v164
	v_lshlrev_b32_e32 v169, 16, v165
	v_and_b32_e32 v165, 0xffff0000, v165
	v_add_f32_e32 v166, 1.0, v172
	v_mul_f32_e32 v163, 0xbfb8aa3b, v163
	v_mul_f32_e32 v164, 0xbfb8aa3b, v164
	v_mul_f32_e32 v165, 0xbfb8aa3b, v165
	v_mul_f32_e32 v167, 0xbfb8aa3b, v167
	v_rcp_f32_e32 v166, v166
	v_min_f32_e32 v163, 0x42a00000, v163
	v_mul_f32_e32 v168, 0xbfb8aa3b, v168
	v_min_f32_e32 v164, 0x42a00000, v164
	v_mul_f32_e32 v169, 0xbfb8aa3b, v169
	v_min_f32_e32 v165, 0x42a00000, v165
	v_min_f32_e32 v167, 0x42a00000, v167
	v_exp_f32_e32 v163, v163
	v_min_f32_e32 v168, 0x42a00000, v168
	v_exp_f32_e32 v164, v164
	v_min_f32_e32 v169, 0x42a00000, v169
	v_exp_f32_e32 v165, v165
	v_exp_f32_e32 v167, v167
	v_exp_f32_e32 v168, v168
	v_exp_f32_e32 v169, v169
	v_mul_f32_e32 v166, v30, v166
	v_mul_f32_e32 v162, v31, v162
	v_add_f32_e32 v163, 1.0, v163
	v_add_f32_e32 v164, 1.0, v164
	v_add_f32_e32 v165, 1.0, v165
	v_cvt_pk_bf16_f32 v162, v166, v162
	v_lshlrev_b32_e32 v166, 16, v158
	v_add_f32_e32 v167, 1.0, v167
	v_rcp_f32_e32 v163, v163
	v_add_f32_e32 v168, 1.0, v168
	v_rcp_f32_e32 v164, v164
	v_add_f32_e32 v169, 1.0, v169
	v_rcp_f32_e32 v165, v165
	v_mul_f32_e32 v166, 0xbfb8aa3b, v166
	v_rcp_f32_e32 v167, v167
	v_rcp_f32_e32 v168, v168
	v_rcp_f32_e32 v169, v169
	v_min_f32_e32 v166, 0x42a00000, v166
	v_and_b32_e32 v158, 0xffff0000, v158
	v_exp_f32_e32 v166, v166
	v_mul_f32_e32 v158, 0xbfb8aa3b, v158
	v_min_f32_e32 v158, 0x42a00000, v158
	v_mul_f32_e32 v163, v33, v163
	v_mul_f32_e32 v164, v27, v164
	v_mul_f32_e32 v165, v29, v165
	v_exp_f32_e32 v158, v158
	v_mul_f32_e32 v167, v32, v167
	v_mul_f32_e32 v168, v26, v168
	v_mul_f32_e32 v169, v28, v169
	v_cvt_pk_bf16_f32 v163, v167, v163
	v_cvt_pk_bf16_f32 v164, v168, v164
	v_cvt_pk_bf16_f32 v165, v169, v165
	global_store_dwordx4 v[170:171], v[162:165], off offset:256 sc0 sc1
	v_lshlrev_b32_e32 v167, 16, v161
	v_and_b32_e32 v161, 0xffff0000, v161
	v_add_f32_e32 v164, 1.0, v166
	v_lshlrev_b32_e32 v165, 16, v159
	v_and_b32_e32 v159, 0xffff0000, v159
	v_lshlrev_b32_e32 v166, 16, v160
	v_and_b32_e32 v160, 0xffff0000, v160
	v_mul_f32_e32 v159, 0xbfb8aa3b, v159
	v_mul_f32_e32 v160, 0xbfb8aa3b, v160
	v_mul_f32_e32 v161, 0xbfb8aa3b, v161
	v_mul_f32_e32 v165, 0xbfb8aa3b, v165
	v_add_f32_e32 v158, 1.0, v158
	v_min_f32_e32 v159, 0x42a00000, v159
	v_mul_f32_e32 v166, 0xbfb8aa3b, v166
	v_min_f32_e32 v160, 0x42a00000, v160
	v_mul_f32_e32 v167, 0xbfb8aa3b, v167
	v_min_f32_e32 v161, 0x42a00000, v161
	v_min_f32_e32 v165, 0x42a00000, v165
	v_rcp_f32_e32 v164, v164
	v_rcp_f32_e32 v158, v158
	v_exp_f32_e32 v159, v159
	v_min_f32_e32 v166, 0x42a00000, v166
	v_exp_f32_e32 v160, v160
	v_min_f32_e32 v167, 0x42a00000, v167
	v_exp_f32_e32 v161, v161
	v_exp_f32_e32 v165, v165
	v_exp_f32_e32 v166, v166
	v_exp_f32_e32 v167, v167
	v_mul_f32_e32 v164, v54, v164
	v_mul_f32_e32 v158, v55, v158
	v_add_f32_e32 v159, 1.0, v159
	v_add_f32_e32 v160, 1.0, v160
	v_add_f32_e32 v161, 1.0, v161
	v_add_f32_e32 v165, 1.0, v165
	v_rcp_f32_e32 v159, v159
	v_add_f32_e32 v166, 1.0, v166
	v_rcp_f32_e32 v160, v160
	v_add_f32_e32 v167, 1.0, v167
	v_rcp_f32_e32 v161, v161
	v_cvt_pk_bf16_f32 v158, v164, v158
	v_lshlrev_b32_e32 v164, 16, v154
	v_and_b32_e32 v154, 0xffff0000, v154
	v_rcp_f32_e32 v165, v165
; __device__ __forceinline__ u32x4 pack8(const f32x4& a, const f32x4& b) { u32x4 w; w.x = cvt_pk_bf16(a[0], a[1]); w.y = cvt_pk_bf16(a[2], a[3]); w.z = cvt_pk_bf16(b[0], b[1]); w.w = cvt_pk_bf16(b[2], b[3]); return w; }
; #define PG8_SB(B) __builtin_amdgcn_rcpf(1.f + expneg(B))
; #define PG8_SB(B) __builtin_amdgcn_rcpf(1.f + expneg(B))
;     __device__ __forceinline__ void operator()(const f32x4 (&acc)[2][2][4][2], const Unit& u, int wr, int wc, int fr, int fq) const {
;     ...
; #pragma unroll
;         for (int ai = 0; ai < 2; ++ai)
; #pragma unroll
;             for (int m = 0; m < 4; ++m) { const size_t r = (size_t)(rowt + ai * HALF + m * 16);
; #pragma unroll
;                 for (int bj = 0; bj < 2; ++bj) { const u32x4 b = gb[ai][m][bj];
;                     f32x4 v0 = acc[ai][bj][m][0], v1 = acc[ai][bj][m][1];
;                     v0[0] *= PG8_SB(bflo(b.x)); v0[1] *= PG8_SB(bfhi(b.x)); v0[2] *= PG8_SB(bflo(b.y)); v0[3] *= PG8_SB(bfhi(b.y));
;                     v1[0] *= PG8_SB(bflo(b.z)); v1[1] *= PG8_SB(bfhi(b.z)); v1[2] *= PG8_SB(bflo(b.w)); v1[3] *= PG8_SB(bfhi(b.w));
;                     *(u32x4*)(mb + r * 2048 + col0 + bj * HALF) = pack8(v0, v1); } }
	v_rcp_f32_e32 v166, v166
	v_rcp_f32_e32 v167, v167
	v_mul_f32_e32 v164, 0xbfb8aa3b, v164
	v_mul_f32_e32 v154, 0xbfb8aa3b, v154
	v_min_f32_e32 v164, 0x42a00000, v164
	v_min_f32_e32 v154, 0x42a00000, v154
	v_lshlrev_b64 v[162:163], 12, v[232:233]
	v_exp_f32_e32 v164, v164
	v_exp_f32_e32 v154, v154
	v_mul_f32_e32 v159, v57, v159
	v_mul_f32_e32 v160, v51, v160
	v_mul_f32_e32 v161, v53, v161
	v_lshl_add_u64 v[162:163], s[48:49], 0, v[162:163]
	v_mul_f32_e32 v165, v56, v165
	v_mul_f32_e32 v166, v50, v166
	v_mul_f32_e32 v167, v52, v167
	v_cvt_pk_bf16_f32 v159, v165, v159
	v_cvt_pk_bf16_f32 v160, v166, v160
	v_cvt_pk_bf16_f32 v161, v167, v161
	v_lshl_add_u64 v[162:163], v[162:163], 0, v[220:221]
	global_store_dwordx4 v[162:163], v[158:161], off sc0 sc1
	v_add_f32_e32 v154, 1.0, v154
	v_rcp_f32_e32 v154, v154
	v_lshlrev_b32_e32 v159, 16, v155
	v_and_b32_e32 v155, 0xffff0000, v155
	v_lshlrev_b32_e32 v160, 16, v156
	v_and_b32_e32 v156, 0xffff0000, v156
	v_lshlrev_b32_e32 v161, 16, v157
	v_and_b32_e32 v157, 0xffff0000, v157
	v_add_f32_e32 v158, 1.0, v164
	v_mul_f32_e32 v155, 0xbfb8aa3b, v155
	v_mul_f32_e32 v156, 0xbfb8aa3b, v156
	v_mul_f32_e32 v157, 0xbfb8aa3b, v157
	v_mul_f32_e32 v159, 0xbfb8aa3b, v159
	v_rcp_f32_e32 v158, v158
	v_min_f32_e32 v155, 0x42a00000, v155
	v_mul_f32_e32 v160, 0xbfb8aa3b, v160
	v_min_f32_e32 v156, 0x42a00000, v156
	v_mul_f32_e32 v161, 0xbfb8aa3b, v161
	v_min_f32_e32 v157, 0x42a00000, v157
	v_min_f32_e32 v159, 0x42a00000, v159
	v_exp_f32_e32 v155, v155
	v_min_f32_e32 v160, 0x42a00000, v160
	v_exp_f32_e32 v156, v156
	v_min_f32_e32 v161, 0x42a00000, v161
	v_exp_f32_e32 v157, v157
	v_exp_f32_e32 v159, v159
	v_exp_f32_e32 v160, v160
	v_exp_f32_e32 v161, v161
	v_mul_f32_e32 v158, v22, v158
	v_mul_f32_e32 v154, v23, v154
	v_add_f32_e32 v155, 1.0, v155
	v_add_f32_e32 v156, 1.0, v156
	v_add_f32_e32 v157, 1.0, v157
	v_cvt_pk_bf16_f32 v154, v158, v154
	v_lshlrev_b32_e32 v158, 16, v150
	v_add_f32_e32 v159, 1.0, v159
	v_rcp_f32_e32 v155, v155
	v_add_f32_e32 v160, 1.0, v160
	v_rcp_f32_e32 v156, v156
	v_add_f32_e32 v161, 1.0, v161
	v_rcp_f32_e32 v157, v157
	v_mul_f32_e32 v158, 0xbfb8aa3b, v158
	v_rcp_f32_e32 v159, v159
	v_rcp_f32_e32 v160, v160
	v_rcp_f32_e32 v161, v161
	v_min_f32_e32 v158, 0x42a00000, v158
	v_and_b32_e32 v150, 0xffff0000, v150
	v_exp_f32_e32 v158, v158
	v_mul_f32_e32 v150, 0xbfb8aa3b, v150
	v_min_f32_e32 v150, 0x42a00000, v150
	v_mul_f32_e32 v155, v25, v155
	v_mul_f32_e32 v156, v19, v156
	v_mul_f32_e32 v157, v21, v157
	v_exp_f32_e32 v150, v150
	v_mul_f32_e32 v159, v24, v159
	v_mul_f32_e32 v160, v18, v160
	v_mul_f32_e32 v161, v20, v161
	v_cvt_pk_bf16_f32 v155, v159, v155
	v_cvt_pk_bf16_f32 v156, v160, v156
	v_cvt_pk_bf16_f32 v157, v161, v157
	global_store_dwordx4 v[162:163], v[154:157], off offset:256 sc0 sc1
	v_lshlrev_b32_e32 v159, 16, v153
	v_and_b32_e32 v153, 0xffff0000, v153
	v_add_f32_e32 v156, 1.0, v158
	v_lshlrev_b32_e32 v157, 16, v151
	v_and_b32_e32 v151, 0xffff0000, v151
	v_lshlrev_b32_e32 v158, 16, v152
	v_and_b32_e32 v152, 0xffff0000, v152
	v_mul_f32_e32 v151, 0xbfb8aa3b, v151
	v_mul_f32_e32 v152, 0xbfb8aa3b, v152
	v_mul_f32_e32 v153, 0xbfb8aa3b, v153
	v_mul_f32_e32 v157, 0xbfb8aa3b, v157
	v_add_f32_e32 v150, 1.0, v150
	v_min_f32_e32 v151, 0x42a00000, v151
	v_mul_f32_e32 v158, 0xbfb8aa3b, v158
	v_min_f32_e32 v152, 0x42a00000, v152
	v_mul_f32_e32 v159, 0xbfb8aa3b, v159
	v_min_f32_e32 v153, 0x42a00000, v153
	v_min_f32_e32 v157, 0x42a00000, v157
	v_rcp_f32_e32 v156, v156
	v_rcp_f32_e32 v150, v150
	v_exp_f32_e32 v151, v151
	v_min_f32_e32 v158, 0x42a00000, v158
	v_exp_f32_e32 v152, v152
	v_min_f32_e32 v159, 0x42a00000, v159
	v_exp_f32_e32 v153, v153
	v_exp_f32_e32 v157, v157
	v_exp_f32_e32 v158, v158
	v_exp_f32_e32 v159, v159
	v_mul_f32_e32 v156, v46, v156
	v_mul_f32_e32 v150, v47, v150
	v_add_f32_e32 v151, 1.0, v151
	v_add_f32_e32 v152, 1.0, v152
	v_add_f32_e32 v153, 1.0, v153
	v_add_f32_e32 v157, 1.0, v157
	v_rcp_f32_e32 v151, v151
	v_add_f32_e32 v158, 1.0, v158
	v_rcp_f32_e32 v152, v152
	v_add_f32_e32 v159, 1.0, v159
	v_rcp_f32_e32 v153, v153
	v_cvt_pk_bf16_f32 v150, v156, v150
	v_lshlrev_b32_e32 v156, 16, v146
	v_and_b32_e32 v146, 0xffff0000, v146
	v_rcp_f32_e32 v157, v157
	v_rcp_f32_e32 v158, v158
	v_rcp_f32_e32 v159, v159
	v_mul_f32_e32 v156, 0xbfb8aa3b, v156
	v_mul_f32_e32 v146, 0xbfb8aa3b, v146
	v_min_f32_e32 v156, 0x42a00000, v156
	v_min_f32_e32 v146, 0x42a00000, v146
	v_lshlrev_b64 v[154:155], 12, v[230:231]
	v_exp_f32_e32 v156, v156
	v_exp_f32_e32 v146, v146
	v_mul_f32_e32 v151, v49, v151
	v_mul_f32_e32 v152, v43, v152
	v_mul_f32_e32 v153, v45, v153
	v_lshl_add_u64 v[154:155], s[48:49], 0, v[154:155]
	v_mul_f32_e32 v157, v48, v157
	v_mul_f32_e32 v158, v42, v158
	v_mul_f32_e32 v159, v44, v159
	v_cvt_pk_bf16_f32 v151, v157, v151
	v_cvt_pk_bf16_f32 v152, v158, v152
	v_cvt_pk_bf16_f32 v153, v159, v153
	v_lshl_add_u64 v[154:155], v[154:155], 0, v[220:221]
	global_store_dwordx4 v[154:155], v[150:153], off sc0 sc1
	v_add_f32_e32 v146, 1.0, v146
	v_rcp_f32_e32 v146, v146
	v_lshlrev_b32_e32 v151, 16, v147
	v_and_b32_e32 v147, 0xffff0000, v147
	v_lshlrev_b32_e32 v152, 16, v148
	v_and_b32_e32 v148, 0xffff0000, v148
	v_lshlrev_b32_e32 v153, 16, v149
	v_and_b32_e32 v149, 0xffff0000, v149
	v_add_f32_e32 v150, 1.0, v156
	v_mul_f32_e32 v147, 0xbfb8aa3b, v147
	v_mul_f32_e32 v148, 0xbfb8aa3b, v148
	v_mul_f32_e32 v149, 0xbfb8aa3b, v149
	v_mul_f32_e32 v151, 0xbfb8aa3b, v151
	v_rcp_f32_e32 v150, v150
	v_min_f32_e32 v147, 0x42a00000, v147
	v_mul_f32_e32 v152, 0xbfb8aa3b, v152
	v_min_f32_e32 v148, 0x42a00000, v148
	v_mul_f32_e32 v153, 0xbfb8aa3b, v153
	v_min_f32_e32 v149, 0x42a00000, v149
	v_min_f32_e32 v151, 0x42a00000, v151
	v_exp_f32_e32 v147, v147
	v_min_f32_e32 v152, 0x42a00000, v152
	v_exp_f32_e32 v148, v148
	v_min_f32_e32 v153, 0x42a00000, v153
	v_exp_f32_e32 v149, v149
	v_exp_f32_e32 v151, v151
	v_exp_f32_e32 v152, v152
	v_exp_f32_e32 v153, v153
	v_mul_f32_e32 v150, v14, v150
	v_mul_f32_e32 v146, v15, v146
	v_add_f32_e32 v147, 1.0, v147
	v_add_f32_e32 v148, 1.0, v148
	v_add_f32_e32 v149, 1.0, v149
	v_cvt_pk_bf16_f32 v146, v150, v146
	s_waitcnt vmcnt(14)
; __device__ __forceinline__ u32x4 pack8(const f32x4& a, const f32x4& b) { u32x4 w; w.x = cvt_pk_bf16(a[0], a[1]); w.y = cvt_pk_bf16(a[2], a[3]); w.z = cvt_pk_bf16(b[0], b[1]); w.w = cvt_pk_bf16(b[2], b[3]); return w; }
; #define PG8_SB(B) __builtin_amdgcn_rcpf(1.f + expneg(B))
; #define PG8_SB(B) __builtin_amdgcn_rcpf(1.f + expneg(B))
;     __device__ __forceinline__ void operator()(const f32x4 (&acc)[2][2][4][2], const Unit& u, int wr, int wc, int fr, int fq) const {
;     ...
; #pragma unroll
;         for (int ai = 0; ai < 2; ++ai)
; #pragma unroll
;             for (int m = 0; m < 4; ++m) { const size_t r = (size_t)(rowt + ai * HALF + m * 16);
; #pragma unroll
;                 for (int bj = 0; bj < 2; ++bj) { const u32x4 b = gb[ai][m][bj];
;                     f32x4 v0 = acc[ai][bj][m][0], v1 = acc[ai][bj][m][1];
;                     v0[0] *= PG8_SB(bflo(b.x)); v0[1] *= PG8_SB(bfhi(b.x)); v0[2] *= PG8_SB(bflo(b.y)); v0[3] *= PG8_SB(bfhi(b.y));
;                     v1[0] *= PG8_SB(bflo(b.z)); v1[1] *= PG8_SB(bfhi(b.z)); v1[2] *= PG8_SB(bflo(b.w)); v1[3] *= PG8_SB(bfhi(b.w));
;                     *(u32x4*)(mb + r * 2048 + col0 + bj * HALF) = pack8(v0, v1); } }
	v_lshlrev_b32_e32 v150, 16, v142
	v_add_f32_e32 v151, 1.0, v151
	v_rcp_f32_e32 v147, v147
	v_add_f32_e32 v152, 1.0, v152
	v_rcp_f32_e32 v148, v148
	v_add_f32_e32 v153, 1.0, v153
	v_rcp_f32_e32 v149, v149
	v_mul_f32_e32 v150, 0xbfb8aa3b, v150
	v_rcp_f32_e32 v151, v151
	v_rcp_f32_e32 v152, v152
	v_rcp_f32_e32 v153, v153
	v_min_f32_e32 v150, 0x42a00000, v150
	v_exp_f32_e32 v150, v150
	v_mul_f32_e32 v147, v17, v147
	v_mul_f32_e32 v148, v11, v148
	v_mul_f32_e32 v149, v13, v149
	v_mul_f32_e32 v151, v16, v151
	v_mul_f32_e32 v152, v10, v152
	v_mul_f32_e32 v153, v12, v153
	v_cvt_pk_bf16_f32 v147, v151, v147
	v_cvt_pk_bf16_f32 v148, v152, v148
	v_cvt_pk_bf16_f32 v149, v153, v149
	v_and_b32_e32 v142, 0xffff0000, v142
	global_store_dwordx4 v[154:155], v[146:149], off offset:256 sc0 sc1
	v_mul_f32_e32 v142, 0xbfb8aa3b, v142
	v_lshlrev_b32_e32 v151, 16, v145
	v_add_f32_e32 v148, 1.0, v150
	v_lshlrev_b32_e32 v149, 16, v143
	v_and_b32_e32 v143, 0xffff0000, v143
	v_lshlrev_b32_e32 v150, 16, v144
	v_and_b32_e32 v144, 0xffff0000, v144
	v_and_b32_e32 v145, 0xffff0000, v145
	v_min_f32_e32 v142, 0x42a00000, v142
	v_mul_f32_e32 v143, 0xbfb8aa3b, v143
	v_mul_f32_e32 v144, 0xbfb8aa3b, v144
	v_mul_f32_e32 v145, 0xbfb8aa3b, v145
	v_exp_f32_e32 v142, v142
	v_mul_f32_e32 v149, 0xbfb8aa3b, v149
	v_min_f32_e32 v143, 0x42a00000, v143
	v_mul_f32_e32 v150, 0xbfb8aa3b, v150
	v_min_f32_e32 v144, 0x42a00000, v144
	v_mul_f32_e32 v151, 0xbfb8aa3b, v151
	v_min_f32_e32 v145, 0x42a00000, v145
	v_min_f32_e32 v149, 0x42a00000, v149
	v_exp_f32_e32 v143, v143
	v_min_f32_e32 v150, 0x42a00000, v150
	v_exp_f32_e32 v144, v144
	v_min_f32_e32 v151, 0x42a00000, v151
	v_exp_f32_e32 v145, v145
	v_exp_f32_e32 v149, v149
	v_exp_f32_e32 v150, v150
	v_exp_f32_e32 v151, v151
	v_add_f32_e32 v142, 1.0, v142
	v_rcp_f32_e32 v148, v148
	v_rcp_f32_e32 v142, v142
	v_add_f32_e32 v143, 1.0, v143
	v_add_f32_e32 v144, 1.0, v144
	v_add_f32_e32 v145, 1.0, v145
	v_add_f32_e32 v149, 1.0, v149
	v_rcp_f32_e32 v143, v143
	v_add_f32_e32 v150, 1.0, v150
	v_rcp_f32_e32 v144, v144
	v_add_f32_e32 v151, 1.0, v151
	v_rcp_f32_e32 v145, v145
	v_rcp_f32_e32 v149, v149
	v_rcp_f32_e32 v150, v150
	v_rcp_f32_e32 v151, v151
	v_lshlrev_b64 v[146:147], 12, v[228:229]
	v_mul_f32_e32 v148, v38, v148
	v_mul_f32_e32 v142, v39, v142
	v_mul_f32_e32 v143, v41, v143
	v_mul_f32_e32 v144, v35, v144
	v_mul_f32_e32 v145, v37, v145
	v_cvt_pk_bf16_f32 v142, v148, v142
	s_waitcnt vmcnt(14)
; __device__ __forceinline__ u32x4 pack8(const f32x4& a, const f32x4& b) { u32x4 w; w.x = cvt_pk_bf16(a[0], a[1]); w.y = cvt_pk_bf16(a[2], a[3]); w.z = cvt_pk_bf16(b[0], b[1]); w.w = cvt_pk_bf16(b[2], b[3]); return w; }
; #define PG8_SB(B) __builtin_amdgcn_rcpf(1.f + expneg(B))
; #define PG8_SB(B) __builtin_amdgcn_rcpf(1.f + expneg(B))
;     __device__ __forceinline__ void operator()(const f32x4 (&acc)[2][2][4][2], const Unit& u, int wr, int wc, int fr, int fq) const {
;     ...
; #pragma unroll
;         for (int ai = 0; ai < 2; ++ai)
; #pragma unroll
;             for (int m = 0; m < 4; ++m) { const size_t r = (size_t)(rowt + ai * HALF + m * 16);
; #pragma unroll
;                 for (int bj = 0; bj < 2; ++bj) { const u32x4 b = gb[ai][m][bj];
;                     f32x4 v0 = acc[ai][bj][m][0], v1 = acc[ai][bj][m][1];
;                     v0[0] *= PG8_SB(bflo(b.x)); v0[1] *= PG8_SB(bfhi(b.x)); v0[2] *= PG8_SB(bflo(b.y)); v0[3] *= PG8_SB(bfhi(b.y));
;                     v1[0] *= PG8_SB(bflo(b.z)); v1[1] *= PG8_SB(bfhi(b.z)); v1[2] *= PG8_SB(bflo(b.w)); v1[3] *= PG8_SB(bfhi(b.w));
;                     *(u32x4*)(mb + r * 2048 + col0 + bj * HALF) = pack8(v0, v1); } }
;     __device__ __forceinline__ void sliver(const f32x4 (&accs)[2], const Unit& u, int srow0, int wr, int wc, int fr, int fq) const {
;         const size_t r = (size_t)(srow0 + 16 * u.pm + fr); const int col0 = u.pn * BM + wr * HALF + wc * 32 + 8 * fq;
;         const u32x4 b = *(const u32x4*)(gg + r * 4096 + 2048 + col0);
;     ...
;         f32x4 v0 = accs[0], v1 = accs[1];
;         v0[0] *= PG8_SB(bflo(b.x)); v0[1] *= PG8_SB(bfhi(b.x)); v0[2] *= PG8_SB(bflo(b.y)); v0[3] *= PG8_SB(bfhi(b.y));
;         v1[0] *= PG8_SB(bflo(b.z)); v1[1] *= PG8_SB(bfhi(b.z)); v1[2] *= PG8_SB(bflo(b.w)); v1[3] *= PG8_SB(bfhi(b.w));
;     ...
;         *(u32x4*)(mb + r * 2048 + col0) = pack8(v0, v1);
;     }
	v_lshlrev_b32_e32 v148, 16, v138
	v_lshl_add_u64 v[146:147], s[48:49], 0, v[146:147]
	v_and_b32_e32 v138, 0xffff0000, v138
	v_mul_f32_e32 v149, v40, v149
	v_mul_f32_e32 v150, v34, v150
	v_mul_f32_e32 v151, v36, v151
	v_cvt_pk_bf16_f32 v143, v149, v143
	v_cvt_pk_bf16_f32 v144, v150, v144
	v_cvt_pk_bf16_f32 v145, v151, v145
	v_mul_f32_e32 v148, 0xbfb8aa3b, v148
	v_lshl_add_u64 v[146:147], v[146:147], 0, v[220:221]
	v_mul_f32_e32 v138, 0xbfb8aa3b, v138
	v_min_f32_e32 v148, 0x42a00000, v148
	global_store_dwordx4 v[146:147], v[142:145], off sc0 sc1
	v_min_f32_e32 v138, 0x42a00000, v138
	v_exp_f32_e32 v148, v148
	v_lshlrev_b32_e32 v143, 16, v139
	v_and_b32_e32 v139, 0xffff0000, v139
	v_lshlrev_b32_e32 v144, 16, v140
	v_and_b32_e32 v140, 0xffff0000, v140
	v_lshlrev_b32_e32 v145, 16, v141
	v_and_b32_e32 v141, 0xffff0000, v141
	v_exp_f32_e32 v138, v138
	v_mul_f32_e32 v143, 0xbfb8aa3b, v143
	v_mul_f32_e32 v139, 0xbfb8aa3b, v139
	v_mul_f32_e32 v140, 0xbfb8aa3b, v140
	v_mul_f32_e32 v141, 0xbfb8aa3b, v141
	v_min_f32_e32 v143, 0x42a00000, v143
	v_min_f32_e32 v139, 0x42a00000, v139
	v_mul_f32_e32 v144, 0xbfb8aa3b, v144
	v_min_f32_e32 v140, 0x42a00000, v140
	v_mul_f32_e32 v145, 0xbfb8aa3b, v145
	v_min_f32_e32 v141, 0x42a00000, v141
	v_exp_f32_e32 v143, v143
	v_exp_f32_e32 v139, v139
	v_min_f32_e32 v144, 0x42a00000, v144
	v_exp_f32_e32 v140, v140
	v_min_f32_e32 v145, 0x42a00000, v145
	v_exp_f32_e32 v141, v141
	v_exp_f32_e32 v144, v144
	v_exp_f32_e32 v145, v145
	v_add_f32_e32 v142, 1.0, v148
	v_add_f32_e32 v138, 1.0, v138
	v_rcp_f32_e32 v142, v142
	v_rcp_f32_e32 v138, v138
	v_add_f32_e32 v143, 1.0, v143
	v_add_f32_e32 v139, 1.0, v139
	v_add_f32_e32 v140, 1.0, v140
	v_add_f32_e32 v141, 1.0, v141
	v_rcp_f32_e32 v143, v143
	v_rcp_f32_e32 v139, v139
	v_add_f32_e32 v144, 1.0, v144
	v_rcp_f32_e32 v140, v140
	v_add_f32_e32 v145, 1.0, v145
	v_rcp_f32_e32 v141, v141
	v_rcp_f32_e32 v144, v144
	v_rcp_f32_e32 v145, v145
	v_mul_f32_e32 v142, v6, v142
	v_mul_f32_e32 v138, v7, v138
	v_cvt_pk_bf16_f32 v138, v142, v138
	v_or_b32_e32 v142, s2, v243
	v_readlane_b32 s2, v254, 45
	v_mul_f32_e32 v143, v8, v143
	v_mul_f32_e32 v139, v9, v139
	v_mul_f32_e32 v140, v3, v140
	v_mul_f32_e32 v141, v5, v141
	s_add_i32 s2, s40, s2
	v_mul_f32_e32 v144, v2, v144
	v_mul_f32_e32 v145, v4, v145
	v_cvt_pk_bf16_f32 v139, v143, v139
	v_cvt_pk_bf16_f32 v140, v144, v140
	v_cvt_pk_bf16_f32 v141, v145, v141
	global_store_dwordx4 v[146:147], v[138:141], off offset:256 sc0 sc1
	v_ashrrev_i32_e32 v143, 31, v142
	s_nop 0
	v_or_b32_e32 v138, s2, v178
	v_lshlrev_b64 v[140:141], 13, v[142:143]
	v_ashrrev_i32_e32 v139, 31, v138
	v_lshl_add_u64 v[140:141], s[42:43], 0, v[140:141]
	v_lshlrev_b64 v[144:145], 1, v[138:139]
	v_lshl_add_u64 v[138:139], v[140:141], 0, v[144:145]
	s_movk_i32 s2, 0x1000
	v_add_co_u32_e32 v138, vcc, s2, v138
	v_lshlrev_b64 v[142:143], 12, v[142:143]
	s_nop 0
	v_addc_co_u32_e32 v139, vcc, 0, v139, vcc
	global_load_dwordx4 v[138:141], v[138:139], off
	v_lshl_add_u64 v[142:143], s[48:49], 0, v[142:143]
	v_lshl_add_u64 v[142:143], v[142:143], 0, v[144:145]
	s_waitcnt vmcnt(0)
	v_lshlrev_b32_e32 v146, 16, v138
	v_and_b32_e32 v138, 0xffff0000, v138
	v_lshlrev_b32_e32 v147, 16, v139
	v_and_b32_e32 v139, 0xffff0000, v139
	v_lshlrev_b32_e32 v148, 16, v140
	v_and_b32_e32 v140, 0xffff0000, v140
	v_lshlrev_b32_e32 v149, 16, v141
	v_and_b32_e32 v141, 0xffff0000, v141
	v_mul_f32_e32 v138, 0xbfb8aa3b, v138
	v_mul_f32_e32 v139, 0xbfb8aa3b, v139
	v_mul_f32_e32 v140, 0xbfb8aa3b, v140
	v_mul_f32_e32 v141, 0xbfb8aa3b, v141
	v_mul_f32_e32 v146, 0xbfb8aa3b, v146
	v_min_f32_e32 v138, 0x42a00000, v138
	v_mul_f32_e32 v147, 0xbfb8aa3b, v147
	v_min_f32_e32 v139, 0x42a00000, v139
	v_mul_f32_e32 v148, 0xbfb8aa3b, v148
	v_min_f32_e32 v140, 0x42a00000, v140
	v_mul_f32_e32 v149, 0xbfb8aa3b, v149
	v_min_f32_e32 v141, 0x42a00000, v141
	v_min_f32_e32 v146, 0x42a00000, v146
	v_exp_f32_e32 v138, v138
	v_min_f32_e32 v147, 0x42a00000, v147
	v_exp_f32_e32 v139, v139
	v_min_f32_e32 v148, 0x42a00000, v148
	v_exp_f32_e32 v140, v140
	v_min_f32_e32 v149, 0x42a00000, v149
	v_exp_f32_e32 v141, v141
	v_exp_f32_e32 v146, v146
	v_exp_f32_e32 v147, v147
	v_exp_f32_e32 v148, v148
	v_exp_f32_e32 v149, v149
	v_add_f32_e32 v138, 1.0, v138
	v_add_f32_e32 v139, 1.0, v139
	v_add_f32_e32 v140, 1.0, v140
	v_add_f32_e32 v141, 1.0, v141
	v_add_f32_e32 v146, 1.0, v146
	v_rcp_f32_e32 v138, v138
	v_add_f32_e32 v147, 1.0, v147
	v_rcp_f32_e32 v139, v139
	v_add_f32_e32 v148, 1.0, v148
	v_rcp_f32_e32 v140, v140
	v_add_f32_e32 v149, 1.0, v149
	v_rcp_f32_e32 v141, v141
	v_rcp_f32_e32 v146, v146
	v_rcp_f32_e32 v147, v147
	v_rcp_f32_e32 v148, v148
	v_rcp_f32_e32 v149, v149
	v_mul_f32_e32 v138, v83, v138
	v_mul_f32_e32 v139, v85, v139
	v_mul_f32_e32 v140, v95, v140
	v_mul_f32_e32 v141, v97, v141
	v_mul_f32_e32 v146, v82, v146
	v_mul_f32_e32 v147, v84, v147
	v_mul_f32_e32 v148, v94, v148
	v_mul_f32_e32 v149, v96, v149
	v_cvt_pk_bf16_f32 v138, v146, v138
	v_cvt_pk_bf16_f32 v139, v147, v139
	v_cvt_pk_bf16_f32 v140, v148, v140
	v_cvt_pk_bf16_f32 v141, v149, v141
	global_store_dwordx4 v[142:143], v[138:141], off sc0 sc1
	s_cbranch_execnz .LBB0_513

; __device__ __forceinline__ u32x4 pack8(const f32x4& a, const f32x4& b) { u32x4 w; w.x = cvt_pk_bf16(a[0], a[1]); w.y = cvt_pk_bf16(a[2], a[3]); w.z = cvt_pk_bf16(b[0], b[1]); w.w = cvt_pk_bf16(b[2], b[3]); return w; }
;     __device__ __forceinline__ void operator()(const f32x4 (&acc)[2][2][4][2], const Unit& u, int wr, int wc, int fr, int fq) const {
;         const int rowt = u.pm * BM + wr * 64 + fr, col0 = u.pn * BM + wc * 32 + 8 * fq;
;         f32x4 gv[2][2];
; #pragma unroll
;         for (int bj = 0; bj < 2; ++bj)
; #pragma unroll
;             for (int n = 0; n < 2; ++n) gv[bj][n] = DST ? *(const f32x4*)(gain + col0 + bj * HALF + n * 4) : (f32x4){0.f, 0.f, 0.f, 0.f};
; #pragma unroll
;         for (int ai = 0; ai < 2; ++ai) {
;             u32x4 xv[4][2];
; #pragma unroll
;             for (int m = 0; m < 4; ++m)
; #pragma unroll
;                 for (int bj = 0; bj < 2; ++bj) xv[m][bj] = *(const u32x4*)(X + (size_t)(rowt + ai * HALF + m * 16) * 2048 + col0 + bj * HALF);
;             asm volatile("" ::: "memory");
; #pragma unroll
;             for (int m = 0; m < 4; ++m) { const int row = rowt + ai * HALF + m * 16; float q = 0.f;
; #pragma unroll
;                 for (int bj = 0; bj < 2; ++bj) { const int col = col0 + bj * HALF; const u32x4 xw = xv[m][bj];
;                     const f32x4 o0 = (f32x4){bflo(xw.x), bfhi(xw.x), bflo(xw.y), bfhi(xw.y)} + acc[ai][bj][m][0], o1 = (f32x4){bflo(xw.z), bfhi(xw.z), bflo(xw.w), bfhi(xw.w)} + acc[ai][bj][m][1];
;                     *(u32x4*)(X + (size_t)row * 2048 + col) = pack8(o0, o1);
;                     q += ((o0[0] * o0[0] + o0[1] * o0[1]) + (o0[2] * o0[2] + o0[3] * o0[3])) + ((o1[0] * o1[0] + o1[1] * o1[1]) + (o1[2] * o1[2] + o1[3] * o1[3]));
;                     if constexpr (DST) *(u32x4*)(dst + (size_t)row * ldd + dcol + col) = pack8(o0 * gv[bj][0], o1 * gv[bj][1]); }
;                 q = fq_sum(q); if (fq == 0) lq[wc * 256 + ai * HALF + wr * 64 + m * 16 + fr] = q; }
.LBB0_608:
	v_mov_b32_e32 v178, v0
	s_lshl_b32 s17, s84, 8
	v_readlane_b32 s12, v254, 52
	s_add_i32 s12, s17, s12
	v_and_b32_e32 v180, 15, v178
	v_bfe_u32 v138, v178, 4, 2
	v_or_b32_e32 v170, s12, v180
	s_lshl_b32 s40, s16, 8
	v_readlane_b32 s12, v254, 54
	v_lshlrev_b32_e32 v181, 3, v138
	s_or_b32 s12, s40, s12
	v_or_b32_e32 v166, s12, v181
	v_ashrrev_i32_e32 v167, 31, v166
	v_lshlrev_b64 v[186:187], 1, v[166:167]
	v_ashrrev_i32_e32 v171, 31, v170
	v_lshl_add_u64 v[168:169], s[42:43], 0, v[186:187]
	v_lshlrev_b64 v[198:199], 12, v[170:171]
	v_cmp_eq_u32_e32 vcc, 0, v138
	v_lshl_add_u64 v[138:139], v[168:169], 0, v[198:199]
	global_load_dwordx4 v[182:185], v[138:139], off
	global_load_dwordx4 v[162:165], v[138:139], off offset:256
	v_or_b32_e32 v138, 16, v170
	v_ashrrev_i32_e32 v139, 31, v138
	v_lshlrev_b64 v[176:177], 12, v[138:139]
	v_lshl_add_u64 v[138:139], v[168:169], 0, v[176:177]
	global_load_dwordx4 v[158:161], v[138:139], off
	global_load_dwordx4 v[154:157], v[138:139], off offset:256
	v_or_b32_e32 v138, 32, v170
	v_ashrrev_i32_e32 v139, 31, v138
	v_lshlrev_b64 v[174:175], 12, v[138:139]
	v_lshl_add_u64 v[138:139], v[168:169], 0, v[174:175]
	global_load_dwordx4 v[150:153], v[138:139], off
	global_load_dwordx4 v[146:149], v[138:139], off offset:256
	v_or_b32_e32 v138, 48, v170
	v_ashrrev_i32_e32 v139, 31, v138
	v_lshlrev_b64 v[172:173], 12, v[138:139]
	v_lshl_add_u64 v[138:139], v[168:169], 0, v[172:173]
	global_load_dwordx4 v[142:145], v[138:139], off
	s_nop 0
	global_load_dwordx4 v[138:141], v[138:139], off offset:256
	v_lshl_add_u64 v[198:199], s[42:43], 0, v[198:199]
	v_lshl_add_u64 v[186:187], v[198:199], 0, v[186:187]
	v_readlane_b32 s12, v254, 63
	s_waitcnt vmcnt(0)
	v_lshlrev_b32_e32 v200, 16, v182
	v_and_b32_e32 v201, 0xffff0000, v182
	v_lshlrev_b32_e32 v182, 16, v183
	v_and_b32_e32 v183, 0xffff0000, v183
	v_pk_add_f32 v[136:137], v[136:137], v[182:183]
	v_lshlrev_b32_e32 v182, 16, v184
	v_and_b32_e32 v183, 0xffff0000, v184
	v_pk_add_f32 v[134:135], v[134:135], v[200:201]
	v_lshlrev_b32_e32 v184, 16, v185
	v_and_b32_e32 v185, 0xffff0000, v185
	v_pk_add_f32 v[182:183], v[130:131], v[182:183]
	v_cvt_pk_bf16_f32 v130, v134, v135
	v_cvt_pk_bf16_f32 v131, v136, v137
	v_pk_add_f32 v[184:185], v[132:133], v[184:185]
	v_cvt_pk_bf16_f32 v132, v182, v183
	s_nop 0
	v_cvt_pk_bf16_f32 v133, v184, v185
	global_store_dwordx4 v[186:187], v[130:133], off sc0 sc1
	s_nop 1
	v_mul_f32_e32 v130, v135, v135
	v_mul_f32_e32 v131, v137, v137
	v_fmac_f32_e32 v130, v134, v134
	v_fmac_f32_e32 v131, v136, v136
	v_add_f32_e32 v130, v130, v131
	v_mul_f32_e32 v131, v183, v183
	v_mul_f32_e32 v132, v185, v185
	v_fmac_f32_e32 v131, v182, v182
	v_fmac_f32_e32 v132, v184, v184
	v_add_f32_e32 v131, v131, v132
	v_add_f32_e32 v134, v130, v131
	v_lshlrev_b32_e32 v130, 16, v162
	v_and_b32_e32 v131, 0xffff0000, v162
	v_lshlrev_b32_e32 v132, 16, v163
	v_and_b32_e32 v133, 0xffff0000, v163
	v_pk_add_f32 v[126:127], v[126:127], v[130:131]
	v_lshlrev_b32_e32 v130, 16, v164
	v_and_b32_e32 v131, 0xffff0000, v164
	v_pk_add_f32 v[128:129], v[128:129], v[132:133]
	v_lshlrev_b32_e32 v132, 16, v165
	v_and_b32_e32 v133, 0xffff0000, v165
	v_pk_add_f32 v[130:131], v[122:123], v[130:131]
	v_cvt_pk_bf16_f32 v122, v126, v127
	v_cvt_pk_bf16_f32 v123, v128, v129
	v_pk_add_f32 v[132:133], v[124:125], v[132:133]
	v_cvt_pk_bf16_f32 v124, v130, v131
	s_nop 0
	v_cvt_pk_bf16_f32 v125, v132, v133
	global_store_dwordx4 v[186:187], v[122:125], off offset:256 sc0 sc1
	s_nop 1
	v_mul_f32_e32 v122, v127, v127
	v_mul_f32_e32 v123, v129, v129
	v_fmac_f32_e32 v122, v126, v126
	v_fmac_f32_e32 v123, v128, v128
	v_add_f32_e32 v122, v122, v123
	v_mul_f32_e32 v123, v131, v131
	v_mul_f32_e32 v124, v133, v133
	v_fmac_f32_e32 v123, v130, v130
	v_fmac_f32_e32 v124, v132, v132
	v_add_f32_e32 v123, v123, v124
	v_add_f32_e32 v122, v122, v123
	v_add_f32_e32 v122, v134, v122
	ds_swizzle_b32 v123, v122 offset:swizzle(SWAP,16)
	s_waitcnt lgkmcnt(0)
	v_add_f32_e32 v123, v122, v123
	v_mov_b32_e32 v124, v123
	v_lshl_add_u32 v122, v180, 2, s12
	s_nop 0
	v_permlane32_swap_b32_e32 v123, v124
	s_and_saveexec_b64 s[12:13], vcc
	v_readlane_b32 s79, v254, 35
	s_movk_i32 s77, 0x70
	s_mov_b64 s[96:97], 0x2c00
	s_mov_b64 s[68:69], 0x4000c00
	v_add_f32_e32 v123, v123, v124
	ds_write_b32 v122, v123
	s_or_b64 exec, exec, s[12:13]
	v_lshlrev_b32_e32 v124, 16, v158
	v_and_b32_e32 v125, 0xffff0000, v158
	v_lshlrev_b32_e32 v126, 16, v159
	v_and_b32_e32 v127, 0xffff0000, v159
	v_pk_add_f32 v[118:119], v[118:119], v[124:125]
	v_lshlrev_b32_e32 v124, 16, v160
	v_and_b32_e32 v125, 0xffff0000, v160
	v_lshl_add_u64 v[128:129], s[42:43], 0, v[176:177]
	v_pk_add_f32 v[120:121], v[120:121], v[126:127]
	v_lshlrev_b32_e32 v126, 16, v161
	v_and_b32_e32 v127, 0xffff0000, v161
	v_pk_add_f32 v[124:125], v[114:115], v[124:125]
	v_cvt_pk_bf16_f32 v114, v118, v119
	v_cvt_pk_bf16_f32 v115, v120, v121
	v_lshl_add_u64 v[128:129], v[166:167], 1, v[128:129]
	v_pk_add_f32 v[126:127], v[116:117], v[126:127]
	v_cvt_pk_bf16_f32 v116, v124, v125
	s_nop 0
	v_cvt_pk_bf16_f32 v117, v126, v127
	global_store_dwordx4 v[128:129], v[114:117], off sc0 sc1
	s_nop 1
	v_mul_f32_e32 v114, v119, v119
	v_mul_f32_e32 v115, v121, v121
	v_fmac_f32_e32 v114, v118, v118
	v_fmac_f32_e32 v115, v120, v120
	v_add_f32_e32 v114, v114, v115
	v_mul_f32_e32 v115, v125, v125
	v_mul_f32_e32 v116, v127, v127
	v_fmac_f32_e32 v115, v124, v124
	v_fmac_f32_e32 v116, v126, v126
	v_add_f32_e32 v115, v115, v116
	v_add_f32_e32 v118, v114, v115
	v_lshlrev_b32_e32 v114, 16, v154
	v_and_b32_e32 v115, 0xffff0000, v154
	v_lshlrev_b32_e32 v116, 16, v155
	v_and_b32_e32 v117, 0xffff0000, v155
	v_pk_add_f32 v[112:113], v[112:113], v[116:117]
	v_pk_add_f32 v[110:111], v[110:111], v[114:115]
	v_lshlrev_b32_e32 v114, 16, v156
	v_and_b32_e32 v115, 0xffff0000, v156
	v_lshlrev_b32_e32 v116, 16, v157
	v_and_b32_e32 v117, 0xffff0000, v157
	v_pk_add_f32 v[116:117], v[108:109], v[116:117]
	v_pk_add_f32 v[108:109], v[106:107], v[114:115]
	v_mul_f32_e32 v107, v111, v111
	v_cvt_pk_bf16_f32 v106, v110, v111
	v_fmac_f32_e32 v107, v110, v110
	v_mul_f32_e32 v110, v113, v113
	v_fmac_f32_e32 v110, v112, v112
	v_add_f32_e32 v107, v107, v110
	v_mul_f32_e32 v110, v109, v109
	v_mul_f32_e32 v111, v117, v117
	v_fmac_f32_e32 v110, v108, v108
	v_fmac_f32_e32 v111, v116, v116
	v_add_f32_e32 v110, v110, v111
	v_add_f32_e32 v107, v107, v110
	v_add_f32_e32 v110, v118, v107
	ds_swizzle_b32 v111, v110 offset:swizzle(SWAP,16)
	v_cvt_pk_bf16_f32 v107, v112, v113
	v_cvt_pk_bf16_f32 v108, v108, v109
	v_cvt_pk_bf16_f32 v109, v116, v117
	global_store_dwordx4 v[128:129], v[106:109], off offset:256 sc0 sc1
	s_waitcnt lgkmcnt(0)
; __device__ __forceinline__ u32x4 pack8(const f32x4& a, const f32x4& b) { u32x4 w; w.x = cvt_pk_bf16(a[0], a[1]); w.y = cvt_pk_bf16(a[2], a[3]); w.z = cvt_pk_bf16(b[0], b[1]); w.w = cvt_pk_bf16(b[2], b[3]); return w; }
;     __device__ __forceinline__ void operator()(const f32x4 (&acc)[2][2][4][2], const Unit& u, int wr, int wc, int fr, int fq) const {
;     ...
;         for (int ai = 0; ai < 2; ++ai) {
;             u32x4 xv[4][2];
; #pragma unroll
;             for (int m = 0; m < 4; ++m)
; #pragma unroll
;                 for (int bj = 0; bj < 2; ++bj) xv[m][bj] = *(const u32x4*)(X + (size_t)(rowt + ai * HALF + m * 16) * 2048 + col0 + bj * HALF);
;             asm volatile("" ::: "memory");
; #pragma unroll
;             for (int m = 0; m < 4; ++m) { const int row = rowt + ai * HALF + m * 16; float q = 0.f;
; #pragma unroll
;                 for (int bj = 0; bj < 2; ++bj) { const int col = col0 + bj * HALF; const u32x4 xw = xv[m][bj];
;                     const f32x4 o0 = (f32x4){bflo(xw.x), bfhi(xw.x), bflo(xw.y), bfhi(xw.y)} + acc[ai][bj][m][0], o1 = (f32x4){bflo(xw.z), bfhi(xw.z), bflo(xw.w), bfhi(xw.w)} + acc[ai][bj][m][1];
;                     *(u32x4*)(X + (size_t)row * 2048 + col) = pack8(o0, o1);
;                     q += ((o0[0] * o0[0] + o0[1] * o0[1]) + (o0[2] * o0[2] + o0[3] * o0[3])) + ((o1[0] * o1[0] + o1[1] * o1[1]) + (o1[2] * o1[2] + o1[3] * o1[3]));
;                     if constexpr (DST) *(u32x4*)(dst + (size_t)row * ldd + dcol + col) = pack8(o0 * gv[bj][0], o1 * gv[bj][1]); }
;                 q = fq_sum(q); if (fq == 0) lq[wc * 256 + ai * HALF + wr * 64 + m * 16 + fr] = q; }
	s_nop 0
	v_add_f32_e32 v106, v110, v111
	v_mov_b32_e32 v107, v106
	s_nop 1
	v_permlane32_swap_b32_e32 v106, v107
	s_and_saveexec_b64 s[12:13], vcc
	v_add_f32_e32 v106, v106, v107
	ds_write_b32 v122, v106 offset:64
	s_or_b64 exec, exec, s[12:13]
	v_lshlrev_b32_e32 v106, 16, v150
	v_and_b32_e32 v107, 0xffff0000, v150
	v_lshlrev_b32_e32 v108, 16, v151
	v_and_b32_e32 v109, 0xffff0000, v151
	v_pk_add_f32 v[102:103], v[102:103], v[106:107]
	v_lshlrev_b32_e32 v106, 16, v152
	v_and_b32_e32 v107, 0xffff0000, v152
	v_lshl_add_u64 v[110:111], s[42:43], 0, v[174:175]
	v_pk_add_f32 v[104:105], v[104:105], v[108:109]
	v_lshlrev_b32_e32 v108, 16, v153
	v_and_b32_e32 v109, 0xffff0000, v153
	v_pk_add_f32 v[106:107], v[98:99], v[106:107]
	v_cvt_pk_bf16_f32 v98, v102, v103
	v_cvt_pk_bf16_f32 v99, v104, v105
	v_lshl_add_u64 v[110:111], v[166:167], 1, v[110:111]
	v_pk_add_f32 v[108:109], v[100:101], v[108:109]
	v_cvt_pk_bf16_f32 v100, v106, v107
	s_nop 0
	v_cvt_pk_bf16_f32 v101, v108, v109
	global_store_dwordx4 v[110:111], v[98:101], off sc0 sc1
	s_nop 1
	v_mul_f32_e32 v98, v103, v103
	v_mul_f32_e32 v99, v105, v105
	v_fmac_f32_e32 v98, v102, v102
	v_fmac_f32_e32 v99, v104, v104
	v_add_f32_e32 v98, v98, v99
	v_mul_f32_e32 v99, v107, v107
	v_mul_f32_e32 v100, v109, v109
	v_fmac_f32_e32 v99, v106, v106
	v_fmac_f32_e32 v100, v108, v108
	v_add_f32_e32 v99, v99, v100
	v_add_f32_e32 v102, v98, v99
	v_lshlrev_b32_e32 v98, 16, v146
	v_and_b32_e32 v99, 0xffff0000, v146
	v_lshlrev_b32_e32 v100, 16, v147
	v_and_b32_e32 v101, 0xffff0000, v147
	v_pk_add_f32 v[96:97], v[96:97], v[100:101]
	v_pk_add_f32 v[94:95], v[94:95], v[98:99]
	v_lshlrev_b32_e32 v98, 16, v148
	v_and_b32_e32 v99, 0xffff0000, v148
	v_lshlrev_b32_e32 v100, 16, v149
	v_and_b32_e32 v101, 0xffff0000, v149
	v_pk_add_f32 v[100:101], v[92:93], v[100:101]
	v_pk_add_f32 v[92:93], v[90:91], v[98:99]
	v_mul_f32_e32 v91, v95, v95
	v_cvt_pk_bf16_f32 v90, v94, v95
	v_fmac_f32_e32 v91, v94, v94
	v_mul_f32_e32 v94, v97, v97
	v_fmac_f32_e32 v94, v96, v96
	v_add_f32_e32 v91, v91, v94
	v_mul_f32_e32 v94, v93, v93
	v_mul_f32_e32 v95, v101, v101
	v_fmac_f32_e32 v94, v92, v92
	v_fmac_f32_e32 v95, v100, v100
	v_add_f32_e32 v94, v94, v95
	v_add_f32_e32 v91, v91, v94
	v_add_f32_e32 v94, v102, v91
	ds_swizzle_b32 v95, v94 offset:swizzle(SWAP,16)
	v_cvt_pk_bf16_f32 v91, v96, v97
	v_cvt_pk_bf16_f32 v92, v92, v93
	v_cvt_pk_bf16_f32 v93, v100, v101
	global_store_dwordx4 v[110:111], v[90:93], off offset:256 sc0 sc1
	s_waitcnt lgkmcnt(0)
	s_nop 0
	v_add_f32_e32 v90, v94, v95
	v_mov_b32_e32 v91, v90
	s_nop 1
	v_permlane32_swap_b32_e32 v90, v91
	s_and_saveexec_b64 s[12:13], vcc
	v_add_f32_e32 v90, v90, v91
	ds_write_b32 v122, v90 offset:128
	s_or_b64 exec, exec, s[12:13]
	v_lshlrev_b32_e32 v90, 16, v142
	v_and_b32_e32 v91, 0xffff0000, v142
	v_lshlrev_b32_e32 v92, 16, v143
	v_and_b32_e32 v93, 0xffff0000, v143
	v_pk_add_f32 v[86:87], v[86:87], v[90:91]
	v_lshlrev_b32_e32 v90, 16, v144
	v_and_b32_e32 v91, 0xffff0000, v144
	v_lshl_add_u64 v[94:95], s[42:43], 0, v[172:173]
	v_pk_add_f32 v[88:89], v[88:89], v[92:93]
	v_lshlrev_b32_e32 v92, 16, v145
	v_and_b32_e32 v93, 0xffff0000, v145
	v_pk_add_f32 v[90:91], v[82:83], v[90:91]
	v_cvt_pk_bf16_f32 v82, v86, v87
	v_cvt_pk_bf16_f32 v83, v88, v89
	v_lshl_add_u64 v[94:95], v[166:167], 1, v[94:95]
	v_pk_add_f32 v[92:93], v[84:85], v[92:93]
	v_cvt_pk_bf16_f32 v84, v90, v91
	s_nop 0
	v_cvt_pk_bf16_f32 v85, v92, v93
	global_store_dwordx4 v[94:95], v[82:85], off sc0 sc1
	s_nop 1
	v_mul_f32_e32 v82, v87, v87
	v_mul_f32_e32 v83, v89, v89
	v_fmac_f32_e32 v82, v86, v86
	v_fmac_f32_e32 v83, v88, v88
	v_add_f32_e32 v82, v82, v83
	v_mul_f32_e32 v83, v91, v91
	v_mul_f32_e32 v84, v93, v93
	v_fmac_f32_e32 v83, v90, v90
	v_fmac_f32_e32 v84, v92, v92
	v_add_f32_e32 v83, v83, v84
	v_add_f32_e32 v86, v82, v83
	v_lshlrev_b32_e32 v82, 16, v138
	v_and_b32_e32 v83, 0xffff0000, v138
	v_lshlrev_b32_e32 v84, 16, v139
	v_and_b32_e32 v85, 0xffff0000, v139
	v_pk_add_f32 v[80:81], v[80:81], v[84:85]
	v_pk_add_f32 v[78:79], v[78:79], v[82:83]
	v_lshlrev_b32_e32 v82, 16, v140
	v_and_b32_e32 v83, 0xffff0000, v140
	v_lshlrev_b32_e32 v84, 16, v141
	v_and_b32_e32 v85, 0xffff0000, v141
	v_pk_add_f32 v[84:85], v[76:77], v[84:85]
	v_pk_add_f32 v[76:77], v[74:75], v[82:83]
	v_mul_f32_e32 v75, v79, v79
	v_cvt_pk_bf16_f32 v74, v78, v79
	v_fmac_f32_e32 v75, v78, v78
	v_mul_f32_e32 v78, v81, v81
	v_fmac_f32_e32 v78, v80, v80
	v_add_f32_e32 v75, v75, v78
	v_mul_f32_e32 v78, v77, v77
	v_mul_f32_e32 v79, v85, v85
	v_fmac_f32_e32 v78, v76, v76
	v_fmac_f32_e32 v79, v84, v84
	v_add_f32_e32 v78, v78, v79
	v_add_f32_e32 v75, v75, v78
	v_add_f32_e32 v78, v86, v75
	ds_swizzle_b32 v79, v78 offset:swizzle(SWAP,16)
	v_cvt_pk_bf16_f32 v75, v80, v81
	v_cvt_pk_bf16_f32 v76, v76, v77
	v_cvt_pk_bf16_f32 v77, v84, v85
	global_store_dwordx4 v[94:95], v[74:77], off offset:256 sc0 sc1
	s_waitcnt lgkmcnt(0)
	s_nop 0
	v_add_f32_e32 v74, v78, v79
	v_mov_b32_e32 v75, v74
	s_nop 1
	v_permlane32_swap_b32_e32 v74, v75
	s_and_saveexec_b64 s[12:13], vcc
	v_add_f32_e32 v74, v74, v75
	ds_write_b32 v122, v74 offset:192
	s_or_b64 exec, exec, s[12:13]
	v_lshlrev_b64 v[74:75], 12, v[170:171]
	v_lshl_add_u64 v[112:113], v[74:75], 0, s[22:23]
	v_lshl_add_u64 v[76:77], v[168:169], 0, v[112:113]
	global_load_dwordx4 v[108:111], v[76:77], off
	global_load_dwordx4 v[98:101], v[76:77], off offset:256
	v_lshl_add_u64 v[106:107], v[74:75], 0, s[46:47]
	s_mov_b64 s[12:13], 0xa0000
	v_lshl_add_u64 v[76:77], v[168:169], 0, v[106:107]
	v_lshl_add_u64 v[104:105], v[74:75], 0, s[12:13]
	v_lshl_add_u64 v[102:103], v[74:75], 0, s[64:65]
	global_load_dwordx4 v[94:97], v[76:77], off
	global_load_dwordx4 v[90:93], v[76:77], off offset:256
	v_lshl_add_u64 v[76:77], v[168:169], 0, v[104:105]
	v_lshl_add_u64 v[74:75], v[168:169], 0, v[102:103]
	global_load_dwordx4 v[86:89], v[76:77], off
	global_load_dwordx4 v[82:85], v[76:77], off offset:256
	global_load_dwordx4 v[78:81], v[74:75], off
	s_nop 0
	global_load_dwordx4 v[74:77], v[74:75], off offset:256
	v_lshl_add_u64 v[112:113], s[42:43], 0, v[112:113]
	v_lshl_add_u64 v[112:113], v[166:167], 1, v[112:113]
	s_waitcnt vmcnt(7)
; __device__ __forceinline__ u32x4 pack8(const f32x4& a, const f32x4& b) { u32x4 w; w.x = cvt_pk_bf16(a[0], a[1]); w.y = cvt_pk_bf16(a[2], a[3]); w.z = cvt_pk_bf16(b[0], b[1]); w.w = cvt_pk_bf16(b[2], b[3]); return w; }
;     __device__ __forceinline__ void operator()(const f32x4 (&acc)[2][2][4][2], const Unit& u, int wr, int wc, int fr, int fq) const {
;     ...
;                 for (int bj = 0; bj < 2; ++bj) xv[m][bj] = *(const u32x4*)(X + (size_t)(rowt + ai * HALF + m * 16) * 2048 + col0 + bj * HALF);
;             asm volatile("" ::: "memory");
; #pragma unroll
;             for (int m = 0; m < 4; ++m) { const int row = rowt + ai * HALF + m * 16; float q = 0.f;
; #pragma unroll
;                 for (int bj = 0; bj < 2; ++bj) { const int col = col0 + bj * HALF; const u32x4 xw = xv[m][bj];
;                     const f32x4 o0 = (f32x4){bflo(xw.x), bfhi(xw.x), bflo(xw.y), bfhi(xw.y)} + acc[ai][bj][m][0], o1 = (f32x4){bflo(xw.z), bfhi(xw.z), bflo(xw.w), bfhi(xw.w)} + acc[ai][bj][m][1];
;                     *(u32x4*)(X + (size_t)row * 2048 + col) = pack8(o0, o1);
;                     q += ((o0[0] * o0[0] + o0[1] * o0[1]) + (o0[2] * o0[2] + o0[3] * o0[3])) + ((o1[0] * o1[0] + o1[1] * o1[1]) + (o1[2] * o1[2] + o1[3] * o1[3]));
;                     if constexpr (DST) *(u32x4*)(dst + (size_t)row * ldd + dcol + col) = pack8(o0 * gv[bj][0], o1 * gv[bj][1]); }
;                 q = fq_sum(q); if (fq == 0) lq[wc * 256 + ai * HALF + wr * 64 + m * 16 + fr] = q; }
	v_lshlrev_b32_e32 v114, 16, v108
	v_and_b32_e32 v115, 0xffff0000, v108
	v_lshlrev_b32_e32 v108, 16, v109
	v_and_b32_e32 v109, 0xffff0000, v109
	v_pk_add_f32 v[72:73], v[72:73], v[108:109]
	v_lshlrev_b32_e32 v108, 16, v110
	v_and_b32_e32 v109, 0xffff0000, v110
	v_pk_add_f32 v[70:71], v[70:71], v[114:115]
	v_lshlrev_b32_e32 v110, 16, v111
	v_and_b32_e32 v111, 0xffff0000, v111
	v_pk_add_f32 v[108:109], v[66:67], v[108:109]
	v_cvt_pk_bf16_f32 v66, v70, v71
	v_cvt_pk_bf16_f32 v67, v72, v73
	v_pk_add_f32 v[110:111], v[68:69], v[110:111]
	v_cvt_pk_bf16_f32 v68, v108, v109
	s_nop 0
	v_cvt_pk_bf16_f32 v69, v110, v111
	global_store_dwordx4 v[112:113], v[66:69], off sc0 sc1
	s_nop 1
	v_mul_f32_e32 v66, v71, v71
	v_mul_f32_e32 v67, v73, v73
	v_fmac_f32_e32 v66, v70, v70
	v_fmac_f32_e32 v67, v72, v72
	v_add_f32_e32 v66, v66, v67
	v_mul_f32_e32 v67, v109, v109
	v_mul_f32_e32 v68, v111, v111
	v_fmac_f32_e32 v67, v108, v108
	v_fmac_f32_e32 v68, v110, v110
	v_add_f32_e32 v67, v67, v68
	v_add_f32_e32 v70, v66, v67
	s_waitcnt vmcnt(7)
	v_lshlrev_b32_e32 v66, 16, v98
	v_and_b32_e32 v67, 0xffff0000, v98
	v_lshlrev_b32_e32 v68, 16, v99
	v_and_b32_e32 v69, 0xffff0000, v99
	v_pk_add_f32 v[62:63], v[62:63], v[66:67]
	v_lshlrev_b32_e32 v66, 16, v100
	v_and_b32_e32 v67, 0xffff0000, v100
	v_pk_add_f32 v[64:65], v[64:65], v[68:69]
	v_lshlrev_b32_e32 v68, 16, v101
	v_and_b32_e32 v69, 0xffff0000, v101
	v_pk_add_f32 v[66:67], v[58:59], v[66:67]
	v_cvt_pk_bf16_f32 v58, v62, v63
	v_cvt_pk_bf16_f32 v59, v64, v65
	v_pk_add_f32 v[68:69], v[60:61], v[68:69]
	v_cvt_pk_bf16_f32 v60, v66, v67
	s_nop 0
	v_cvt_pk_bf16_f32 v61, v68, v69
	global_store_dwordx4 v[112:113], v[58:61], off offset:256 sc0 sc1
	s_nop 1
	v_mul_f32_e32 v58, v63, v63
	v_mul_f32_e32 v59, v65, v65
	v_fmac_f32_e32 v58, v62, v62
	v_fmac_f32_e32 v59, v64, v64
	v_add_f32_e32 v58, v58, v59
	v_mul_f32_e32 v59, v67, v67
	v_mul_f32_e32 v60, v69, v69
	v_fmac_f32_e32 v59, v66, v66
	v_fmac_f32_e32 v60, v68, v68
	v_add_f32_e32 v59, v59, v60
	v_add_f32_e32 v58, v58, v59
	v_add_f32_e32 v58, v70, v58
	ds_swizzle_b32 v59, v58 offset:swizzle(SWAP,16)
	s_waitcnt lgkmcnt(0)
	v_add_f32_e32 v58, v58, v59
	v_mov_b32_e32 v59, v58
	s_nop 1
	v_permlane32_swap_b32_e32 v58, v59
	s_and_saveexec_b64 s[12:13], vcc
	v_add_f32_e32 v58, v58, v59
	ds_write_b32 v122, v58 offset:512
	s_or_b64 exec, exec, s[12:13]
	s_waitcnt vmcnt(7)
	v_lshlrev_b32_e32 v58, 16, v94
	v_and_b32_e32 v59, 0xffff0000, v94
	v_lshlrev_b32_e32 v60, 16, v95
	v_and_b32_e32 v61, 0xffff0000, v95
	v_pk_add_f32 v[54:55], v[54:55], v[58:59]
	v_lshlrev_b32_e32 v58, 16, v96
	v_and_b32_e32 v59, 0xffff0000, v96
	v_lshl_add_u64 v[62:63], s[42:43], 0, v[106:107]
	v_pk_add_f32 v[56:57], v[56:57], v[60:61]
	v_lshlrev_b32_e32 v60, 16, v97
	v_and_b32_e32 v61, 0xffff0000, v97
	v_pk_add_f32 v[58:59], v[50:51], v[58:59]
	v_cvt_pk_bf16_f32 v50, v54, v55
	v_cvt_pk_bf16_f32 v51, v56, v57
	v_lshl_add_u64 v[62:63], v[166:167], 1, v[62:63]
	v_pk_add_f32 v[60:61], v[52:53], v[60:61]
	v_cvt_pk_bf16_f32 v52, v58, v59
	s_nop 0
	v_cvt_pk_bf16_f32 v53, v60, v61
	global_store_dwordx4 v[62:63], v[50:53], off sc0 sc1
	s_nop 1
	v_mul_f32_e32 v50, v55, v55
	v_mul_f32_e32 v51, v57, v57
	v_fmac_f32_e32 v50, v54, v54
	v_fmac_f32_e32 v51, v56, v56
	v_add_f32_e32 v50, v50, v51
	v_mul_f32_e32 v51, v59, v59
	v_mul_f32_e32 v52, v61, v61
	v_fmac_f32_e32 v51, v58, v58
	v_fmac_f32_e32 v52, v60, v60
	v_add_f32_e32 v51, v51, v52
	v_add_f32_e32 v54, v50, v51
	s_waitcnt vmcnt(7)
	v_lshlrev_b32_e32 v50, 16, v90
	v_and_b32_e32 v51, 0xffff0000, v90
	v_lshlrev_b32_e32 v52, 16, v91
	v_and_b32_e32 v53, 0xffff0000, v91
	v_pk_add_f32 v[48:49], v[48:49], v[52:53]
	v_pk_add_f32 v[46:47], v[46:47], v[50:51]
	v_lshlrev_b32_e32 v50, 16, v92
	v_and_b32_e32 v51, 0xffff0000, v92
	v_lshlrev_b32_e32 v52, 16, v93
	v_and_b32_e32 v53, 0xffff0000, v93
	v_pk_add_f32 v[52:53], v[44:45], v[52:53]
	v_pk_add_f32 v[44:45], v[42:43], v[50:51]
	v_mul_f32_e32 v43, v47, v47
	v_cvt_pk_bf16_f32 v42, v46, v47
	v_fmac_f32_e32 v43, v46, v46
	v_mul_f32_e32 v46, v49, v49
	v_fmac_f32_e32 v46, v48, v48
	v_add_f32_e32 v43, v43, v46
	v_mul_f32_e32 v46, v45, v45
	v_mul_f32_e32 v47, v53, v53
	v_fmac_f32_e32 v46, v44, v44
	v_fmac_f32_e32 v47, v52, v52
	v_add_f32_e32 v46, v46, v47
	v_add_f32_e32 v43, v43, v46
	v_add_f32_e32 v46, v54, v43
	ds_swizzle_b32 v47, v46 offset:swizzle(SWAP,16)
	v_cvt_pk_bf16_f32 v43, v48, v49
	v_cvt_pk_bf16_f32 v44, v44, v45
	v_cvt_pk_bf16_f32 v45, v52, v53
	global_store_dwordx4 v[62:63], v[42:45], off offset:256 sc0 sc1
	s_waitcnt lgkmcnt(0)
	s_nop 0
	v_add_f32_e32 v42, v46, v47
	v_mov_b32_e32 v43, v42
	s_nop 1
	v_permlane32_swap_b32_e32 v42, v43
	s_and_saveexec_b64 s[12:13], vcc
	v_add_f32_e32 v42, v42, v43
	ds_write_b32 v122, v42 offset:576
	s_or_b64 exec, exec, s[12:13]
	s_waitcnt vmcnt(7)
	v_lshlrev_b32_e32 v42, 16, v86
	v_and_b32_e32 v43, 0xffff0000, v86
	v_lshlrev_b32_e32 v44, 16, v87
	v_and_b32_e32 v45, 0xffff0000, v87
	v_pk_add_f32 v[38:39], v[38:39], v[42:43]
	v_lshlrev_b32_e32 v42, 16, v88
	v_and_b32_e32 v43, 0xffff0000, v88
	v_lshl_add_u64 v[46:47], s[42:43], 0, v[104:105]
	v_pk_add_f32 v[40:41], v[40:41], v[44:45]
	v_lshlrev_b32_e32 v44, 16, v89
	v_and_b32_e32 v45, 0xffff0000, v89
	v_pk_add_f32 v[42:43], v[34:35], v[42:43]
	v_cvt_pk_bf16_f32 v34, v38, v39
	v_cvt_pk_bf16_f32 v35, v40, v41
	v_lshl_add_u64 v[46:47], v[166:167], 1, v[46:47]
	v_pk_add_f32 v[44:45], v[36:37], v[44:45]
	v_cvt_pk_bf16_f32 v36, v42, v43
	s_nop 0
	v_cvt_pk_bf16_f32 v37, v44, v45
	global_store_dwordx4 v[46:47], v[34:37], off sc0 sc1
	s_nop 1
	v_mul_f32_e32 v34, v39, v39
	v_mul_f32_e32 v35, v41, v41
	v_fmac_f32_e32 v34, v38, v38
	v_fmac_f32_e32 v35, v40, v40
	v_add_f32_e32 v34, v34, v35
	v_mul_f32_e32 v35, v43, v43
	v_mul_f32_e32 v36, v45, v45
	v_fmac_f32_e32 v35, v42, v42
	v_fmac_f32_e32 v36, v44, v44
	v_add_f32_e32 v35, v35, v36
	v_add_f32_e32 v38, v34, v35
	s_waitcnt vmcnt(7)
; __device__ __forceinline__ u32x4 pack8(const f32x4& a, const f32x4& b) { u32x4 w; w.x = cvt_pk_bf16(a[0], a[1]); w.y = cvt_pk_bf16(a[2], a[3]); w.z = cvt_pk_bf16(b[0], b[1]); w.w = cvt_pk_bf16(b[2], b[3]); return w; }
;     __device__ __forceinline__ void operator()(const f32x4 (&acc)[2][2][4][2], const Unit& u, int wr, int wc, int fr, int fq) const {
;     ...
;             for (int m = 0; m < 4; ++m) { const int row = rowt + ai * HALF + m * 16; float q = 0.f;
; #pragma unroll
;                 for (int bj = 0; bj < 2; ++bj) { const int col = col0 + bj * HALF; const u32x4 xw = xv[m][bj];
;                     const f32x4 o0 = (f32x4){bflo(xw.x), bfhi(xw.x), bflo(xw.y), bfhi(xw.y)} + acc[ai][bj][m][0], o1 = (f32x4){bflo(xw.z), bfhi(xw.z), bflo(xw.w), bfhi(xw.w)} + acc[ai][bj][m][1];
;                     *(u32x4*)(X + (size_t)row * 2048 + col) = pack8(o0, o1);
;                     q += ((o0[0] * o0[0] + o0[1] * o0[1]) + (o0[2] * o0[2] + o0[3] * o0[3])) + ((o1[0] * o1[0] + o1[1] * o1[1]) + (o1[2] * o1[2] + o1[3] * o1[3]));
;                     if constexpr (DST) *(u32x4*)(dst + (size_t)row * ldd + dcol + col) = pack8(o0 * gv[bj][0], o1 * gv[bj][1]); }
;                 q = fq_sum(q); if (fq == 0) lq[wc * 256 + ai * HALF + wr * 64 + m * 16 + fr] = q; }
;     __device__ __forceinline__ void sliver(const f32x4 (&accs)[2], const Unit& u, int srow0, int wr, int wc, int fr, int fq) const {
;         const int row = srow0 + 16 * u.pm + fr, col = u.pn * BM + wr * HALF + wc * 32 + 8 * fq;
;         const u32x4 xw = *(const u32x4*)(X + (size_t)row * 2048 + col);
;         const f32x4 o0 = (f32x4){bflo(xw.x), bfhi(xw.x), bflo(xw.y), bfhi(xw.y)} + accs[0], o1 = (f32x4){bflo(xw.z), bfhi(xw.z), bflo(xw.w), bfhi(xw.w)} + accs[1];
;         *(u32x4*)(X + (size_t)row * 2048 + col) = pack8(o0, o1);
;         float q = ((o0[0] * o0[0] + o0[1] * o0[1]) + (o0[2] * o0[2] + o0[3] * o0[3])) + ((o1[0] * o1[0] + o1[1] * o1[1]) + (o1[2] * o1[2] + o1[3] * o1[3]));
;         if constexpr (DST) { const f32x4 g0 = *(const f32x4*)(gain + col), g1 = *(const f32x4*)(gain + col + 4); *(u32x4*)(dst + (size_t)row * ldd + dcol + col) = pack8(o0 * g0, o1 * g1); }
;         q = fq_sum(q); if (fq == 0) lq[1024 + (wr * 4 + wc) * 16 + fr] = q;
	v_lshlrev_b32_e32 v34, 16, v82
	v_and_b32_e32 v35, 0xffff0000, v82
	v_lshlrev_b32_e32 v36, 16, v83
	v_and_b32_e32 v37, 0xffff0000, v83
	v_pk_add_f32 v[32:33], v[32:33], v[36:37]
	v_pk_add_f32 v[30:31], v[30:31], v[34:35]
	v_lshlrev_b32_e32 v34, 16, v84
	v_and_b32_e32 v35, 0xffff0000, v84
	v_lshlrev_b32_e32 v36, 16, v85
	v_and_b32_e32 v37, 0xffff0000, v85
	v_pk_add_f32 v[36:37], v[28:29], v[36:37]
	v_pk_add_f32 v[28:29], v[26:27], v[34:35]
	v_mul_f32_e32 v27, v31, v31
	v_cvt_pk_bf16_f32 v26, v30, v31
	v_fmac_f32_e32 v27, v30, v30
	v_mul_f32_e32 v30, v33, v33
	v_fmac_f32_e32 v30, v32, v32
	v_add_f32_e32 v27, v27, v30
	v_mul_f32_e32 v30, v29, v29
	v_mul_f32_e32 v31, v37, v37
	v_fmac_f32_e32 v30, v28, v28
	v_fmac_f32_e32 v31, v36, v36
	v_add_f32_e32 v30, v30, v31
	v_add_f32_e32 v27, v27, v30
	v_add_f32_e32 v30, v38, v27
	ds_swizzle_b32 v31, v30 offset:swizzle(SWAP,16)
	v_cvt_pk_bf16_f32 v27, v32, v33
	v_cvt_pk_bf16_f32 v28, v28, v29
	v_cvt_pk_bf16_f32 v29, v36, v37
	global_store_dwordx4 v[46:47], v[26:29], off offset:256 sc0 sc1
	s_waitcnt lgkmcnt(0)
	s_nop 0
	v_add_f32_e32 v26, v30, v31
	v_mov_b32_e32 v27, v26
	s_nop 1
	v_permlane32_swap_b32_e32 v26, v27
	s_and_saveexec_b64 s[12:13], vcc
	v_add_f32_e32 v26, v26, v27
	ds_write_b32 v122, v26 offset:640
	s_or_b64 exec, exec, s[12:13]
	s_waitcnt vmcnt(7)
	v_lshlrev_b32_e32 v26, 16, v78
	v_and_b32_e32 v27, 0xffff0000, v78
	v_lshlrev_b32_e32 v28, 16, v79
	v_and_b32_e32 v29, 0xffff0000, v79
	v_pk_add_f32 v[22:23], v[22:23], v[26:27]
	v_lshlrev_b32_e32 v26, 16, v80
	v_and_b32_e32 v27, 0xffff0000, v80
	v_lshl_add_u64 v[30:31], s[42:43], 0, v[102:103]
	v_pk_add_f32 v[24:25], v[24:25], v[28:29]
	v_lshlrev_b32_e32 v28, 16, v81
	v_and_b32_e32 v29, 0xffff0000, v81
	v_pk_add_f32 v[26:27], v[18:19], v[26:27]
	v_cvt_pk_bf16_f32 v18, v22, v23
	v_cvt_pk_bf16_f32 v19, v24, v25
	v_lshl_add_u64 v[30:31], v[166:167], 1, v[30:31]
	v_pk_add_f32 v[28:29], v[20:21], v[28:29]
	v_cvt_pk_bf16_f32 v20, v26, v27
	s_nop 0
	v_cvt_pk_bf16_f32 v21, v28, v29
	global_store_dwordx4 v[30:31], v[18:21], off sc0 sc1
	s_nop 1
	v_mul_f32_e32 v18, v23, v23
	v_mul_f32_e32 v19, v25, v25
	v_fmac_f32_e32 v18, v22, v22
	v_fmac_f32_e32 v19, v24, v24
	v_add_f32_e32 v18, v18, v19
	v_mul_f32_e32 v19, v27, v27
	v_mul_f32_e32 v20, v29, v29
	v_fmac_f32_e32 v19, v26, v26
	v_fmac_f32_e32 v20, v28, v28
	v_add_f32_e32 v19, v19, v20
	v_add_f32_e32 v22, v18, v19
	s_waitcnt vmcnt(7)
	v_lshlrev_b32_e32 v18, 16, v74
	v_and_b32_e32 v19, 0xffff0000, v74
	v_lshlrev_b32_e32 v20, 16, v75
	v_and_b32_e32 v21, 0xffff0000, v75
	v_pk_add_f32 v[16:17], v[16:17], v[20:21]
	v_pk_add_f32 v[14:15], v[14:15], v[18:19]
	v_lshlrev_b32_e32 v18, 16, v76
	v_and_b32_e32 v19, 0xffff0000, v76
	v_lshlrev_b32_e32 v20, 16, v77
	v_and_b32_e32 v21, 0xffff0000, v77
	v_pk_add_f32 v[20:21], v[12:13], v[20:21]
	v_pk_add_f32 v[12:13], v[10:11], v[18:19]
	v_mul_f32_e32 v11, v15, v15
	v_cvt_pk_bf16_f32 v10, v14, v15
	v_fmac_f32_e32 v11, v14, v14
	v_mul_f32_e32 v14, v17, v17
	v_fmac_f32_e32 v14, v16, v16
	v_add_f32_e32 v11, v11, v14
	v_mul_f32_e32 v14, v13, v13
	v_mul_f32_e32 v15, v21, v21
	v_fmac_f32_e32 v14, v12, v12
	v_fmac_f32_e32 v15, v20, v20
	v_add_f32_e32 v14, v14, v15
	v_add_f32_e32 v11, v11, v14
	v_add_f32_e32 v14, v22, v11
	ds_swizzle_b32 v15, v14 offset:swizzle(SWAP,16)
	v_cvt_pk_bf16_f32 v11, v16, v17
	v_cvt_pk_bf16_f32 v12, v12, v13
	v_cvt_pk_bf16_f32 v13, v20, v21
	global_store_dwordx4 v[30:31], v[10:13], off offset:256 sc0 sc1
	s_waitcnt lgkmcnt(0)
	s_nop 0
	v_add_f32_e32 v10, v14, v15
	v_mov_b32_e32 v11, v10
	s_nop 1
	v_permlane32_swap_b32_e32 v10, v11
	s_and_saveexec_b64 s[12:13], vcc
	v_add_f32_e32 v10, v10, v11
	ds_write_b32 v122, v10 offset:704
	s_or_b64 exec, exec, s[12:13]
	s_lshl_b32 s55, s84, 4
	s_addk_i32 s55, 0x2000
	v_or_b32_e32 v10, s55, v180
	v_readlane_b32 s12, v254, 60
	s_add_i32 s12, s12, s40
	v_ashrrev_i32_e32 v11, 31, v10
	v_or_b32_e32 v12, s12, v181
	v_lshlrev_b64 v[10:11], 12, v[10:11]
	v_lshl_add_u64 v[10:11], s[42:43], 0, v[10:11]
	v_ashrrev_i32_e32 v13, 31, v12
	v_lshl_add_u64 v[14:15], v[12:13], 1, v[10:11]
	global_load_dwordx4 v[10:13], v[14:15], off
	s_waitcnt vmcnt(0)
	v_lshlrev_b32_e32 v16, 16, v10
	v_and_b32_e32 v17, 0xffff0000, v10
	v_lshlrev_b32_e32 v10, 16, v11
	v_and_b32_e32 v11, 0xffff0000, v11
	v_pk_add_f32 v[8:9], v[8:9], v[10:11]
	v_lshlrev_b32_e32 v10, 16, v12
	v_and_b32_e32 v11, 0xffff0000, v12
	v_pk_add_f32 v[6:7], v[6:7], v[16:17]
	v_lshlrev_b32_e32 v12, 16, v13
	v_and_b32_e32 v13, 0xffff0000, v13
	v_pk_add_f32 v[10:11], v[2:3], v[10:11]
	v_cvt_pk_bf16_f32 v2, v6, v7
	v_cvt_pk_bf16_f32 v3, v8, v9
	v_pk_add_f32 v[12:13], v[4:5], v[12:13]
	v_cvt_pk_bf16_f32 v4, v10, v11
	s_nop 0
	v_cvt_pk_bf16_f32 v5, v12, v13
	global_store_dwordx4 v[14:15], v[2:5], off sc0 sc1
	s_nop 1
	v_mul_f32_e32 v2, v7, v7
	v_mul_f32_e32 v3, v9, v9
	v_fmac_f32_e32 v2, v6, v6
	v_fmac_f32_e32 v3, v8, v8
	v_add_f32_e32 v2, v2, v3
	v_mul_f32_e32 v3, v11, v11
	v_mul_f32_e32 v4, v13, v13
	v_fmac_f32_e32 v3, v10, v10
	v_fmac_f32_e32 v4, v12, v12
	v_add_f32_e32 v3, v3, v4
	v_add_f32_e32 v2, v2, v3
	ds_swizzle_b32 v3, v2 offset:swizzle(SWAP,16)
	s_waitcnt lgkmcnt(0)
	v_add_f32_e32 v2, v2, v3
	v_mov_b32_e32 v3, v2
	s_nop 1
	v_permlane32_swap_b32_e32 v2, v3
	s_and_saveexec_b64 s[12:13], vcc
	s_cbranch_execz .LBB0_626
	v_readlane_b32 s40, v252, 4
	v_add_f32_e32 v2, v2, v3
	s_nop 0
	v_lshl_add_u32 v4, v180, 2, s40
	ds_write_b32 v4, v2 offset:4096

; __device__ __forceinline__ u32x4 pack8(const f32x4& a, const f32x4& b) { u32x4 w; w.x = cvt_pk_bf16(a[0], a[1]); w.y = cvt_pk_bf16(a[2], a[3]); w.z = cvt_pk_bf16(b[0], b[1]); w.w = cvt_pk_bf16(b[2], b[3]); return w; }
;     __device__ __forceinline__ void operator()(const f32x4 (&acc)[2][2][4][2], const Unit& u, int wr, int wc, int fr, int fq) const {
;         const int rowt = u.pm * BM + wr * 64 + fr, col0 = u.pn * BM + wc * 32 + 8 * fq;
;         f32x4 gv[2][2];
; #pragma unroll
;         for (int bj = 0; bj < 2; ++bj)
; #pragma unroll
;             for (int n = 0; n < 2; ++n) gv[bj][n] = DST ? *(const f32x4*)(gain + col0 + bj * HALF + n * 4) : (f32x4){0.f, 0.f, 0.f, 0.f};
; #pragma unroll
;         for (int ai = 0; ai < 2; ++ai) {
;             u32x4 xv[4][2];
; #pragma unroll
;             for (int m = 0; m < 4; ++m)
; #pragma unroll
;                 for (int bj = 0; bj < 2; ++bj) xv[m][bj] = *(const u32x4*)(X + (size_t)(rowt + ai * HALF + m * 16) * 2048 + col0 + bj * HALF);
;             asm volatile("" ::: "memory");
; #pragma unroll
;             for (int m = 0; m < 4; ++m) { const int row = rowt + ai * HALF + m * 16; float q = 0.f;
; #pragma unroll
;                 for (int bj = 0; bj < 2; ++bj) { const int col = col0 + bj * HALF; const u32x4 xw = xv[m][bj];
;                     const f32x4 o0 = (f32x4){bflo(xw.x), bfhi(xw.x), bflo(xw.y), bfhi(xw.y)} + acc[ai][bj][m][0], o1 = (f32x4){bflo(xw.z), bfhi(xw.z), bflo(xw.w), bfhi(xw.w)} + acc[ai][bj][m][1];
;                     *(u32x4*)(X + (size_t)row * 2048 + col) = pack8(o0, o1);
;                     q += ((o0[0] * o0[0] + o0[1] * o0[1]) + (o0[2] * o0[2] + o0[3] * o0[3])) + ((o1[0] * o1[0] + o1[1] * o1[1]) + (o1[2] * o1[2] + o1[3] * o1[3]));
;                     if constexpr (DST) *(u32x4*)(dst + (size_t)row * ldd + dcol + col) = pack8(o0 * gv[bj][0], o1 * gv[bj][1]); }
;                 q = fq_sum(q); if (fq == 0) lq[wc * 256 + ai * HALF + wr * 64 + m * 16 + fr] = q; }
.LBB0_823:
	v_mov_b32_e32 v178, v0
	s_lshl_b32 s2, s17, 8
	v_readlane_b32 s3, v254, 45
	s_add_i32 s12, s2, s3
	v_bfe_u32 v148, v178, 4, 2
	s_lshl_b32 s3, s16, 8
	v_readlane_b32 s13, v254, 39
	v_lshlrev_b32_e32 v219, 3, v148
	s_or_b32 s13, s3, s13
	v_and_b32_e32 v218, 15, v178
	v_or_b32_e32 v146, s13, v219
	v_ashrrev_i32_e32 v147, 31, v146
	v_or_b32_e32 v186, s12, v218
	v_readlane_b32 s40, v254, 43
	v_lshlrev_b64 v[184:185], 1, v[146:147]
	v_ashrrev_i32_e32 v187, 31, v186
	v_readlane_b32 s41, v254, 44
	v_lshl_add_u64 v[188:189], s[42:43], 0, v[184:185]
	v_lshlrev_b64 v[208:209], 12, v[186:187]
	v_lshl_add_u64 v[70:71], v[146:147], 2, s[40:41]
	v_lshl_add_u64 v[146:147], v[188:189], 0, v[208:209]
	global_load_dwordx4 v[74:77], v[70:71], off offset:16
	global_load_dwordx4 v[78:81], v[70:71], off
	global_load_dwordx4 v[66:69], v[70:71], off offset:528
	s_nop 0
	global_load_dwordx4 v[70:73], v[70:71], off offset:512
	s_nop 0
	global_load_dwordx4 v[224:227], v[146:147], off
	global_load_dwordx4 v[180:183], v[146:147], off offset:256
	v_or_b32_e32 v214, 16, v186
	v_ashrrev_i32_e32 v215, 31, v214
	v_or_b32_e32 v194, 32, v186
	v_lshlrev_b64 v[216:217], 12, v[214:215]
	v_ashrrev_i32_e32 v195, 31, v194
	v_or_b32_e32 v190, 48, v186
	v_lshl_add_u64 v[146:147], v[188:189], 0, v[216:217]
	v_lshlrev_b64 v[212:213], 12, v[194:195]
	v_ashrrev_i32_e32 v191, 31, v190
	global_load_dwordx4 v[174:177], v[146:147], off
	global_load_dwordx4 v[162:165], v[146:147], off offset:256
	v_lshl_add_u64 v[146:147], v[188:189], 0, v[212:213]
	v_lshlrev_b64 v[192:193], 12, v[190:191]
	global_load_dwordx4 v[158:161], v[146:147], off
	global_load_dwordx4 v[154:157], v[146:147], off offset:256
	v_lshl_add_u64 v[146:147], v[188:189], 0, v[192:193]
	v_cmp_eq_u32_e32 vcc, 0, v148
	global_load_dwordx4 v[150:153], v[146:147], off
	s_nop 0
	global_load_dwordx4 v[146:149], v[146:147], off offset:256
	s_movk_i32 s62, 0x1200
	s_waitcnt vmcnt(0)
	v_lshlrev_b32_e32 v228, 16, v224
	v_and_b32_e32 v229, 0xffff0000, v224
	v_lshlrev_b32_e32 v224, 16, v225
	v_and_b32_e32 v225, 0xffff0000, v225
	v_pk_add_f32 v[172:173], v[172:173], v[224:225]
	v_pk_add_f32 v[224:225], v[170:171], v[228:229]
	v_lshlrev_b32_e32 v170, 16, v226
	v_and_b32_e32 v171, 0xffff0000, v226
	v_pk_add_f32 v[228:229], v[166:167], v[170:171]
	v_lshl_add_u64 v[170:171], s[42:43], 0, v[208:209]
	v_lshlrev_b32_e32 v226, 16, v227
	v_and_b32_e32 v227, 0xffff0000, v227
	v_cvt_pk_bf16_f32 v166, v224, v225
	v_cvt_pk_bf16_f32 v167, v172, v173
	v_lshl_add_u64 v[170:171], v[170:171], 0, v[184:185]
	v_pk_add_f32 v[226:227], v[168:169], v[226:227]
	v_cvt_pk_bf16_f32 v168, v228, v229
	v_pk_mul_f32 v[208:209], v[74:75], v[228:229]
	v_cvt_pk_bf16_f32 v169, v226, v227
	global_store_dwordx4 v[170:171], v[166:169], off sc0 sc1
	s_nop 1
	v_mul_f32_e32 v166, v225, v225
	v_mul_f32_e32 v167, v173, v173
	v_fmac_f32_e32 v166, v224, v224
	v_fmac_f32_e32 v167, v172, v172
	v_add_f32_e32 v166, v166, v167
	v_mul_f32_e32 v167, v229, v229
	v_mul_f32_e32 v168, v227, v227
	v_fmac_f32_e32 v167, v228, v228
	v_fmac_f32_e32 v168, v226, v226
	v_add_f32_e32 v167, v167, v168
	v_add_f32_e32 v187, v166, v167
	v_pk_mul_f32 v[168:169], v[80:81], v[172:173]
	v_pk_mul_f32 v[166:167], v[78:79], v[224:225]
	v_pk_mul_f32 v[172:173], v[76:77], v[226:227]
	v_cvt_pk_bf16_f32 v166, v166, v167
	v_cvt_pk_bf16_f32 v167, v168, v169
	v_cvt_pk_bf16_f32 v168, v208, v209
	s_nop 0
	v_cvt_pk_bf16_f32 v169, v172, v173
	v_mov_b64_e32 v[172:173], s[50:51]
	v_mad_i64_i32 v[172:173], s[12:13], v186, s62, v[172:173]
	v_lshl_add_u64 v[172:173], v[172:173], 0, v[184:185]
	global_store_dwordx4 v[172:173], v[166:169], off offset:512 sc0 sc1
	v_readlane_b32 s12, v254, 52
	s_nop 0
	v_lshlrev_b32_e32 v166, 16, v180
	v_and_b32_e32 v167, 0xffff0000, v180
	v_lshlrev_b32_e32 v168, 16, v181
	v_and_b32_e32 v169, 0xffff0000, v181
	v_pk_add_f32 v[142:143], v[142:143], v[166:167]
	v_lshlrev_b32_e32 v166, 16, v182
	v_and_b32_e32 v167, 0xffff0000, v182
	v_pk_add_f32 v[144:145], v[144:145], v[168:169]
	v_lshlrev_b32_e32 v168, 16, v183
	v_and_b32_e32 v169, 0xffff0000, v183
	v_pk_add_f32 v[166:167], v[138:139], v[166:167]
	v_cvt_pk_bf16_f32 v138, v142, v143
	v_cvt_pk_bf16_f32 v139, v144, v145
	v_pk_add_f32 v[168:169], v[140:141], v[168:169]
	v_cvt_pk_bf16_f32 v140, v166, v167
	s_nop 0
	v_cvt_pk_bf16_f32 v141, v168, v169
	global_store_dwordx4 v[170:171], v[138:141], off offset:256 sc0 sc1
	s_nop 1
	v_mul_f32_e32 v138, v143, v143
	v_mul_f32_e32 v139, v145, v145
	v_fmac_f32_e32 v138, v142, v142
	v_fmac_f32_e32 v139, v144, v144
	v_add_f32_e32 v138, v138, v139
	v_mul_f32_e32 v139, v167, v167
	v_mul_f32_e32 v140, v169, v169
	v_fmac_f32_e32 v139, v166, v166
	v_fmac_f32_e32 v140, v168, v168
	v_add_f32_e32 v139, v139, v140
	v_add_f32_e32 v138, v138, v139
	v_add_f32_e32 v170, v187, v138
	v_pk_mul_f32 v[138:139], v[70:71], v[142:143]
	v_pk_mul_f32 v[140:141], v[72:73], v[144:145]
	v_cvt_pk_bf16_f32 v138, v138, v139
	v_pk_mul_f32 v[142:143], v[68:69], v[168:169]
	v_pk_mul_f32 v[144:145], v[66:67], v[166:167]
	v_cvt_pk_bf16_f32 v139, v140, v141
	s_nop 0
	v_cvt_pk_bf16_f32 v140, v144, v145
	v_cvt_pk_bf16_f32 v141, v142, v143
	global_store_dwordx4 v[172:173], v[138:141], off offset:768 sc0 sc1
	ds_swizzle_b32 v138, v170 offset:swizzle(SWAP,16)
	s_waitcnt lgkmcnt(0)
; __device__ __forceinline__ u32x4 pack8(const f32x4& a, const f32x4& b) { u32x4 w; w.x = cvt_pk_bf16(a[0], a[1]); w.y = cvt_pk_bf16(a[2], a[3]); w.z = cvt_pk_bf16(b[0], b[1]); w.w = cvt_pk_bf16(b[2], b[3]); return w; }
;     __device__ __forceinline__ void operator()(const f32x4 (&acc)[2][2][4][2], const Unit& u, int wr, int wc, int fr, int fq) const {
;     ...
;         for (int ai = 0; ai < 2; ++ai) {
;             u32x4 xv[4][2];
; #pragma unroll
;             for (int m = 0; m < 4; ++m)
; #pragma unroll
;                 for (int bj = 0; bj < 2; ++bj) xv[m][bj] = *(const u32x4*)(X + (size_t)(rowt + ai * HALF + m * 16) * 2048 + col0 + bj * HALF);
;             asm volatile("" ::: "memory");
; #pragma unroll
;             for (int m = 0; m < 4; ++m) { const int row = rowt + ai * HALF + m * 16; float q = 0.f;
; #pragma unroll
;                 for (int bj = 0; bj < 2; ++bj) { const int col = col0 + bj * HALF; const u32x4 xw = xv[m][bj];
;                     const f32x4 o0 = (f32x4){bflo(xw.x), bfhi(xw.x), bflo(xw.y), bfhi(xw.y)} + acc[ai][bj][m][0], o1 = (f32x4){bflo(xw.z), bfhi(xw.z), bflo(xw.w), bfhi(xw.w)} + acc[ai][bj][m][1];
;                     *(u32x4*)(X + (size_t)row * 2048 + col) = pack8(o0, o1);
;                     q += ((o0[0] * o0[0] + o0[1] * o0[1]) + (o0[2] * o0[2] + o0[3] * o0[3])) + ((o1[0] * o1[0] + o1[1] * o1[1]) + (o1[2] * o1[2] + o1[3] * o1[3]));
;                     if constexpr (DST) *(u32x4*)(dst + (size_t)row * ldd + dcol + col) = pack8(o0 * gv[bj][0], o1 * gv[bj][1]); }
;                 q = fq_sum(q); if (fq == 0) lq[wc * 256 + ai * HALF + wr * 64 + m * 16 + fr] = q; }
;             asm volatile("" ::: "memory");
	v_add_f32_e32 v139, v170, v138
	v_mov_b32_e32 v140, v139
	v_lshl_add_u32 v138, v218, 2, s12
	s_nop 0
	v_permlane32_swap_b32_e32 v139, v140
	s_and_saveexec_b64 s[12:13], vcc
	s_mov_b64 s[94:95], 0x3000
	s_mov_b64 s[68:69], 0x4000c00
	v_add_f32_e32 v139, v139, v140
	ds_write_b32 v138, v139
	s_or_b64 exec, exec, s[12:13]
	v_lshlrev_b32_e32 v140, 16, v174
	v_and_b32_e32 v141, 0xffff0000, v174
	v_lshlrev_b32_e32 v142, 16, v175
	v_and_b32_e32 v143, 0xffff0000, v175
	v_pk_add_f32 v[134:135], v[134:135], v[140:141]
	v_lshlrev_b32_e32 v140, 16, v176
	v_and_b32_e32 v141, 0xffff0000, v176
	v_lshl_add_u64 v[144:145], s[42:43], 0, v[216:217]
	v_pk_add_f32 v[136:137], v[136:137], v[142:143]
	v_lshlrev_b32_e32 v142, 16, v177
	v_and_b32_e32 v143, 0xffff0000, v177
	v_pk_add_f32 v[140:141], v[130:131], v[140:141]
	v_cvt_pk_bf16_f32 v130, v134, v135
	v_cvt_pk_bf16_f32 v131, v136, v137
	v_lshl_add_u64 v[144:145], v[144:145], 0, v[184:185]
	v_pk_add_f32 v[142:143], v[132:133], v[142:143]
	v_cvt_pk_bf16_f32 v132, v140, v141
	s_nop 0
	v_cvt_pk_bf16_f32 v133, v142, v143
	global_store_dwordx4 v[144:145], v[130:133], off sc0 sc1
	s_nop 1
	v_mul_f32_e32 v130, v135, v135
	v_mul_f32_e32 v131, v137, v137
	v_fmac_f32_e32 v130, v134, v134
	v_fmac_f32_e32 v131, v136, v136
	v_add_f32_e32 v130, v130, v131
	v_mul_f32_e32 v131, v141, v141
	v_mul_f32_e32 v132, v143, v143
	v_fmac_f32_e32 v131, v140, v140
	v_fmac_f32_e32 v132, v142, v142
	v_add_f32_e32 v131, v131, v132
	v_add_f32_e32 v139, v130, v131
	v_pk_mul_f32 v[132:133], v[80:81], v[136:137]
	v_pk_mul_f32 v[130:131], v[78:79], v[134:135]
	v_pk_mul_f32 v[134:135], v[76:77], v[142:143]
	v_pk_mul_f32 v[136:137], v[74:75], v[140:141]
	v_cvt_pk_bf16_f32 v130, v130, v131
	v_cvt_pk_bf16_f32 v131, v132, v133
	s_nop 0
	v_cvt_pk_bf16_f32 v132, v136, v137
	v_cvt_pk_bf16_f32 v133, v134, v135
	v_mov_b64_e32 v[134:135], s[50:51]
	v_mad_i64_i32 v[134:135], s[12:13], v214, s62, v[134:135]
	v_lshl_add_u64 v[134:135], v[134:135], 0, v[184:185]
	global_store_dwordx4 v[134:135], v[130:133], off offset:512 sc0 sc1
	s_nop 1
	v_lshlrev_b32_e32 v130, 16, v162
	v_and_b32_e32 v131, 0xffff0000, v162
	v_lshlrev_b32_e32 v132, 16, v163
	v_and_b32_e32 v133, 0xffff0000, v163
	v_pk_add_f32 v[126:127], v[126:127], v[130:131]
	v_lshlrev_b32_e32 v130, 16, v164
	v_and_b32_e32 v131, 0xffff0000, v164
	v_pk_add_f32 v[128:129], v[128:129], v[132:133]
	v_lshlrev_b32_e32 v132, 16, v165
	v_and_b32_e32 v133, 0xffff0000, v165
	v_pk_add_f32 v[130:131], v[122:123], v[130:131]
	v_cvt_pk_bf16_f32 v122, v126, v127
	v_cvt_pk_bf16_f32 v123, v128, v129
	v_pk_add_f32 v[132:133], v[124:125], v[132:133]
	v_cvt_pk_bf16_f32 v124, v130, v131
	s_nop 0
	v_cvt_pk_bf16_f32 v125, v132, v133
	global_store_dwordx4 v[144:145], v[122:125], off offset:256 sc0 sc1
	s_nop 1
	v_mul_f32_e32 v122, v127, v127
	v_mul_f32_e32 v123, v129, v129
	v_fmac_f32_e32 v122, v126, v126
	v_fmac_f32_e32 v123, v128, v128
	v_add_f32_e32 v122, v122, v123
	v_mul_f32_e32 v123, v131, v131
	v_mul_f32_e32 v124, v133, v133
	v_fmac_f32_e32 v123, v130, v130
	v_fmac_f32_e32 v124, v132, v132
	v_add_f32_e32 v123, v123, v124
	v_add_f32_e32 v122, v122, v123
	v_add_f32_e32 v136, v139, v122
	v_pk_mul_f32 v[124:125], v[72:73], v[128:129]
	v_pk_mul_f32 v[128:129], v[66:67], v[130:131]
	ds_swizzle_b32 v130, v136 offset:swizzle(SWAP,16)
	v_pk_mul_f32 v[122:123], v[70:71], v[126:127]
	v_pk_mul_f32 v[126:127], v[68:69], v[132:133]
	v_cvt_pk_bf16_f32 v122, v122, v123
	v_cvt_pk_bf16_f32 v123, v124, v125
	v_cvt_pk_bf16_f32 v124, v128, v129
	s_nop 0
	v_cvt_pk_bf16_f32 v125, v126, v127
	global_store_dwordx4 v[134:135], v[122:125], off offset:768 sc0 sc1
	s_waitcnt lgkmcnt(0)
	s_nop 0
	v_add_f32_e32 v122, v136, v130
	v_mov_b32_e32 v123, v122
	s_nop 1
	v_permlane32_swap_b32_e32 v122, v123
	s_and_saveexec_b64 s[12:13], vcc
	v_add_f32_e32 v122, v122, v123
	ds_write_b32 v138, v122 offset:64
	s_or_b64 exec, exec, s[12:13]
	v_lshlrev_b32_e32 v122, 16, v158
	v_and_b32_e32 v123, 0xffff0000, v158
	v_lshlrev_b32_e32 v124, 16, v159
	v_and_b32_e32 v125, 0xffff0000, v159
	v_pk_add_f32 v[118:119], v[118:119], v[122:123]
	v_lshlrev_b32_e32 v122, 16, v160
	v_and_b32_e32 v123, 0xffff0000, v160
	v_lshl_add_u64 v[126:127], s[42:43], 0, v[212:213]
	v_pk_add_f32 v[120:121], v[120:121], v[124:125]
	v_lshlrev_b32_e32 v124, 16, v161
	v_and_b32_e32 v125, 0xffff0000, v161
	v_pk_add_f32 v[122:123], v[114:115], v[122:123]
	v_cvt_pk_bf16_f32 v114, v118, v119
	v_cvt_pk_bf16_f32 v115, v120, v121
	v_lshl_add_u64 v[126:127], v[126:127], 0, v[184:185]
	v_pk_add_f32 v[124:125], v[116:117], v[124:125]
	v_cvt_pk_bf16_f32 v116, v122, v123
	s_nop 0
	v_cvt_pk_bf16_f32 v117, v124, v125
	global_store_dwordx4 v[126:127], v[114:117], off sc0 sc1
	s_nop 1
	v_mul_f32_e32 v114, v119, v119
	v_mul_f32_e32 v115, v121, v121
	v_fmac_f32_e32 v114, v118, v118
	v_fmac_f32_e32 v115, v120, v120
	v_add_f32_e32 v114, v114, v115
	v_mul_f32_e32 v115, v123, v123
	v_mul_f32_e32 v116, v125, v125
	v_fmac_f32_e32 v115, v122, v122
	v_fmac_f32_e32 v116, v124, v124
	v_add_f32_e32 v115, v115, v116
	v_add_f32_e32 v128, v114, v115
	v_pk_mul_f32 v[116:117], v[80:81], v[120:121]
	v_pk_mul_f32 v[114:115], v[78:79], v[118:119]
	v_pk_mul_f32 v[118:119], v[76:77], v[124:125]
	v_pk_mul_f32 v[120:121], v[74:75], v[122:123]
	v_cvt_pk_bf16_f32 v114, v114, v115
	v_cvt_pk_bf16_f32 v115, v116, v117
	s_nop 0
	v_cvt_pk_bf16_f32 v116, v120, v121
	v_cvt_pk_bf16_f32 v117, v118, v119
	v_mov_b64_e32 v[118:119], s[50:51]
	v_mad_i64_i32 v[118:119], s[12:13], v194, s62, v[118:119]
	v_lshl_add_u64 v[118:119], v[118:119], 0, v[184:185]
	global_store_dwordx4 v[118:119], v[114:117], off offset:512 sc0 sc1
	s_nop 1
	v_lshlrev_b32_e32 v114, 16, v154
; __device__ __forceinline__ u32x4 pack8(const f32x4& a, const f32x4& b) { u32x4 w; w.x = cvt_pk_bf16(a[0], a[1]); w.y = cvt_pk_bf16(a[2], a[3]); w.z = cvt_pk_bf16(b[0], b[1]); w.w = cvt_pk_bf16(b[2], b[3]); return w; }
;     __device__ __forceinline__ void operator()(const f32x4 (&acc)[2][2][4][2], const Unit& u, int wr, int wc, int fr, int fq) const {
;     ...
;         for (int ai = 0; ai < 2; ++ai) {
;             u32x4 xv[4][2];
; #pragma unroll
;             for (int m = 0; m < 4; ++m)
; #pragma unroll
;                 for (int bj = 0; bj < 2; ++bj) xv[m][bj] = *(const u32x4*)(X + (size_t)(rowt + ai * HALF + m * 16) * 2048 + col0 + bj * HALF);
;             asm volatile("" ::: "memory");
; #pragma unroll
;             for (int m = 0; m < 4; ++m) { const int row = rowt + ai * HALF + m * 16; float q = 0.f;
; #pragma unroll
;                 for (int bj = 0; bj < 2; ++bj) { const int col = col0 + bj * HALF; const u32x4 xw = xv[m][bj];
;                     const f32x4 o0 = (f32x4){bflo(xw.x), bfhi(xw.x), bflo(xw.y), bfhi(xw.y)} + acc[ai][bj][m][0], o1 = (f32x4){bflo(xw.z), bfhi(xw.z), bflo(xw.w), bfhi(xw.w)} + acc[ai][bj][m][1];
;                     *(u32x4*)(X + (size_t)row * 2048 + col) = pack8(o0, o1);
;                     q += ((o0[0] * o0[0] + o0[1] * o0[1]) + (o0[2] * o0[2] + o0[3] * o0[3])) + ((o1[0] * o1[0] + o1[1] * o1[1]) + (o1[2] * o1[2] + o1[3] * o1[3]));
;                     if constexpr (DST) *(u32x4*)(dst + (size_t)row * ldd + dcol + col) = pack8(o0 * gv[bj][0], o1 * gv[bj][1]); }
;                 q = fq_sum(q); if (fq == 0) lq[wc * 256 + ai * HALF + wr * 64 + m * 16 + fr] = q; }
;             asm volatile("" ::: "memory");
	v_and_b32_e32 v115, 0xffff0000, v154
	v_lshlrev_b32_e32 v116, 16, v155
	v_and_b32_e32 v117, 0xffff0000, v155
	v_pk_add_f32 v[110:111], v[110:111], v[114:115]
	v_lshlrev_b32_e32 v114, 16, v156
	v_and_b32_e32 v115, 0xffff0000, v156
	v_pk_add_f32 v[112:113], v[112:113], v[116:117]
	v_lshlrev_b32_e32 v116, 16, v157
	v_and_b32_e32 v117, 0xffff0000, v157
	v_pk_add_f32 v[114:115], v[106:107], v[114:115]
	v_cvt_pk_bf16_f32 v106, v110, v111
	v_cvt_pk_bf16_f32 v107, v112, v113
	v_pk_add_f32 v[116:117], v[108:109], v[116:117]
	v_cvt_pk_bf16_f32 v108, v114, v115
	s_nop 0
	v_cvt_pk_bf16_f32 v109, v116, v117
	global_store_dwordx4 v[126:127], v[106:109], off offset:256 sc0 sc1
	s_nop 1
	v_mul_f32_e32 v106, v111, v111
	v_mul_f32_e32 v107, v113, v113
	v_fmac_f32_e32 v106, v110, v110
	v_fmac_f32_e32 v107, v112, v112
	v_add_f32_e32 v106, v106, v107
	v_mul_f32_e32 v107, v115, v115
	v_mul_f32_e32 v108, v117, v117
	v_fmac_f32_e32 v107, v114, v114
	v_fmac_f32_e32 v108, v116, v116
	v_add_f32_e32 v107, v107, v108
	v_add_f32_e32 v106, v106, v107
	v_add_f32_e32 v120, v128, v106
	v_pk_mul_f32 v[108:109], v[72:73], v[112:113]
	v_pk_mul_f32 v[112:113], v[66:67], v[114:115]
	ds_swizzle_b32 v114, v120 offset:swizzle(SWAP,16)
	v_pk_mul_f32 v[106:107], v[70:71], v[110:111]
	v_pk_mul_f32 v[110:111], v[68:69], v[116:117]
	v_cvt_pk_bf16_f32 v106, v106, v107
	v_cvt_pk_bf16_f32 v107, v108, v109
	v_cvt_pk_bf16_f32 v108, v112, v113
	s_nop 0
	v_cvt_pk_bf16_f32 v109, v110, v111
	global_store_dwordx4 v[118:119], v[106:109], off offset:768 sc0 sc1
	s_waitcnt lgkmcnt(0)
	s_nop 0
	v_add_f32_e32 v106, v120, v114
	v_mov_b32_e32 v107, v106
	s_nop 1
	v_permlane32_swap_b32_e32 v106, v107
	s_and_saveexec_b64 s[12:13], vcc
	v_add_f32_e32 v106, v106, v107
	ds_write_b32 v138, v106 offset:128
	s_or_b64 exec, exec, s[12:13]
	v_lshlrev_b32_e32 v106, 16, v150
	v_and_b32_e32 v107, 0xffff0000, v150
	v_lshlrev_b32_e32 v108, 16, v151
	v_and_b32_e32 v109, 0xffff0000, v151
	v_pk_add_f32 v[102:103], v[102:103], v[106:107]
	v_lshlrev_b32_e32 v106, 16, v152
	v_and_b32_e32 v107, 0xffff0000, v152
	v_lshl_add_u64 v[110:111], s[42:43], 0, v[192:193]
	v_pk_add_f32 v[104:105], v[104:105], v[108:109]
	v_lshlrev_b32_e32 v108, 16, v153
	v_and_b32_e32 v109, 0xffff0000, v153
	v_pk_add_f32 v[106:107], v[98:99], v[106:107]
	v_cvt_pk_bf16_f32 v98, v102, v103
	v_cvt_pk_bf16_f32 v99, v104, v105
	v_lshl_add_u64 v[110:111], v[110:111], 0, v[184:185]
	v_pk_add_f32 v[108:109], v[100:101], v[108:109]
	v_cvt_pk_bf16_f32 v100, v106, v107
	s_nop 0
	v_cvt_pk_bf16_f32 v101, v108, v109
	global_store_dwordx4 v[110:111], v[98:101], off sc0 sc1
	s_nop 1
	v_mul_f32_e32 v98, v103, v103
	v_mul_f32_e32 v99, v105, v105
	v_fmac_f32_e32 v98, v102, v102
	v_fmac_f32_e32 v99, v104, v104
	v_add_f32_e32 v98, v98, v99
	v_mul_f32_e32 v99, v107, v107
	v_mul_f32_e32 v100, v109, v109
	v_fmac_f32_e32 v99, v106, v106
	v_fmac_f32_e32 v100, v108, v108
	v_add_f32_e32 v99, v99, v100
	v_add_f32_e32 v112, v98, v99
	v_pk_mul_f32 v[100:101], v[80:81], v[104:105]
	v_pk_mul_f32 v[98:99], v[78:79], v[102:103]
	v_pk_mul_f32 v[102:103], v[76:77], v[108:109]
	v_pk_mul_f32 v[104:105], v[74:75], v[106:107]
	v_cvt_pk_bf16_f32 v98, v98, v99
	v_cvt_pk_bf16_f32 v99, v100, v101
	s_nop 0
	v_cvt_pk_bf16_f32 v100, v104, v105
	v_cvt_pk_bf16_f32 v101, v102, v103
	v_mov_b64_e32 v[102:103], s[50:51]
	v_mad_i64_i32 v[102:103], s[12:13], v190, s62, v[102:103]
	v_lshl_add_u64 v[102:103], v[102:103], 0, v[184:185]
	global_store_dwordx4 v[102:103], v[98:101], off offset:512 sc0 sc1
	s_nop 1
	v_lshlrev_b32_e32 v98, 16, v146
	v_and_b32_e32 v99, 0xffff0000, v146
	v_lshlrev_b32_e32 v100, 16, v147
	v_and_b32_e32 v101, 0xffff0000, v147
	v_pk_add_f32 v[94:95], v[94:95], v[98:99]
	v_lshlrev_b32_e32 v98, 16, v148
	v_and_b32_e32 v99, 0xffff0000, v148
	v_pk_add_f32 v[96:97], v[96:97], v[100:101]
	v_lshlrev_b32_e32 v100, 16, v149
	v_and_b32_e32 v101, 0xffff0000, v149
	v_pk_add_f32 v[98:99], v[90:91], v[98:99]
	v_cvt_pk_bf16_f32 v90, v94, v95
	v_cvt_pk_bf16_f32 v91, v96, v97
	v_pk_add_f32 v[100:101], v[92:93], v[100:101]
	v_cvt_pk_bf16_f32 v92, v98, v99
	s_nop 0
	v_cvt_pk_bf16_f32 v93, v100, v101
	global_store_dwordx4 v[110:111], v[90:93], off offset:256 sc0 sc1
	s_nop 1
	v_mul_f32_e32 v90, v95, v95
	v_mul_f32_e32 v91, v97, v97
	v_fmac_f32_e32 v90, v94, v94
	v_fmac_f32_e32 v91, v96, v96
	v_add_f32_e32 v90, v90, v91
	v_mul_f32_e32 v91, v99, v99
	v_mul_f32_e32 v92, v101, v101
	v_fmac_f32_e32 v91, v98, v98
	v_fmac_f32_e32 v92, v100, v100
	v_add_f32_e32 v91, v91, v92
	v_add_f32_e32 v90, v90, v91
	v_add_f32_e32 v104, v112, v90
	v_pk_mul_f32 v[92:93], v[72:73], v[96:97]
	v_pk_mul_f32 v[96:97], v[66:67], v[98:99]
	ds_swizzle_b32 v98, v104 offset:swizzle(SWAP,16)
	v_pk_mul_f32 v[90:91], v[70:71], v[94:95]
	v_pk_mul_f32 v[94:95], v[68:69], v[100:101]
	v_cvt_pk_bf16_f32 v90, v90, v91
	v_cvt_pk_bf16_f32 v91, v92, v93
	v_cvt_pk_bf16_f32 v92, v96, v97
	s_nop 0
	v_cvt_pk_bf16_f32 v93, v94, v95
	global_store_dwordx4 v[102:103], v[90:93], off offset:768 sc0 sc1
	s_waitcnt lgkmcnt(0)
; __device__ __forceinline__ u32x4 pack8(const f32x4& a, const f32x4& b) { u32x4 w; w.x = cvt_pk_bf16(a[0], a[1]); w.y = cvt_pk_bf16(a[2], a[3]); w.z = cvt_pk_bf16(b[0], b[1]); w.w = cvt_pk_bf16(b[2], b[3]); return w; }
;     __device__ __forceinline__ void operator()(const f32x4 (&acc)[2][2][4][2], const Unit& u, int wr, int wc, int fr, int fq) const {
;     ...
;         for (int ai = 0; ai < 2; ++ai) {
;             u32x4 xv[4][2];
; #pragma unroll
;             for (int m = 0; m < 4; ++m)
; #pragma unroll
;                 for (int bj = 0; bj < 2; ++bj) xv[m][bj] = *(const u32x4*)(X + (size_t)(rowt + ai * HALF + m * 16) * 2048 + col0 + bj * HALF);
;             asm volatile("" ::: "memory");
; #pragma unroll
;             for (int m = 0; m < 4; ++m) { const int row = rowt + ai * HALF + m * 16; float q = 0.f;
; #pragma unroll
;                 for (int bj = 0; bj < 2; ++bj) { const int col = col0 + bj * HALF; const u32x4 xw = xv[m][bj];
;                     const f32x4 o0 = (f32x4){bflo(xw.x), bfhi(xw.x), bflo(xw.y), bfhi(xw.y)} + acc[ai][bj][m][0], o1 = (f32x4){bflo(xw.z), bfhi(xw.z), bflo(xw.w), bfhi(xw.w)} + acc[ai][bj][m][1];
;                     *(u32x4*)(X + (size_t)row * 2048 + col) = pack8(o0, o1);
;                     q += ((o0[0] * o0[0] + o0[1] * o0[1]) + (o0[2] * o0[2] + o0[3] * o0[3])) + ((o1[0] * o1[0] + o1[1] * o1[1]) + (o1[2] * o1[2] + o1[3] * o1[3]));
;                     if constexpr (DST) *(u32x4*)(dst + (size_t)row * ldd + dcol + col) = pack8(o0 * gv[bj][0], o1 * gv[bj][1]); }
;                 q = fq_sum(q); if (fq == 0) lq[wc * 256 + ai * HALF + wr * 64 + m * 16 + fr] = q; }
;             asm volatile("" ::: "memory");
	s_nop 0
	v_add_f32_e32 v90, v104, v98
	v_mov_b32_e32 v91, v90
	s_nop 1
	v_permlane32_swap_b32_e32 v90, v91
	s_and_saveexec_b64 s[12:13], vcc
	v_add_f32_e32 v90, v90, v91
	ds_write_b32 v138, v90 offset:192
	s_or_b64 exec, exec, s[12:13]
	v_add_u32_e32 v130, 0x80, v186
	v_ashrrev_i32_e32 v131, 31, v130
	v_lshlrev_b64 v[136:137], 12, v[130:131]
	v_lshl_add_u64 v[90:91], v[188:189], 0, v[136:137]
	global_load_dwordx4 v[132:135], v[90:91], off
	global_load_dwordx4 v[114:117], v[90:91], off offset:256
	v_add_u32_e32 v126, 0x90, v186
	v_ashrrev_i32_e32 v127, 31, v126
	v_add_u32_e32 v122, 0xa0, v186
	v_lshlrev_b64 v[128:129], 12, v[126:127]
	v_ashrrev_i32_e32 v123, 31, v122
	v_add_u32_e32 v118, 0xb0, v186
	v_lshl_add_u64 v[90:91], v[188:189], 0, v[128:129]
	v_lshlrev_b64 v[124:125], 12, v[122:123]
	v_ashrrev_i32_e32 v119, 31, v118
	global_load_dwordx4 v[110:113], v[90:91], off
	global_load_dwordx4 v[106:109], v[90:91], off offset:256
	v_lshl_add_u64 v[90:91], v[188:189], 0, v[124:125]
	v_lshlrev_b64 v[120:121], 12, v[118:119]
	global_load_dwordx4 v[102:105], v[90:91], off
	global_load_dwordx4 v[98:101], v[90:91], off offset:256
	v_lshl_add_u64 v[90:91], v[188:189], 0, v[120:121]
	global_load_dwordx4 v[94:97], v[90:91], off
	s_nop 0
	global_load_dwordx4 v[90:93], v[90:91], off offset:256
	s_waitcnt vmcnt(7)
	v_lshlrev_b32_e32 v140, 16, v132
	v_and_b32_e32 v141, 0xffff0000, v132
	v_lshlrev_b32_e32 v132, 16, v133
	v_and_b32_e32 v133, 0xffff0000, v133
	v_pk_add_f32 v[88:89], v[88:89], v[132:133]
	v_pk_add_f32 v[132:133], v[86:87], v[140:141]
	v_lshlrev_b32_e32 v86, 16, v134
	v_and_b32_e32 v87, 0xffff0000, v134
	v_pk_add_f32 v[140:141], v[82:83], v[86:87]
	v_lshl_add_u64 v[86:87], s[42:43], 0, v[136:137]
	v_lshlrev_b32_e32 v134, 16, v135
	v_and_b32_e32 v135, 0xffff0000, v135
	v_cvt_pk_bf16_f32 v82, v132, v133
	v_cvt_pk_bf16_f32 v83, v88, v89
	v_lshl_add_u64 v[86:87], v[86:87], 0, v[184:185]
	v_pk_add_f32 v[134:135], v[84:85], v[134:135]
	v_cvt_pk_bf16_f32 v84, v140, v141
	s_nop 0
	v_cvt_pk_bf16_f32 v85, v134, v135
	global_store_dwordx4 v[86:87], v[82:85], off sc0 sc1
	s_nop 1
	v_mul_f32_e32 v82, v133, v133
	v_mul_f32_e32 v83, v89, v89
	v_fmac_f32_e32 v82, v132, v132
	v_fmac_f32_e32 v83, v88, v88
	v_add_f32_e32 v82, v82, v83
	v_mul_f32_e32 v83, v141, v141
	v_mul_f32_e32 v84, v135, v135
	v_fmac_f32_e32 v83, v140, v140
	v_fmac_f32_e32 v84, v134, v134
	v_add_f32_e32 v83, v83, v84
	v_add_f32_e32 v119, v82, v83
	v_pk_mul_f32 v[84:85], v[80:81], v[88:89]
	v_pk_mul_f32 v[82:83], v[78:79], v[132:133]
	v_pk_mul_f32 v[88:89], v[76:77], v[134:135]
	v_pk_mul_f32 v[132:133], v[74:75], v[140:141]
	v_cvt_pk_bf16_f32 v82, v82, v83
	v_cvt_pk_bf16_f32 v83, v84, v85
	s_nop 0
	v_cvt_pk_bf16_f32 v84, v132, v133
	v_cvt_pk_bf16_f32 v85, v88, v89
	v_mov_b64_e32 v[88:89], s[50:51]
	v_mad_i64_i32 v[88:89], s[12:13], v130, s62, v[88:89]
	v_lshl_add_u64 v[88:89], v[88:89], 0, v[184:185]
	global_store_dwordx4 v[88:89], v[82:85], off offset:512 sc0 sc1
	s_waitcnt vmcnt(8)
	s_nop 0
	v_lshlrev_b32_e32 v82, 16, v114
	v_and_b32_e32 v83, 0xffff0000, v114
	v_lshlrev_b32_e32 v84, 16, v115
	v_and_b32_e32 v85, 0xffff0000, v115
	v_pk_add_f32 v[62:63], v[62:63], v[82:83]
	v_lshlrev_b32_e32 v82, 16, v116
	v_and_b32_e32 v83, 0xffff0000, v116
	v_pk_add_f32 v[64:65], v[64:65], v[84:85]
	v_lshlrev_b32_e32 v84, 16, v117
	v_and_b32_e32 v85, 0xffff0000, v117
	v_pk_add_f32 v[82:83], v[58:59], v[82:83]
	v_cvt_pk_bf16_f32 v58, v62, v63
	v_cvt_pk_bf16_f32 v59, v64, v65
	v_pk_add_f32 v[84:85], v[60:61], v[84:85]
	v_cvt_pk_bf16_f32 v60, v82, v83
	s_nop 0
	v_cvt_pk_bf16_f32 v61, v84, v85
	global_store_dwordx4 v[86:87], v[58:61], off offset:256 sc0 sc1
	s_nop 1
	v_mul_f32_e32 v58, v63, v63
	v_mul_f32_e32 v59, v65, v65
	v_fmac_f32_e32 v58, v62, v62
	v_fmac_f32_e32 v59, v64, v64
	v_add_f32_e32 v58, v58, v59
	v_mul_f32_e32 v59, v83, v83
	v_mul_f32_e32 v60, v85, v85
	v_fmac_f32_e32 v59, v82, v82
	v_fmac_f32_e32 v60, v84, v84
	v_add_f32_e32 v59, v59, v60
	v_add_f32_e32 v58, v58, v59
	v_add_f32_e32 v86, v119, v58
	v_pk_mul_f32 v[58:59], v[70:71], v[62:63]
	v_pk_mul_f32 v[60:61], v[72:73], v[64:65]
	v_cvt_pk_bf16_f32 v58, v58, v59
	v_pk_mul_f32 v[62:63], v[68:69], v[84:85]
	v_pk_mul_f32 v[64:65], v[66:67], v[82:83]
	v_cvt_pk_bf16_f32 v59, v60, v61
	s_nop 0
	v_cvt_pk_bf16_f32 v60, v64, v65
	v_cvt_pk_bf16_f32 v61, v62, v63
	global_store_dwordx4 v[88:89], v[58:61], off offset:768 sc0 sc1
	ds_swizzle_b32 v58, v86 offset:swizzle(SWAP,16)
	s_waitcnt lgkmcnt(0)
	v_add_f32_e32 v58, v86, v58
	v_mov_b32_e32 v59, v58
	s_nop 1
	v_permlane32_swap_b32_e32 v58, v59
	s_and_saveexec_b64 s[12:13], vcc
	v_add_f32_e32 v58, v58, v59
	ds_write_b32 v138, v58 offset:512
	s_or_b64 exec, exec, s[12:13]
	s_waitcnt vmcnt(9)
	v_lshlrev_b32_e32 v58, 16, v110
	v_and_b32_e32 v59, 0xffff0000, v110
	v_lshlrev_b32_e32 v60, 16, v111
	v_and_b32_e32 v61, 0xffff0000, v111
	v_pk_add_f32 v[54:55], v[54:55], v[58:59]
	v_lshlrev_b32_e32 v58, 16, v112
	v_and_b32_e32 v59, 0xffff0000, v112
	v_lshl_add_u64 v[62:63], s[42:43], 0, v[128:129]
	v_pk_add_f32 v[56:57], v[56:57], v[60:61]
	v_lshlrev_b32_e32 v60, 16, v113
	v_and_b32_e32 v61, 0xffff0000, v113
	v_pk_add_f32 v[58:59], v[50:51], v[58:59]
	v_cvt_pk_bf16_f32 v50, v54, v55
	v_cvt_pk_bf16_f32 v51, v56, v57
	v_lshl_add_u64 v[62:63], v[62:63], 0, v[184:185]
	v_pk_add_f32 v[60:61], v[52:53], v[60:61]
	v_cvt_pk_bf16_f32 v52, v58, v59
	s_nop 0
	v_cvt_pk_bf16_f32 v53, v60, v61
	global_store_dwordx4 v[62:63], v[50:53], off sc0 sc1
	s_nop 1
	v_mul_f32_e32 v50, v55, v55
	v_mul_f32_e32 v51, v57, v57
	v_fmac_f32_e32 v50, v54, v54
	v_fmac_f32_e32 v51, v56, v56
	v_add_f32_e32 v50, v50, v51
	v_mul_f32_e32 v51, v59, v59
	v_mul_f32_e32 v52, v61, v61
	v_fmac_f32_e32 v51, v58, v58
	v_fmac_f32_e32 v52, v60, v60
	v_add_f32_e32 v51, v51, v52
	v_add_f32_e32 v64, v50, v51
	v_pk_mul_f32 v[52:53], v[80:81], v[56:57]
	v_pk_mul_f32 v[50:51], v[78:79], v[54:55]
	v_pk_mul_f32 v[54:55], v[76:77], v[60:61]
	v_pk_mul_f32 v[56:57], v[74:75], v[58:59]
	v_cvt_pk_bf16_f32 v50, v50, v51
	v_cvt_pk_bf16_f32 v51, v52, v53
	s_nop 0
	v_cvt_pk_bf16_f32 v52, v56, v57
	v_cvt_pk_bf16_f32 v53, v54, v55
	v_mov_b64_e32 v[54:55], s[50:51]
	v_mad_i64_i32 v[54:55], s[12:13], v126, s62, v[54:55]
	v_lshl_add_u64 v[54:55], v[54:55], 0, v[184:185]
	global_store_dwordx4 v[54:55], v[50:53], off offset:512 sc0 sc1
	s_waitcnt vmcnt(10)
; __device__ __forceinline__ u32x4 pack8(const f32x4& a, const f32x4& b) { u32x4 w; w.x = cvt_pk_bf16(a[0], a[1]); w.y = cvt_pk_bf16(a[2], a[3]); w.z = cvt_pk_bf16(b[0], b[1]); w.w = cvt_pk_bf16(b[2], b[3]); return w; }
;     __device__ __forceinline__ void operator()(const f32x4 (&acc)[2][2][4][2], const Unit& u, int wr, int wc, int fr, int fq) const {
;     ...
;         for (int ai = 0; ai < 2; ++ai) {
;             u32x4 xv[4][2];
; #pragma unroll
;             for (int m = 0; m < 4; ++m)
; #pragma unroll
;                 for (int bj = 0; bj < 2; ++bj) xv[m][bj] = *(const u32x4*)(X + (size_t)(rowt + ai * HALF + m * 16) * 2048 + col0 + bj * HALF);
;             asm volatile("" ::: "memory");
; #pragma unroll
;             for (int m = 0; m < 4; ++m) { const int row = rowt + ai * HALF + m * 16; float q = 0.f;
; #pragma unroll
;                 for (int bj = 0; bj < 2; ++bj) { const int col = col0 + bj * HALF; const u32x4 xw = xv[m][bj];
;                     const f32x4 o0 = (f32x4){bflo(xw.x), bfhi(xw.x), bflo(xw.y), bfhi(xw.y)} + acc[ai][bj][m][0], o1 = (f32x4){bflo(xw.z), bfhi(xw.z), bflo(xw.w), bfhi(xw.w)} + acc[ai][bj][m][1];
;                     *(u32x4*)(X + (size_t)row * 2048 + col) = pack8(o0, o1);
;                     q += ((o0[0] * o0[0] + o0[1] * o0[1]) + (o0[2] * o0[2] + o0[3] * o0[3])) + ((o1[0] * o1[0] + o1[1] * o1[1]) + (o1[2] * o1[2] + o1[3] * o1[3]));
;                     if constexpr (DST) *(u32x4*)(dst + (size_t)row * ldd + dcol + col) = pack8(o0 * gv[bj][0], o1 * gv[bj][1]); }
;                 q = fq_sum(q); if (fq == 0) lq[wc * 256 + ai * HALF + wr * 64 + m * 16 + fr] = q; }
;             asm volatile("" ::: "memory");
	s_nop 0
	v_lshlrev_b32_e32 v50, 16, v106
	v_and_b32_e32 v51, 0xffff0000, v106
	v_lshlrev_b32_e32 v52, 16, v107
	v_and_b32_e32 v53, 0xffff0000, v107
	v_pk_add_f32 v[46:47], v[46:47], v[50:51]
	v_lshlrev_b32_e32 v50, 16, v108
	v_and_b32_e32 v51, 0xffff0000, v108
	v_pk_add_f32 v[48:49], v[48:49], v[52:53]
	v_lshlrev_b32_e32 v52, 16, v109
	v_and_b32_e32 v53, 0xffff0000, v109
	v_pk_add_f32 v[50:51], v[42:43], v[50:51]
	v_cvt_pk_bf16_f32 v42, v46, v47
	v_cvt_pk_bf16_f32 v43, v48, v49
	v_pk_add_f32 v[52:53], v[44:45], v[52:53]
	v_cvt_pk_bf16_f32 v44, v50, v51
	s_nop 0
	v_cvt_pk_bf16_f32 v45, v52, v53
	global_store_dwordx4 v[62:63], v[42:45], off offset:256 sc0 sc1
	s_nop 1
	v_mul_f32_e32 v42, v47, v47
	v_mul_f32_e32 v43, v49, v49
	v_fmac_f32_e32 v42, v46, v46
	v_fmac_f32_e32 v43, v48, v48
	v_add_f32_e32 v42, v42, v43
	v_mul_f32_e32 v43, v51, v51
	v_mul_f32_e32 v44, v53, v53
	v_fmac_f32_e32 v43, v50, v50
	v_fmac_f32_e32 v44, v52, v52
	v_add_f32_e32 v43, v43, v44
	v_add_f32_e32 v42, v42, v43
	v_add_f32_e32 v56, v64, v42
	v_pk_mul_f32 v[44:45], v[72:73], v[48:49]
	v_pk_mul_f32 v[48:49], v[66:67], v[50:51]
	ds_swizzle_b32 v50, v56 offset:swizzle(SWAP,16)
	v_pk_mul_f32 v[42:43], v[70:71], v[46:47]
	v_pk_mul_f32 v[46:47], v[68:69], v[52:53]
	v_cvt_pk_bf16_f32 v42, v42, v43
	v_cvt_pk_bf16_f32 v43, v44, v45
	v_cvt_pk_bf16_f32 v44, v48, v49
	s_nop 0
	v_cvt_pk_bf16_f32 v45, v46, v47
	global_store_dwordx4 v[54:55], v[42:45], off offset:768 sc0 sc1
	s_waitcnt lgkmcnt(0)
	s_nop 0
	v_add_f32_e32 v42, v56, v50
	v_mov_b32_e32 v43, v42
	s_nop 1
	v_permlane32_swap_b32_e32 v42, v43
	s_and_saveexec_b64 s[12:13], vcc
	v_add_f32_e32 v42, v42, v43
	ds_write_b32 v138, v42 offset:576
	s_or_b64 exec, exec, s[12:13]
	s_waitcnt vmcnt(11)
	v_lshlrev_b32_e32 v42, 16, v102
	v_and_b32_e32 v43, 0xffff0000, v102
	v_lshlrev_b32_e32 v44, 16, v103
	v_and_b32_e32 v45, 0xffff0000, v103
	v_pk_add_f32 v[38:39], v[38:39], v[42:43]
	v_lshlrev_b32_e32 v42, 16, v104
	v_and_b32_e32 v43, 0xffff0000, v104
	v_lshl_add_u64 v[46:47], s[42:43], 0, v[124:125]
	v_pk_add_f32 v[40:41], v[40:41], v[44:45]
	v_lshlrev_b32_e32 v44, 16, v105
	v_and_b32_e32 v45, 0xffff0000, v105
	v_pk_add_f32 v[42:43], v[34:35], v[42:43]
	v_cvt_pk_bf16_f32 v34, v38, v39
	v_cvt_pk_bf16_f32 v35, v40, v41
	v_lshl_add_u64 v[46:47], v[46:47], 0, v[184:185]
	v_pk_add_f32 v[44:45], v[36:37], v[44:45]
	v_cvt_pk_bf16_f32 v36, v42, v43
	s_nop 0
	v_cvt_pk_bf16_f32 v37, v44, v45
	global_store_dwordx4 v[46:47], v[34:37], off sc0 sc1
	s_nop 1
	v_mul_f32_e32 v34, v39, v39
	v_mul_f32_e32 v35, v41, v41
	v_fmac_f32_e32 v34, v38, v38
	v_fmac_f32_e32 v35, v40, v40
	v_add_f32_e32 v34, v34, v35
	v_mul_f32_e32 v35, v43, v43
	v_mul_f32_e32 v36, v45, v45
	v_fmac_f32_e32 v35, v42, v42
	v_fmac_f32_e32 v36, v44, v44
	v_add_f32_e32 v35, v35, v36
	v_add_f32_e32 v48, v34, v35
	v_pk_mul_f32 v[36:37], v[80:81], v[40:41]
	v_pk_mul_f32 v[34:35], v[78:79], v[38:39]
	v_pk_mul_f32 v[38:39], v[76:77], v[44:45]
	v_pk_mul_f32 v[40:41], v[74:75], v[42:43]
	v_cvt_pk_bf16_f32 v34, v34, v35
	v_cvt_pk_bf16_f32 v35, v36, v37
	s_nop 0
	v_cvt_pk_bf16_f32 v36, v40, v41
	v_cvt_pk_bf16_f32 v37, v38, v39
	v_mov_b64_e32 v[38:39], s[50:51]
	v_mad_i64_i32 v[38:39], s[12:13], v122, s62, v[38:39]
	v_lshl_add_u64 v[38:39], v[38:39], 0, v[184:185]
	global_store_dwordx4 v[38:39], v[34:37], off offset:512 sc0 sc1
	s_waitcnt vmcnt(12)
	s_nop 0
	v_lshlrev_b32_e32 v34, 16, v98
	v_and_b32_e32 v35, 0xffff0000, v98
	v_lshlrev_b32_e32 v36, 16, v99
	v_and_b32_e32 v37, 0xffff0000, v99
	v_pk_add_f32 v[30:31], v[30:31], v[34:35]
	v_lshlrev_b32_e32 v34, 16, v100
	v_and_b32_e32 v35, 0xffff0000, v100
	v_pk_add_f32 v[32:33], v[32:33], v[36:37]
	v_lshlrev_b32_e32 v36, 16, v101
	v_and_b32_e32 v37, 0xffff0000, v101
	v_pk_add_f32 v[34:35], v[26:27], v[34:35]
	v_cvt_pk_bf16_f32 v26, v30, v31
	v_cvt_pk_bf16_f32 v27, v32, v33
	v_pk_add_f32 v[36:37], v[28:29], v[36:37]
	v_cvt_pk_bf16_f32 v28, v34, v35
	s_nop 0
	v_cvt_pk_bf16_f32 v29, v36, v37
	global_store_dwordx4 v[46:47], v[26:29], off offset:256 sc0 sc1
	s_nop 1
	v_mul_f32_e32 v26, v31, v31
	v_mul_f32_e32 v27, v33, v33
	v_fmac_f32_e32 v26, v30, v30
	v_fmac_f32_e32 v27, v32, v32
	v_add_f32_e32 v26, v26, v27
	v_mul_f32_e32 v27, v35, v35
	v_mul_f32_e32 v28, v37, v37
	v_fmac_f32_e32 v27, v34, v34
	v_fmac_f32_e32 v28, v36, v36
	v_add_f32_e32 v27, v27, v28
	v_add_f32_e32 v26, v26, v27
	v_add_f32_e32 v40, v48, v26
	v_pk_mul_f32 v[28:29], v[72:73], v[32:33]
	v_pk_mul_f32 v[32:33], v[66:67], v[34:35]
	ds_swizzle_b32 v34, v40 offset:swizzle(SWAP,16)
	v_pk_mul_f32 v[26:27], v[70:71], v[30:31]
	v_pk_mul_f32 v[30:31], v[68:69], v[36:37]
	v_cvt_pk_bf16_f32 v26, v26, v27
	v_cvt_pk_bf16_f32 v27, v28, v29
	v_cvt_pk_bf16_f32 v28, v32, v33
	s_nop 0
	v_cvt_pk_bf16_f32 v29, v30, v31
	global_store_dwordx4 v[38:39], v[26:29], off offset:768 sc0 sc1
	s_waitcnt lgkmcnt(0)
	s_nop 0
	v_add_f32_e32 v26, v40, v34
	v_mov_b32_e32 v27, v26
	s_nop 1
	v_permlane32_swap_b32_e32 v26, v27
	s_and_saveexec_b64 s[12:13], vcc
	v_add_f32_e32 v26, v26, v27
	ds_write_b32 v138, v26 offset:640
	s_or_b64 exec, exec, s[12:13]
	s_waitcnt vmcnt(13)
; __device__ __forceinline__ u32x4 pack8(const f32x4& a, const f32x4& b) { u32x4 w; w.x = cvt_pk_bf16(a[0], a[1]); w.y = cvt_pk_bf16(a[2], a[3]); w.z = cvt_pk_bf16(b[0], b[1]); w.w = cvt_pk_bf16(b[2], b[3]); return w; }
;     __device__ __forceinline__ void operator()(const f32x4 (&acc)[2][2][4][2], const Unit& u, int wr, int wc, int fr, int fq) const {
;     ...
;             for (int m = 0; m < 4; ++m) { const int row = rowt + ai * HALF + m * 16; float q = 0.f;
; #pragma unroll
;                 for (int bj = 0; bj < 2; ++bj) { const int col = col0 + bj * HALF; const u32x4 xw = xv[m][bj];
;                     const f32x4 o0 = (f32x4){bflo(xw.x), bfhi(xw.x), bflo(xw.y), bfhi(xw.y)} + acc[ai][bj][m][0], o1 = (f32x4){bflo(xw.z), bfhi(xw.z), bflo(xw.w), bfhi(xw.w)} + acc[ai][bj][m][1];
;                     *(u32x4*)(X + (size_t)row * 2048 + col) = pack8(o0, o1);
;                     q += ((o0[0] * o0[0] + o0[1] * o0[1]) + (o0[2] * o0[2] + o0[3] * o0[3])) + ((o1[0] * o1[0] + o1[1] * o1[1]) + (o1[2] * o1[2] + o1[3] * o1[3]));
;                     if constexpr (DST) *(u32x4*)(dst + (size_t)row * ldd + dcol + col) = pack8(o0 * gv[bj][0], o1 * gv[bj][1]); }
;                 q = fq_sum(q); if (fq == 0) lq[wc * 256 + ai * HALF + wr * 64 + m * 16 + fr] = q; }
;     __device__ __forceinline__ void sliver(const f32x4 (&accs)[2], const Unit& u, int srow0, int wr, int wc, int fr, int fq) const {
;         const int row = srow0 + 16 * u.pm + fr, col = u.pn * BM + wr * HALF + wc * 32 + 8 * fq;
;         const u32x4 xw = *(const u32x4*)(X + (size_t)row * 2048 + col);
;         const f32x4 o0 = (f32x4){bflo(xw.x), bfhi(xw.x), bflo(xw.y), bfhi(xw.y)} + accs[0], o1 = (f32x4){bflo(xw.z), bfhi(xw.z), bflo(xw.w), bfhi(xw.w)} + accs[1];
;         *(u32x4*)(X + (size_t)row * 2048 + col) = pack8(o0, o1);
;         float q = ((o0[0] * o0[0] + o0[1] * o0[1]) + (o0[2] * o0[2] + o0[3] * o0[3])) + ((o1[0] * o1[0] + o1[1] * o1[1]) + (o1[2] * o1[2] + o1[3] * o1[3]));
;         if constexpr (DST) { const f32x4 g0 = *(const f32x4*)(gain + col), g1 = *(const f32x4*)(gain + col + 4); *(u32x4*)(dst + (size_t)row * ldd + dcol + col) = pack8(o0 * g0, o1 * g1); }
;         q = fq_sum(q); if (fq == 0) lq[1024 + (wr * 4 + wc) * 16 + fr] = q;
	v_lshlrev_b32_e32 v26, 16, v94
	v_and_b32_e32 v27, 0xffff0000, v94
	v_lshlrev_b32_e32 v28, 16, v95
	v_and_b32_e32 v29, 0xffff0000, v95
	v_pk_add_f32 v[22:23], v[22:23], v[26:27]
	v_lshlrev_b32_e32 v26, 16, v96
	v_and_b32_e32 v27, 0xffff0000, v96
	v_lshl_add_u64 v[30:31], s[42:43], 0, v[120:121]
	v_pk_add_f32 v[24:25], v[24:25], v[28:29]
	v_lshlrev_b32_e32 v28, 16, v97
	v_and_b32_e32 v29, 0xffff0000, v97
	v_pk_add_f32 v[26:27], v[18:19], v[26:27]
	v_cvt_pk_bf16_f32 v18, v22, v23
	v_cvt_pk_bf16_f32 v19, v24, v25
	v_lshl_add_u64 v[30:31], v[30:31], 0, v[184:185]
	v_pk_add_f32 v[28:29], v[20:21], v[28:29]
	v_cvt_pk_bf16_f32 v20, v26, v27
	s_nop 0
	v_cvt_pk_bf16_f32 v21, v28, v29
	global_store_dwordx4 v[30:31], v[18:21], off sc0 sc1
	s_nop 1
	v_mul_f32_e32 v18, v23, v23
	v_mul_f32_e32 v19, v25, v25
	v_fmac_f32_e32 v18, v22, v22
	v_fmac_f32_e32 v19, v24, v24
	v_add_f32_e32 v18, v18, v19
	v_mul_f32_e32 v19, v27, v27
	v_mul_f32_e32 v20, v29, v29
	v_fmac_f32_e32 v19, v26, v26
	v_fmac_f32_e32 v20, v28, v28
	v_add_f32_e32 v19, v19, v20
	v_add_f32_e32 v32, v18, v19
	v_pk_mul_f32 v[20:21], v[80:81], v[24:25]
	v_pk_mul_f32 v[18:19], v[78:79], v[22:23]
	v_pk_mul_f32 v[22:23], v[76:77], v[28:29]
	v_pk_mul_f32 v[24:25], v[74:75], v[26:27]
	v_cvt_pk_bf16_f32 v18, v18, v19
	v_cvt_pk_bf16_f32 v19, v20, v21
	s_nop 0
	v_cvt_pk_bf16_f32 v20, v24, v25
	v_cvt_pk_bf16_f32 v21, v22, v23
	v_mov_b64_e32 v[22:23], s[50:51]
	v_mad_i64_i32 v[22:23], s[12:13], v118, s62, v[22:23]
	v_lshl_add_u64 v[22:23], v[22:23], 0, v[184:185]
	global_store_dwordx4 v[22:23], v[18:21], off offset:512 sc0 sc1
	s_waitcnt vmcnt(14)
	s_nop 0
	v_lshlrev_b32_e32 v18, 16, v90
	v_and_b32_e32 v19, 0xffff0000, v90
	v_lshlrev_b32_e32 v20, 16, v91
	v_and_b32_e32 v21, 0xffff0000, v91
	v_pk_add_f32 v[14:15], v[14:15], v[18:19]
	v_lshlrev_b32_e32 v18, 16, v92
	v_and_b32_e32 v19, 0xffff0000, v92
	v_pk_add_f32 v[16:17], v[16:17], v[20:21]
	v_lshlrev_b32_e32 v20, 16, v93
	v_and_b32_e32 v21, 0xffff0000, v93
	v_pk_add_f32 v[18:19], v[10:11], v[18:19]
	v_cvt_pk_bf16_f32 v10, v14, v15
	v_cvt_pk_bf16_f32 v11, v16, v17
	v_pk_add_f32 v[20:21], v[12:13], v[20:21]
	v_cvt_pk_bf16_f32 v12, v18, v19
	s_nop 0
	v_cvt_pk_bf16_f32 v13, v20, v21
	global_store_dwordx4 v[30:31], v[10:13], off offset:256 sc0 sc1
	s_nop 1
	v_mul_f32_e32 v10, v15, v15
	v_mul_f32_e32 v11, v17, v17
	v_fmac_f32_e32 v10, v14, v14
	v_fmac_f32_e32 v11, v16, v16
	v_add_f32_e32 v10, v10, v11
	v_mul_f32_e32 v11, v19, v19
	v_mul_f32_e32 v12, v21, v21
	v_fmac_f32_e32 v11, v18, v18
	v_fmac_f32_e32 v12, v20, v20
	v_add_f32_e32 v11, v11, v12
	v_add_f32_e32 v10, v10, v11
	v_add_f32_e32 v24, v32, v10
	v_pk_mul_f32 v[12:13], v[72:73], v[16:17]
	v_pk_mul_f32 v[16:17], v[66:67], v[18:19]
	ds_swizzle_b32 v18, v24 offset:swizzle(SWAP,16)
	v_pk_mul_f32 v[10:11], v[70:71], v[14:15]
	v_pk_mul_f32 v[14:15], v[68:69], v[20:21]
	v_cvt_pk_bf16_f32 v10, v10, v11
	v_cvt_pk_bf16_f32 v11, v12, v13
	v_cvt_pk_bf16_f32 v12, v16, v17
	s_nop 0
	v_cvt_pk_bf16_f32 v13, v14, v15
	global_store_dwordx4 v[22:23], v[10:13], off offset:768 sc0 sc1
	s_waitcnt lgkmcnt(0)
	s_nop 0
	v_add_f32_e32 v10, v24, v18
	v_mov_b32_e32 v11, v10
	s_nop 1
	v_permlane32_swap_b32_e32 v10, v11
	s_and_saveexec_b64 s[12:13], vcc
	v_add_f32_e32 v10, v10, v11
	ds_write_b32 v138, v10 offset:704
	s_or_b64 exec, exec, s[12:13]
	s_lshl_b32 s17, s17, 4
	s_addk_i32 s17, 0x2000
	v_readlane_b32 s12, v254, 53
	v_or_b32_e32 v10, s17, v218
	s_add_i32 s3, s12, s3
	v_or_b32_e32 v18, s3, v219
	v_ashrrev_i32_e32 v11, 31, v10
	v_lshlrev_b64 v[12:13], 12, v[10:11]
	v_ashrrev_i32_e32 v19, 31, v18
	v_lshl_add_u64 v[14:15], s[42:43], 0, v[12:13]
	v_lshlrev_b64 v[12:13], 1, v[18:19]
	v_lshl_add_u64 v[20:21], v[14:15], 0, v[12:13]
	global_load_dwordx4 v[14:17], v[20:21], off
	v_readlane_b32 s12, v254, 43
	v_readlane_b32 s13, v254, 44
	s_waitcnt vmcnt(0)
	v_lshlrev_b32_e32 v22, 16, v14
	v_and_b32_e32 v23, 0xffff0000, v14
	v_lshlrev_b32_e32 v14, 16, v15
	v_and_b32_e32 v15, 0xffff0000, v15
	v_pk_add_f32 v[22:23], v[6:7], v[22:23]
	v_lshlrev_b32_e32 v6, 16, v16
	v_and_b32_e32 v7, 0xffff0000, v16
	v_pk_add_f32 v[14:15], v[8:9], v[14:15]
	v_lshlrev_b32_e32 v8, 16, v17
	v_and_b32_e32 v9, 0xffff0000, v17
	v_pk_add_f32 v[24:25], v[2:3], v[6:7]
	v_cvt_pk_bf16_f32 v2, v22, v23
	v_cvt_pk_bf16_f32 v3, v14, v15
	v_pk_add_f32 v[16:17], v[4:5], v[8:9]
	v_cvt_pk_bf16_f32 v4, v24, v25
	v_lshl_add_u64 v[6:7], v[18:19], 2, s[12:13]
	v_cvt_pk_bf16_f32 v5, v16, v17
	global_store_dwordx4 v[20:21], v[2:5], off sc0 sc1
	s_nop 1
	v_mul_f32_e32 v2, v23, v23
	v_mul_f32_e32 v3, v15, v15
	v_fmac_f32_e32 v2, v22, v22
	v_fmac_f32_e32 v3, v14, v14
	v_add_f32_e32 v2, v2, v3
	v_mul_f32_e32 v3, v25, v25
	v_mul_f32_e32 v4, v17, v17
	v_fmac_f32_e32 v3, v24, v24
	v_fmac_f32_e32 v4, v16, v16
	v_add_f32_e32 v3, v3, v4
	v_add_f32_e32 v11, v2, v3
	global_load_dwordx4 v[2:5], v[6:7], off offset:16
	s_nop 0
	global_load_dwordx4 v[6:9], v[6:7], off
	s_waitcnt vmcnt(0)
	v_pk_mul_f32 v[6:7], v[6:7], v[22:23]
	v_pk_mul_f32 v[8:9], v[8:9], v[14:15]
	v_pk_mul_f32 v[14:15], v[4:5], v[16:17]
	v_pk_mul_f32 v[4:5], v[2:3], v[24:25]
	v_cvt_pk_bf16_f32 v2, v6, v7
	v_mov_b64_e32 v[6:7], s[50:51]
	v_mad_i64_i32 v[6:7], s[12:13], v10, s62, v[6:7]
	v_lshl_add_u64 v[6:7], v[6:7], 0, v[12:13]
	v_cvt_pk_bf16_f32 v3, v8, v9
	v_cvt_pk_bf16_f32 v4, v4, v5
	v_cvt_pk_bf16_f32 v5, v14, v15
	global_store_dwordx4 v[6:7], v[2:5], off offset:512 sc0 sc1
	ds_swizzle_b32 v2, v11 offset:swizzle(SWAP,16)
	s_waitcnt lgkmcnt(0)
	v_add_f32_e32 v2, v11, v2
	v_mov_b32_e32 v3, v2
	s_nop 1
	v_permlane32_swap_b32_e32 v2, v3
	s_and_saveexec_b64 s[12:13], vcc
	s_cbranch_execz .LBB0_841
	v_readlane_b32 s3, v252, 4
	v_add_f32_e32 v2, v2, v3
	s_nop 0
	v_lshl_add_u32 v4, v218, 2, s3
	ds_write_b32 v4, v2 offset:4096

; __device__ __forceinline__ float expneg(float g) { return ex2(fminf(-g * 1.4426950408889634f, 80.f)); }
; __device__ __forceinline__ float ss_total(const u32x4 a) { return ((bflo(a.x) + bfhi(a.x)) + (bflo(a.y) + bfhi(a.y))) + ((bflo(a.z) + bfhi(a.z)) + (bflo(a.w) + bfhi(a.w))); }
;     __device__ __forceinline__ void operator()(const f32x4 (&acc)[2][2][4][2], const Unit& u, int wr, int wc, int fr, int fq) const {
;     ...
;                 for (int m2 = 0; m2 < 2; ++m2) { const int row = rowt + ai * HALF + (mh * 2 + m2) * 16; sa[m2] = *(const u32x4*)(ss3 + (size_t)row * 8);
; #pragma unroll
;                     for (int bj = 0; bj < 2; ++bj) { const size_t o_ = (size_t)row * 2048 + col0 + bj * HALF; xv[m2][bj] = *(const u32x4*)(X + o_); pv[m2][bj] = *(const u32x4*)(PP + o_); } }
;                 asm volatile("" ::: "memory");
; #pragma unroll
;                 for (int m2 = 0; m2 < 2; ++m2) { const int m = mh * 2 + m2, row = rowt + ai * HALF + m * 16; float q = 0.f;
;                     const float rs = __builtin_amdgcn_rsqf(ss_total(sa[m2]) * (1.f / 2048.f) + 1e-6f);
; #pragma unroll
;                     for (int bj = 0; bj < 2; ++bj) { const int col = col0 + bj * HALF; const u32x4 xw = xv[m2][bj], pw = pv[m2][bj];
;                         const f32x4 x0 = {bflo(xw.x), bfhi(xw.x), bflo(xw.y), bfhi(xw.y)}, x1 = {bflo(xw.z), bfhi(xw.z), bflo(xw.w), bfhi(xw.w)};
;                         const f32x4 p0 = {bflo(pw.x), bfhi(pw.x), bflo(pw.y), bfhi(pw.y)}, p1 = {bflo(pw.z), bfhi(pw.z), bflo(pw.w), bfhi(pw.w)};
;                         const f32x4 a0 = acc[ai][bj][m][0], a1 = acc[ai][bj][m][1]; f32x4 o0, o1;
; #pragma unroll
;                         for (int i = 0; i < 4; ++i) { o0[i] = x0[i] + p0[i] * __builtin_amdgcn_rcpf(1.f + expneg(a0[i] * rs)); o1[i] = x1[i] + p1[i] * __builtin_amdgcn_rcpf(1.f + expneg(a1[i] * rs)); }
.LBB0_946:
	s_cmp_lg_u32 s3, 0
	s_cselect_b64 s[54:55], -1, 0
	s_lshl_b32 s17, s52, 8
	v_readlane_b32 s2, v254, 52
	v_mov_b32_e32 v187, v0
	s_add_i32 s2, s17, s2
	s_cmp_eq_u32 s3, 0
	v_and_b32_e32 v186, 15, v187
	v_or_b32_e32 v174, s2, v186
	v_or_b32_e32 v176, 16, v174
	v_bfe_u32 v178, v187, 4, 2
	v_ashrrev_i32_e32 v175, 31, v174
	v_ashrrev_i32_e32 v177, 31, v176
	s_mov_b32 s45, 0xf800000
	s_mov_b32 s66, s78
	s_cbranch_scc1 .LBB0_992
	v_lshl_add_u64 v[138:139], v[174:175], 4, s[86:87]
	global_load_dwordx4 v[182:185], v[138:139], off
	s_lshl_b32 s62, s16, 8
	v_readlane_b32 s2, v254, 47
	v_lshlrev_b32_e32 v198, 3, v178
	s_or_b32 s2, s62, s2
	v_or_b32_e32 v180, s2, v198
	v_ashrrev_i32_e32 v181, 31, v180
	v_lshlrev_b64 v[138:139], 11, v[174:175]
	v_lshl_add_u64 v[138:139], v[138:139], 0, v[180:181]
	v_lshlrev_b64 v[138:139], 1, v[138:139]
	v_lshl_add_u64 v[140:141], s[82:83], 0, v[138:139]
	global_load_dwordx4 v[170:173], v[140:141], off
	v_lshl_add_u64 v[140:141], s[84:85], 0, v[138:139]
	global_load_dwordx4 v[166:169], v[140:141], off
	v_or_b32_e32 v138, 0x100, v138
	v_lshl_add_u64 v[140:141], s[82:83], 0, v[138:139]
	v_lshl_add_u64 v[138:139], s[84:85], 0, v[138:139]
	global_load_dwordx4 v[162:165], v[140:141], off
	global_load_dwordx4 v[158:161], v[138:139], off
	v_lshl_add_u64 v[138:139], v[176:177], 4, s[86:87]
	global_load_dwordx4 v[154:157], v[138:139], off
	v_lshlrev_b64 v[138:139], 11, v[176:177]
	v_lshl_add_u64 v[138:139], v[138:139], 0, v[180:181]
	v_lshlrev_b64 v[138:139], 1, v[138:139]
	v_lshl_add_u64 v[140:141], s[82:83], 0, v[138:139]
	global_load_dwordx4 v[150:153], v[140:141], off
	v_lshl_add_u64 v[140:141], s[84:85], 0, v[138:139]
	v_or_b32_e32 v138, 0x100, v138
	global_load_dwordx4 v[146:149], v[140:141], off
	v_lshl_add_u64 v[140:141], s[82:83], 0, v[138:139]
	v_lshl_add_u64 v[138:139], s[84:85], 0, v[138:139]
	global_load_dwordx4 v[142:145], v[140:141], off
	v_readlane_b32 s2, v254, 58
	global_load_dwordx4 v[138:141], v[138:139], off
	v_readlane_b32 s3, v254, 59
	v_cmp_eq_u32_e64 s[40:41], 0, v178
	s_andn2_b64 vcc, exec, s[2:3]
	s_waitcnt vmcnt(0)
	v_lshlrev_b32_e32 v199, 16, v182
	v_and_b32_e32 v182, 0xffff0000, v182
	v_add_f32_e32 v182, v199, v182
	v_lshlrev_b32_e32 v199, 16, v183
	v_and_b32_e32 v183, 0xffff0000, v183
	v_add_f32_e32 v183, v199, v183
	v_add_f32_e32 v182, v182, v183
	v_lshlrev_b32_e32 v183, 16, v184
	v_and_b32_e32 v184, 0xffff0000, v184
	v_add_f32_e32 v183, v183, v184
	v_lshlrev_b32_e32 v184, 16, v185
	v_and_b32_e32 v185, 0xffff0000, v185
	v_add_f32_e32 v184, v184, v185
	v_add_f32_e32 v183, v183, v184
	v_add_f32_e32 v182, v182, v183
	v_fmamk_f32 v182, v182, 0x3a000000, v1
	v_rsq_f32_e32 v184, v182
	v_lshlrev_b32_e32 v185, 16, v170
	v_lshlrev_b32_e32 v202, 16, v166
	v_lshlrev_b32_e32 v200, 16, v172
	v_mul_f32_e32 v210, v134, v184
	v_mul_f32_e32 v210, 0xbfb8aa3b, v210
	v_min_f32_e32 v210, 0x42a00000, v210
	v_exp_f32_e32 v210, v210
	v_lshlrev_b32_e32 v208, 16, v168
	v_and_b32_e32 v199, 0xffff0000, v170
	v_and_b32_e32 v166, 0xffff0000, v166
	v_add_f32_e32 v210, 1.0, v210
	v_rcp_f32_e32 v210, v210
	v_and_b32_e32 v201, 0xffff0000, v172
	v_and_b32_e32 v168, 0xffff0000, v168
	v_lshlrev_b32_e32 v170, 16, v171
	v_fmac_f32_e32 v185, v210, v202
	v_mul_f32_e32 v202, v130, v184
	v_mul_f32_e32 v202, 0xbfb8aa3b, v202
	v_min_f32_e32 v202, 0x42a00000, v202
	v_exp_f32_e32 v202, v202
	v_lshlrev_b32_e32 v203, 16, v167
	v_lshlrev_b32_e32 v172, 16, v173
	v_lshlrev_b32_e32 v209, 16, v169
	v_add_f32_e32 v202, 1.0, v202
	v_rcp_f32_e32 v202, v202
	v_and_b32_e32 v171, 0xffff0000, v171
	v_and_b32_e32 v167, 0xffff0000, v167
	v_mul_f32_e32 v210, v118, v184
	v_fmac_f32_e32 v200, v202, v208
	v_mul_f32_e32 v202, v135, v184
	v_mul_f32_e32 v202, 0xbfb8aa3b, v202
	v_min_f32_e32 v202, 0x42a00000, v202
	v_exp_f32_e32 v202, v202
	v_mul_f32_e32 v210, 0xbfb8aa3b, v210
	v_min_f32_e32 v210, 0x42a00000, v210
	v_exp_f32_e32 v210, v210
	v_add_f32_e32 v202, 1.0, v202
	v_rcp_f32_e32 v202, v202
	v_lshlrev_b64 v[182:183], 12, v[174:175]
	v_add_f32_e32 v210, 1.0, v210
	v_rcp_f32_e32 v210, v210
	v_fmac_f32_e32 v199, v202, v166
	v_mul_f32_e32 v166, v131, v184
	v_mul_f32_e32 v166, 0xbfb8aa3b, v166
	v_min_f32_e32 v166, 0x42a00000, v166
	v_exp_f32_e32 v166, v166
	v_and_b32_e32 v173, 0xffff0000, v173
	v_and_b32_e32 v169, 0xffff0000, v169
	v_lshl_add_u64 v[182:183], s[82:83], 0, v[182:183]
	v_add_f32_e32 v166, 1.0, v166
	v_rcp_f32_e32 v166, v166
	v_lshlrev_b32_e32 v208, 16, v160
	v_and_b32_e32 v160, 0xffff0000, v160
	v_fmac_f32_e32 v201, v166, v168
	v_mul_f32_e32 v166, v136, v184
	v_mul_f32_e32 v166, 0xbfb8aa3b, v166
	v_min_f32_e32 v166, 0x42a00000, v166
	v_exp_f32_e32 v166, v166
	s_nop 0
	v_add_f32_e32 v166, 1.0, v166
; __device__ __forceinline__ u32x4 pack8(const f32x4& a, const f32x4& b) { u32x4 w; w.x = cvt_pk_bf16(a[0], a[1]); w.y = cvt_pk_bf16(a[2], a[3]); w.z = cvt_pk_bf16(b[0], b[1]); w.w = cvt_pk_bf16(b[2], b[3]); return w; }
; __device__ __forceinline__ float expneg(float g) { return ex2(fminf(-g * 1.4426950408889634f, 80.f)); }
; __device__ __forceinline__ float ss_total(const u32x4 a) { return ((bflo(a.x) + bfhi(a.x)) + (bflo(a.y) + bfhi(a.y))) + ((bflo(a.z) + bfhi(a.z)) + (bflo(a.w) + bfhi(a.w))); }
;     __device__ __forceinline__ void operator()(const f32x4 (&acc)[2][2][4][2], const Unit& u, int wr, int wc, int fr, int fq) const {
;     ...
;                 for (int m2 = 0; m2 < 2; ++m2) { const int m = mh * 2 + m2, row = rowt + ai * HALF + m * 16; float q = 0.f;
;                     const float rs = __builtin_amdgcn_rsqf(ss_total(sa[m2]) * (1.f / 2048.f) + 1e-6f);
; #pragma unroll
;                     for (int bj = 0; bj < 2; ++bj) { const int col = col0 + bj * HALF; const u32x4 xw = xv[m2][bj], pw = pv[m2][bj];
;                         const f32x4 x0 = {bflo(xw.x), bfhi(xw.x), bflo(xw.y), bfhi(xw.y)}, x1 = {bflo(xw.z), bfhi(xw.z), bflo(xw.w), bfhi(xw.w)};
;                         const f32x4 p0 = {bflo(pw.x), bfhi(pw.x), bflo(pw.y), bfhi(pw.y)}, p1 = {bflo(pw.z), bfhi(pw.z), bflo(pw.w), bfhi(pw.w)};
;                         const f32x4 a0 = acc[ai][bj][m][0], a1 = acc[ai][bj][m][1]; f32x4 o0, o1;
; #pragma unroll
;                         for (int i = 0; i < 4; ++i) { o0[i] = x0[i] + p0[i] * __builtin_amdgcn_rcpf(1.f + expneg(a0[i] * rs)); o1[i] = x1[i] + p1[i] * __builtin_amdgcn_rcpf(1.f + expneg(a1[i] * rs)); }
;                         *(u32x4*)(X + (size_t)row * 2048 + col) = pack8(o0, o1);
;                         if (gain) q += ((o0[0] * o0[0] + o0[1] * o0[1]) + (o0[2] * o0[2] + o0[3] * o0[3])) + ((o1[0] * o1[0] + o1[1] * o1[1]) + (o1[2] * o1[2] + o1[3] * o1[3])); }
;                     if (gain) { q = fq_sum(q); if (fq == 0) lq[wc * 256 + ai * HALF + wr * 64 + m * 16 + fr] = q; } }
	v_rcp_f32_e32 v166, v166
	s_nop 0
	v_fmac_f32_e32 v170, v166, v203
	v_mul_f32_e32 v166, v132, v184
	v_mul_f32_e32 v166, 0xbfb8aa3b, v166
	v_min_f32_e32 v166, 0x42a00000, v166
	v_exp_f32_e32 v166, v166
	v_lshl_add_u64 v[202:203], v[180:181], 1, v[182:183]
	v_and_b32_e32 v182, 0xffff0000, v162
	v_lshlrev_b32_e32 v183, 16, v159
	v_add_f32_e32 v166, 1.0, v166
	v_rcp_f32_e32 v166, v166
	v_and_b32_e32 v159, 0xffff0000, v159
	v_fmac_f32_e32 v172, v166, v209
	v_mul_f32_e32 v166, v137, v184
	v_mul_f32_e32 v166, 0xbfb8aa3b, v166
	v_min_f32_e32 v166, 0x42a00000, v166
	v_exp_f32_e32 v166, v166
	v_lshlrev_b32_e32 v209, 16, v161
	v_and_b32_e32 v161, 0xffff0000, v161
	v_add_f32_e32 v166, 1.0, v166
	v_rcp_f32_e32 v166, v166
	s_nop 0
	v_fmac_f32_e32 v171, v166, v167
	v_mul_f32_e32 v166, v133, v184
	v_mul_f32_e32 v166, 0xbfb8aa3b, v166
	v_min_f32_e32 v166, 0x42a00000, v166
	v_exp_f32_e32 v166, v166
	s_nop 0
	v_add_f32_e32 v166, 1.0, v166
	v_rcp_f32_e32 v166, v166
	s_nop 0
	v_fmac_f32_e32 v173, v166, v169
	v_cvt_pk_bf16_f32 v166, v185, v199
	v_cvt_pk_bf16_f32 v167, v170, v171
	v_cvt_pk_bf16_f32 v168, v200, v201
	v_cvt_pk_bf16_f32 v169, v172, v173
	global_store_dwordx4 v[202:203], v[166:169], off sc0 sc1
	s_nop 1
	v_lshlrev_b32_e32 v167, 16, v162
	v_lshlrev_b32_e32 v166, 16, v163
	v_and_b32_e32 v169, 0xffff0000, v163
	v_lshlrev_b32_e32 v163, 16, v164
	v_and_b32_e32 v168, 0xffff0000, v164
	v_lshlrev_b32_e32 v162, 16, v165
	v_and_b32_e32 v164, 0xffff0000, v165
	v_lshlrev_b32_e32 v165, 16, v158
	v_fmac_f32_e32 v167, v210, v165
	v_mul_f32_e32 v165, v110, v184
	v_mul_f32_e32 v165, 0xbfb8aa3b, v165
	v_min_f32_e32 v165, 0x42a00000, v165
	v_exp_f32_e32 v165, v165
	v_and_b32_e32 v158, 0xffff0000, v158
	v_add_f32_e32 v165, 1.0, v165
	v_rcp_f32_e32 v165, v165
	s_nop 0
	v_fmac_f32_e32 v163, v165, v208
	v_mul_f32_e32 v165, v119, v184
	v_mul_f32_e32 v165, 0xbfb8aa3b, v165
	v_min_f32_e32 v165, 0x42a00000, v165
	v_exp_f32_e32 v165, v165
	s_nop 0
	v_add_f32_e32 v165, 1.0, v165
	v_rcp_f32_e32 v165, v165
	s_nop 0
	v_fmac_f32_e32 v182, v165, v158
	v_mul_f32_e32 v158, v111, v184
	v_mul_f32_e32 v158, 0xbfb8aa3b, v158
	v_min_f32_e32 v158, 0x42a00000, v158
	v_exp_f32_e32 v158, v158
	s_nop 0
	v_add_f32_e32 v158, 1.0, v158
	v_rcp_f32_e32 v158, v158
	s_nop 0
	v_fmac_f32_e32 v168, v158, v160
	v_mul_f32_e32 v158, v120, v184
	v_mul_f32_e32 v158, 0xbfb8aa3b, v158
	v_min_f32_e32 v158, 0x42a00000, v158
	v_exp_f32_e32 v158, v158
	s_nop 0
	v_add_f32_e32 v158, 1.0, v158
	v_rcp_f32_e32 v158, v158
	s_nop 0
	v_fmac_f32_e32 v166, v158, v183
	v_mul_f32_e32 v158, v112, v184
	v_mul_f32_e32 v158, 0xbfb8aa3b, v158
	v_min_f32_e32 v158, 0x42a00000, v158
	v_exp_f32_e32 v158, v158
	s_nop 0
	v_add_f32_e32 v158, 1.0, v158
	v_rcp_f32_e32 v158, v158
	s_nop 0
	v_fmac_f32_e32 v162, v158, v209
	v_mul_f32_e32 v158, v121, v184
	v_mul_f32_e32 v158, 0xbfb8aa3b, v158
	v_min_f32_e32 v158, 0x42a00000, v158
	v_exp_f32_e32 v158, v158
	s_nop 0
	v_add_f32_e32 v158, 1.0, v158
	v_rcp_f32_e32 v158, v158
	s_nop 0
	v_fmac_f32_e32 v169, v158, v159
	v_mul_f32_e32 v158, v113, v184
	v_mul_f32_e32 v158, 0xbfb8aa3b, v158
	v_min_f32_e32 v158, 0x42a00000, v158
	v_exp_f32_e32 v158, v158
	s_nop 0
	v_add_f32_e32 v158, 1.0, v158
	v_rcp_f32_e32 v158, v158
	s_nop 0
	v_fmac_f32_e32 v164, v158, v161
	v_cvt_pk_bf16_f32 v158, v167, v182
	v_cvt_pk_bf16_f32 v159, v166, v169
	v_cvt_pk_bf16_f32 v160, v163, v168
	v_cvt_pk_bf16_f32 v161, v162, v164
	global_store_dwordx4 v[202:203], v[158:161], off offset:256 sc0 sc1
	s_nop 1
	v_cndmask_b32_e64 v158, 0, 1, s[2:3]
	v_cmp_ne_u32_e64 s[42:43], 1, v158
	s_cbranch_vccnz .LBB0_951
	v_mul_f32_e32 v158, v201, v201
	v_mul_f32_e32 v159, v173, v173
	v_fmac_f32_e32 v158, v200, v200
	v_fmac_f32_e32 v159, v172, v172
	v_add_f32_e32 v158, v158, v159
	v_mul_f32_e32 v159, v199, v199
	v_mul_f32_e32 v160, v171, v171
	v_fmac_f32_e32 v159, v185, v185
	v_fmac_f32_e32 v160, v170, v170
	v_add_f32_e32 v159, v159, v160
	v_add_f32_e32 v158, v159, v158
	v_mul_f32_e32 v159, v182, v182
	v_mul_f32_e32 v160, v169, v169
	v_fmac_f32_e32 v159, v167, v167
	v_fmac_f32_e32 v160, v166, v166
	v_add_f32_e32 v159, v159, v160
	v_mul_f32_e32 v160, v168, v168
	v_mul_f32_e32 v161, v164, v164
	v_fmac_f32_e32 v160, v163, v163
	v_fmac_f32_e32 v161, v162, v162
	v_add_f32_e32 v160, v160, v161
	v_add_f32_e32 v159, v159, v160
	v_add_f32_e32 v158, v158, v159
	ds_swizzle_b32 v159, v158 offset:swizzle(SWAP,16)
	s_waitcnt lgkmcnt(0)
	v_add_f32_e32 v158, v158, v159
	v_mov_b32_e32 v159, v158
	s_nop 1
	v_permlane32_swap_b32_e32 v158, v159
	s_and_saveexec_b64 s[12:13], s[40:41]
	s_cbranch_execz .LBB0_950
	v_readlane_b32 s2, v254, 50
	v_add_f32_e32 v158, v158, v159
	s_nop 0
	v_lshl_add_u32 v160, v186, 2, s2
	ds_write_b32 v160, v158

; __device__ __forceinline__ u32x4 pack8(const f32x4& a, const f32x4& b) { u32x4 w; w.x = cvt_pk_bf16(a[0], a[1]); w.y = cvt_pk_bf16(a[2], a[3]); w.z = cvt_pk_bf16(b[0], b[1]); w.w = cvt_pk_bf16(b[2], b[3]); return w; }
; __device__ __forceinline__ float expneg(float g) { return ex2(fminf(-g * 1.4426950408889634f, 80.f)); }
; __device__ __forceinline__ float ss_total(const u32x4 a) { return ((bflo(a.x) + bfhi(a.x)) + (bflo(a.y) + bfhi(a.y))) + ((bflo(a.z) + bfhi(a.z)) + (bflo(a.w) + bfhi(a.w))); }
;     __device__ __forceinline__ void operator()(const f32x4 (&acc)[2][2][4][2], const Unit& u, int wr, int wc, int fr, int fq) const {
;     ...
;                 for (int m2 = 0; m2 < 2; ++m2) { const int m = mh * 2 + m2, row = rowt + ai * HALF + m * 16; float q = 0.f;
;                     const float rs = __builtin_amdgcn_rsqf(ss_total(sa[m2]) * (1.f / 2048.f) + 1e-6f);
; #pragma unroll
;                     for (int bj = 0; bj < 2; ++bj) { const int col = col0 + bj * HALF; const u32x4 xw = xv[m2][bj], pw = pv[m2][bj];
;                         const f32x4 x0 = {bflo(xw.x), bfhi(xw.x), bflo(xw.y), bfhi(xw.y)}, x1 = {bflo(xw.z), bfhi(xw.z), bflo(xw.w), bfhi(xw.w)};
;                         const f32x4 p0 = {bflo(pw.x), bfhi(pw.x), bflo(pw.y), bfhi(pw.y)}, p1 = {bflo(pw.z), bfhi(pw.z), bflo(pw.w), bfhi(pw.w)};
;                         const f32x4 a0 = acc[ai][bj][m][0], a1 = acc[ai][bj][m][1]; f32x4 o0, o1;
; #pragma unroll
;                         for (int i = 0; i < 4; ++i) { o0[i] = x0[i] + p0[i] * __builtin_amdgcn_rcpf(1.f + expneg(a0[i] * rs)); o1[i] = x1[i] + p1[i] * __builtin_amdgcn_rcpf(1.f + expneg(a1[i] * rs)); }
;                         *(u32x4*)(X + (size_t)row * 2048 + col) = pack8(o0, o1);
;                         if (gain) q += ((o0[0] * o0[0] + o0[1] * o0[1]) + (o0[2] * o0[2] + o0[3] * o0[3])) + ((o1[0] * o1[0] + o1[1] * o1[1]) + (o1[2] * o1[2] + o1[3] * o1[3])); }
.LBB0_951:
	v_lshlrev_b32_e32 v158, 16, v154
	v_and_b32_e32 v154, 0xffff0000, v154
	v_add_f32_e32 v154, v158, v154
	v_lshlrev_b32_e32 v158, 16, v155
	v_and_b32_e32 v155, 0xffff0000, v155
	v_add_f32_e32 v155, v158, v155
	v_add_f32_e32 v154, v154, v155
	v_lshlrev_b32_e32 v155, 16, v156
	v_and_b32_e32 v156, 0xffff0000, v156
	v_add_f32_e32 v155, v155, v156
	v_lshlrev_b32_e32 v156, 16, v157
	v_and_b32_e32 v157, 0xffff0000, v157
	v_add_f32_e32 v156, v156, v157
	v_add_f32_e32 v155, v155, v156
	v_add_f32_e32 v154, v154, v155
	v_fmamk_f32 v154, v154, 0x3a000000, v1
	v_rsq_f32_e32 v162, v154
	v_lshlrev_b32_e32 v154, 16, v150
	v_lshlrev_b32_e32 v160, 16, v146
	v_lshlrev_b32_e32 v156, 16, v152
	v_mul_f32_e32 v165, v126, v162
	v_mul_f32_e32 v165, 0xbfb8aa3b, v165
	v_min_f32_e32 v165, 0x42a00000, v165
	v_exp_f32_e32 v165, v165
	v_lshlrev_b32_e32 v163, 16, v148
	v_and_b32_e32 v155, 0xffff0000, v150
	v_and_b32_e32 v146, 0xffff0000, v146
	v_add_f32_e32 v165, 1.0, v165
	v_rcp_f32_e32 v165, v165
	v_and_b32_e32 v157, 0xffff0000, v152
	v_and_b32_e32 v148, 0xffff0000, v148
	v_lshlrev_b32_e32 v150, 16, v151
	v_fmac_f32_e32 v154, v165, v160
	v_mul_f32_e32 v160, v122, v162
	v_mul_f32_e32 v160, 0xbfb8aa3b, v160
	v_min_f32_e32 v160, 0x42a00000, v160
	v_exp_f32_e32 v160, v160
	v_lshlrev_b32_e32 v161, 16, v147
	v_lshlrev_b32_e32 v152, 16, v153
	v_lshlrev_b32_e32 v164, 16, v149
	v_add_f32_e32 v160, 1.0, v160
	v_rcp_f32_e32 v160, v160
	v_and_b32_e32 v151, 0xffff0000, v151
	v_and_b32_e32 v147, 0xffff0000, v147
	v_mul_f32_e32 v165, v102, v162
	v_fmac_f32_e32 v156, v160, v163
	v_mul_f32_e32 v160, v127, v162
	v_mul_f32_e32 v160, 0xbfb8aa3b, v160
	v_min_f32_e32 v160, 0x42a00000, v160
	v_exp_f32_e32 v160, v160
	v_mul_f32_e32 v165, 0xbfb8aa3b, v165
	v_min_f32_e32 v165, 0x42a00000, v165
	v_exp_f32_e32 v165, v165
	v_add_f32_e32 v160, 1.0, v160
	v_rcp_f32_e32 v160, v160
	v_lshlrev_b64 v[158:159], 12, v[176:177]
	v_add_f32_e32 v165, 1.0, v165
	v_rcp_f32_e32 v165, v165
	v_fmac_f32_e32 v155, v160, v146
	v_mul_f32_e32 v146, v123, v162
	v_mul_f32_e32 v146, 0xbfb8aa3b, v146
	v_min_f32_e32 v146, 0x42a00000, v146
	v_exp_f32_e32 v146, v146
	v_and_b32_e32 v153, 0xffff0000, v153
	v_and_b32_e32 v149, 0xffff0000, v149
	v_lshl_add_u64 v[158:159], s[82:83], 0, v[158:159]
	v_add_f32_e32 v146, 1.0, v146
	v_rcp_f32_e32 v146, v146
	v_lshlrev_b32_e32 v163, 16, v140
	v_and_b32_e32 v140, 0xffff0000, v140
	s_and_b64 vcc, exec, s[42:43]
	v_fmac_f32_e32 v157, v146, v148
	v_mul_f32_e32 v146, v128, v162
	v_mul_f32_e32 v146, 0xbfb8aa3b, v146
	v_min_f32_e32 v146, 0x42a00000, v146
	v_exp_f32_e32 v146, v146
	s_nop 0
	v_add_f32_e32 v146, 1.0, v146
	v_rcp_f32_e32 v146, v146
	s_nop 0
	v_fmac_f32_e32 v150, v146, v161
	v_mul_f32_e32 v146, v124, v162
	v_mul_f32_e32 v146, 0xbfb8aa3b, v146
	v_min_f32_e32 v146, 0x42a00000, v146
	v_exp_f32_e32 v146, v146
	v_lshl_add_u64 v[160:161], v[180:181], 1, v[158:159]
	v_and_b32_e32 v158, 0xffff0000, v142
	v_lshlrev_b32_e32 v159, 16, v139
	v_add_f32_e32 v146, 1.0, v146
	v_rcp_f32_e32 v146, v146
	v_and_b32_e32 v139, 0xffff0000, v139
	v_fmac_f32_e32 v152, v146, v164
	v_mul_f32_e32 v146, v129, v162
	v_mul_f32_e32 v146, 0xbfb8aa3b, v146
	v_min_f32_e32 v146, 0x42a00000, v146
	v_exp_f32_e32 v146, v146
	v_lshlrev_b32_e32 v164, 16, v141
	v_and_b32_e32 v141, 0xffff0000, v141
	v_add_f32_e32 v146, 1.0, v146
	v_rcp_f32_e32 v146, v146
	s_nop 0
	v_fmac_f32_e32 v151, v146, v147
	v_mul_f32_e32 v146, v125, v162
	v_mul_f32_e32 v146, 0xbfb8aa3b, v146
	v_min_f32_e32 v146, 0x42a00000, v146
	v_exp_f32_e32 v146, v146
	s_nop 0
	v_add_f32_e32 v146, 1.0, v146
	v_rcp_f32_e32 v146, v146
	s_nop 0
	v_fmac_f32_e32 v153, v146, v149
	v_cvt_pk_bf16_f32 v146, v154, v155
	v_cvt_pk_bf16_f32 v147, v150, v151
	v_cvt_pk_bf16_f32 v148, v156, v157
	v_cvt_pk_bf16_f32 v149, v152, v153
	global_store_dwordx4 v[160:161], v[146:149], off sc0 sc1
	s_nop 1
	v_lshlrev_b32_e32 v147, 16, v142
	v_lshlrev_b32_e32 v146, 16, v143
	v_and_b32_e32 v149, 0xffff0000, v143
	v_lshlrev_b32_e32 v143, 16, v144
	v_and_b32_e32 v148, 0xffff0000, v144
	v_lshlrev_b32_e32 v142, 16, v145
	v_and_b32_e32 v144, 0xffff0000, v145
	v_lshlrev_b32_e32 v145, 16, v138
	v_fmac_f32_e32 v147, v165, v145
	v_mul_f32_e32 v145, v94, v162
	v_mul_f32_e32 v145, 0xbfb8aa3b, v145
	v_min_f32_e32 v145, 0x42a00000, v145
	v_exp_f32_e32 v145, v145
	v_and_b32_e32 v138, 0xffff0000, v138
	v_add_f32_e32 v145, 1.0, v145
	v_rcp_f32_e32 v145, v145
	s_nop 0
	v_fmac_f32_e32 v143, v145, v163
	v_mul_f32_e32 v145, v103, v162
	v_mul_f32_e32 v145, 0xbfb8aa3b, v145
	v_min_f32_e32 v145, 0x42a00000, v145
	v_exp_f32_e32 v145, v145
	s_nop 0
	v_add_f32_e32 v145, 1.0, v145
	v_rcp_f32_e32 v145, v145
	s_nop 0
	v_fmac_f32_e32 v158, v145, v138
	v_mul_f32_e32 v138, v95, v162
	v_mul_f32_e32 v138, 0xbfb8aa3b, v138
	v_min_f32_e32 v138, 0x42a00000, v138
	v_exp_f32_e32 v138, v138
	s_nop 0
	v_add_f32_e32 v138, 1.0, v138
	v_rcp_f32_e32 v138, v138
	s_nop 0
	v_fmac_f32_e32 v148, v138, v140
	v_mul_f32_e32 v138, v104, v162
	v_mul_f32_e32 v138, 0xbfb8aa3b, v138
	v_min_f32_e32 v138, 0x42a00000, v138
	v_exp_f32_e32 v138, v138
	s_nop 0
	v_add_f32_e32 v138, 1.0, v138
	v_rcp_f32_e32 v138, v138
	s_nop 0
	v_fmac_f32_e32 v146, v138, v159
	v_mul_f32_e32 v138, v96, v162
	v_mul_f32_e32 v138, 0xbfb8aa3b, v138
	v_min_f32_e32 v138, 0x42a00000, v138
	v_exp_f32_e32 v138, v138
	s_nop 0
	v_add_f32_e32 v138, 1.0, v138
	v_rcp_f32_e32 v138, v138
	s_nop 0
	v_fmac_f32_e32 v142, v138, v164
	v_mul_f32_e32 v138, v105, v162
	v_mul_f32_e32 v138, 0xbfb8aa3b, v138
	v_min_f32_e32 v138, 0x42a00000, v138
	v_exp_f32_e32 v138, v138
	s_nop 0
	v_add_f32_e32 v138, 1.0, v138
	v_rcp_f32_e32 v138, v138
	s_nop 0
	v_fmac_f32_e32 v149, v138, v139
	v_mul_f32_e32 v138, v97, v162
	v_mul_f32_e32 v138, 0xbfb8aa3b, v138
	v_min_f32_e32 v138, 0x42a00000, v138
	v_exp_f32_e32 v138, v138
	s_nop 0
	v_add_f32_e32 v138, 1.0, v138
	v_rcp_f32_e32 v138, v138
	s_nop 0
	v_fmac_f32_e32 v144, v138, v141
	v_cvt_pk_bf16_f32 v138, v147, v158
	v_cvt_pk_bf16_f32 v139, v146, v149
	v_cvt_pk_bf16_f32 v140, v143, v148
	v_cvt_pk_bf16_f32 v141, v142, v144
	global_store_dwordx4 v[160:161], v[138:141], off offset:256 sc0 sc1
	s_cbranch_vccnz .LBB0_955
;     __device__ __forceinline__ void operator()(const f32x4 (&acc)[2][2][4][2], const Unit& u, int wr, int wc, int fr, int fq) const {
;     ...
;                         if (gain) q += ((o0[0] * o0[0] + o0[1] * o0[1]) + (o0[2] * o0[2] + o0[3] * o0[3])) + ((o1[0] * o1[0] + o1[1] * o1[1]) + (o1[2] * o1[2] + o1[3] * o1[3])); }
;                     if (gain) { q = fq_sum(q); if (fq == 0) lq[wc * 256 + ai * HALF + wr * 64 + m * 16 + fr] = q; } }
	s_nop 0
	v_mul_f32_e32 v138, v157, v157
	v_mul_f32_e32 v139, v153, v153
	v_fmac_f32_e32 v138, v156, v156
	v_fmac_f32_e32 v139, v152, v152
	v_add_f32_e32 v138, v138, v139
	v_mul_f32_e32 v139, v155, v155
	v_mul_f32_e32 v140, v151, v151
	v_fmac_f32_e32 v139, v154, v154
	v_fmac_f32_e32 v140, v150, v150
	v_add_f32_e32 v139, v139, v140
	v_add_f32_e32 v138, v139, v138
	v_mul_f32_e32 v139, v158, v158
	v_mul_f32_e32 v140, v149, v149
	v_fmac_f32_e32 v139, v147, v147
	v_fmac_f32_e32 v140, v146, v146
	v_add_f32_e32 v139, v139, v140
	v_mul_f32_e32 v140, v148, v148
	v_mul_f32_e32 v141, v144, v144
	v_fmac_f32_e32 v140, v143, v143
	v_fmac_f32_e32 v141, v142, v142
	v_add_f32_e32 v140, v140, v141
	v_add_f32_e32 v139, v139, v140
	v_add_f32_e32 v138, v138, v139
	ds_swizzle_b32 v139, v138 offset:swizzle(SWAP,16)
	s_waitcnt lgkmcnt(0)
	v_add_f32_e32 v138, v138, v139
	v_mov_b32_e32 v139, v138
	s_nop 1
	v_permlane32_swap_b32_e32 v138, v139
	s_and_saveexec_b64 s[12:13], s[40:41]
	s_cbranch_execz .LBB0_954
	v_readlane_b32 s2, v254, 50
	v_add_f32_e32 v138, v138, v139
	s_nop 0
	v_lshl_add_u32 v140, v186, 2, s2
	ds_write_b32 v140, v138 offset:64

; __device__ __forceinline__ float expneg(float g) { return ex2(fminf(-g * 1.4426950408889634f, 80.f)); }
; __device__ __forceinline__ float ss_total(const u32x4 a) { return ((bflo(a.x) + bfhi(a.x)) + (bflo(a.y) + bfhi(a.y))) + ((bflo(a.z) + bfhi(a.z)) + (bflo(a.w) + bfhi(a.w))); }
;     __device__ __forceinline__ void operator()(const f32x4 (&acc)[2][2][4][2], const Unit& u, int wr, int wc, int fr, int fq) const {
;     ...
;                 for (int m2 = 0; m2 < 2; ++m2) { const int row = rowt + ai * HALF + (mh * 2 + m2) * 16; sa[m2] = *(const u32x4*)(ss3 + (size_t)row * 8);
; #pragma unroll
;                     for (int bj = 0; bj < 2; ++bj) { const size_t o_ = (size_t)row * 2048 + col0 + bj * HALF; xv[m2][bj] = *(const u32x4*)(X + o_); pv[m2][bj] = *(const u32x4*)(PP + o_); } }
;                 asm volatile("" ::: "memory");
; #pragma unroll
;                 for (int m2 = 0; m2 < 2; ++m2) { const int m = mh * 2 + m2, row = rowt + ai * HALF + m * 16; float q = 0.f;
;                     const float rs = __builtin_amdgcn_rsqf(ss_total(sa[m2]) * (1.f / 2048.f) + 1e-6f);
; #pragma unroll
;                     for (int bj = 0; bj < 2; ++bj) { const int col = col0 + bj * HALF; const u32x4 xw = xv[m2][bj], pw = pv[m2][bj];
;                         const f32x4 x0 = {bflo(xw.x), bfhi(xw.x), bflo(xw.y), bfhi(xw.y)}, x1 = {bflo(xw.z), bfhi(xw.z), bflo(xw.w), bfhi(xw.w)};
;                         const f32x4 p0 = {bflo(pw.x), bfhi(pw.x), bflo(pw.y), bfhi(pw.y)}, p1 = {bflo(pw.z), bfhi(pw.z), bflo(pw.w), bfhi(pw.w)};
;                         const f32x4 a0 = acc[ai][bj][m][0], a1 = acc[ai][bj][m][1]; f32x4 o0, o1;
; #pragma unroll
;                         for (int i = 0; i < 4; ++i) { o0[i] = x0[i] + p0[i] * __builtin_amdgcn_rcpf(1.f + expneg(a0[i] * rs)); o1[i] = x1[i] + p1[i] * __builtin_amdgcn_rcpf(1.f + expneg(a1[i] * rs)); }
.LBB0_955:
	v_or_b32_e32 v184, 32, v174
	v_ashrrev_i32_e32 v185, 31, v184
	v_lshl_add_u64 v[138:139], v[184:185], 4, s[86:87]
	global_load_dwordx4 v[200:203], v[138:139], off
	v_lshlrev_b64 v[138:139], 11, v[184:185]
	v_lshl_add_u64 v[138:139], v[138:139], 0, v[180:181]
	v_lshlrev_b64 v[138:139], 1, v[138:139]
	v_lshl_add_u64 v[140:141], s[82:83], 0, v[138:139]
	global_load_dwordx4 v[170:173], v[140:141], off
	v_lshl_add_u64 v[140:141], s[84:85], 0, v[138:139]
	global_load_dwordx4 v[166:169], v[140:141], off
	v_or_b32_e32 v138, 0x100, v138
	v_lshl_add_u64 v[140:141], s[82:83], 0, v[138:139]
	v_lshl_add_u64 v[138:139], s[84:85], 0, v[138:139]
	global_load_dwordx4 v[162:165], v[140:141], off
	global_load_dwordx4 v[158:161], v[138:139], off
	v_or_b32_e32 v182, 48, v174
	v_ashrrev_i32_e32 v183, 31, v182
	v_lshl_add_u64 v[138:139], v[182:183], 4, s[86:87]
	global_load_dwordx4 v[154:157], v[138:139], off
	v_lshlrev_b64 v[138:139], 11, v[182:183]
	v_lshl_add_u64 v[138:139], v[138:139], 0, v[180:181]
	v_lshlrev_b64 v[138:139], 1, v[138:139]
	v_lshl_add_u64 v[140:141], s[82:83], 0, v[138:139]
	global_load_dwordx4 v[150:153], v[140:141], off
	v_lshl_add_u64 v[140:141], s[84:85], 0, v[138:139]
	v_or_b32_e32 v138, 0x100, v138
	v_lshlrev_b64 v[184:185], 12, v[184:185]
	global_load_dwordx4 v[146:149], v[140:141], off
	v_lshl_add_u64 v[140:141], s[82:83], 0, v[138:139]
	v_lshl_add_u64 v[138:139], s[84:85], 0, v[138:139]
	v_lshl_add_u64 v[184:185], s[82:83], 0, v[184:185]
	global_load_dwordx4 v[142:145], v[140:141], off
	s_and_b64 vcc, exec, s[42:43]
	global_load_dwordx4 v[138:141], v[138:139], off
	s_waitcnt vmcnt(9)
	v_lshlrev_b32_e32 v199, 16, v200
	v_and_b32_e32 v200, 0xffff0000, v200
	v_add_f32_e32 v199, v199, v200
	v_lshlrev_b32_e32 v200, 16, v201
	v_and_b32_e32 v201, 0xffff0000, v201
	v_add_f32_e32 v200, v200, v201
	v_add_f32_e32 v199, v199, v200
	v_lshlrev_b32_e32 v200, 16, v202
	v_and_b32_e32 v201, 0xffff0000, v202
	v_add_f32_e32 v200, v200, v201
	v_lshlrev_b32_e32 v201, 16, v203
	v_and_b32_e32 v202, 0xffff0000, v203
	v_add_f32_e32 v201, v201, v202
	v_add_f32_e32 v200, v200, v201
	v_add_f32_e32 v199, v199, v200
	v_fmamk_f32 v199, v199, 0x3a000000, v1
	v_rsq_f32_e32 v199, v199
	s_waitcnt vmcnt(8)
	v_lshlrev_b32_e32 v200, 16, v170
	s_waitcnt vmcnt(7)
	v_lshlrev_b32_e32 v208, 16, v166
	v_lshlrev_b32_e32 v202, 16, v172
	v_mul_f32_e32 v216, v114, v199
	v_mul_f32_e32 v216, 0xbfb8aa3b, v216
	v_min_f32_e32 v216, 0x42a00000, v216
	v_exp_f32_e32 v216, v216
	v_lshlrev_b32_e32 v210, 16, v168
	v_and_b32_e32 v201, 0xffff0000, v170
	v_and_b32_e32 v166, 0xffff0000, v166
	v_add_f32_e32 v216, 1.0, v216
	v_rcp_f32_e32 v216, v216
	v_and_b32_e32 v203, 0xffff0000, v172
	v_and_b32_e32 v168, 0xffff0000, v168
	v_lshlrev_b32_e32 v170, 16, v171
	v_fmac_f32_e32 v200, v216, v208
	v_mul_f32_e32 v208, v106, v199
	v_mul_f32_e32 v208, 0xbfb8aa3b, v208
	v_min_f32_e32 v208, 0x42a00000, v208
	v_exp_f32_e32 v208, v208
	v_lshlrev_b32_e32 v209, 16, v167
	v_lshlrev_b32_e32 v172, 16, v173
	v_lshlrev_b32_e32 v211, 16, v169
	v_add_f32_e32 v208, 1.0, v208
	v_rcp_f32_e32 v208, v208
	v_and_b32_e32 v171, 0xffff0000, v171
	v_and_b32_e32 v167, 0xffff0000, v167
	v_mul_f32_e32 v216, v86, v199
	v_fmac_f32_e32 v202, v208, v210
	v_mul_f32_e32 v208, v115, v199
	v_mul_f32_e32 v208, 0xbfb8aa3b, v208
	v_min_f32_e32 v208, 0x42a00000, v208
	v_exp_f32_e32 v208, v208
	v_mul_f32_e32 v216, 0xbfb8aa3b, v216
	v_min_f32_e32 v216, 0x42a00000, v216
	v_exp_f32_e32 v216, v216
	v_add_f32_e32 v208, 1.0, v208
	v_rcp_f32_e32 v208, v208
	v_and_b32_e32 v173, 0xffff0000, v173
	v_add_f32_e32 v216, 1.0, v216
	v_rcp_f32_e32 v216, v216
	v_fmac_f32_e32 v201, v208, v166
	v_mul_f32_e32 v166, v107, v199
	v_mul_f32_e32 v166, 0xbfb8aa3b, v166
	v_min_f32_e32 v166, 0x42a00000, v166
	v_exp_f32_e32 v166, v166
	v_and_b32_e32 v169, 0xffff0000, v169
	s_waitcnt vmcnt(5)
; __device__ __forceinline__ u32x4 pack8(const f32x4& a, const f32x4& b) { u32x4 w; w.x = cvt_pk_bf16(a[0], a[1]); w.y = cvt_pk_bf16(a[2], a[3]); w.z = cvt_pk_bf16(b[0], b[1]); w.w = cvt_pk_bf16(b[2], b[3]); return w; }
; __device__ __forceinline__ float expneg(float g) { return ex2(fminf(-g * 1.4426950408889634f, 80.f)); }
;     __device__ __forceinline__ void operator()(const f32x4 (&acc)[2][2][4][2], const Unit& u, int wr, int wc, int fr, int fq) const {
;     ...
;                     for (int bj = 0; bj < 2; ++bj) { const int col = col0 + bj * HALF; const u32x4 xw = xv[m2][bj], pw = pv[m2][bj];
;                         const f32x4 x0 = {bflo(xw.x), bfhi(xw.x), bflo(xw.y), bfhi(xw.y)}, x1 = {bflo(xw.z), bfhi(xw.z), bflo(xw.w), bfhi(xw.w)};
;                         const f32x4 p0 = {bflo(pw.x), bfhi(pw.x), bflo(pw.y), bfhi(pw.y)}, p1 = {bflo(pw.z), bfhi(pw.z), bflo(pw.w), bfhi(pw.w)};
;                         const f32x4 a0 = acc[ai][bj][m][0], a1 = acc[ai][bj][m][1]; f32x4 o0, o1;
; #pragma unroll
;                         for (int i = 0; i < 4; ++i) { o0[i] = x0[i] + p0[i] * __builtin_amdgcn_rcpf(1.f + expneg(a0[i] * rs)); o1[i] = x1[i] + p1[i] * __builtin_amdgcn_rcpf(1.f + expneg(a1[i] * rs)); }
;                         *(u32x4*)(X + (size_t)row * 2048 + col) = pack8(o0, o1);
;                         if (gain) q += ((o0[0] * o0[0] + o0[1] * o0[1]) + (o0[2] * o0[2] + o0[3] * o0[3])) + ((o1[0] * o1[0] + o1[1] * o1[1]) + (o1[2] * o1[2] + o1[3] * o1[3])); }
;                     if (gain) { q = fq_sum(q); if (fq == 0) lq[wc * 256 + ai * HALF + wr * 64 + m * 16 + fr] = q; } }
	v_lshlrev_b32_e32 v210, 16, v160
	v_and_b32_e32 v160, 0xffff0000, v160
	v_add_f32_e32 v166, 1.0, v166
	v_rcp_f32_e32 v166, v166
	s_nop 0
	v_fmac_f32_e32 v203, v166, v168
	v_mul_f32_e32 v166, v116, v199
	v_mul_f32_e32 v166, 0xbfb8aa3b, v166
	v_min_f32_e32 v166, 0x42a00000, v166
	v_exp_f32_e32 v166, v166
	s_nop 0
	v_add_f32_e32 v166, 1.0, v166
	v_rcp_f32_e32 v166, v166
	s_nop 0
	v_fmac_f32_e32 v170, v166, v209
	v_mul_f32_e32 v166, v108, v199
	v_mul_f32_e32 v166, 0xbfb8aa3b, v166
	v_min_f32_e32 v166, 0x42a00000, v166
	v_exp_f32_e32 v166, v166
	v_lshl_add_u64 v[208:209], v[180:181], 1, v[184:185]
	v_and_b32_e32 v184, 0xffff0000, v162
	v_lshlrev_b32_e32 v185, 16, v159
	v_add_f32_e32 v166, 1.0, v166
	v_rcp_f32_e32 v166, v166
	v_and_b32_e32 v159, 0xffff0000, v159
	v_fmac_f32_e32 v172, v166, v211
	v_mul_f32_e32 v166, v117, v199
	v_mul_f32_e32 v166, 0xbfb8aa3b, v166
	v_min_f32_e32 v166, 0x42a00000, v166
	v_exp_f32_e32 v166, v166
	v_lshlrev_b32_e32 v211, 16, v161
	v_and_b32_e32 v161, 0xffff0000, v161
	v_add_f32_e32 v166, 1.0, v166
	v_rcp_f32_e32 v166, v166
	s_nop 0
	v_fmac_f32_e32 v171, v166, v167
	v_mul_f32_e32 v166, v109, v199
	v_mul_f32_e32 v166, 0xbfb8aa3b, v166
	v_min_f32_e32 v166, 0x42a00000, v166
	v_exp_f32_e32 v166, v166
	s_nop 0
	v_add_f32_e32 v166, 1.0, v166
	v_rcp_f32_e32 v166, v166
	s_nop 0
	v_fmac_f32_e32 v173, v166, v169
	v_cvt_pk_bf16_f32 v166, v200, v201
	v_cvt_pk_bf16_f32 v167, v170, v171
	v_cvt_pk_bf16_f32 v168, v202, v203
	v_cvt_pk_bf16_f32 v169, v172, v173
	global_store_dwordx4 v[208:209], v[166:169], off sc0 sc1
	s_nop 1
	v_lshlrev_b32_e32 v167, 16, v162
	v_lshlrev_b32_e32 v166, 16, v163
	v_and_b32_e32 v169, 0xffff0000, v163
	v_lshlrev_b32_e32 v163, 16, v164
	v_and_b32_e32 v168, 0xffff0000, v164
	v_lshlrev_b32_e32 v162, 16, v165
	v_and_b32_e32 v164, 0xffff0000, v165
	v_lshlrev_b32_e32 v165, 16, v158
	v_fmac_f32_e32 v167, v216, v165
	v_mul_f32_e32 v165, v82, v199
	v_mul_f32_e32 v165, 0xbfb8aa3b, v165
	v_min_f32_e32 v165, 0x42a00000, v165
	v_exp_f32_e32 v165, v165
	v_and_b32_e32 v158, 0xffff0000, v158
	v_add_f32_e32 v165, 1.0, v165
	v_rcp_f32_e32 v165, v165
	s_nop 0
	v_fmac_f32_e32 v163, v165, v210
	v_mul_f32_e32 v165, v87, v199
	v_mul_f32_e32 v165, 0xbfb8aa3b, v165
	v_min_f32_e32 v165, 0x42a00000, v165
	v_exp_f32_e32 v165, v165
	s_nop 0
	v_add_f32_e32 v165, 1.0, v165
	v_rcp_f32_e32 v165, v165
	s_nop 0
	v_fmac_f32_e32 v184, v165, v158
	v_mul_f32_e32 v158, v83, v199
	v_mul_f32_e32 v158, 0xbfb8aa3b, v158
	v_min_f32_e32 v158, 0x42a00000, v158
	v_exp_f32_e32 v158, v158
	s_nop 0
	v_add_f32_e32 v158, 1.0, v158
	v_rcp_f32_e32 v158, v158
	s_nop 0
	v_fmac_f32_e32 v168, v158, v160
	v_mul_f32_e32 v158, v88, v199
	v_mul_f32_e32 v158, 0xbfb8aa3b, v158
	v_min_f32_e32 v158, 0x42a00000, v158
	v_exp_f32_e32 v158, v158
	s_nop 0
	v_add_f32_e32 v158, 1.0, v158
	v_rcp_f32_e32 v158, v158
	s_nop 0
	v_fmac_f32_e32 v166, v158, v185
	v_mul_f32_e32 v158, v84, v199
	v_mul_f32_e32 v158, 0xbfb8aa3b, v158
	v_min_f32_e32 v158, 0x42a00000, v158
	v_exp_f32_e32 v158, v158
	s_nop 0
	v_add_f32_e32 v158, 1.0, v158
	v_rcp_f32_e32 v158, v158
	s_nop 0
	v_fmac_f32_e32 v162, v158, v211
	v_mul_f32_e32 v158, v89, v199
	v_mul_f32_e32 v158, 0xbfb8aa3b, v158
	v_min_f32_e32 v158, 0x42a00000, v158
	v_exp_f32_e32 v158, v158
	s_nop 0
	v_add_f32_e32 v158, 1.0, v158
	v_rcp_f32_e32 v158, v158
	s_nop 0
	v_fmac_f32_e32 v169, v158, v159
	v_mul_f32_e32 v158, v85, v199
	v_mul_f32_e32 v158, 0xbfb8aa3b, v158
	v_min_f32_e32 v158, 0x42a00000, v158
	v_exp_f32_e32 v158, v158
	s_nop 0
	v_add_f32_e32 v158, 1.0, v158
	v_rcp_f32_e32 v158, v158
	s_nop 0
	v_fmac_f32_e32 v164, v158, v161
	v_cvt_pk_bf16_f32 v158, v167, v184
	v_cvt_pk_bf16_f32 v159, v166, v169
	v_cvt_pk_bf16_f32 v160, v163, v168
	v_cvt_pk_bf16_f32 v161, v162, v164
	global_store_dwordx4 v[208:209], v[158:161], off offset:256 sc0 sc1
	s_cbranch_vccnz .LBB0_959
	s_nop 0
	v_mul_f32_e32 v158, v203, v203
	v_mul_f32_e32 v159, v173, v173
	v_fmac_f32_e32 v158, v202, v202
	v_fmac_f32_e32 v159, v172, v172
	v_add_f32_e32 v158, v158, v159
	v_mul_f32_e32 v159, v201, v201
	v_mul_f32_e32 v160, v171, v171
	v_fmac_f32_e32 v159, v200, v200
	v_fmac_f32_e32 v160, v170, v170
	v_add_f32_e32 v159, v159, v160
	v_add_f32_e32 v158, v159, v158
	v_mul_f32_e32 v159, v184, v184
	v_mul_f32_e32 v160, v169, v169
	v_fmac_f32_e32 v159, v167, v167
	v_fmac_f32_e32 v160, v166, v166
	v_add_f32_e32 v159, v159, v160
	v_mul_f32_e32 v160, v168, v168
	v_mul_f32_e32 v161, v164, v164
	v_fmac_f32_e32 v160, v163, v163
	v_fmac_f32_e32 v161, v162, v162
	v_add_f32_e32 v160, v160, v161
	v_add_f32_e32 v159, v159, v160
	v_add_f32_e32 v158, v158, v159
	ds_swizzle_b32 v159, v158 offset:swizzle(SWAP,16)
	s_waitcnt lgkmcnt(0)
	v_add_f32_e32 v158, v158, v159
	v_mov_b32_e32 v159, v158
	s_nop 1
	v_permlane32_swap_b32_e32 v158, v159
	s_and_saveexec_b64 s[12:13], s[40:41]
	s_cbranch_execz .LBB0_958
	v_readlane_b32 s2, v254, 50
	v_add_f32_e32 v158, v158, v159
	s_nop 0
	v_lshl_add_u32 v160, v186, 2, s2
	ds_write_b32 v160, v158 offset:128

; __device__ __forceinline__ u32x4 pack8(const f32x4& a, const f32x4& b) { u32x4 w; w.x = cvt_pk_bf16(a[0], a[1]); w.y = cvt_pk_bf16(a[2], a[3]); w.z = cvt_pk_bf16(b[0], b[1]); w.w = cvt_pk_bf16(b[2], b[3]); return w; }
; __device__ __forceinline__ float expneg(float g) { return ex2(fminf(-g * 1.4426950408889634f, 80.f)); }
; __device__ __forceinline__ float ss_total(const u32x4 a) { return ((bflo(a.x) + bfhi(a.x)) + (bflo(a.y) + bfhi(a.y))) + ((bflo(a.z) + bfhi(a.z)) + (bflo(a.w) + bfhi(a.w))); }
;     __device__ __forceinline__ void operator()(const f32x4 (&acc)[2][2][4][2], const Unit& u, int wr, int wc, int fr, int fq) const {
;     ...
;                 for (int m2 = 0; m2 < 2; ++m2) { const int m = mh * 2 + m2, row = rowt + ai * HALF + m * 16; float q = 0.f;
;                     const float rs = __builtin_amdgcn_rsqf(ss_total(sa[m2]) * (1.f / 2048.f) + 1e-6f);
; #pragma unroll
;                     for (int bj = 0; bj < 2; ++bj) { const int col = col0 + bj * HALF; const u32x4 xw = xv[m2][bj], pw = pv[m2][bj];
;                         const f32x4 x0 = {bflo(xw.x), bfhi(xw.x), bflo(xw.y), bfhi(xw.y)}, x1 = {bflo(xw.z), bfhi(xw.z), bflo(xw.w), bfhi(xw.w)};
;                         const f32x4 p0 = {bflo(pw.x), bfhi(pw.x), bflo(pw.y), bfhi(pw.y)}, p1 = {bflo(pw.z), bfhi(pw.z), bflo(pw.w), bfhi(pw.w)};
;                         const f32x4 a0 = acc[ai][bj][m][0], a1 = acc[ai][bj][m][1]; f32x4 o0, o1;
; #pragma unroll
;                         for (int i = 0; i < 4; ++i) { o0[i] = x0[i] + p0[i] * __builtin_amdgcn_rcpf(1.f + expneg(a0[i] * rs)); o1[i] = x1[i] + p1[i] * __builtin_amdgcn_rcpf(1.f + expneg(a1[i] * rs)); }
;                         *(u32x4*)(X + (size_t)row * 2048 + col) = pack8(o0, o1);
;                         if (gain) q += ((o0[0] * o0[0] + o0[1] * o0[1]) + (o0[2] * o0[2] + o0[3] * o0[3])) + ((o1[0] * o1[0] + o1[1] * o1[1]) + (o1[2] * o1[2] + o1[3] * o1[3])); }
.LBB0_959:
	s_waitcnt vmcnt(6)
	v_lshlrev_b32_e32 v158, 16, v154
	v_and_b32_e32 v154, 0xffff0000, v154
	v_add_f32_e32 v154, v158, v154
	v_lshlrev_b32_e32 v158, 16, v155
	v_and_b32_e32 v155, 0xffff0000, v155
	v_add_f32_e32 v155, v158, v155
	v_add_f32_e32 v154, v154, v155
	v_lshlrev_b32_e32 v155, 16, v156
	v_and_b32_e32 v156, 0xffff0000, v156
	v_add_f32_e32 v155, v155, v156
	v_lshlrev_b32_e32 v156, 16, v157
	v_and_b32_e32 v157, 0xffff0000, v157
	v_add_f32_e32 v156, v156, v157
	v_add_f32_e32 v155, v155, v156
	v_add_f32_e32 v154, v154, v155
	v_fmamk_f32 v154, v154, 0x3a000000, v1
	v_rsq_f32_e32 v162, v154
	s_waitcnt vmcnt(5)
	v_lshlrev_b32_e32 v154, 16, v150
	s_waitcnt vmcnt(4)
	v_lshlrev_b32_e32 v160, 16, v146
	v_lshlrev_b32_e32 v156, 16, v152
	v_mul_f32_e32 v165, v98, v162
	v_mul_f32_e32 v165, 0xbfb8aa3b, v165
	v_min_f32_e32 v165, 0x42a00000, v165
	v_exp_f32_e32 v165, v165
	v_lshlrev_b32_e32 v163, 16, v148
	v_and_b32_e32 v155, 0xffff0000, v150
	v_and_b32_e32 v146, 0xffff0000, v146
	v_add_f32_e32 v165, 1.0, v165
	v_rcp_f32_e32 v165, v165
	v_and_b32_e32 v157, 0xffff0000, v152
	v_and_b32_e32 v148, 0xffff0000, v148
	v_lshlrev_b32_e32 v150, 16, v151
	v_fmac_f32_e32 v154, v165, v160
	v_mul_f32_e32 v160, v90, v162
	v_mul_f32_e32 v160, 0xbfb8aa3b, v160
	v_min_f32_e32 v160, 0x42a00000, v160
	v_exp_f32_e32 v160, v160
	v_lshlrev_b32_e32 v161, 16, v147
	v_lshlrev_b32_e32 v152, 16, v153
	v_lshlrev_b32_e32 v164, 16, v149
	v_add_f32_e32 v160, 1.0, v160
	v_rcp_f32_e32 v160, v160
	v_and_b32_e32 v151, 0xffff0000, v151
	v_and_b32_e32 v147, 0xffff0000, v147
	v_mul_f32_e32 v165, v78, v162
	v_fmac_f32_e32 v156, v160, v163
	v_mul_f32_e32 v160, v99, v162
	v_mul_f32_e32 v160, 0xbfb8aa3b, v160
	v_min_f32_e32 v160, 0x42a00000, v160
	v_exp_f32_e32 v160, v160
	v_mul_f32_e32 v165, 0xbfb8aa3b, v165
	v_min_f32_e32 v165, 0x42a00000, v165
	v_exp_f32_e32 v165, v165
	v_add_f32_e32 v160, 1.0, v160
	v_rcp_f32_e32 v160, v160
	v_lshlrev_b64 v[158:159], 12, v[182:183]
	v_add_f32_e32 v165, 1.0, v165
	v_rcp_f32_e32 v165, v165
	v_fmac_f32_e32 v155, v160, v146
	v_mul_f32_e32 v146, v91, v162
	v_mul_f32_e32 v146, 0xbfb8aa3b, v146
	v_min_f32_e32 v146, 0x42a00000, v146
	v_exp_f32_e32 v146, v146
	v_and_b32_e32 v153, 0xffff0000, v153
	v_and_b32_e32 v149, 0xffff0000, v149
	v_lshl_add_u64 v[158:159], s[82:83], 0, v[158:159]
	v_add_f32_e32 v146, 1.0, v146
	v_rcp_f32_e32 v146, v146
	s_waitcnt vmcnt(2)
	v_lshlrev_b32_e32 v163, 16, v140
	v_and_b32_e32 v140, 0xffff0000, v140
	s_and_b64 vcc, exec, s[42:43]
	v_fmac_f32_e32 v157, v146, v148
	v_mul_f32_e32 v146, v100, v162
	v_mul_f32_e32 v146, 0xbfb8aa3b, v146
	v_min_f32_e32 v146, 0x42a00000, v146
	v_exp_f32_e32 v146, v146
	s_nop 0
	v_add_f32_e32 v146, 1.0, v146
	v_rcp_f32_e32 v146, v146
	s_nop 0
	v_fmac_f32_e32 v150, v146, v161
	v_mul_f32_e32 v146, v92, v162
	v_mul_f32_e32 v146, 0xbfb8aa3b, v146
	v_min_f32_e32 v146, 0x42a00000, v146
	v_exp_f32_e32 v146, v146
	v_lshl_add_u64 v[160:161], v[180:181], 1, v[158:159]
	v_and_b32_e32 v158, 0xffff0000, v142
	v_lshlrev_b32_e32 v159, 16, v139
	v_add_f32_e32 v146, 1.0, v146
	v_rcp_f32_e32 v146, v146
	v_and_b32_e32 v139, 0xffff0000, v139
	v_fmac_f32_e32 v152, v146, v164
	v_mul_f32_e32 v146, v101, v162
	v_mul_f32_e32 v146, 0xbfb8aa3b, v146
	v_min_f32_e32 v146, 0x42a00000, v146
	v_exp_f32_e32 v146, v146
	v_lshlrev_b32_e32 v164, 16, v141
	v_and_b32_e32 v141, 0xffff0000, v141
	v_add_f32_e32 v146, 1.0, v146
	v_rcp_f32_e32 v146, v146
	s_nop 0
	v_fmac_f32_e32 v151, v146, v147
	v_mul_f32_e32 v146, v93, v162
	v_mul_f32_e32 v146, 0xbfb8aa3b, v146
	v_min_f32_e32 v146, 0x42a00000, v146
	v_exp_f32_e32 v146, v146
	s_nop 0
	v_add_f32_e32 v146, 1.0, v146
	v_rcp_f32_e32 v146, v146
	s_nop 0
	v_fmac_f32_e32 v153, v146, v149
	v_cvt_pk_bf16_f32 v146, v154, v155
	v_cvt_pk_bf16_f32 v147, v150, v151
	v_cvt_pk_bf16_f32 v148, v156, v157
	v_cvt_pk_bf16_f32 v149, v152, v153
	global_store_dwordx4 v[160:161], v[146:149], off sc0 sc1
	s_nop 1
	v_lshlrev_b32_e32 v147, 16, v142
	v_lshlrev_b32_e32 v146, 16, v143
	v_and_b32_e32 v149, 0xffff0000, v143
	v_lshlrev_b32_e32 v143, 16, v144
	v_and_b32_e32 v148, 0xffff0000, v144
	v_lshlrev_b32_e32 v142, 16, v145
	v_and_b32_e32 v144, 0xffff0000, v145
	v_lshlrev_b32_e32 v145, 16, v138
	v_fmac_f32_e32 v147, v165, v145
	v_mul_f32_e32 v145, v74, v162
	v_mul_f32_e32 v145, 0xbfb8aa3b, v145
	v_min_f32_e32 v145, 0x42a00000, v145
	v_exp_f32_e32 v145, v145
	v_and_b32_e32 v138, 0xffff0000, v138
	v_add_f32_e32 v145, 1.0, v145
	v_rcp_f32_e32 v145, v145
	s_nop 0
	v_fmac_f32_e32 v143, v145, v163
	v_mul_f32_e32 v145, v79, v162
	v_mul_f32_e32 v145, 0xbfb8aa3b, v145
	v_min_f32_e32 v145, 0x42a00000, v145
	v_exp_f32_e32 v145, v145
	s_nop 0
	v_add_f32_e32 v145, 1.0, v145
	v_rcp_f32_e32 v145, v145
	s_nop 0
	v_fmac_f32_e32 v158, v145, v138
	v_mul_f32_e32 v138, v75, v162
	v_mul_f32_e32 v138, 0xbfb8aa3b, v138
	v_min_f32_e32 v138, 0x42a00000, v138
	v_exp_f32_e32 v138, v138
	s_nop 0
	v_add_f32_e32 v138, 1.0, v138
	v_rcp_f32_e32 v138, v138
	s_nop 0
	v_fmac_f32_e32 v148, v138, v140
	v_mul_f32_e32 v138, v80, v162
	v_mul_f32_e32 v138, 0xbfb8aa3b, v138
	v_min_f32_e32 v138, 0x42a00000, v138
	v_exp_f32_e32 v138, v138
	s_nop 0
	v_add_f32_e32 v138, 1.0, v138
	v_rcp_f32_e32 v138, v138
	s_nop 0
	v_fmac_f32_e32 v146, v138, v159
	v_mul_f32_e32 v138, v76, v162
	v_mul_f32_e32 v138, 0xbfb8aa3b, v138
	v_min_f32_e32 v138, 0x42a00000, v138
	v_exp_f32_e32 v138, v138
	s_nop 0
	v_add_f32_e32 v138, 1.0, v138
	v_rcp_f32_e32 v138, v138
	s_nop 0
	v_fmac_f32_e32 v142, v138, v164
	v_mul_f32_e32 v138, v81, v162
	v_mul_f32_e32 v138, 0xbfb8aa3b, v138
	v_min_f32_e32 v138, 0x42a00000, v138
	v_exp_f32_e32 v138, v138
	s_nop 0
	v_add_f32_e32 v138, 1.0, v138
	v_rcp_f32_e32 v138, v138
	s_nop 0
	v_fmac_f32_e32 v149, v138, v139
	v_mul_f32_e32 v138, v77, v162
	v_mul_f32_e32 v138, 0xbfb8aa3b, v138
	v_min_f32_e32 v138, 0x42a00000, v138
	v_exp_f32_e32 v138, v138
	s_nop 0
	v_add_f32_e32 v138, 1.0, v138
	v_rcp_f32_e32 v138, v138
	s_nop 0
	v_fmac_f32_e32 v144, v138, v141
	v_cvt_pk_bf16_f32 v138, v147, v158
	v_cvt_pk_bf16_f32 v139, v146, v149
	v_cvt_pk_bf16_f32 v140, v143, v148
	v_cvt_pk_bf16_f32 v141, v142, v144
	global_store_dwordx4 v[160:161], v[138:141], off offset:256 sc0 sc1
	s_cbranch_vccnz .LBB0_963
;     __device__ __forceinline__ void operator()(const f32x4 (&acc)[2][2][4][2], const Unit& u, int wr, int wc, int fr, int fq) const {
;     ...
;                         if (gain) q += ((o0[0] * o0[0] + o0[1] * o0[1]) + (o0[2] * o0[2] + o0[3] * o0[3])) + ((o1[0] * o1[0] + o1[1] * o1[1]) + (o1[2] * o1[2] + o1[3] * o1[3])); }
;                     if (gain) { q = fq_sum(q); if (fq == 0) lq[wc * 256 + ai * HALF + wr * 64 + m * 16 + fr] = q; } }
	s_nop 0
	v_mul_f32_e32 v138, v157, v157
	v_mul_f32_e32 v139, v153, v153
	v_fmac_f32_e32 v138, v156, v156
	v_fmac_f32_e32 v139, v152, v152
	v_add_f32_e32 v138, v138, v139
	v_mul_f32_e32 v139, v155, v155
	v_mul_f32_e32 v140, v151, v151
	v_fmac_f32_e32 v139, v154, v154
	v_fmac_f32_e32 v140, v150, v150
	v_add_f32_e32 v139, v139, v140
	v_add_f32_e32 v138, v139, v138
	v_mul_f32_e32 v139, v158, v158
	v_mul_f32_e32 v140, v149, v149
	v_fmac_f32_e32 v139, v147, v147
	v_fmac_f32_e32 v140, v146, v146
	v_add_f32_e32 v139, v139, v140
	v_mul_f32_e32 v140, v148, v148
	v_mul_f32_e32 v141, v144, v144
	v_fmac_f32_e32 v140, v143, v143
	v_fmac_f32_e32 v141, v142, v142
	v_add_f32_e32 v140, v140, v141
	v_add_f32_e32 v139, v139, v140
	v_add_f32_e32 v138, v138, v139
	ds_swizzle_b32 v139, v138 offset:swizzle(SWAP,16)
	s_waitcnt lgkmcnt(0)
	v_add_f32_e32 v138, v138, v139
	v_mov_b32_e32 v139, v138
	s_nop 1
	v_permlane32_swap_b32_e32 v138, v139
	s_and_saveexec_b64 s[12:13], s[40:41]
	s_cbranch_execz .LBB0_962
	v_readlane_b32 s2, v254, 50
	v_add_f32_e32 v138, v138, v139
	s_nop 0
	v_lshl_add_u32 v140, v186, 2, s2
	ds_write_b32 v140, v138 offset:192

; __device__ __forceinline__ float expneg(float g) { return ex2(fminf(-g * 1.4426950408889634f, 80.f)); }
; __device__ __forceinline__ float ss_total(const u32x4 a) { return ((bflo(a.x) + bfhi(a.x)) + (bflo(a.y) + bfhi(a.y))) + ((bflo(a.z) + bfhi(a.z)) + (bflo(a.w) + bfhi(a.w))); }
;     __device__ __forceinline__ void operator()(const f32x4 (&acc)[2][2][4][2], const Unit& u, int wr, int wc, int fr, int fq) const {
;     ...
;                 for (int m2 = 0; m2 < 2; ++m2) { const int row = rowt + ai * HALF + (mh * 2 + m2) * 16; sa[m2] = *(const u32x4*)(ss3 + (size_t)row * 8);
; #pragma unroll
;                     for (int bj = 0; bj < 2; ++bj) { const size_t o_ = (size_t)row * 2048 + col0 + bj * HALF; xv[m2][bj] = *(const u32x4*)(X + o_); pv[m2][bj] = *(const u32x4*)(PP + o_); } }
;                 asm volatile("" ::: "memory");
; #pragma unroll
;                 for (int m2 = 0; m2 < 2; ++m2) { const int m = mh * 2 + m2, row = rowt + ai * HALF + m * 16; float q = 0.f;
;                     const float rs = __builtin_amdgcn_rsqf(ss_total(sa[m2]) * (1.f / 2048.f) + 1e-6f);
; #pragma unroll
;                     for (int bj = 0; bj < 2; ++bj) { const int col = col0 + bj * HALF; const u32x4 xw = xv[m2][bj], pw = pv[m2][bj];
;                         const f32x4 x0 = {bflo(xw.x), bfhi(xw.x), bflo(xw.y), bfhi(xw.y)}, x1 = {bflo(xw.z), bfhi(xw.z), bflo(xw.w), bfhi(xw.w)};
;                         const f32x4 p0 = {bflo(pw.x), bfhi(pw.x), bflo(pw.y), bfhi(pw.y)}, p1 = {bflo(pw.z), bfhi(pw.z), bflo(pw.w), bfhi(pw.w)};
;                         const f32x4 a0 = acc[ai][bj][m][0], a1 = acc[ai][bj][m][1]; f32x4 o0, o1;
; #pragma unroll
;                         for (int i = 0; i < 4; ++i) { o0[i] = x0[i] + p0[i] * __builtin_amdgcn_rcpf(1.f + expneg(a0[i] * rs)); o1[i] = x1[i] + p1[i] * __builtin_amdgcn_rcpf(1.f + expneg(a1[i] * rs)); }
.LBB0_963:
	v_add_u32_e32 v184, 0x80, v174
	v_ashrrev_i32_e32 v185, 31, v184
	v_lshl_add_u64 v[138:139], v[184:185], 4, s[86:87]
	global_load_dwordx4 v[200:203], v[138:139], off
	v_lshlrev_b64 v[138:139], 11, v[184:185]
	v_lshl_add_u64 v[138:139], v[138:139], 0, v[180:181]
	v_lshlrev_b64 v[138:139], 1, v[138:139]
	v_lshl_add_u64 v[140:141], s[82:83], 0, v[138:139]
	global_load_dwordx4 v[170:173], v[140:141], off
	v_lshl_add_u64 v[140:141], s[84:85], 0, v[138:139]
	global_load_dwordx4 v[166:169], v[140:141], off
	v_or_b32_e32 v138, 0x100, v138
	v_lshl_add_u64 v[140:141], s[82:83], 0, v[138:139]
	v_lshl_add_u64 v[138:139], s[84:85], 0, v[138:139]
	global_load_dwordx4 v[162:165], v[140:141], off
	global_load_dwordx4 v[158:161], v[138:139], off
	v_add_u32_e32 v182, 0x90, v174
	v_ashrrev_i32_e32 v183, 31, v182
	v_lshl_add_u64 v[138:139], v[182:183], 4, s[86:87]
	global_load_dwordx4 v[154:157], v[138:139], off
	v_lshlrev_b64 v[138:139], 11, v[182:183]
	v_lshl_add_u64 v[138:139], v[138:139], 0, v[180:181]
	v_lshlrev_b64 v[138:139], 1, v[138:139]
	v_lshl_add_u64 v[140:141], s[82:83], 0, v[138:139]
	global_load_dwordx4 v[150:153], v[140:141], off
	v_lshl_add_u64 v[140:141], s[84:85], 0, v[138:139]
	v_or_b32_e32 v138, 0x100, v138
	v_lshlrev_b64 v[184:185], 12, v[184:185]
	global_load_dwordx4 v[146:149], v[140:141], off
	v_lshl_add_u64 v[140:141], s[82:83], 0, v[138:139]
	v_lshl_add_u64 v[138:139], s[84:85], 0, v[138:139]
	v_lshl_add_u64 v[184:185], s[82:83], 0, v[184:185]
	global_load_dwordx4 v[142:145], v[140:141], off
	s_and_b64 vcc, exec, s[42:43]
	global_load_dwordx4 v[138:141], v[138:139], off
	s_waitcnt vmcnt(9)
	v_lshlrev_b32_e32 v199, 16, v200
	v_and_b32_e32 v200, 0xffff0000, v200
	v_add_f32_e32 v199, v199, v200
	v_lshlrev_b32_e32 v200, 16, v201
	v_and_b32_e32 v201, 0xffff0000, v201
	v_add_f32_e32 v200, v200, v201
	v_add_f32_e32 v199, v199, v200
	v_lshlrev_b32_e32 v200, 16, v202
	v_and_b32_e32 v201, 0xffff0000, v202
	v_add_f32_e32 v200, v200, v201
	v_lshlrev_b32_e32 v201, 16, v203
	v_and_b32_e32 v202, 0xffff0000, v203
	v_add_f32_e32 v201, v201, v202
	v_add_f32_e32 v200, v200, v201
	v_add_f32_e32 v199, v199, v200
	v_fmamk_f32 v199, v199, 0x3a000000, v1
	v_rsq_f32_e32 v199, v199
	s_waitcnt vmcnt(8)
	v_lshlrev_b32_e32 v200, 16, v170
	s_waitcnt vmcnt(7)
	v_lshlrev_b32_e32 v208, 16, v166
	v_lshlrev_b32_e32 v202, 16, v172
	v_mul_f32_e32 v216, v70, v199
	v_mul_f32_e32 v216, 0xbfb8aa3b, v216
	v_min_f32_e32 v216, 0x42a00000, v216
	v_exp_f32_e32 v216, v216
	v_lshlrev_b32_e32 v210, 16, v168
	v_and_b32_e32 v201, 0xffff0000, v170
	v_and_b32_e32 v166, 0xffff0000, v166
	v_add_f32_e32 v216, 1.0, v216
	v_rcp_f32_e32 v216, v216
	v_and_b32_e32 v203, 0xffff0000, v172
	v_and_b32_e32 v168, 0xffff0000, v168
	v_lshlrev_b32_e32 v170, 16, v171
	v_fmac_f32_e32 v200, v216, v208
	v_mul_f32_e32 v208, v66, v199
	v_mul_f32_e32 v208, 0xbfb8aa3b, v208
	v_min_f32_e32 v208, 0x42a00000, v208
	v_exp_f32_e32 v208, v208
	v_lshlrev_b32_e32 v209, 16, v167
	v_lshlrev_b32_e32 v172, 16, v173
	v_lshlrev_b32_e32 v211, 16, v169
	v_add_f32_e32 v208, 1.0, v208
	v_rcp_f32_e32 v208, v208
	v_and_b32_e32 v171, 0xffff0000, v171
	v_and_b32_e32 v167, 0xffff0000, v167
	v_mul_f32_e32 v216, v54, v199
	v_fmac_f32_e32 v202, v208, v210
	v_mul_f32_e32 v208, v71, v199
	v_mul_f32_e32 v208, 0xbfb8aa3b, v208
	v_min_f32_e32 v208, 0x42a00000, v208
	v_exp_f32_e32 v208, v208
	v_mul_f32_e32 v216, 0xbfb8aa3b, v216
	v_min_f32_e32 v216, 0x42a00000, v216
	v_exp_f32_e32 v216, v216
	v_add_f32_e32 v208, 1.0, v208
	v_rcp_f32_e32 v208, v208
	v_and_b32_e32 v173, 0xffff0000, v173
	v_add_f32_e32 v216, 1.0, v216
	v_rcp_f32_e32 v216, v216
	v_fmac_f32_e32 v201, v208, v166
	v_mul_f32_e32 v166, v67, v199
	v_mul_f32_e32 v166, 0xbfb8aa3b, v166
	v_min_f32_e32 v166, 0x42a00000, v166
	v_exp_f32_e32 v166, v166
	v_and_b32_e32 v169, 0xffff0000, v169
	s_waitcnt vmcnt(5)
; __device__ __forceinline__ u32x4 pack8(const f32x4& a, const f32x4& b) { u32x4 w; w.x = cvt_pk_bf16(a[0], a[1]); w.y = cvt_pk_bf16(a[2], a[3]); w.z = cvt_pk_bf16(b[0], b[1]); w.w = cvt_pk_bf16(b[2], b[3]); return w; }
; __device__ __forceinline__ float expneg(float g) { return ex2(fminf(-g * 1.4426950408889634f, 80.f)); }
;     __device__ __forceinline__ void operator()(const f32x4 (&acc)[2][2][4][2], const Unit& u, int wr, int wc, int fr, int fq) const {
;     ...
;                     for (int bj = 0; bj < 2; ++bj) { const int col = col0 + bj * HALF; const u32x4 xw = xv[m2][bj], pw = pv[m2][bj];
;                         const f32x4 x0 = {bflo(xw.x), bfhi(xw.x), bflo(xw.y), bfhi(xw.y)}, x1 = {bflo(xw.z), bfhi(xw.z), bflo(xw.w), bfhi(xw.w)};
;                         const f32x4 p0 = {bflo(pw.x), bfhi(pw.x), bflo(pw.y), bfhi(pw.y)}, p1 = {bflo(pw.z), bfhi(pw.z), bflo(pw.w), bfhi(pw.w)};
;                         const f32x4 a0 = acc[ai][bj][m][0], a1 = acc[ai][bj][m][1]; f32x4 o0, o1;
; #pragma unroll
;                         for (int i = 0; i < 4; ++i) { o0[i] = x0[i] + p0[i] * __builtin_amdgcn_rcpf(1.f + expneg(a0[i] * rs)); o1[i] = x1[i] + p1[i] * __builtin_amdgcn_rcpf(1.f + expneg(a1[i] * rs)); }
;                         *(u32x4*)(X + (size_t)row * 2048 + col) = pack8(o0, o1);
;                         if (gain) q += ((o0[0] * o0[0] + o0[1] * o0[1]) + (o0[2] * o0[2] + o0[3] * o0[3])) + ((o1[0] * o1[0] + o1[1] * o1[1]) + (o1[2] * o1[2] + o1[3] * o1[3])); }
;                     if (gain) { q = fq_sum(q); if (fq == 0) lq[wc * 256 + ai * HALF + wr * 64 + m * 16 + fr] = q; } }
	v_lshlrev_b32_e32 v210, 16, v160
	v_and_b32_e32 v160, 0xffff0000, v160
	v_add_f32_e32 v166, 1.0, v166
	v_rcp_f32_e32 v166, v166
	s_nop 0
	v_fmac_f32_e32 v203, v166, v168
	v_mul_f32_e32 v166, v72, v199
	v_mul_f32_e32 v166, 0xbfb8aa3b, v166
	v_min_f32_e32 v166, 0x42a00000, v166
	v_exp_f32_e32 v166, v166
	s_nop 0
	v_add_f32_e32 v166, 1.0, v166
	v_rcp_f32_e32 v166, v166
	s_nop 0
	v_fmac_f32_e32 v170, v166, v209
	v_mul_f32_e32 v166, v68, v199
	v_mul_f32_e32 v166, 0xbfb8aa3b, v166
	v_min_f32_e32 v166, 0x42a00000, v166
	v_exp_f32_e32 v166, v166
	v_lshl_add_u64 v[208:209], v[180:181], 1, v[184:185]
	v_and_b32_e32 v184, 0xffff0000, v162
	v_lshlrev_b32_e32 v185, 16, v159
	v_add_f32_e32 v166, 1.0, v166
	v_rcp_f32_e32 v166, v166
	v_and_b32_e32 v159, 0xffff0000, v159
	v_fmac_f32_e32 v172, v166, v211
	v_mul_f32_e32 v166, v73, v199
	v_mul_f32_e32 v166, 0xbfb8aa3b, v166
	v_min_f32_e32 v166, 0x42a00000, v166
	v_exp_f32_e32 v166, v166
	v_lshlrev_b32_e32 v211, 16, v161
	v_and_b32_e32 v161, 0xffff0000, v161
	v_add_f32_e32 v166, 1.0, v166
	v_rcp_f32_e32 v166, v166
	s_nop 0
	v_fmac_f32_e32 v171, v166, v167
	v_mul_f32_e32 v166, v69, v199
	v_mul_f32_e32 v166, 0xbfb8aa3b, v166
	v_min_f32_e32 v166, 0x42a00000, v166
	v_exp_f32_e32 v166, v166
	s_nop 0
	v_add_f32_e32 v166, 1.0, v166
	v_rcp_f32_e32 v166, v166
	s_nop 0
	v_fmac_f32_e32 v173, v166, v169
	v_cvt_pk_bf16_f32 v166, v200, v201
	v_cvt_pk_bf16_f32 v167, v170, v171
	v_cvt_pk_bf16_f32 v168, v202, v203
	v_cvt_pk_bf16_f32 v169, v172, v173
	global_store_dwordx4 v[208:209], v[166:169], off sc0 sc1
	s_nop 1
	v_lshlrev_b32_e32 v167, 16, v162
	v_lshlrev_b32_e32 v166, 16, v163
	v_and_b32_e32 v169, 0xffff0000, v163
	v_lshlrev_b32_e32 v163, 16, v164
	v_and_b32_e32 v168, 0xffff0000, v164
	v_lshlrev_b32_e32 v162, 16, v165
	v_and_b32_e32 v164, 0xffff0000, v165
	v_lshlrev_b32_e32 v165, 16, v158
	v_fmac_f32_e32 v167, v216, v165
	v_mul_f32_e32 v165, v46, v199
	v_mul_f32_e32 v165, 0xbfb8aa3b, v165
	v_min_f32_e32 v165, 0x42a00000, v165
	v_exp_f32_e32 v165, v165
	v_and_b32_e32 v158, 0xffff0000, v158
	v_add_f32_e32 v165, 1.0, v165
	v_rcp_f32_e32 v165, v165
	s_nop 0
	v_fmac_f32_e32 v163, v165, v210
	v_mul_f32_e32 v165, v55, v199
	v_mul_f32_e32 v165, 0xbfb8aa3b, v165
	v_min_f32_e32 v165, 0x42a00000, v165
	v_exp_f32_e32 v165, v165
	s_nop 0
	v_add_f32_e32 v165, 1.0, v165
	v_rcp_f32_e32 v165, v165
	s_nop 0
	v_fmac_f32_e32 v184, v165, v158
	v_mul_f32_e32 v158, v47, v199
	v_mul_f32_e32 v158, 0xbfb8aa3b, v158
	v_min_f32_e32 v158, 0x42a00000, v158
	v_exp_f32_e32 v158, v158
	s_nop 0
	v_add_f32_e32 v158, 1.0, v158
	v_rcp_f32_e32 v158, v158
	s_nop 0
	v_fmac_f32_e32 v168, v158, v160
	v_mul_f32_e32 v158, v56, v199
	v_mul_f32_e32 v158, 0xbfb8aa3b, v158
	v_min_f32_e32 v158, 0x42a00000, v158
	v_exp_f32_e32 v158, v158
	s_nop 0
	v_add_f32_e32 v158, 1.0, v158
	v_rcp_f32_e32 v158, v158
	s_nop 0
	v_fmac_f32_e32 v166, v158, v185
	v_mul_f32_e32 v158, v48, v199
	v_mul_f32_e32 v158, 0xbfb8aa3b, v158
	v_min_f32_e32 v158, 0x42a00000, v158
	v_exp_f32_e32 v158, v158
	s_nop 0
	v_add_f32_e32 v158, 1.0, v158
	v_rcp_f32_e32 v158, v158
	s_nop 0
	v_fmac_f32_e32 v162, v158, v211
	v_mul_f32_e32 v158, v57, v199
	v_mul_f32_e32 v158, 0xbfb8aa3b, v158
	v_min_f32_e32 v158, 0x42a00000, v158
	v_exp_f32_e32 v158, v158
	s_nop 0
	v_add_f32_e32 v158, 1.0, v158
	v_rcp_f32_e32 v158, v158
	s_nop 0
	v_fmac_f32_e32 v169, v158, v159
	v_mul_f32_e32 v158, v49, v199
	v_mul_f32_e32 v158, 0xbfb8aa3b, v158
	v_min_f32_e32 v158, 0x42a00000, v158
	v_exp_f32_e32 v158, v158
	s_nop 0
	v_add_f32_e32 v158, 1.0, v158
	v_rcp_f32_e32 v158, v158
	s_nop 0
	v_fmac_f32_e32 v164, v158, v161
	v_cvt_pk_bf16_f32 v158, v167, v184
	v_cvt_pk_bf16_f32 v159, v166, v169
	v_cvt_pk_bf16_f32 v160, v163, v168
	v_cvt_pk_bf16_f32 v161, v162, v164
	global_store_dwordx4 v[208:209], v[158:161], off offset:256 sc0 sc1
	s_cbranch_vccnz .LBB0_967
	s_nop 0
	v_mul_f32_e32 v158, v203, v203
	v_mul_f32_e32 v159, v173, v173
	v_fmac_f32_e32 v158, v202, v202
	v_fmac_f32_e32 v159, v172, v172
	v_add_f32_e32 v158, v158, v159
	v_mul_f32_e32 v159, v201, v201
	v_mul_f32_e32 v160, v171, v171
	v_fmac_f32_e32 v159, v200, v200
	v_fmac_f32_e32 v160, v170, v170
	v_add_f32_e32 v159, v159, v160
	v_add_f32_e32 v158, v159, v158
	v_mul_f32_e32 v159, v184, v184
	v_mul_f32_e32 v160, v169, v169
	v_fmac_f32_e32 v159, v167, v167
	v_fmac_f32_e32 v160, v166, v166
	v_add_f32_e32 v159, v159, v160
	v_mul_f32_e32 v160, v168, v168
	v_mul_f32_e32 v161, v164, v164
	v_fmac_f32_e32 v160, v163, v163
	v_fmac_f32_e32 v161, v162, v162
	v_add_f32_e32 v160, v160, v161
	v_add_f32_e32 v159, v159, v160
	v_add_f32_e32 v158, v158, v159
	ds_swizzle_b32 v159, v158 offset:swizzle(SWAP,16)
	s_waitcnt lgkmcnt(0)
	v_add_f32_e32 v158, v158, v159
	v_mov_b32_e32 v159, v158
	s_nop 1
	v_permlane32_swap_b32_e32 v158, v159
	s_and_saveexec_b64 s[12:13], s[40:41]
	s_cbranch_execz .LBB0_966
	v_readlane_b32 s2, v254, 50
	v_add_f32_e32 v158, v158, v159
	s_nop 0
	v_lshl_add_u32 v160, v186, 2, s2
	ds_write_b32 v160, v158 offset:512

; __device__ __forceinline__ u32x4 pack8(const f32x4& a, const f32x4& b) { u32x4 w; w.x = cvt_pk_bf16(a[0], a[1]); w.y = cvt_pk_bf16(a[2], a[3]); w.z = cvt_pk_bf16(b[0], b[1]); w.w = cvt_pk_bf16(b[2], b[3]); return w; }
; __device__ __forceinline__ float expneg(float g) { return ex2(fminf(-g * 1.4426950408889634f, 80.f)); }
; __device__ __forceinline__ float ss_total(const u32x4 a) { return ((bflo(a.x) + bfhi(a.x)) + (bflo(a.y) + bfhi(a.y))) + ((bflo(a.z) + bfhi(a.z)) + (bflo(a.w) + bfhi(a.w))); }
;     __device__ __forceinline__ void operator()(const f32x4 (&acc)[2][2][4][2], const Unit& u, int wr, int wc, int fr, int fq) const {
;     ...
;                 for (int m2 = 0; m2 < 2; ++m2) { const int m = mh * 2 + m2, row = rowt + ai * HALF + m * 16; float q = 0.f;
;                     const float rs = __builtin_amdgcn_rsqf(ss_total(sa[m2]) * (1.f / 2048.f) + 1e-6f);
; #pragma unroll
;                     for (int bj = 0; bj < 2; ++bj) { const int col = col0 + bj * HALF; const u32x4 xw = xv[m2][bj], pw = pv[m2][bj];
;                         const f32x4 x0 = {bflo(xw.x), bfhi(xw.x), bflo(xw.y), bfhi(xw.y)}, x1 = {bflo(xw.z), bfhi(xw.z), bflo(xw.w), bfhi(xw.w)};
;                         const f32x4 p0 = {bflo(pw.x), bfhi(pw.x), bflo(pw.y), bfhi(pw.y)}, p1 = {bflo(pw.z), bfhi(pw.z), bflo(pw.w), bfhi(pw.w)};
;                         const f32x4 a0 = acc[ai][bj][m][0], a1 = acc[ai][bj][m][1]; f32x4 o0, o1;
; #pragma unroll
;                         for (int i = 0; i < 4; ++i) { o0[i] = x0[i] + p0[i] * __builtin_amdgcn_rcpf(1.f + expneg(a0[i] * rs)); o1[i] = x1[i] + p1[i] * __builtin_amdgcn_rcpf(1.f + expneg(a1[i] * rs)); }
;                         *(u32x4*)(X + (size_t)row * 2048 + col) = pack8(o0, o1);
;                         if (gain) q += ((o0[0] * o0[0] + o0[1] * o0[1]) + (o0[2] * o0[2] + o0[3] * o0[3])) + ((o1[0] * o1[0] + o1[1] * o1[1]) + (o1[2] * o1[2] + o1[3] * o1[3])); }
.LBB0_967:
	s_waitcnt vmcnt(6)
	v_lshlrev_b32_e32 v158, 16, v154
	v_and_b32_e32 v154, 0xffff0000, v154
	v_add_f32_e32 v154, v158, v154
	v_lshlrev_b32_e32 v158, 16, v155
	v_and_b32_e32 v155, 0xffff0000, v155
	v_add_f32_e32 v155, v158, v155
	v_add_f32_e32 v154, v154, v155
	v_lshlrev_b32_e32 v155, 16, v156
	v_and_b32_e32 v156, 0xffff0000, v156
	v_add_f32_e32 v155, v155, v156
	v_lshlrev_b32_e32 v156, 16, v157
	v_and_b32_e32 v157, 0xffff0000, v157
	v_add_f32_e32 v156, v156, v157
	v_add_f32_e32 v155, v155, v156
	v_add_f32_e32 v154, v154, v155
	v_fmamk_f32 v154, v154, 0x3a000000, v1
	v_rsq_f32_e32 v162, v154
	s_waitcnt vmcnt(5)
	v_lshlrev_b32_e32 v154, 16, v150
	s_waitcnt vmcnt(4)
	v_lshlrev_b32_e32 v160, 16, v146
	v_lshlrev_b32_e32 v156, 16, v152
	v_mul_f32_e32 v165, v62, v162
	v_mul_f32_e32 v165, 0xbfb8aa3b, v165
	v_min_f32_e32 v165, 0x42a00000, v165
	v_exp_f32_e32 v165, v165
	v_lshlrev_b32_e32 v163, 16, v148
	v_and_b32_e32 v155, 0xffff0000, v150
	v_and_b32_e32 v146, 0xffff0000, v146
	v_add_f32_e32 v165, 1.0, v165
	v_rcp_f32_e32 v165, v165
	v_and_b32_e32 v157, 0xffff0000, v152
	v_and_b32_e32 v148, 0xffff0000, v148
	v_lshlrev_b32_e32 v150, 16, v151
	v_fmac_f32_e32 v154, v165, v160
	v_mul_f32_e32 v160, v58, v162
	v_mul_f32_e32 v160, 0xbfb8aa3b, v160
	v_min_f32_e32 v160, 0x42a00000, v160
	v_exp_f32_e32 v160, v160
	v_lshlrev_b32_e32 v161, 16, v147
	v_lshlrev_b32_e32 v152, 16, v153
	v_lshlrev_b32_e32 v164, 16, v149
	v_add_f32_e32 v160, 1.0, v160
	v_rcp_f32_e32 v160, v160
	v_and_b32_e32 v151, 0xffff0000, v151
	v_and_b32_e32 v147, 0xffff0000, v147
	v_mul_f32_e32 v165, v38, v162
	v_fmac_f32_e32 v156, v160, v163
	v_mul_f32_e32 v160, v63, v162
	v_mul_f32_e32 v160, 0xbfb8aa3b, v160
	v_min_f32_e32 v160, 0x42a00000, v160
	v_exp_f32_e32 v160, v160
	v_mul_f32_e32 v165, 0xbfb8aa3b, v165
	v_min_f32_e32 v165, 0x42a00000, v165
	v_exp_f32_e32 v165, v165
	v_add_f32_e32 v160, 1.0, v160
	v_rcp_f32_e32 v160, v160
	v_lshlrev_b64 v[158:159], 12, v[182:183]
	v_add_f32_e32 v165, 1.0, v165
	v_rcp_f32_e32 v165, v165
	v_fmac_f32_e32 v155, v160, v146
	v_mul_f32_e32 v146, v59, v162
	v_mul_f32_e32 v146, 0xbfb8aa3b, v146
	v_min_f32_e32 v146, 0x42a00000, v146
	v_exp_f32_e32 v146, v146
	v_and_b32_e32 v153, 0xffff0000, v153
	v_and_b32_e32 v149, 0xffff0000, v149
	v_lshl_add_u64 v[158:159], s[82:83], 0, v[158:159]
	v_add_f32_e32 v146, 1.0, v146
	v_rcp_f32_e32 v146, v146
	s_waitcnt vmcnt(2)
	v_lshlrev_b32_e32 v163, 16, v140
	v_and_b32_e32 v140, 0xffff0000, v140
	s_and_b64 vcc, exec, s[42:43]
	v_fmac_f32_e32 v157, v146, v148
	v_mul_f32_e32 v146, v64, v162
	v_mul_f32_e32 v146, 0xbfb8aa3b, v146
	v_min_f32_e32 v146, 0x42a00000, v146
	v_exp_f32_e32 v146, v146
	s_nop 0
	v_add_f32_e32 v146, 1.0, v146
	v_rcp_f32_e32 v146, v146
	s_nop 0
	v_fmac_f32_e32 v150, v146, v161
	v_mul_f32_e32 v146, v60, v162
	v_mul_f32_e32 v146, 0xbfb8aa3b, v146
	v_min_f32_e32 v146, 0x42a00000, v146
	v_exp_f32_e32 v146, v146
	v_lshl_add_u64 v[160:161], v[180:181], 1, v[158:159]
	v_and_b32_e32 v158, 0xffff0000, v142
	v_lshlrev_b32_e32 v159, 16, v139
	v_add_f32_e32 v146, 1.0, v146
	v_rcp_f32_e32 v146, v146
	v_and_b32_e32 v139, 0xffff0000, v139
	v_fmac_f32_e32 v152, v146, v164
	v_mul_f32_e32 v146, v65, v162
	v_mul_f32_e32 v146, 0xbfb8aa3b, v146
	v_min_f32_e32 v146, 0x42a00000, v146
	v_exp_f32_e32 v146, v146
	v_lshlrev_b32_e32 v164, 16, v141
	v_and_b32_e32 v141, 0xffff0000, v141
	v_add_f32_e32 v146, 1.0, v146
	v_rcp_f32_e32 v146, v146
	s_nop 0
	v_fmac_f32_e32 v151, v146, v147
	v_mul_f32_e32 v146, v61, v162
	v_mul_f32_e32 v146, 0xbfb8aa3b, v146
	v_min_f32_e32 v146, 0x42a00000, v146
	v_exp_f32_e32 v146, v146
	s_nop 0
	v_add_f32_e32 v146, 1.0, v146
	v_rcp_f32_e32 v146, v146
	s_nop 0
	v_fmac_f32_e32 v153, v146, v149
	v_cvt_pk_bf16_f32 v146, v154, v155
	v_cvt_pk_bf16_f32 v147, v150, v151
	v_cvt_pk_bf16_f32 v148, v156, v157
	v_cvt_pk_bf16_f32 v149, v152, v153
	global_store_dwordx4 v[160:161], v[146:149], off sc0 sc1
	s_nop 1
	v_lshlrev_b32_e32 v147, 16, v142
	v_lshlrev_b32_e32 v146, 16, v143
	v_and_b32_e32 v149, 0xffff0000, v143
	v_lshlrev_b32_e32 v143, 16, v144
	v_and_b32_e32 v148, 0xffff0000, v144
	v_lshlrev_b32_e32 v142, 16, v145
	v_and_b32_e32 v144, 0xffff0000, v145
	v_lshlrev_b32_e32 v145, 16, v138
	v_fmac_f32_e32 v147, v165, v145
	v_mul_f32_e32 v145, v30, v162
	v_mul_f32_e32 v145, 0xbfb8aa3b, v145
	v_min_f32_e32 v145, 0x42a00000, v145
	v_exp_f32_e32 v145, v145
	v_and_b32_e32 v138, 0xffff0000, v138
	v_add_f32_e32 v145, 1.0, v145
	v_rcp_f32_e32 v145, v145
	s_nop 0
	v_fmac_f32_e32 v143, v145, v163
	v_mul_f32_e32 v145, v39, v162
	v_mul_f32_e32 v145, 0xbfb8aa3b, v145
	v_min_f32_e32 v145, 0x42a00000, v145
	v_exp_f32_e32 v145, v145
	s_nop 0
	v_add_f32_e32 v145, 1.0, v145
	v_rcp_f32_e32 v145, v145
	s_nop 0
	v_fmac_f32_e32 v158, v145, v138
	v_mul_f32_e32 v138, v31, v162
	v_mul_f32_e32 v138, 0xbfb8aa3b, v138
	v_min_f32_e32 v138, 0x42a00000, v138
	v_exp_f32_e32 v138, v138
	s_nop 0
	v_add_f32_e32 v138, 1.0, v138
	v_rcp_f32_e32 v138, v138
	s_nop 0
	v_fmac_f32_e32 v148, v138, v140
	v_mul_f32_e32 v138, v40, v162
	v_mul_f32_e32 v138, 0xbfb8aa3b, v138
	v_min_f32_e32 v138, 0x42a00000, v138
	v_exp_f32_e32 v138, v138
	s_nop 0
	v_add_f32_e32 v138, 1.0, v138
	v_rcp_f32_e32 v138, v138
	s_nop 0
	v_fmac_f32_e32 v146, v138, v159
	v_mul_f32_e32 v138, v32, v162
	v_mul_f32_e32 v138, 0xbfb8aa3b, v138
	v_min_f32_e32 v138, 0x42a00000, v138
	v_exp_f32_e32 v138, v138
	s_nop 0
	v_add_f32_e32 v138, 1.0, v138
	v_rcp_f32_e32 v138, v138
	s_nop 0
	v_fmac_f32_e32 v142, v138, v164
	v_mul_f32_e32 v138, v41, v162
	v_mul_f32_e32 v138, 0xbfb8aa3b, v138
	v_min_f32_e32 v138, 0x42a00000, v138
	v_exp_f32_e32 v138, v138
	s_nop 0
	v_add_f32_e32 v138, 1.0, v138
	v_rcp_f32_e32 v138, v138
	s_nop 0
	v_fmac_f32_e32 v149, v138, v139
	v_mul_f32_e32 v138, v33, v162
	v_mul_f32_e32 v138, 0xbfb8aa3b, v138
	v_min_f32_e32 v138, 0x42a00000, v138
	v_exp_f32_e32 v138, v138
	s_nop 0
	v_add_f32_e32 v138, 1.0, v138
	v_rcp_f32_e32 v138, v138
	s_nop 0
	v_fmac_f32_e32 v144, v138, v141
	v_cvt_pk_bf16_f32 v138, v147, v158
	v_cvt_pk_bf16_f32 v139, v146, v149
	v_cvt_pk_bf16_f32 v140, v143, v148
	v_cvt_pk_bf16_f32 v141, v142, v144
	global_store_dwordx4 v[160:161], v[138:141], off offset:256 sc0 sc1
	s_cbranch_vccnz .LBB0_971
;     __device__ __forceinline__ void operator()(const f32x4 (&acc)[2][2][4][2], const Unit& u, int wr, int wc, int fr, int fq) const {
;     ...
;                         if (gain) q += ((o0[0] * o0[0] + o0[1] * o0[1]) + (o0[2] * o0[2] + o0[3] * o0[3])) + ((o1[0] * o1[0] + o1[1] * o1[1]) + (o1[2] * o1[2] + o1[3] * o1[3])); }
;                     if (gain) { q = fq_sum(q); if (fq == 0) lq[wc * 256 + ai * HALF + wr * 64 + m * 16 + fr] = q; } }
	s_nop 0
	v_mul_f32_e32 v138, v157, v157
	v_mul_f32_e32 v139, v153, v153
	v_fmac_f32_e32 v138, v156, v156
	v_fmac_f32_e32 v139, v152, v152
	v_add_f32_e32 v138, v138, v139
	v_mul_f32_e32 v139, v155, v155
	v_mul_f32_e32 v140, v151, v151
	v_fmac_f32_e32 v139, v154, v154
	v_fmac_f32_e32 v140, v150, v150
	v_add_f32_e32 v139, v139, v140
	v_add_f32_e32 v138, v139, v138
	v_mul_f32_e32 v139, v158, v158
	v_mul_f32_e32 v140, v149, v149
	v_fmac_f32_e32 v139, v147, v147
	v_fmac_f32_e32 v140, v146, v146
	v_add_f32_e32 v139, v139, v140
	v_mul_f32_e32 v140, v148, v148
	v_mul_f32_e32 v141, v144, v144
	v_fmac_f32_e32 v140, v143, v143
	v_fmac_f32_e32 v141, v142, v142
	v_add_f32_e32 v140, v140, v141
	v_add_f32_e32 v139, v139, v140
	v_add_f32_e32 v138, v138, v139
	ds_swizzle_b32 v139, v138 offset:swizzle(SWAP,16)
	s_waitcnt lgkmcnt(0)
	v_add_f32_e32 v138, v138, v139
	v_mov_b32_e32 v139, v138
	s_nop 1
	v_permlane32_swap_b32_e32 v138, v139
	s_and_saveexec_b64 s[12:13], s[40:41]
	s_cbranch_execz .LBB0_970
	v_readlane_b32 s2, v254, 50
	v_add_f32_e32 v138, v138, v139
	s_nop 0
	v_lshl_add_u32 v140, v186, 2, s2
	ds_write_b32 v140, v138 offset:576

; __device__ __forceinline__ float expneg(float g) { return ex2(fminf(-g * 1.4426950408889634f, 80.f)); }
; __device__ __forceinline__ float ss_total(const u32x4 a) { return ((bflo(a.x) + bfhi(a.x)) + (bflo(a.y) + bfhi(a.y))) + ((bflo(a.z) + bfhi(a.z)) + (bflo(a.w) + bfhi(a.w))); }
;     __device__ __forceinline__ void operator()(const f32x4 (&acc)[2][2][4][2], const Unit& u, int wr, int wc, int fr, int fq) const {
;     ...
;                 for (int m2 = 0; m2 < 2; ++m2) { const int row = rowt + ai * HALF + (mh * 2 + m2) * 16; sa[m2] = *(const u32x4*)(ss3 + (size_t)row * 8);
; #pragma unroll
;                     for (int bj = 0; bj < 2; ++bj) { const size_t o_ = (size_t)row * 2048 + col0 + bj * HALF; xv[m2][bj] = *(const u32x4*)(X + o_); pv[m2][bj] = *(const u32x4*)(PP + o_); } }
;                 asm volatile("" ::: "memory");
; #pragma unroll
;                 for (int m2 = 0; m2 < 2; ++m2) { const int m = mh * 2 + m2, row = rowt + ai * HALF + m * 16; float q = 0.f;
;                     const float rs = __builtin_amdgcn_rsqf(ss_total(sa[m2]) * (1.f / 2048.f) + 1e-6f);
; #pragma unroll
;                     for (int bj = 0; bj < 2; ++bj) { const int col = col0 + bj * HALF; const u32x4 xw = xv[m2][bj], pw = pv[m2][bj];
;                         const f32x4 x0 = {bflo(xw.x), bfhi(xw.x), bflo(xw.y), bfhi(xw.y)}, x1 = {bflo(xw.z), bfhi(xw.z), bflo(xw.w), bfhi(xw.w)};
;                         const f32x4 p0 = {bflo(pw.x), bfhi(pw.x), bflo(pw.y), bfhi(pw.y)}, p1 = {bflo(pw.z), bfhi(pw.z), bflo(pw.w), bfhi(pw.w)};
;                         const f32x4 a0 = acc[ai][bj][m][0], a1 = acc[ai][bj][m][1]; f32x4 o0, o1;
; #pragma unroll
;                         for (int i = 0; i < 4; ++i) { o0[i] = x0[i] + p0[i] * __builtin_amdgcn_rcpf(1.f + expneg(a0[i] * rs)); o1[i] = x1[i] + p1[i] * __builtin_amdgcn_rcpf(1.f + expneg(a1[i] * rs)); }
.LBB0_971:
	v_add_u32_e32 v184, 0xa0, v174
	v_ashrrev_i32_e32 v185, 31, v184
	v_lshl_add_u64 v[138:139], v[184:185], 4, s[86:87]
	global_load_dwordx4 v[200:203], v[138:139], off
	v_lshlrev_b64 v[138:139], 11, v[184:185]
	v_lshl_add_u64 v[138:139], v[138:139], 0, v[180:181]
	v_lshlrev_b64 v[138:139], 1, v[138:139]
	v_lshl_add_u64 v[140:141], s[82:83], 0, v[138:139]
	global_load_dwordx4 v[170:173], v[140:141], off
	v_lshl_add_u64 v[140:141], s[84:85], 0, v[138:139]
	global_load_dwordx4 v[166:169], v[140:141], off
	v_or_b32_e32 v138, 0x100, v138
	v_lshl_add_u64 v[140:141], s[82:83], 0, v[138:139]
	v_lshl_add_u64 v[138:139], s[84:85], 0, v[138:139]
	global_load_dwordx4 v[162:165], v[140:141], off
	global_load_dwordx4 v[158:161], v[138:139], off
	v_add_u32_e32 v182, 0xb0, v174
	v_ashrrev_i32_e32 v183, 31, v182
	v_lshl_add_u64 v[138:139], v[182:183], 4, s[86:87]
	global_load_dwordx4 v[154:157], v[138:139], off
	v_lshlrev_b64 v[138:139], 11, v[182:183]
	v_lshl_add_u64 v[138:139], v[138:139], 0, v[180:181]
	v_lshlrev_b64 v[138:139], 1, v[138:139]
	v_lshl_add_u64 v[140:141], s[82:83], 0, v[138:139]
	global_load_dwordx4 v[150:153], v[140:141], off
	v_lshl_add_u64 v[140:141], s[84:85], 0, v[138:139]
	v_or_b32_e32 v138, 0x100, v138
	v_lshlrev_b64 v[184:185], 12, v[184:185]
	global_load_dwordx4 v[146:149], v[140:141], off
	v_lshl_add_u64 v[140:141], s[82:83], 0, v[138:139]
	v_lshl_add_u64 v[138:139], s[84:85], 0, v[138:139]
	v_lshl_add_u64 v[184:185], s[82:83], 0, v[184:185]
	global_load_dwordx4 v[142:145], v[140:141], off
	s_and_b64 vcc, exec, s[42:43]
	global_load_dwordx4 v[138:141], v[138:139], off
	s_waitcnt vmcnt(9)
	v_lshlrev_b32_e32 v199, 16, v200
	v_and_b32_e32 v200, 0xffff0000, v200
	v_add_f32_e32 v199, v199, v200
	v_lshlrev_b32_e32 v200, 16, v201
	v_and_b32_e32 v201, 0xffff0000, v201
	v_add_f32_e32 v200, v200, v201
	v_add_f32_e32 v199, v199, v200
	v_lshlrev_b32_e32 v200, 16, v202
	v_and_b32_e32 v201, 0xffff0000, v202
	v_add_f32_e32 v200, v200, v201
	v_lshlrev_b32_e32 v201, 16, v203
	v_and_b32_e32 v202, 0xffff0000, v203
	v_add_f32_e32 v201, v201, v202
	v_add_f32_e32 v200, v200, v201
	v_add_f32_e32 v199, v199, v200
	v_fmamk_f32 v199, v199, 0x3a000000, v1
	v_rsq_f32_e32 v199, v199
	s_waitcnt vmcnt(8)
	v_lshlrev_b32_e32 v200, 16, v170
	s_waitcnt vmcnt(7)
	v_lshlrev_b32_e32 v208, 16, v166
	v_lshlrev_b32_e32 v202, 16, v172
	v_mul_f32_e32 v216, v50, v199
	v_mul_f32_e32 v216, 0xbfb8aa3b, v216
	v_min_f32_e32 v216, 0x42a00000, v216
	v_exp_f32_e32 v216, v216
	v_lshlrev_b32_e32 v210, 16, v168
	v_and_b32_e32 v201, 0xffff0000, v170
	v_and_b32_e32 v166, 0xffff0000, v166
	v_add_f32_e32 v216, 1.0, v216
	v_rcp_f32_e32 v216, v216
	v_and_b32_e32 v203, 0xffff0000, v172
	v_and_b32_e32 v168, 0xffff0000, v168
	v_lshlrev_b32_e32 v170, 16, v171
	v_fmac_f32_e32 v200, v216, v208
	v_mul_f32_e32 v208, v42, v199
	v_mul_f32_e32 v208, 0xbfb8aa3b, v208
	v_min_f32_e32 v208, 0x42a00000, v208
	v_exp_f32_e32 v208, v208
	v_lshlrev_b32_e32 v209, 16, v167
	v_lshlrev_b32_e32 v172, 16, v173
	v_lshlrev_b32_e32 v211, 16, v169
	v_add_f32_e32 v208, 1.0, v208
	v_rcp_f32_e32 v208, v208
	v_and_b32_e32 v171, 0xffff0000, v171
	v_and_b32_e32 v167, 0xffff0000, v167
	v_mul_f32_e32 v216, v22, v199
	v_fmac_f32_e32 v202, v208, v210
	v_mul_f32_e32 v208, v51, v199
	v_mul_f32_e32 v208, 0xbfb8aa3b, v208
	v_min_f32_e32 v208, 0x42a00000, v208
	v_exp_f32_e32 v208, v208
	v_mul_f32_e32 v216, 0xbfb8aa3b, v216
	v_min_f32_e32 v216, 0x42a00000, v216
	v_exp_f32_e32 v216, v216
	v_add_f32_e32 v208, 1.0, v208
	v_rcp_f32_e32 v208, v208
	v_and_b32_e32 v173, 0xffff0000, v173
	v_add_f32_e32 v216, 1.0, v216
	v_rcp_f32_e32 v216, v216
	v_fmac_f32_e32 v201, v208, v166
	v_mul_f32_e32 v166, v43, v199
	v_mul_f32_e32 v166, 0xbfb8aa3b, v166
	v_min_f32_e32 v166, 0x42a00000, v166
	v_exp_f32_e32 v166, v166
	v_and_b32_e32 v169, 0xffff0000, v169
	s_waitcnt vmcnt(5)
; __device__ __forceinline__ u32x4 pack8(const f32x4& a, const f32x4& b) { u32x4 w; w.x = cvt_pk_bf16(a[0], a[1]); w.y = cvt_pk_bf16(a[2], a[3]); w.z = cvt_pk_bf16(b[0], b[1]); w.w = cvt_pk_bf16(b[2], b[3]); return w; }
; __device__ __forceinline__ float expneg(float g) { return ex2(fminf(-g * 1.4426950408889634f, 80.f)); }
;     __device__ __forceinline__ void operator()(const f32x4 (&acc)[2][2][4][2], const Unit& u, int wr, int wc, int fr, int fq) const {
;     ...
;                     for (int bj = 0; bj < 2; ++bj) { const int col = col0 + bj * HALF; const u32x4 xw = xv[m2][bj], pw = pv[m2][bj];
;                         const f32x4 x0 = {bflo(xw.x), bfhi(xw.x), bflo(xw.y), bfhi(xw.y)}, x1 = {bflo(xw.z), bfhi(xw.z), bflo(xw.w), bfhi(xw.w)};
;                         const f32x4 p0 = {bflo(pw.x), bfhi(pw.x), bflo(pw.y), bfhi(pw.y)}, p1 = {bflo(pw.z), bfhi(pw.z), bflo(pw.w), bfhi(pw.w)};
;                         const f32x4 a0 = acc[ai][bj][m][0], a1 = acc[ai][bj][m][1]; f32x4 o0, o1;
; #pragma unroll
;                         for (int i = 0; i < 4; ++i) { o0[i] = x0[i] + p0[i] * __builtin_amdgcn_rcpf(1.f + expneg(a0[i] * rs)); o1[i] = x1[i] + p1[i] * __builtin_amdgcn_rcpf(1.f + expneg(a1[i] * rs)); }
;                         *(u32x4*)(X + (size_t)row * 2048 + col) = pack8(o0, o1);
;                         if (gain) q += ((o0[0] * o0[0] + o0[1] * o0[1]) + (o0[2] * o0[2] + o0[3] * o0[3])) + ((o1[0] * o1[0] + o1[1] * o1[1]) + (o1[2] * o1[2] + o1[3] * o1[3])); }
;                     if (gain) { q = fq_sum(q); if (fq == 0) lq[wc * 256 + ai * HALF + wr * 64 + m * 16 + fr] = q; } }
	v_lshlrev_b32_e32 v210, 16, v160
	v_and_b32_e32 v160, 0xffff0000, v160
	v_add_f32_e32 v166, 1.0, v166
	v_rcp_f32_e32 v166, v166
	s_nop 0
	v_fmac_f32_e32 v203, v166, v168
	v_mul_f32_e32 v166, v52, v199
	v_mul_f32_e32 v166, 0xbfb8aa3b, v166
	v_min_f32_e32 v166, 0x42a00000, v166
	v_exp_f32_e32 v166, v166
	s_nop 0
	v_add_f32_e32 v166, 1.0, v166
	v_rcp_f32_e32 v166, v166
	s_nop 0
	v_fmac_f32_e32 v170, v166, v209
	v_mul_f32_e32 v166, v44, v199
	v_mul_f32_e32 v166, 0xbfb8aa3b, v166
	v_min_f32_e32 v166, 0x42a00000, v166
	v_exp_f32_e32 v166, v166
	v_lshl_add_u64 v[208:209], v[180:181], 1, v[184:185]
	v_and_b32_e32 v184, 0xffff0000, v162
	v_lshlrev_b32_e32 v185, 16, v159
	v_add_f32_e32 v166, 1.0, v166
	v_rcp_f32_e32 v166, v166
	v_and_b32_e32 v159, 0xffff0000, v159
	v_fmac_f32_e32 v172, v166, v211
	v_mul_f32_e32 v166, v53, v199
	v_mul_f32_e32 v166, 0xbfb8aa3b, v166
	v_min_f32_e32 v166, 0x42a00000, v166
	v_exp_f32_e32 v166, v166
	v_lshlrev_b32_e32 v211, 16, v161
	v_and_b32_e32 v161, 0xffff0000, v161
	v_add_f32_e32 v166, 1.0, v166
	v_rcp_f32_e32 v166, v166
	s_nop 0
	v_fmac_f32_e32 v171, v166, v167
	v_mul_f32_e32 v166, v45, v199
	v_mul_f32_e32 v166, 0xbfb8aa3b, v166
	v_min_f32_e32 v166, 0x42a00000, v166
	v_exp_f32_e32 v166, v166
	s_nop 0
	v_add_f32_e32 v166, 1.0, v166
	v_rcp_f32_e32 v166, v166
	s_nop 0
	v_fmac_f32_e32 v173, v166, v169
	v_cvt_pk_bf16_f32 v166, v200, v201
	v_cvt_pk_bf16_f32 v167, v170, v171
	v_cvt_pk_bf16_f32 v168, v202, v203
	v_cvt_pk_bf16_f32 v169, v172, v173
	global_store_dwordx4 v[208:209], v[166:169], off sc0 sc1
	s_nop 1
	v_lshlrev_b32_e32 v167, 16, v162
	v_lshlrev_b32_e32 v166, 16, v163
	v_and_b32_e32 v169, 0xffff0000, v163
	v_lshlrev_b32_e32 v163, 16, v164
	v_and_b32_e32 v168, 0xffff0000, v164
	v_lshlrev_b32_e32 v162, 16, v165
	v_and_b32_e32 v164, 0xffff0000, v165
	v_lshlrev_b32_e32 v165, 16, v158
	v_fmac_f32_e32 v167, v216, v165
	v_mul_f32_e32 v165, v18, v199
	v_mul_f32_e32 v165, 0xbfb8aa3b, v165
	v_min_f32_e32 v165, 0x42a00000, v165
	v_exp_f32_e32 v165, v165
	v_and_b32_e32 v158, 0xffff0000, v158
	v_add_f32_e32 v165, 1.0, v165
	v_rcp_f32_e32 v165, v165
	s_nop 0
	v_fmac_f32_e32 v163, v165, v210
	v_mul_f32_e32 v165, v23, v199
	v_mul_f32_e32 v165, 0xbfb8aa3b, v165
	v_min_f32_e32 v165, 0x42a00000, v165
	v_exp_f32_e32 v165, v165
	s_nop 0
	v_add_f32_e32 v165, 1.0, v165
	v_rcp_f32_e32 v165, v165
	s_nop 0
	v_fmac_f32_e32 v184, v165, v158
	v_mul_f32_e32 v158, v19, v199
	v_mul_f32_e32 v158, 0xbfb8aa3b, v158
	v_min_f32_e32 v158, 0x42a00000, v158
	v_exp_f32_e32 v158, v158
	s_nop 0
	v_add_f32_e32 v158, 1.0, v158
	v_rcp_f32_e32 v158, v158
	s_nop 0
	v_fmac_f32_e32 v168, v158, v160
	v_mul_f32_e32 v158, v24, v199
	v_mul_f32_e32 v158, 0xbfb8aa3b, v158
	v_min_f32_e32 v158, 0x42a00000, v158
	v_exp_f32_e32 v158, v158
	s_nop 0
	v_add_f32_e32 v158, 1.0, v158
	v_rcp_f32_e32 v158, v158
	s_nop 0
	v_fmac_f32_e32 v166, v158, v185
	v_mul_f32_e32 v158, v20, v199
	v_mul_f32_e32 v158, 0xbfb8aa3b, v158
	v_min_f32_e32 v158, 0x42a00000, v158
	v_exp_f32_e32 v158, v158
	s_nop 0
	v_add_f32_e32 v158, 1.0, v158
	v_rcp_f32_e32 v158, v158
	s_nop 0
	v_fmac_f32_e32 v162, v158, v211
	v_mul_f32_e32 v158, v25, v199
	v_mul_f32_e32 v158, 0xbfb8aa3b, v158
	v_min_f32_e32 v158, 0x42a00000, v158
	v_exp_f32_e32 v158, v158
	s_nop 0
	v_add_f32_e32 v158, 1.0, v158
	v_rcp_f32_e32 v158, v158
	s_nop 0
	v_fmac_f32_e32 v169, v158, v159
	v_mul_f32_e32 v158, v21, v199
	v_mul_f32_e32 v158, 0xbfb8aa3b, v158
	v_min_f32_e32 v158, 0x42a00000, v158
	v_exp_f32_e32 v158, v158
	s_nop 0
	v_add_f32_e32 v158, 1.0, v158
	v_rcp_f32_e32 v158, v158
	s_nop 0
	v_fmac_f32_e32 v164, v158, v161
	v_cvt_pk_bf16_f32 v158, v167, v184
	v_cvt_pk_bf16_f32 v159, v166, v169
	v_cvt_pk_bf16_f32 v160, v163, v168
	v_cvt_pk_bf16_f32 v161, v162, v164
	global_store_dwordx4 v[208:209], v[158:161], off offset:256 sc0 sc1
	s_cbranch_vccnz .LBB0_975
	s_nop 0
	v_mul_f32_e32 v158, v203, v203
	v_mul_f32_e32 v159, v173, v173
	v_fmac_f32_e32 v158, v202, v202
	v_fmac_f32_e32 v159, v172, v172
	v_add_f32_e32 v158, v158, v159
	v_mul_f32_e32 v159, v201, v201
	v_mul_f32_e32 v160, v171, v171
	v_fmac_f32_e32 v159, v200, v200
	v_fmac_f32_e32 v160, v170, v170
	v_add_f32_e32 v159, v159, v160
	v_add_f32_e32 v158, v159, v158
	v_mul_f32_e32 v159, v184, v184
	v_mul_f32_e32 v160, v169, v169
	v_fmac_f32_e32 v159, v167, v167
	v_fmac_f32_e32 v160, v166, v166
	v_add_f32_e32 v159, v159, v160
	v_mul_f32_e32 v160, v168, v168
	v_mul_f32_e32 v161, v164, v164
	v_fmac_f32_e32 v160, v163, v163
	v_fmac_f32_e32 v161, v162, v162
	v_add_f32_e32 v160, v160, v161
	v_add_f32_e32 v159, v159, v160
	v_add_f32_e32 v158, v158, v159
	ds_swizzle_b32 v159, v158 offset:swizzle(SWAP,16)
	s_waitcnt lgkmcnt(0)
	v_add_f32_e32 v158, v158, v159
	v_mov_b32_e32 v159, v158
	s_nop 1
	v_permlane32_swap_b32_e32 v158, v159
	s_and_saveexec_b64 s[12:13], s[40:41]
	s_cbranch_execz .LBB0_974
	v_readlane_b32 s2, v254, 50
	v_add_f32_e32 v158, v158, v159
	s_nop 0
	v_lshl_add_u32 v160, v186, 2, s2
	ds_write_b32 v160, v158 offset:640

; __device__ __forceinline__ u32x4 pack8(const f32x4& a, const f32x4& b) { u32x4 w; w.x = cvt_pk_bf16(a[0], a[1]); w.y = cvt_pk_bf16(a[2], a[3]); w.z = cvt_pk_bf16(b[0], b[1]); w.w = cvt_pk_bf16(b[2], b[3]); return w; }
; __device__ __forceinline__ float expneg(float g) { return ex2(fminf(-g * 1.4426950408889634f, 80.f)); }
; __device__ __forceinline__ float ss_total(const u32x4 a) { return ((bflo(a.x) + bfhi(a.x)) + (bflo(a.y) + bfhi(a.y))) + ((bflo(a.z) + bfhi(a.z)) + (bflo(a.w) + bfhi(a.w))); }
;     __device__ __forceinline__ void operator()(const f32x4 (&acc)[2][2][4][2], const Unit& u, int wr, int wc, int fr, int fq) const {
;     ...
;                 for (int m2 = 0; m2 < 2; ++m2) { const int m = mh * 2 + m2, row = rowt + ai * HALF + m * 16; float q = 0.f;
;                     const float rs = __builtin_amdgcn_rsqf(ss_total(sa[m2]) * (1.f / 2048.f) + 1e-6f);
; #pragma unroll
;                     for (int bj = 0; bj < 2; ++bj) { const int col = col0 + bj * HALF; const u32x4 xw = xv[m2][bj], pw = pv[m2][bj];
;                         const f32x4 x0 = {bflo(xw.x), bfhi(xw.x), bflo(xw.y), bfhi(xw.y)}, x1 = {bflo(xw.z), bfhi(xw.z), bflo(xw.w), bfhi(xw.w)};
;                         const f32x4 p0 = {bflo(pw.x), bfhi(pw.x), bflo(pw.y), bfhi(pw.y)}, p1 = {bflo(pw.z), bfhi(pw.z), bflo(pw.w), bfhi(pw.w)};
;                         const f32x4 a0 = acc[ai][bj][m][0], a1 = acc[ai][bj][m][1]; f32x4 o0, o1;
; #pragma unroll
;                         for (int i = 0; i < 4; ++i) { o0[i] = x0[i] + p0[i] * __builtin_amdgcn_rcpf(1.f + expneg(a0[i] * rs)); o1[i] = x1[i] + p1[i] * __builtin_amdgcn_rcpf(1.f + expneg(a1[i] * rs)); }
;                         *(u32x4*)(X + (size_t)row * 2048 + col) = pack8(o0, o1);
;                         if (gain) q += ((o0[0] * o0[0] + o0[1] * o0[1]) + (o0[2] * o0[2] + o0[3] * o0[3])) + ((o1[0] * o1[0] + o1[1] * o1[1]) + (o1[2] * o1[2] + o1[3] * o1[3])); }
.LBB0_975:
	s_waitcnt vmcnt(6)
	v_lshlrev_b32_e32 v158, 16, v154
	v_and_b32_e32 v154, 0xffff0000, v154
	v_add_f32_e32 v154, v158, v154
	v_lshlrev_b32_e32 v158, 16, v155
	v_and_b32_e32 v155, 0xffff0000, v155
	v_add_f32_e32 v155, v158, v155
	v_add_f32_e32 v154, v154, v155
	v_lshlrev_b32_e32 v155, 16, v156
	v_and_b32_e32 v156, 0xffff0000, v156
	v_add_f32_e32 v155, v155, v156
	v_lshlrev_b32_e32 v156, 16, v157
	v_and_b32_e32 v157, 0xffff0000, v157
	v_add_f32_e32 v156, v156, v157
	v_add_f32_e32 v155, v155, v156
	v_add_f32_e32 v154, v154, v155
	v_fmamk_f32 v154, v154, 0x3a000000, v1
	v_rsq_f32_e32 v162, v154
	s_waitcnt vmcnt(5)
	v_lshlrev_b32_e32 v154, 16, v150
	s_waitcnt vmcnt(4)
	v_lshlrev_b32_e32 v160, 16, v146
	v_lshlrev_b32_e32 v156, 16, v152
	v_mul_f32_e32 v165, v34, v162
	v_mul_f32_e32 v165, 0xbfb8aa3b, v165
	v_min_f32_e32 v165, 0x42a00000, v165
	v_exp_f32_e32 v165, v165
	v_lshlrev_b32_e32 v163, 16, v148
	v_and_b32_e32 v155, 0xffff0000, v150
	v_and_b32_e32 v146, 0xffff0000, v146
	v_add_f32_e32 v165, 1.0, v165
	v_rcp_f32_e32 v165, v165
	v_and_b32_e32 v157, 0xffff0000, v152
	v_and_b32_e32 v148, 0xffff0000, v148
	v_lshlrev_b32_e32 v150, 16, v151
	v_fmac_f32_e32 v154, v165, v160
	v_mul_f32_e32 v160, v26, v162
	v_mul_f32_e32 v160, 0xbfb8aa3b, v160
	v_min_f32_e32 v160, 0x42a00000, v160
	v_exp_f32_e32 v160, v160
	v_lshlrev_b32_e32 v161, 16, v147
	v_lshlrev_b32_e32 v152, 16, v153
	v_lshlrev_b32_e32 v164, 16, v149
	v_add_f32_e32 v160, 1.0, v160
	v_rcp_f32_e32 v160, v160
	v_and_b32_e32 v151, 0xffff0000, v151
	v_and_b32_e32 v147, 0xffff0000, v147
	v_mul_f32_e32 v165, v14, v162
	v_fmac_f32_e32 v156, v160, v163
	v_mul_f32_e32 v160, v35, v162
	v_mul_f32_e32 v160, 0xbfb8aa3b, v160
	v_min_f32_e32 v160, 0x42a00000, v160
	v_exp_f32_e32 v160, v160
	v_mul_f32_e32 v165, 0xbfb8aa3b, v165
	v_min_f32_e32 v165, 0x42a00000, v165
	v_exp_f32_e32 v165, v165
	v_add_f32_e32 v160, 1.0, v160
	v_rcp_f32_e32 v160, v160
	v_lshlrev_b64 v[158:159], 12, v[182:183]
	v_add_f32_e32 v165, 1.0, v165
	v_rcp_f32_e32 v165, v165
	v_fmac_f32_e32 v155, v160, v146
	v_mul_f32_e32 v146, v27, v162
	v_mul_f32_e32 v146, 0xbfb8aa3b, v146
	v_min_f32_e32 v146, 0x42a00000, v146
	v_exp_f32_e32 v146, v146
	v_and_b32_e32 v153, 0xffff0000, v153
	v_and_b32_e32 v149, 0xffff0000, v149
	v_lshl_add_u64 v[158:159], s[82:83], 0, v[158:159]
	v_add_f32_e32 v146, 1.0, v146
	v_rcp_f32_e32 v146, v146
	s_waitcnt vmcnt(2)
	v_lshlrev_b32_e32 v163, 16, v140
	v_and_b32_e32 v140, 0xffff0000, v140
	s_and_b64 vcc, exec, s[42:43]
	v_fmac_f32_e32 v157, v146, v148
	v_mul_f32_e32 v146, v36, v162
	v_mul_f32_e32 v146, 0xbfb8aa3b, v146
	v_min_f32_e32 v146, 0x42a00000, v146
	v_exp_f32_e32 v146, v146
	s_nop 0
	v_add_f32_e32 v146, 1.0, v146
	v_rcp_f32_e32 v146, v146
	s_nop 0
	v_fmac_f32_e32 v150, v146, v161
	v_mul_f32_e32 v146, v28, v162
	v_mul_f32_e32 v146, 0xbfb8aa3b, v146
	v_min_f32_e32 v146, 0x42a00000, v146
	v_exp_f32_e32 v146, v146
	v_lshl_add_u64 v[160:161], v[180:181], 1, v[158:159]
	v_and_b32_e32 v158, 0xffff0000, v142
	v_lshlrev_b32_e32 v159, 16, v139
	v_add_f32_e32 v146, 1.0, v146
	v_rcp_f32_e32 v146, v146
	v_and_b32_e32 v139, 0xffff0000, v139
	v_fmac_f32_e32 v152, v146, v164
	v_mul_f32_e32 v146, v37, v162
	v_mul_f32_e32 v146, 0xbfb8aa3b, v146
	v_min_f32_e32 v146, 0x42a00000, v146
	v_exp_f32_e32 v146, v146
	v_lshlrev_b32_e32 v164, 16, v141
	v_and_b32_e32 v141, 0xffff0000, v141
	v_add_f32_e32 v146, 1.0, v146
	v_rcp_f32_e32 v146, v146
	s_nop 0
	v_fmac_f32_e32 v151, v146, v147
	v_mul_f32_e32 v146, v29, v162
	v_mul_f32_e32 v146, 0xbfb8aa3b, v146
	v_min_f32_e32 v146, 0x42a00000, v146
	v_exp_f32_e32 v146, v146
	s_nop 0
	v_add_f32_e32 v146, 1.0, v146
	v_rcp_f32_e32 v146, v146
	s_nop 0
	v_fmac_f32_e32 v153, v146, v149
	v_cvt_pk_bf16_f32 v146, v154, v155
	v_cvt_pk_bf16_f32 v147, v150, v151
	v_cvt_pk_bf16_f32 v148, v156, v157
	v_cvt_pk_bf16_f32 v149, v152, v153
	global_store_dwordx4 v[160:161], v[146:149], off sc0 sc1
	s_nop 1
	v_lshlrev_b32_e32 v147, 16, v142
	v_lshlrev_b32_e32 v146, 16, v143
	v_and_b32_e32 v149, 0xffff0000, v143
	v_lshlrev_b32_e32 v143, 16, v144
	v_and_b32_e32 v148, 0xffff0000, v144
	v_lshlrev_b32_e32 v142, 16, v145
	v_and_b32_e32 v144, 0xffff0000, v145
	v_lshlrev_b32_e32 v145, 16, v138
	v_fmac_f32_e32 v147, v165, v145
	v_mul_f32_e32 v145, v10, v162
	v_mul_f32_e32 v145, 0xbfb8aa3b, v145
	v_min_f32_e32 v145, 0x42a00000, v145
	v_exp_f32_e32 v145, v145
	v_and_b32_e32 v138, 0xffff0000, v138
	v_add_f32_e32 v145, 1.0, v145
	v_rcp_f32_e32 v145, v145
	s_nop 0
	v_fmac_f32_e32 v143, v145, v163
	v_mul_f32_e32 v145, v15, v162
	v_mul_f32_e32 v145, 0xbfb8aa3b, v145
	v_min_f32_e32 v145, 0x42a00000, v145
	v_exp_f32_e32 v145, v145
	s_nop 0
	v_add_f32_e32 v145, 1.0, v145
	v_rcp_f32_e32 v145, v145
	s_nop 0
	v_fmac_f32_e32 v158, v145, v138
	v_mul_f32_e32 v138, v11, v162
	v_mul_f32_e32 v138, 0xbfb8aa3b, v138
	v_min_f32_e32 v138, 0x42a00000, v138
	v_exp_f32_e32 v138, v138
	s_nop 0
	v_add_f32_e32 v138, 1.0, v138
	v_rcp_f32_e32 v138, v138
	s_nop 0
	v_fmac_f32_e32 v148, v138, v140
	v_mul_f32_e32 v138, v16, v162
	v_mul_f32_e32 v138, 0xbfb8aa3b, v138
	v_min_f32_e32 v138, 0x42a00000, v138
	v_exp_f32_e32 v138, v138
	s_nop 0
	v_add_f32_e32 v138, 1.0, v138
	v_rcp_f32_e32 v138, v138
	s_nop 0
	v_fmac_f32_e32 v146, v138, v159
	v_mul_f32_e32 v138, v12, v162
	v_mul_f32_e32 v138, 0xbfb8aa3b, v138
	v_min_f32_e32 v138, 0x42a00000, v138
	v_exp_f32_e32 v138, v138
	s_nop 0
	v_add_f32_e32 v138, 1.0, v138
	v_rcp_f32_e32 v138, v138
	s_nop 0
	v_fmac_f32_e32 v142, v138, v164
	v_mul_f32_e32 v138, v17, v162
	v_mul_f32_e32 v138, 0xbfb8aa3b, v138
	v_min_f32_e32 v138, 0x42a00000, v138
	v_exp_f32_e32 v138, v138
	s_nop 0
	v_add_f32_e32 v138, 1.0, v138
	v_rcp_f32_e32 v138, v138
	s_nop 0
	v_fmac_f32_e32 v149, v138, v139
	v_mul_f32_e32 v138, v13, v162
	v_mul_f32_e32 v138, 0xbfb8aa3b, v138
	v_min_f32_e32 v138, 0x42a00000, v138
	v_exp_f32_e32 v138, v138
	s_nop 0
	v_add_f32_e32 v138, 1.0, v138
	v_rcp_f32_e32 v138, v138
	s_nop 0
	v_fmac_f32_e32 v144, v138, v141
	v_cvt_pk_bf16_f32 v138, v147, v158
	v_cvt_pk_bf16_f32 v139, v146, v149
	v_cvt_pk_bf16_f32 v140, v143, v148
	v_cvt_pk_bf16_f32 v141, v142, v144
	global_store_dwordx4 v[160:161], v[138:141], off offset:256 sc0 sc1
	s_cbranch_vccnz .LBB0_979
;     __device__ __forceinline__ void operator()(const f32x4 (&acc)[2][2][4][2], const Unit& u, int wr, int wc, int fr, int fq) const {
;     ...
;                         if (gain) q += ((o0[0] * o0[0] + o0[1] * o0[1]) + (o0[2] * o0[2] + o0[3] * o0[3])) + ((o1[0] * o1[0] + o1[1] * o1[1]) + (o1[2] * o1[2] + o1[3] * o1[3])); }
;                     if (gain) { q = fq_sum(q); if (fq == 0) lq[wc * 256 + ai * HALF + wr * 64 + m * 16 + fr] = q; } }
	s_nop 0
	v_mul_f32_e32 v138, v157, v157
	v_mul_f32_e32 v139, v153, v153
	v_fmac_f32_e32 v138, v156, v156
	v_fmac_f32_e32 v139, v152, v152
	v_add_f32_e32 v138, v138, v139
	v_mul_f32_e32 v139, v155, v155
	v_mul_f32_e32 v140, v151, v151
	v_fmac_f32_e32 v139, v154, v154
	v_fmac_f32_e32 v140, v150, v150
	v_add_f32_e32 v139, v139, v140
	v_add_f32_e32 v138, v139, v138
	v_mul_f32_e32 v139, v158, v158
	v_mul_f32_e32 v140, v149, v149
	v_fmac_f32_e32 v139, v147, v147
	v_fmac_f32_e32 v140, v146, v146
	v_add_f32_e32 v139, v139, v140
	v_mul_f32_e32 v140, v148, v148
	v_mul_f32_e32 v141, v144, v144
	v_fmac_f32_e32 v140, v143, v143
	v_fmac_f32_e32 v141, v142, v142
	v_add_f32_e32 v140, v140, v141
	v_add_f32_e32 v139, v139, v140
	v_add_f32_e32 v138, v138, v139
	ds_swizzle_b32 v139, v138 offset:swizzle(SWAP,16)
	s_waitcnt lgkmcnt(0)
	v_add_f32_e32 v138, v138, v139
	v_mov_b32_e32 v139, v138
	s_nop 1
	v_permlane32_swap_b32_e32 v138, v139
	s_and_saveexec_b64 s[12:13], s[40:41]
	s_cbranch_execz .LBB0_978
	v_readlane_b32 s2, v254, 50
	v_add_f32_e32 v138, v138, v139
	s_nop 0
	v_lshl_add_u32 v140, v186, 2, s2
	ds_write_b32 v140, v138 offset:704

; __device__ __forceinline__ u32x4 pack8(const f32x4& a, const f32x4& b) { u32x4 w; w.x = cvt_pk_bf16(a[0], a[1]); w.y = cvt_pk_bf16(a[2], a[3]); w.z = cvt_pk_bf16(b[0], b[1]); w.w = cvt_pk_bf16(b[2], b[3]); return w; }
; __device__ __forceinline__ float expneg(float g) { return ex2(fminf(-g * 1.4426950408889634f, 80.f)); }
;     __device__ __forceinline__ void sliver(const f32x4 (&accs)[2], const Unit& u, int srow0, int wr, int wc, int fr, int fq) const {
;         const int row = srow0 + 16 * u.pm + fr, col = u.pn * BM + wr * HALF + wc * 32 + 8 * fq; const size_t off = (size_t)row * 2048 + col; const float rs = row_rstd(ss3, row);
;         const u32x4 xw = *(const u32x4*)(X + off), pw = *(const u32x4*)(PP + off);
;         const f32x4 x0 = {bflo(xw.x), bfhi(xw.x), bflo(xw.y), bfhi(xw.y)}, x1 = {bflo(xw.z), bfhi(xw.z), bflo(xw.w), bfhi(xw.w)};
;         const f32x4 p0 = {bflo(pw.x), bfhi(pw.x), bflo(pw.y), bfhi(pw.y)}, p1 = {bflo(pw.z), bfhi(pw.z), bflo(pw.w), bfhi(pw.w)}; f32x4 o0, o1;
; #pragma unroll
;         for (int i = 0; i < 4; ++i) { o0[i] = x0[i] + p0[i] * __builtin_amdgcn_rcpf(1.f + expneg(accs[0][i] * rs)); o1[i] = x1[i] + p1[i] * __builtin_amdgcn_rcpf(1.f + expneg(accs[1][i] * rs)); }
;         *(u32x4*)(X + off) = pack8(o0, o1);
;         if (gain) { float q = ((o0[0] * o0[0] + o0[1] * o0[1]) + (o0[2] * o0[2] + o0[3] * o0[3])) + ((o1[0] * o1[0] + o1[1] * o1[1]) + (o1[2] * o1[2] + o1[3] * o1[3]));
;             q = fq_sum(q); if (fq == 0) lq[1024 + (wr * 4 + wc) * 16 + fr] = q; }
.LBB0_979:
	s_lshl_b32 s2, s52, 4
	s_addk_i32 s2, 0x2000
	v_readlane_b32 s3, v254, 62
	v_or_b32_e32 v138, s2, v186
	s_add_i32 s3, s3, s62
	v_or_b32_e32 v140, s3, v198
	v_ashrrev_i32_e32 v139, 31, v138
	v_lshlrev_b64 v[142:143], 11, v[138:139]
	v_ashrrev_i32_e32 v141, 31, v140
	v_lshl_add_u64 v[138:139], v[138:139], 4, s[86:87]
	v_lshl_add_u64 v[142:143], v[142:143], 0, v[140:141]
	global_load_dwordx4 v[138:141], v[138:139], off
	s_and_b64 vcc, exec, s[42:43]
	s_waitcnt vmcnt(0)
	v_lshlrev_b32_e32 v144, 16, v138
	v_and_b32_e32 v138, 0xffff0000, v138
	v_add_f32_e32 v138, v144, v138
	v_lshlrev_b32_e32 v144, 16, v139
	v_and_b32_e32 v139, 0xffff0000, v139
	v_add_f32_e32 v139, v144, v139
	v_add_f32_e32 v138, v138, v139
	v_lshlrev_b32_e32 v139, 16, v140
	v_and_b32_e32 v140, 0xffff0000, v140
	v_add_f32_e32 v139, v139, v140
	v_lshlrev_b32_e32 v140, 16, v141
	v_and_b32_e32 v141, 0xffff0000, v141
	v_add_f32_e32 v140, v140, v141
	v_add_f32_e32 v139, v139, v140
	v_add_f32_e32 v138, v138, v139
	v_fmamk_f32 v138, v138, 0x3a000000, v1
	v_lshlrev_b64 v[140:141], 1, v[142:143]
	v_rsq_f32_e32 v156, v138
	v_lshl_add_u64 v[138:139], s[82:83], 0, v[140:141]
	v_lshl_add_u64 v[140:141], s[84:85], 0, v[140:141]
	global_load_dwordx4 v[148:151], v[138:139], off
	global_load_dwordx4 v[152:155], v[140:141], off
	v_mul_f32_e32 v157, v6, v156
	v_mul_f32_e32 v157, 0xbfb8aa3b, v157
	v_min_f32_e32 v157, 0x42a00000, v157
	v_exp_f32_e32 v157, v157
	s_waitcnt vmcnt(1)
	v_lshlrev_b32_e32 v144, 16, v148
	v_add_f32_e32 v157, 1.0, v157
	v_rcp_f32_e32 v157, v157
	v_and_b32_e32 v147, 0xffff0000, v148
	s_waitcnt vmcnt(0)
	v_lshlrev_b32_e32 v148, 16, v152
	v_lshlrev_b32_e32 v142, 16, v149
	v_fmac_f32_e32 v144, v157, v148
	v_mul_f32_e32 v148, v2, v156
	v_mul_f32_e32 v148, 0xbfb8aa3b, v148
	v_min_f32_e32 v148, 0x42a00000, v148
	v_exp_f32_e32 v148, v148
	v_and_b32_e32 v146, 0xffff0000, v149
	v_lshlrev_b32_e32 v141, 16, v150
	v_and_b32_e32 v149, 0xffff0000, v152
	v_add_f32_e32 v148, 1.0, v148
	v_rcp_f32_e32 v148, v148
	v_lshlrev_b32_e32 v152, 16, v154
	v_and_b32_e32 v145, 0xffff0000, v150
	v_lshlrev_b32_e32 v140, 16, v151
	v_fmac_f32_e32 v141, v148, v152
	v_mul_f32_e32 v148, v7, v156
	v_mul_f32_e32 v148, 0xbfb8aa3b, v148
	v_min_f32_e32 v148, 0x42a00000, v148
	v_exp_f32_e32 v148, v148
	v_and_b32_e32 v143, 0xffff0000, v151
	v_lshlrev_b32_e32 v150, 16, v153
	v_and_b32_e32 v151, 0xffff0000, v153
	v_add_f32_e32 v148, 1.0, v148
	v_rcp_f32_e32 v148, v148
	v_and_b32_e32 v153, 0xffff0000, v154
	v_lshlrev_b32_e32 v154, 16, v155
	v_and_b32_e32 v155, 0xffff0000, v155
	v_fmac_f32_e32 v147, v148, v149
	v_mul_f32_e32 v148, v3, v156
	v_mul_f32_e32 v148, 0xbfb8aa3b, v148
	v_min_f32_e32 v148, 0x42a00000, v148
	v_exp_f32_e32 v148, v148
	s_nop 0
	v_add_f32_e32 v148, 1.0, v148
	v_rcp_f32_e32 v148, v148
	s_nop 0
	v_fmac_f32_e32 v145, v148, v153
	v_mul_f32_e32 v148, v8, v156
	v_mul_f32_e32 v148, 0xbfb8aa3b, v148
	v_min_f32_e32 v148, 0x42a00000, v148
	v_exp_f32_e32 v148, v148
	s_nop 0
	v_add_f32_e32 v148, 1.0, v148
	v_rcp_f32_e32 v148, v148
	s_nop 0
	v_fmac_f32_e32 v142, v148, v150
	v_mul_f32_e32 v148, v4, v156
	v_mul_f32_e32 v148, 0xbfb8aa3b, v148
	v_min_f32_e32 v148, 0x42a00000, v148
	v_exp_f32_e32 v148, v148
	s_nop 0
	v_add_f32_e32 v148, 1.0, v148
	v_rcp_f32_e32 v148, v148
	s_nop 0
	v_fmac_f32_e32 v140, v148, v154
	v_mul_f32_e32 v148, v9, v156
	v_mul_f32_e32 v148, 0xbfb8aa3b, v148
	v_min_f32_e32 v148, 0x42a00000, v148
	v_exp_f32_e32 v148, v148
	s_nop 0
	v_add_f32_e32 v148, 1.0, v148
	v_rcp_f32_e32 v148, v148
	s_nop 0
	v_fmac_f32_e32 v146, v148, v151
	v_mul_f32_e32 v148, v5, v156
	v_mul_f32_e32 v148, 0xbfb8aa3b, v148
	v_min_f32_e32 v148, 0x42a00000, v148
	v_exp_f32_e32 v148, v148
	s_nop 0
	v_add_f32_e32 v148, 1.0, v148
	v_rcp_f32_e32 v148, v148
	s_nop 0
	v_fmac_f32_e32 v143, v148, v155
	v_cvt_pk_bf16_f32 v148, v144, v147
	v_cvt_pk_bf16_f32 v149, v142, v146
	v_cvt_pk_bf16_f32 v150, v141, v145
	v_cvt_pk_bf16_f32 v151, v140, v143
	global_store_dwordx4 v[138:139], v[148:151], off sc0 sc1
	s_cbranch_vccnz .LBB0_983
	v_mul_f32_e32 v138, v147, v147
	v_mul_f32_e32 v139, v146, v146
	v_fmac_f32_e32 v138, v144, v144
	v_fmac_f32_e32 v139, v142, v142
	v_add_f32_e32 v138, v138, v139
	v_mul_f32_e32 v139, v145, v145
	v_fmac_f32_e32 v139, v141, v141
	v_mul_f32_e32 v141, v143, v143
	v_fmac_f32_e32 v141, v140, v140
	v_add_f32_e32 v139, v139, v141
	v_add_f32_e32 v138, v139, v138
	ds_swizzle_b32 v139, v138 offset:swizzle(SWAP,16)
	s_waitcnt lgkmcnt(0)
	v_add_f32_e32 v138, v138, v139
	v_mov_b32_e32 v139, v138
	s_nop 1
	v_permlane32_swap_b32_e32 v138, v139
	s_and_saveexec_b64 s[12:13], s[40:41]
	s_cbranch_execz .LBB0_982
	v_readlane_b32 s3, v252, 13
	v_add_f32_e32 v138, v138, v139
	s_nop 0
	v_lshl_add_u32 v140, v186, 2, s3
	ds_write_b32 v140, v138 offset:4096
